# saddr-addressed st_bf16 epilogues for MT3 UP/XQ/QA/QB + batched rel-bias LDS lookups + pipelined MT2 K-loops (all 9)
# speedup vs baseline: 1.1439x; 1.0086x over previous
; #define MFMA32(a, b, c) __builtin_amdgcn_mfma_f32_32x32x16_f16((a), (b), (c), 0, 0, 0)
; template <int K, class Epi>
; DI void gemm64_res(const bf16_t* A, int lda, const bf16_t* Wp, int NU, unsigned char* lds, const Epi& epi) {
;     ...
;     const unsigned char* ab = lds + r * LD + 16 * h;
; #pragma unroll 1
;     for (int unit = wave; unit < NU; unit += NWAVE) {
;         const u32x4* bp = Bw + (size_t)(unit * NT) * 64 + lane;
;         f32x16 acc[2][NT];
; #pragma unroll
;         for (int mi = 0; mi < 2; ++mi)
; #pragma unroll
;             for (int nj = 0; nj < NT; ++nj)
; #pragma unroll
;                 for (int i = 0; i < 16; ++i) acc[mi][nj][i] = 0.f;
;         u32x4 bq[PD][NT];
; #pragma unroll
;         for (int s = 0; s < PD; ++s)
; #pragma unroll
;             for (int j = 0; j < NT; ++j) bq[s][j] = bp[(size_t)((s + rot) & (KS - 1)) * kstr + j * 64];
; #pragma unroll 1
;         for (int kk = 0; kk < KS; kk += PD) {
; #pragma unroll
;             for (int s = 0; s < PD; ++s) {
;                 const int ks = kk + s, ksr = (ks + rot) & (KS - 1);
;                 const bf16x8 a0 = *(const bf16x8*)(ab + ksr * 32), a1 = *(const bf16x8*)(ab + 32 * LD + ksr * 32);
; #pragma unroll
;                 for (int j = 0; j < NT; ++j) { acc[0][j] = MFMA32(a0, __builtin_bit_cast(bf16x8, bq[s][j]), acc[0][j]); acc[1][j] = MFMA32(a1, __builtin_bit_cast(bf16x8, bq[s][j]), acc[1][j]); }
;                 int nk = ks + PD; nk = nk < KS ? nk : KS - 1; nk = (nk + rot) & (KS - 1);
; #pragma unroll
;                 for (int j = 0; j < NT; ++j) bq[s][j] = bp[(size_t)nk * kstr + j * 64];
;             }
.LBB0_211:
	s_lshl_b32 s28, s13, 1
	s_ashr_i32 s29, s28, 31
	s_lshl_b64 s[28:29], s[28:29], 10
	v_lshl_add_u64 v[68:69], v[66:67], 0, s[28:29]
	s_mov_b32 s11, s5
	v_lshl_add_u64 v[0:1], v[68:69], 0, s[10:11]
	s_mov_b64 s[28:29], 0x22400
	v_lshl_add_u64 v[70:71], v[0:1], 0, s[28:29]
	v_mov_b32_e32 v0, 0
	s_mov_b32 s59, -4
	s_mov_b32 s11, s50
	s_mov_b32 s61, s49
	s_mov_b32 s60, s48
	s_mov_b32 s28, s47
	s_mov_b32 s29, s45
	v_mov_b32_e32 v1, v0
	v_mov_b32_e32 v2, v0
	v_mov_b32_e32 v3, v0
	v_mov_b32_e32 v4, v0
	v_mov_b32_e32 v5, v0
	v_mov_b32_e32 v6, v0
	v_mov_b32_e32 v7, v0
	v_mov_b32_e32 v8, v0
	v_mov_b32_e32 v9, v0
	v_mov_b32_e32 v10, v0
	v_mov_b32_e32 v11, v0
	v_mov_b32_e32 v12, v0
	v_mov_b32_e32 v13, v0
	v_mov_b32_e32 v14, v0
	v_mov_b32_e32 v15, v0
	v_mov_b32_e32 v16, v0
	v_mov_b32_e32 v17, v0
	v_mov_b32_e32 v18, v0
	v_mov_b32_e32 v19, v0
	v_mov_b32_e32 v20, v0
	v_mov_b32_e32 v21, v0
	v_mov_b32_e32 v22, v0
	v_mov_b32_e32 v23, v0
	v_mov_b32_e32 v24, v0
	v_mov_b32_e32 v25, v0
	v_mov_b32_e32 v26, v0
	v_mov_b32_e32 v27, v0
	v_mov_b32_e32 v28, v0
	v_mov_b32_e32 v29, v0
	v_mov_b32_e32 v30, v0
	v_mov_b32_e32 v31, v0
	v_mov_b32_e32 v32, v0
	v_mov_b32_e32 v33, v0
	v_mov_b32_e32 v34, v0
	v_mov_b32_e32 v35, v0
	v_mov_b32_e32 v36, v0
	v_mov_b32_e32 v37, v0
	v_mov_b32_e32 v38, v0
	v_mov_b32_e32 v39, v0
	v_mov_b32_e32 v40, v0
	v_mov_b32_e32 v41, v0
	v_mov_b32_e32 v42, v0
	v_mov_b32_e32 v43, v0
	v_mov_b32_e32 v44, v0
	v_mov_b32_e32 v45, v0
	v_mov_b32_e32 v46, v0
	v_mov_b32_e32 v47, v0
	v_mov_b32_e32 v48, v0
	v_mov_b32_e32 v49, v0
	v_mov_b32_e32 v50, v0
	v_mov_b32_e32 v51, v0
	v_mov_b32_e32 v52, v0
	v_mov_b32_e32 v53, v0
	v_mov_b32_e32 v54, v0
	v_mov_b32_e32 v55, v0
	v_mov_b32_e32 v56, v0
	v_mov_b32_e32 v57, v0
	v_mov_b32_e32 v58, v0
	v_mov_b32_e32 v59, v0
	v_mov_b32_e32 v60, v0
	v_mov_b32_e32 v61, v0
	v_mov_b32_e32 v62, v0
	v_mov_b32_e32 v63, v0
	s_add_i32 s4, s46, -4
	s_mov_b32 s101, 0
	s_mov_b32 s28, s4
	s_and_b32 s29, s28, 63
	s_add_i32 s28, s28, 1
	s_mul_i32 s100, s29, 0x22000
	v_lshl_add_u64 v[102:103], v[68:69], 0, s[100:101]
	global_load_dwordx4 v[104:107], v[102:103], off
	global_load_dwordx4 v[108:111], v[102:103], off offset:1024
	s_and_b32 s29, s28, 63
	s_add_i32 s28, s28, 1
	s_mul_i32 s100, s29, 0x22000
	v_lshl_add_u64 v[102:103], v[68:69], 0, s[100:101]
	global_load_dwordx4 v[116:119], v[102:103], off
	global_load_dwordx4 v[120:123], v[102:103], off offset:1024
	s_and_b32 s29, s28, 63
	s_add_i32 s28, s28, 1
	s_mul_i32 s100, s29, 0x22000
	v_lshl_add_u64 v[102:103], v[68:69], 0, s[100:101]
	global_load_dwordx4 v[124:127], v[102:103], off
	global_load_dwordx4 v[128:131], v[102:103], off offset:1024
	s_and_b32 s29, s28, 63
	s_add_i32 s28, s28, 1
	s_mul_i32 s100, s29, 0x22000
	v_lshl_add_u64 v[102:103], v[68:69], 0, s[100:101]
	global_load_dwordx4 v[132:135], v[102:103], off
	global_load_dwordx4 v[136:139], v[102:103], off offset:1024
	s_and_b32 s29, s28, 63
	s_add_i32 s28, s28, 1
	s_mul_i32 s100, s29, 0x22000
	v_lshl_add_u64 v[102:103], v[68:69], 0, s[100:101]
	global_load_dwordx4 v[140:143], v[102:103], off
	global_load_dwordx4 v[144:147], v[102:103], off offset:1024
	s_and_b32 s29, s28, 63
	s_add_i32 s28, s28, 1
	s_mul_i32 s100, s29, 0x22000
	v_lshl_add_u64 v[102:103], v[68:69], 0, s[100:101]
	global_load_dwordx4 v[148:151], v[102:103], off
	global_load_dwordx4 v[152:155], v[102:103], off offset:1024
	s_and_b32 s29, s28, 63
	s_add_i32 s28, s28, 1
	s_mul_i32 s100, s29, 0x22000
	v_lshl_add_u64 v[102:103], v[68:69], 0, s[100:101]
	global_load_dwordx4 v[156:159], v[102:103], off
	global_load_dwordx4 v[160:163], v[102:103], off offset:1024
	s_and_b32 s29, s28, 63
	s_add_i32 s28, s28, 1
	s_mul_i32 s100, s29, 0x22000
	v_lshl_add_u64 v[102:103], v[68:69], 0, s[100:101]
	global_load_dwordx4 v[164:167], v[102:103], off
	global_load_dwordx4 v[168:171], v[102:103], off offset:1024
	s_mov_b32 s11, s4
	s_and_b32 s29, s11, 63
	s_lshl_b32 s29, s29, 5
	s_add_i32 s11, s11, 1
	v_add_u32_e32 v64, s29, v100
	v_add_u32_e32 v112, s29, v101
	ds_read_b128 v[172:175], v64
	ds_read_b128 v[180:183], v112
	s_mov_b32 s59, 7
.Lka0_loop:
	s_and_b32 s29, s11, 63
	s_lshl_b32 s29, s29, 5
	s_add_i32 s11, s11, 1
	v_add_u32_e32 v64, s29, v100
	v_add_u32_e32 v112, s29, v101
	ds_read_b128 v[184:187], v64
	ds_read_b128 v[188:191], v112
	s_waitcnt vmcnt(15) lgkmcnt(2)
	v_mfma_f32_32x32x16_f16 v[48:63], v[172:175], v[104:107], v[48:63]
	v_mfma_f32_32x32x16_f16 v[16:31], v[180:183], v[104:107], v[16:31]
	s_waitcnt vmcnt(14)
	v_mfma_f32_32x32x16_f16 v[32:47], v[172:175], v[108:111], v[32:47]
	v_mfma_f32_32x32x16_f16 v[0:15], v[180:183], v[108:111], v[0:15]
	s_and_b32 s29, s28, 63
	s_add_i32 s28, s28, 1
	s_mul_i32 s100, s29, 0x22000
	v_lshl_add_u64 v[102:103], v[68:69], 0, s[100:101]
	global_load_dwordx4 v[104:107], v[102:103], off
	global_load_dwordx4 v[108:111], v[102:103], off offset:1024
	s_and_b32 s29, s11, 63
	s_lshl_b32 s29, s29, 5
	s_add_i32 s11, s11, 1
	v_add_u32_e32 v64, s29, v100
	v_add_u32_e32 v112, s29, v101
	ds_read_b128 v[172:175], v64
	ds_read_b128 v[180:183], v112
	s_waitcnt vmcnt(15) lgkmcnt(2)
	v_mfma_f32_32x32x16_f16 v[48:63], v[184:187], v[116:119], v[48:63]
	v_mfma_f32_32x32x16_f16 v[16:31], v[188:191], v[116:119], v[16:31]
	s_waitcnt vmcnt(14)
	v_mfma_f32_32x32x16_f16 v[32:47], v[184:187], v[120:123], v[32:47]
	v_mfma_f32_32x32x16_f16 v[0:15], v[188:191], v[120:123], v[0:15]
	s_and_b32 s29, s28, 63
	s_add_i32 s28, s28, 1
	s_mul_i32 s100, s29, 0x22000
	v_lshl_add_u64 v[102:103], v[68:69], 0, s[100:101]
	global_load_dwordx4 v[116:119], v[102:103], off
	global_load_dwordx4 v[120:123], v[102:103], off offset:1024
	s_and_b32 s29, s11, 63
	s_lshl_b32 s29, s29, 5
	s_add_i32 s11, s11, 1
	v_add_u32_e32 v64, s29, v100
	v_add_u32_e32 v112, s29, v101
	ds_read_b128 v[184:187], v64
	ds_read_b128 v[188:191], v112
	s_waitcnt vmcnt(15) lgkmcnt(2)
; #define MFMA32(a, b, c) __builtin_amdgcn_mfma_f32_32x32x16_f16((a), (b), (c), 0, 0, 0)
; template <int K, class Epi>
; DI void gemm64_res(const bf16_t* A, int lda, const bf16_t* Wp, int NU, unsigned char* lds, const Epi& epi) {
;     ...
;         for (int kk = 0; kk < KS; kk += PD) {
; #pragma unroll
;             for (int s = 0; s < PD; ++s) {
;                 const int ks = kk + s, ksr = (ks + rot) & (KS - 1);
;                 const bf16x8 a0 = *(const bf16x8*)(ab + ksr * 32), a1 = *(const bf16x8*)(ab + 32 * LD + ksr * 32);
; #pragma unroll
;                 for (int j = 0; j < NT; ++j) { acc[0][j] = MFMA32(a0, __builtin_bit_cast(bf16x8, bq[s][j]), acc[0][j]); acc[1][j] = MFMA32(a1, __builtin_bit_cast(bf16x8, bq[s][j]), acc[1][j]); }
;                 int nk = ks + PD; nk = nk < KS ? nk : KS - 1; nk = (nk + rot) & (KS - 1);
; #pragma unroll
;                 for (int j = 0; j < NT; ++j) bq[s][j] = bp[(size_t)nk * kstr + j * 64];
;             }
	v_mfma_f32_32x32x16_f16 v[48:63], v[172:175], v[124:127], v[48:63]
	v_mfma_f32_32x32x16_f16 v[16:31], v[180:183], v[124:127], v[16:31]
	s_waitcnt vmcnt(14)
	v_mfma_f32_32x32x16_f16 v[32:47], v[172:175], v[128:131], v[32:47]
	v_mfma_f32_32x32x16_f16 v[0:15], v[180:183], v[128:131], v[0:15]
	s_and_b32 s29, s28, 63
	s_add_i32 s28, s28, 1
	s_mul_i32 s100, s29, 0x22000
	v_lshl_add_u64 v[102:103], v[68:69], 0, s[100:101]
	global_load_dwordx4 v[124:127], v[102:103], off
	global_load_dwordx4 v[128:131], v[102:103], off offset:1024
	s_and_b32 s29, s11, 63
	s_lshl_b32 s29, s29, 5
	s_add_i32 s11, s11, 1
	v_add_u32_e32 v64, s29, v100
	v_add_u32_e32 v112, s29, v101
	ds_read_b128 v[172:175], v64
	ds_read_b128 v[180:183], v112
	s_waitcnt vmcnt(15) lgkmcnt(2)
	v_mfma_f32_32x32x16_f16 v[48:63], v[184:187], v[132:135], v[48:63]
	v_mfma_f32_32x32x16_f16 v[16:31], v[188:191], v[132:135], v[16:31]
	s_waitcnt vmcnt(14)
	v_mfma_f32_32x32x16_f16 v[32:47], v[184:187], v[136:139], v[32:47]
	v_mfma_f32_32x32x16_f16 v[0:15], v[188:191], v[136:139], v[0:15]
	s_and_b32 s29, s28, 63
	s_add_i32 s28, s28, 1
	s_mul_i32 s100, s29, 0x22000
	v_lshl_add_u64 v[102:103], v[68:69], 0, s[100:101]
	global_load_dwordx4 v[132:135], v[102:103], off
	global_load_dwordx4 v[136:139], v[102:103], off offset:1024
	s_and_b32 s29, s11, 63
	s_lshl_b32 s29, s29, 5
	s_add_i32 s11, s11, 1
	v_add_u32_e32 v64, s29, v100
	v_add_u32_e32 v112, s29, v101
	ds_read_b128 v[184:187], v64
	ds_read_b128 v[188:191], v112
	s_waitcnt vmcnt(15) lgkmcnt(2)
	v_mfma_f32_32x32x16_f16 v[48:63], v[172:175], v[140:143], v[48:63]
	v_mfma_f32_32x32x16_f16 v[16:31], v[180:183], v[140:143], v[16:31]
	s_waitcnt vmcnt(14)
	v_mfma_f32_32x32x16_f16 v[32:47], v[172:175], v[144:147], v[32:47]
	v_mfma_f32_32x32x16_f16 v[0:15], v[180:183], v[144:147], v[0:15]
	s_and_b32 s29, s28, 63
	s_add_i32 s28, s28, 1
	s_mul_i32 s100, s29, 0x22000
	v_lshl_add_u64 v[102:103], v[68:69], 0, s[100:101]
	global_load_dwordx4 v[140:143], v[102:103], off
	global_load_dwordx4 v[144:147], v[102:103], off offset:1024
	s_and_b32 s29, s11, 63
	s_lshl_b32 s29, s29, 5
	s_add_i32 s11, s11, 1
	v_add_u32_e32 v64, s29, v100
	v_add_u32_e32 v112, s29, v101
	ds_read_b128 v[172:175], v64
	ds_read_b128 v[180:183], v112
	s_waitcnt vmcnt(15) lgkmcnt(2)
	v_mfma_f32_32x32x16_f16 v[48:63], v[184:187], v[148:151], v[48:63]
	v_mfma_f32_32x32x16_f16 v[16:31], v[188:191], v[148:151], v[16:31]
	s_waitcnt vmcnt(14)
	v_mfma_f32_32x32x16_f16 v[32:47], v[184:187], v[152:155], v[32:47]
	v_mfma_f32_32x32x16_f16 v[0:15], v[188:191], v[152:155], v[0:15]
	s_and_b32 s29, s28, 63
	s_add_i32 s28, s28, 1
	s_mul_i32 s100, s29, 0x22000
	v_lshl_add_u64 v[102:103], v[68:69], 0, s[100:101]
	global_load_dwordx4 v[148:151], v[102:103], off
	global_load_dwordx4 v[152:155], v[102:103], off offset:1024
	s_and_b32 s29, s11, 63
	s_lshl_b32 s29, s29, 5
	s_add_i32 s11, s11, 1
	v_add_u32_e32 v64, s29, v100
	v_add_u32_e32 v112, s29, v101
	ds_read_b128 v[184:187], v64
	ds_read_b128 v[188:191], v112
	s_waitcnt vmcnt(15) lgkmcnt(2)
	v_mfma_f32_32x32x16_f16 v[48:63], v[172:175], v[156:159], v[48:63]
	v_mfma_f32_32x32x16_f16 v[16:31], v[180:183], v[156:159], v[16:31]
	s_waitcnt vmcnt(14)
	v_mfma_f32_32x32x16_f16 v[32:47], v[172:175], v[160:163], v[32:47]
	v_mfma_f32_32x32x16_f16 v[0:15], v[180:183], v[160:163], v[0:15]
	s_and_b32 s29, s28, 63
	s_add_i32 s28, s28, 1
	s_mul_i32 s100, s29, 0x22000
	v_lshl_add_u64 v[102:103], v[68:69], 0, s[100:101]
	global_load_dwordx4 v[156:159], v[102:103], off
	global_load_dwordx4 v[160:163], v[102:103], off offset:1024
	s_and_b32 s29, s11, 63
	s_lshl_b32 s29, s29, 5
	s_add_i32 s11, s11, 1
	v_add_u32_e32 v64, s29, v100
	v_add_u32_e32 v112, s29, v101
	ds_read_b128 v[172:175], v64
	ds_read_b128 v[180:183], v112
	s_waitcnt vmcnt(15) lgkmcnt(2)
	v_mfma_f32_32x32x16_f16 v[48:63], v[184:187], v[164:167], v[48:63]
	v_mfma_f32_32x32x16_f16 v[16:31], v[188:191], v[164:167], v[16:31]
	s_waitcnt vmcnt(14)
	v_mfma_f32_32x32x16_f16 v[32:47], v[184:187], v[168:171], v[32:47]
	v_mfma_f32_32x32x16_f16 v[0:15], v[188:191], v[168:171], v[0:15]
	s_and_b32 s29, s28, 63
	s_add_i32 s28, s28, 1
	s_mul_i32 s100, s29, 0x22000
	v_lshl_add_u64 v[102:103], v[68:69], 0, s[100:101]
	global_load_dwordx4 v[164:167], v[102:103], off
	global_load_dwordx4 v[168:171], v[102:103], off offset:1024
	s_add_i32 s59, s59, -1
	s_cmp_lg_u32 s59, 0
	s_cbranch_scc1 .Lka0_loop
; #define MFMA32(a, b, c) __builtin_amdgcn_mfma_f32_32x32x16_f16((a), (b), (c), 0, 0, 0)
; template <int K, class Epi>
; DI void gemm64_res(const bf16_t* A, int lda, const bf16_t* Wp, int NU, unsigned char* lds, const Epi& epi) {
;     ...
;         for (int kk = 0; kk < KS; kk += PD) {
; #pragma unroll
;             for (int s = 0; s < PD; ++s) {
;                 const int ks = kk + s, ksr = (ks + rot) & (KS - 1);
;                 const bf16x8 a0 = *(const bf16x8*)(ab + ksr * 32), a1 = *(const bf16x8*)(ab + 32 * LD + ksr * 32);
; #pragma unroll
;                 for (int j = 0; j < NT; ++j) { acc[0][j] = MFMA32(a0, __builtin_bit_cast(bf16x8, bq[s][j]), acc[0][j]); acc[1][j] = MFMA32(a1, __builtin_bit_cast(bf16x8, bq[s][j]), acc[1][j]); }
;                 int nk = ks + PD; nk = nk < KS ? nk : KS - 1; nk = (nk + rot) & (KS - 1);
; #pragma unroll
;                 for (int j = 0; j < NT; ++j) bq[s][j] = bp[(size_t)nk * kstr + j * 64];
;             }
;         }
;         epi(unit, acc);
	s_and_b32 s29, s11, 63
	s_lshl_b32 s29, s29, 5
	s_add_i32 s11, s11, 1
	v_add_u32_e32 v64, s29, v100
	v_add_u32_e32 v112, s29, v101
	ds_read_b128 v[184:187], v64
	ds_read_b128 v[188:191], v112
	s_waitcnt vmcnt(15) lgkmcnt(2)
	v_mfma_f32_32x32x16_f16 v[48:63], v[172:175], v[104:107], v[48:63]
	v_mfma_f32_32x32x16_f16 v[16:31], v[180:183], v[104:107], v[16:31]
	s_waitcnt vmcnt(14)
	v_mfma_f32_32x32x16_f16 v[32:47], v[172:175], v[108:111], v[32:47]
	v_mfma_f32_32x32x16_f16 v[0:15], v[180:183], v[108:111], v[0:15]
	s_and_b32 s29, s11, 63
	s_lshl_b32 s29, s29, 5
	s_add_i32 s11, s11, 1
	v_add_u32_e32 v64, s29, v100
	v_add_u32_e32 v112, s29, v101
	ds_read_b128 v[172:175], v64
	ds_read_b128 v[180:183], v112
	s_waitcnt vmcnt(13) lgkmcnt(2)
	v_mfma_f32_32x32x16_f16 v[48:63], v[184:187], v[116:119], v[48:63]
	v_mfma_f32_32x32x16_f16 v[16:31], v[188:191], v[116:119], v[16:31]
	s_waitcnt vmcnt(12)
	v_mfma_f32_32x32x16_f16 v[32:47], v[184:187], v[120:123], v[32:47]
	v_mfma_f32_32x32x16_f16 v[0:15], v[188:191], v[120:123], v[0:15]
	s_and_b32 s29, s11, 63
	s_lshl_b32 s29, s29, 5
	s_add_i32 s11, s11, 1
	v_add_u32_e32 v64, s29, v100
	v_add_u32_e32 v112, s29, v101
	ds_read_b128 v[184:187], v64
	ds_read_b128 v[188:191], v112
	s_waitcnt vmcnt(11) lgkmcnt(2)
	v_mfma_f32_32x32x16_f16 v[48:63], v[172:175], v[124:127], v[48:63]
	v_mfma_f32_32x32x16_f16 v[16:31], v[180:183], v[124:127], v[16:31]
	s_waitcnt vmcnt(10)
	v_mfma_f32_32x32x16_f16 v[32:47], v[172:175], v[128:131], v[32:47]
	v_mfma_f32_32x32x16_f16 v[0:15], v[180:183], v[128:131], v[0:15]
	s_and_b32 s29, s11, 63
	s_lshl_b32 s29, s29, 5
	s_add_i32 s11, s11, 1
	v_add_u32_e32 v64, s29, v100
	v_add_u32_e32 v112, s29, v101
	ds_read_b128 v[172:175], v64
	ds_read_b128 v[180:183], v112
	s_waitcnt vmcnt(9) lgkmcnt(2)
	v_mfma_f32_32x32x16_f16 v[48:63], v[184:187], v[132:135], v[48:63]
	v_mfma_f32_32x32x16_f16 v[16:31], v[188:191], v[132:135], v[16:31]
	s_waitcnt vmcnt(8)
	v_mfma_f32_32x32x16_f16 v[32:47], v[184:187], v[136:139], v[32:47]
	v_mfma_f32_32x32x16_f16 v[0:15], v[188:191], v[136:139], v[0:15]
	s_and_b32 s29, s11, 63
	s_lshl_b32 s29, s29, 5
	s_add_i32 s11, s11, 1
	v_add_u32_e32 v64, s29, v100
	v_add_u32_e32 v112, s29, v101
	ds_read_b128 v[184:187], v64
	ds_read_b128 v[188:191], v112
	s_waitcnt vmcnt(7) lgkmcnt(2)
	v_mfma_f32_32x32x16_f16 v[48:63], v[172:175], v[140:143], v[48:63]
	v_mfma_f32_32x32x16_f16 v[16:31], v[180:183], v[140:143], v[16:31]
	s_waitcnt vmcnt(6)
	v_mfma_f32_32x32x16_f16 v[32:47], v[172:175], v[144:147], v[32:47]
	v_mfma_f32_32x32x16_f16 v[0:15], v[180:183], v[144:147], v[0:15]
	s_and_b32 s29, s11, 63
	s_lshl_b32 s29, s29, 5
	s_add_i32 s11, s11, 1
	v_add_u32_e32 v64, s29, v100
	v_add_u32_e32 v112, s29, v101
	ds_read_b128 v[172:175], v64
	ds_read_b128 v[180:183], v112
	s_waitcnt vmcnt(5) lgkmcnt(2)
	v_mfma_f32_32x32x16_f16 v[48:63], v[184:187], v[148:151], v[48:63]
	v_mfma_f32_32x32x16_f16 v[16:31], v[188:191], v[148:151], v[16:31]
	s_waitcnt vmcnt(4)
	v_mfma_f32_32x32x16_f16 v[32:47], v[184:187], v[152:155], v[32:47]
	v_mfma_f32_32x32x16_f16 v[0:15], v[188:191], v[152:155], v[0:15]
	s_and_b32 s29, s11, 63
	s_lshl_b32 s29, s29, 5
	s_add_i32 s11, s11, 1
	v_add_u32_e32 v64, s29, v100
	v_add_u32_e32 v112, s29, v101
	ds_read_b128 v[184:187], v64
	ds_read_b128 v[188:191], v112
	s_waitcnt vmcnt(3) lgkmcnt(2)
	v_mfma_f32_32x32x16_f16 v[48:63], v[172:175], v[156:159], v[48:63]
	v_mfma_f32_32x32x16_f16 v[16:31], v[180:183], v[156:159], v[16:31]
	s_waitcnt vmcnt(2)
	v_mfma_f32_32x32x16_f16 v[32:47], v[172:175], v[160:163], v[32:47]
	v_mfma_f32_32x32x16_f16 v[0:15], v[180:183], v[160:163], v[0:15]
	s_waitcnt vmcnt(1) lgkmcnt(0)
	v_mfma_f32_32x32x16_f16 v[48:63], v[184:187], v[164:167], v[48:63]
	v_mfma_f32_32x32x16_f16 v[16:31], v[188:191], v[164:167], v[16:31]
	s_waitcnt vmcnt(0)
	v_mfma_f32_32x32x16_f16 v[32:47], v[184:187], v[168:171], v[32:47]
	v_mfma_f32_32x32x16_f16 v[0:15], v[188:191], v[168:171], v[0:15]
	s_nop 7
	s_nop 3
	s_cmp_gt_i32 s13, 7
	s_mov_b64 s[28:29], -1
	s_cbranch_scc1 .LBB0_215
	s_andn2_b64 vcc, exec, s[28:29]
	s_cbranch_vccnz .LBB0_210
	s_branch .LBB0_240

; #define MFMA32(a, b, c) __builtin_amdgcn_mfma_f32_32x32x16_f16((a), (b), (c), 0, 0, 0)
; template <int K, class Epi>
; DI void gemm64_res(const bf16_t* A, int lda, const bf16_t* Wp, int NU, unsigned char* lds, const Epi& epi) {
;     ...
;     for (int unit = wave; unit < NU; unit += NWAVE) {
;         const u32x4* bp = Bw + (size_t)(unit * NT) * 64 + lane;
;         f32x16 acc[2][NT];
; #pragma unroll
;         for (int mi = 0; mi < 2; ++mi)
; #pragma unroll
;             for (int nj = 0; nj < NT; ++nj)
; #pragma unroll
;                 for (int i = 0; i < 16; ++i) acc[mi][nj][i] = 0.f;
;         u32x4 bq[PD][NT];
; #pragma unroll
;         for (int s = 0; s < PD; ++s)
; #pragma unroll
;             for (int j = 0; j < NT; ++j) bq[s][j] = bp[(size_t)((s + rot) & (KS - 1)) * kstr + j * 64];
; #pragma unroll 1
;         for (int kk = 0; kk < KS; kk += PD) {
; #pragma unroll
;             for (int s = 0; s < PD; ++s) {
;                 const int ks = kk + s, ksr = (ks + rot) & (KS - 1);
;                 const bf16x8 a0 = *(const bf16x8*)(ab + ksr * 32), a1 = *(const bf16x8*)(ab + 32 * LD + ksr * 32);
; #pragma unroll
;                 for (int j = 0; j < NT; ++j) { acc[0][j] = MFMA32(a0, __builtin_bit_cast(bf16x8, bq[s][j]), acc[0][j]); acc[1][j] = MFMA32(a1, __builtin_bit_cast(bf16x8, bq[s][j]), acc[1][j]); }
;                 int nk = ks + PD; nk = nk < KS ? nk : KS - 1; nk = (nk + rot) & (KS - 1);
; #pragma unroll
;                 for (int j = 0; j < NT; ++j) bq[s][j] = bp[(size_t)nk * kstr + j * 64];
;             }
.LBB0_248:
	s_lshl_b32 s12, s35, 1
	s_ashr_i32 s13, s12, 31
	s_lshl_b64 s[12:13], s[12:13], 10
	v_lshl_add_u64 v[68:69], v[66:67], 0, s[12:13]
	s_mov_b32 s19, s1
	v_lshl_add_u64 v[0:1], v[68:69], 0, s[18:19]
	s_mov_b64 s[12:13], 0x4400
	v_lshl_add_u64 v[70:71], v[0:1], 0, s[12:13]
	v_mov_b32_e32 v0, 0
	s_mov_b32 s38, -4
	s_mov_b32 s19, s31
	s_mov_b32 s39, s30
	s_mov_b32 s12, s29
	s_mov_b32 s14, s28
	s_mov_b32 s16, s27
	v_mov_b32_e32 v1, v0
	v_mov_b32_e32 v2, v0
	v_mov_b32_e32 v3, v0
	v_mov_b32_e32 v4, v0
	v_mov_b32_e32 v5, v0
	v_mov_b32_e32 v6, v0
	v_mov_b32_e32 v7, v0
	v_mov_b32_e32 v8, v0
	v_mov_b32_e32 v9, v0
	v_mov_b32_e32 v10, v0
	v_mov_b32_e32 v11, v0
	v_mov_b32_e32 v12, v0
	v_mov_b32_e32 v13, v0
	v_mov_b32_e32 v14, v0
	v_mov_b32_e32 v15, v0
	v_mov_b32_e32 v16, v0
	v_mov_b32_e32 v17, v0
	v_mov_b32_e32 v18, v0
	v_mov_b32_e32 v19, v0
	v_mov_b32_e32 v20, v0
	v_mov_b32_e32 v21, v0
	v_mov_b32_e32 v22, v0
	v_mov_b32_e32 v23, v0
	v_mov_b32_e32 v24, v0
	v_mov_b32_e32 v25, v0
	v_mov_b32_e32 v26, v0
	v_mov_b32_e32 v27, v0
	v_mov_b32_e32 v28, v0
	v_mov_b32_e32 v29, v0
	v_mov_b32_e32 v30, v0
	v_mov_b32_e32 v31, v0
	v_mov_b32_e32 v32, v0
	v_mov_b32_e32 v33, v0
	v_mov_b32_e32 v34, v0
	v_mov_b32_e32 v35, v0
	v_mov_b32_e32 v36, v0
	v_mov_b32_e32 v37, v0
	v_mov_b32_e32 v38, v0
	v_mov_b32_e32 v39, v0
	v_mov_b32_e32 v40, v0
	v_mov_b32_e32 v41, v0
	v_mov_b32_e32 v42, v0
	v_mov_b32_e32 v43, v0
	v_mov_b32_e32 v44, v0
	v_mov_b32_e32 v45, v0
	v_mov_b32_e32 v46, v0
	v_mov_b32_e32 v47, v0
	v_mov_b32_e32 v48, v0
	v_mov_b32_e32 v49, v0
	v_mov_b32_e32 v50, v0
	v_mov_b32_e32 v51, v0
	v_mov_b32_e32 v52, v0
	v_mov_b32_e32 v53, v0
	v_mov_b32_e32 v54, v0
	v_mov_b32_e32 v55, v0
	v_mov_b32_e32 v56, v0
	v_mov_b32_e32 v57, v0
	v_mov_b32_e32 v58, v0
	v_mov_b32_e32 v59, v0
	v_mov_b32_e32 v60, v0
	v_mov_b32_e32 v61, v0
	v_mov_b32_e32 v62, v0
	v_mov_b32_e32 v63, v0
	s_add_i32 s12, s26, -4
	s_mov_b32 s101, 0
	s_mov_b32 s14, s12
	s_and_b32 s15, s14, 63
	s_add_i32 s14, s14, 1
	s_mul_i32 s100, s15, 0x4000
	v_lshl_add_u64 v[74:75], v[68:69], 0, s[100:101]
	global_load_dwordx4 v[76:79], v[74:75], off
	global_load_dwordx4 v[80:83], v[74:75], off offset:1024
	s_and_b32 s15, s14, 63
	s_add_i32 s14, s14, 1
	s_mul_i32 s100, s15, 0x4000
	v_lshl_add_u64 v[74:75], v[68:69], 0, s[100:101]
	global_load_dwordx4 v[84:87], v[74:75], off
	global_load_dwordx4 v[88:91], v[74:75], off offset:1024
	s_and_b32 s15, s14, 63
	s_add_i32 s14, s14, 1
	s_mul_i32 s100, s15, 0x4000
	v_lshl_add_u64 v[74:75], v[68:69], 0, s[100:101]
	global_load_dwordx4 v[92:95], v[74:75], off
	global_load_dwordx4 v[96:99], v[74:75], off offset:1024
	s_and_b32 s15, s14, 63
	s_add_i32 s14, s14, 1
	s_mul_i32 s100, s15, 0x4000
	v_lshl_add_u64 v[74:75], v[68:69], 0, s[100:101]
	global_load_dwordx4 v[100:103], v[74:75], off
	global_load_dwordx4 v[104:107], v[74:75], off offset:1024
	s_and_b32 s15, s14, 63
	s_add_i32 s14, s14, 1
	s_mul_i32 s100, s15, 0x4000
	v_lshl_add_u64 v[74:75], v[68:69], 0, s[100:101]
	global_load_dwordx4 v[108:111], v[74:75], off
	global_load_dwordx4 v[116:119], v[74:75], off offset:1024
	s_and_b32 s15, s14, 63
	s_add_i32 s14, s14, 1
	s_mul_i32 s100, s15, 0x4000
	v_lshl_add_u64 v[74:75], v[68:69], 0, s[100:101]
	global_load_dwordx4 v[120:123], v[74:75], off
	global_load_dwordx4 v[124:127], v[74:75], off offset:1024
	s_and_b32 s15, s14, 63
	s_add_i32 s14, s14, 1
	s_mul_i32 s100, s15, 0x4000
	v_lshl_add_u64 v[74:75], v[68:69], 0, s[100:101]
	global_load_dwordx4 v[128:131], v[74:75], off
	global_load_dwordx4 v[132:135], v[74:75], off offset:1024
	s_and_b32 s15, s14, 63
	s_add_i32 s14, s14, 1
	s_mul_i32 s100, s15, 0x4000
	v_lshl_add_u64 v[74:75], v[68:69], 0, s[100:101]
	global_load_dwordx4 v[136:139], v[74:75], off
	global_load_dwordx4 v[140:143], v[74:75], off offset:1024
	s_mov_b32 s13, s12
	s_and_b32 s15, s13, 63
	s_lshl_b32 s15, s15, 5
	s_add_i32 s13, s13, 1
	v_add_u32_e32 v64, s15, v72
	v_add_u32_e32 v112, s15, v73
	ds_read_b128 v[144:147], v64
	ds_read_b128 v[148:151], v112
	s_mov_b32 s16, 7
.Lkmemkv_loop:
	s_and_b32 s15, s13, 63
	s_lshl_b32 s15, s15, 5
	s_add_i32 s13, s13, 1
	v_add_u32_e32 v64, s15, v72
	v_add_u32_e32 v112, s15, v73
	ds_read_b128 v[152:155], v64
	ds_read_b128 v[156:159], v112
	s_waitcnt vmcnt(15) lgkmcnt(2)
	v_mfma_f32_32x32x16_f16 v[48:63], v[144:147], v[76:79], v[48:63]
	v_mfma_f32_32x32x16_f16 v[16:31], v[148:151], v[76:79], v[16:31]
	s_waitcnt vmcnt(14)
	v_mfma_f32_32x32x16_f16 v[32:47], v[144:147], v[80:83], v[32:47]
	v_mfma_f32_32x32x16_f16 v[0:15], v[148:151], v[80:83], v[0:15]
	s_and_b32 s15, s14, 63
	s_add_i32 s14, s14, 1
	s_mul_i32 s100, s15, 0x4000
	v_lshl_add_u64 v[74:75], v[68:69], 0, s[100:101]
	global_load_dwordx4 v[76:79], v[74:75], off
	global_load_dwordx4 v[80:83], v[74:75], off offset:1024
	s_and_b32 s15, s13, 63
	s_lshl_b32 s15, s15, 5
	s_add_i32 s13, s13, 1
	v_add_u32_e32 v64, s15, v72
	v_add_u32_e32 v112, s15, v73
	ds_read_b128 v[144:147], v64
	ds_read_b128 v[148:151], v112
	s_waitcnt vmcnt(15) lgkmcnt(2)
	v_mfma_f32_32x32x16_f16 v[48:63], v[152:155], v[84:87], v[48:63]
	v_mfma_f32_32x32x16_f16 v[16:31], v[156:159], v[84:87], v[16:31]
	s_waitcnt vmcnt(14)
	v_mfma_f32_32x32x16_f16 v[32:47], v[152:155], v[88:91], v[32:47]
	v_mfma_f32_32x32x16_f16 v[0:15], v[156:159], v[88:91], v[0:15]
	s_and_b32 s15, s14, 63
	s_add_i32 s14, s14, 1
	s_mul_i32 s100, s15, 0x4000
	v_lshl_add_u64 v[74:75], v[68:69], 0, s[100:101]
	global_load_dwordx4 v[84:87], v[74:75], off
	global_load_dwordx4 v[88:91], v[74:75], off offset:1024
	s_and_b32 s15, s13, 63
	s_lshl_b32 s15, s15, 5
	s_add_i32 s13, s13, 1
	v_add_u32_e32 v64, s15, v72
	v_add_u32_e32 v112, s15, v73
	ds_read_b128 v[152:155], v64
	ds_read_b128 v[156:159], v112
	s_waitcnt vmcnt(15) lgkmcnt(2)
; #define MFMA32(a, b, c) __builtin_amdgcn_mfma_f32_32x32x16_f16((a), (b), (c), 0, 0, 0)
; template <int K, class Epi>
; DI void gemm64_res(const bf16_t* A, int lda, const bf16_t* Wp, int NU, unsigned char* lds, const Epi& epi) {
;     ...
;         for (int kk = 0; kk < KS; kk += PD) {
; #pragma unroll
;             for (int s = 0; s < PD; ++s) {
;                 const int ks = kk + s, ksr = (ks + rot) & (KS - 1);
;                 const bf16x8 a0 = *(const bf16x8*)(ab + ksr * 32), a1 = *(const bf16x8*)(ab + 32 * LD + ksr * 32);
; #pragma unroll
;                 for (int j = 0; j < NT; ++j) { acc[0][j] = MFMA32(a0, __builtin_bit_cast(bf16x8, bq[s][j]), acc[0][j]); acc[1][j] = MFMA32(a1, __builtin_bit_cast(bf16x8, bq[s][j]), acc[1][j]); }
;                 int nk = ks + PD; nk = nk < KS ? nk : KS - 1; nk = (nk + rot) & (KS - 1);
; #pragma unroll
;                 for (int j = 0; j < NT; ++j) bq[s][j] = bp[(size_t)nk * kstr + j * 64];
;             }
	v_mfma_f32_32x32x16_f16 v[48:63], v[144:147], v[92:95], v[48:63]
	v_mfma_f32_32x32x16_f16 v[16:31], v[148:151], v[92:95], v[16:31]
	s_waitcnt vmcnt(14)
	v_mfma_f32_32x32x16_f16 v[32:47], v[144:147], v[96:99], v[32:47]
	v_mfma_f32_32x32x16_f16 v[0:15], v[148:151], v[96:99], v[0:15]
	s_and_b32 s15, s14, 63
	s_add_i32 s14, s14, 1
	s_mul_i32 s100, s15, 0x4000
	v_lshl_add_u64 v[74:75], v[68:69], 0, s[100:101]
	global_load_dwordx4 v[92:95], v[74:75], off
	global_load_dwordx4 v[96:99], v[74:75], off offset:1024
	s_and_b32 s15, s13, 63
	s_lshl_b32 s15, s15, 5
	s_add_i32 s13, s13, 1
	v_add_u32_e32 v64, s15, v72
	v_add_u32_e32 v112, s15, v73
	ds_read_b128 v[144:147], v64
	ds_read_b128 v[148:151], v112
	s_waitcnt vmcnt(15) lgkmcnt(2)
	v_mfma_f32_32x32x16_f16 v[48:63], v[152:155], v[100:103], v[48:63]
	v_mfma_f32_32x32x16_f16 v[16:31], v[156:159], v[100:103], v[16:31]
	s_waitcnt vmcnt(14)
	v_mfma_f32_32x32x16_f16 v[32:47], v[152:155], v[104:107], v[32:47]
	v_mfma_f32_32x32x16_f16 v[0:15], v[156:159], v[104:107], v[0:15]
	s_and_b32 s15, s14, 63
	s_add_i32 s14, s14, 1
	s_mul_i32 s100, s15, 0x4000
	v_lshl_add_u64 v[74:75], v[68:69], 0, s[100:101]
	global_load_dwordx4 v[100:103], v[74:75], off
	global_load_dwordx4 v[104:107], v[74:75], off offset:1024
	s_and_b32 s15, s13, 63
	s_lshl_b32 s15, s15, 5
	s_add_i32 s13, s13, 1
	v_add_u32_e32 v64, s15, v72
	v_add_u32_e32 v112, s15, v73
	ds_read_b128 v[152:155], v64
	ds_read_b128 v[156:159], v112
	s_waitcnt vmcnt(15) lgkmcnt(2)
	v_mfma_f32_32x32x16_f16 v[48:63], v[144:147], v[108:111], v[48:63]
	v_mfma_f32_32x32x16_f16 v[16:31], v[148:151], v[108:111], v[16:31]
	s_waitcnt vmcnt(14)
	v_mfma_f32_32x32x16_f16 v[32:47], v[144:147], v[116:119], v[32:47]
	v_mfma_f32_32x32x16_f16 v[0:15], v[148:151], v[116:119], v[0:15]
	s_and_b32 s15, s14, 63
	s_add_i32 s14, s14, 1
	s_mul_i32 s100, s15, 0x4000
	v_lshl_add_u64 v[74:75], v[68:69], 0, s[100:101]
	global_load_dwordx4 v[108:111], v[74:75], off
	global_load_dwordx4 v[116:119], v[74:75], off offset:1024
	s_and_b32 s15, s13, 63
	s_lshl_b32 s15, s15, 5
	s_add_i32 s13, s13, 1
	v_add_u32_e32 v64, s15, v72
	v_add_u32_e32 v112, s15, v73
	ds_read_b128 v[144:147], v64
	ds_read_b128 v[148:151], v112
	s_waitcnt vmcnt(15) lgkmcnt(2)
	v_mfma_f32_32x32x16_f16 v[48:63], v[152:155], v[120:123], v[48:63]
	v_mfma_f32_32x32x16_f16 v[16:31], v[156:159], v[120:123], v[16:31]
	s_waitcnt vmcnt(14)
	v_mfma_f32_32x32x16_f16 v[32:47], v[152:155], v[124:127], v[32:47]
	v_mfma_f32_32x32x16_f16 v[0:15], v[156:159], v[124:127], v[0:15]
	s_and_b32 s15, s14, 63
	s_add_i32 s14, s14, 1
	s_mul_i32 s100, s15, 0x4000
	v_lshl_add_u64 v[74:75], v[68:69], 0, s[100:101]
	global_load_dwordx4 v[120:123], v[74:75], off
	global_load_dwordx4 v[124:127], v[74:75], off offset:1024
	s_and_b32 s15, s13, 63
	s_lshl_b32 s15, s15, 5
	s_add_i32 s13, s13, 1
	v_add_u32_e32 v64, s15, v72
	v_add_u32_e32 v112, s15, v73
	ds_read_b128 v[152:155], v64
	ds_read_b128 v[156:159], v112
	s_waitcnt vmcnt(15) lgkmcnt(2)
	v_mfma_f32_32x32x16_f16 v[48:63], v[144:147], v[128:131], v[48:63]
	v_mfma_f32_32x32x16_f16 v[16:31], v[148:151], v[128:131], v[16:31]
	s_waitcnt vmcnt(14)
	v_mfma_f32_32x32x16_f16 v[32:47], v[144:147], v[132:135], v[32:47]
	v_mfma_f32_32x32x16_f16 v[0:15], v[148:151], v[132:135], v[0:15]
	s_and_b32 s15, s14, 63
	s_add_i32 s14, s14, 1
	s_mul_i32 s100, s15, 0x4000
	v_lshl_add_u64 v[74:75], v[68:69], 0, s[100:101]
	global_load_dwordx4 v[128:131], v[74:75], off
	global_load_dwordx4 v[132:135], v[74:75], off offset:1024
	s_and_b32 s15, s13, 63
	s_lshl_b32 s15, s15, 5
	s_add_i32 s13, s13, 1
	v_add_u32_e32 v64, s15, v72
	v_add_u32_e32 v112, s15, v73
	ds_read_b128 v[144:147], v64
	ds_read_b128 v[148:151], v112
	s_waitcnt vmcnt(15) lgkmcnt(2)
	v_mfma_f32_32x32x16_f16 v[48:63], v[152:155], v[136:139], v[48:63]
	v_mfma_f32_32x32x16_f16 v[16:31], v[156:159], v[136:139], v[16:31]
	s_waitcnt vmcnt(14)
	v_mfma_f32_32x32x16_f16 v[32:47], v[152:155], v[140:143], v[32:47]
	v_mfma_f32_32x32x16_f16 v[0:15], v[156:159], v[140:143], v[0:15]
	s_and_b32 s15, s14, 63
	s_add_i32 s14, s14, 1
	s_mul_i32 s100, s15, 0x4000
	v_lshl_add_u64 v[74:75], v[68:69], 0, s[100:101]
	global_load_dwordx4 v[136:139], v[74:75], off
	global_load_dwordx4 v[140:143], v[74:75], off offset:1024
	s_add_i32 s16, s16, -1
	s_cmp_lg_u32 s16, 0
	s_cbranch_scc1 .Lkmemkv_loop
; #define MFMA32(a, b, c) __builtin_amdgcn_mfma_f32_32x32x16_f16((a), (b), (c), 0, 0, 0)
; DI int otid() { int t = threadIdx.x; asm volatile("" : "+v"(t)); return t; }
; DI unsigned pk2(float lo, float hi) { f32x2 v = {lo, hi}; bf2_t b = __builtin_convertvector(v, bf2_t); return __builtin_bit_cast(unsigned, b); }
; template <int K, class Epi>
; DI void gemm64_res(const bf16_t* A, int lda, const bf16_t* Wp, int NU, unsigned char* lds, const Epi& epi) {
;     ...
;         for (int kk = 0; kk < KS; kk += PD) {
; #pragma unroll
;             for (int s = 0; s < PD; ++s) {
;                 const int ks = kk + s, ksr = (ks + rot) & (KS - 1);
;                 const bf16x8 a0 = *(const bf16x8*)(ab + ksr * 32), a1 = *(const bf16x8*)(ab + 32 * LD + ksr * 32);
; #pragma unroll
;                 for (int j = 0; j < NT; ++j) { acc[0][j] = MFMA32(a0, __builtin_bit_cast(bf16x8, bq[s][j]), acc[0][j]); acc[1][j] = MFMA32(a1, __builtin_bit_cast(bf16x8, bq[s][j]), acc[1][j]); }
;                 int nk = ks + PD; nk = nk < KS ? nk : KS - 1; nk = (nk + rot) & (KS - 1);
; #pragma unroll
;                 for (int j = 0; j < NT; ++j) bq[s][j] = bp[(size_t)nk * kstr + j * 64];
;             }
;         }
;         epi(unit, acc);
; template <int MT> DI void st_vp(bf16_t* vp, int DTt, int dd0, int tb0, int tb2, const f32x16 (&acc)[MT][NT]) {
;     const int lane = otid() & 63;
; #pragma unroll
;     for (int mi = 0; mi < MT; ++mi)
; #pragma unroll
;         for (int nj = 0; nj < NT; ++nj)
; #pragma unroll
;             for (int sp_ = 0; sp_ < 2; ++sp_) {
;                 const int tb = mi == 2 ? tb2 : tb0 + mi;
;                 u32x4 w = {pk2(acc[mi][nj][8 * sp_], acc[mi][nj][8 * sp_ + 1]), pk2(acc[mi][nj][8 * sp_ + 2], acc[mi][nj][8 * sp_ + 3]),
;                            pk2(acc[mi][nj][8 * sp_ + 4], acc[mi][nj][8 * sp_ + 5]), pk2(acc[mi][nj][8 * sp_ + 6], acc[mi][nj][8 * sp_ + 7])};
;                 *(u32x4*)(vp + ((((tb * DTt + dd0 + nj) * 2 + sp_) * 64 + lane) * 8)) = w;
;             }
	s_and_b32 s15, s13, 63
	s_lshl_b32 s15, s15, 5
	s_add_i32 s13, s13, 1
	v_add_u32_e32 v64, s15, v72
	v_add_u32_e32 v112, s15, v73
	ds_read_b128 v[152:155], v64
	ds_read_b128 v[156:159], v112
	s_waitcnt vmcnt(15) lgkmcnt(2)
	v_mfma_f32_32x32x16_f16 v[48:63], v[144:147], v[76:79], v[48:63]
	v_mfma_f32_32x32x16_f16 v[16:31], v[148:151], v[76:79], v[16:31]
	s_waitcnt vmcnt(14)
	v_mfma_f32_32x32x16_f16 v[32:47], v[144:147], v[80:83], v[32:47]
	v_mfma_f32_32x32x16_f16 v[0:15], v[148:151], v[80:83], v[0:15]
	s_and_b32 s15, s13, 63
	s_lshl_b32 s15, s15, 5
	s_add_i32 s13, s13, 1
	v_add_u32_e32 v64, s15, v72
	v_add_u32_e32 v112, s15, v73
	ds_read_b128 v[144:147], v64
	ds_read_b128 v[148:151], v112
	s_waitcnt vmcnt(13) lgkmcnt(2)
	v_mfma_f32_32x32x16_f16 v[48:63], v[152:155], v[84:87], v[48:63]
	v_mfma_f32_32x32x16_f16 v[16:31], v[156:159], v[84:87], v[16:31]
	s_waitcnt vmcnt(12)
	v_mfma_f32_32x32x16_f16 v[32:47], v[152:155], v[88:91], v[32:47]
	v_mfma_f32_32x32x16_f16 v[0:15], v[156:159], v[88:91], v[0:15]
	s_and_b32 s15, s13, 63
	s_lshl_b32 s15, s15, 5
	s_add_i32 s13, s13, 1
	v_add_u32_e32 v64, s15, v72
	v_add_u32_e32 v112, s15, v73
	ds_read_b128 v[152:155], v64
	ds_read_b128 v[156:159], v112
	s_waitcnt vmcnt(11) lgkmcnt(2)
	v_mfma_f32_32x32x16_f16 v[48:63], v[144:147], v[92:95], v[48:63]
	v_mfma_f32_32x32x16_f16 v[16:31], v[148:151], v[92:95], v[16:31]
	s_waitcnt vmcnt(10)
	v_mfma_f32_32x32x16_f16 v[32:47], v[144:147], v[96:99], v[32:47]
	v_mfma_f32_32x32x16_f16 v[0:15], v[148:151], v[96:99], v[0:15]
	s_and_b32 s15, s13, 63
	s_lshl_b32 s15, s15, 5
	s_add_i32 s13, s13, 1
	v_add_u32_e32 v64, s15, v72
	v_add_u32_e32 v112, s15, v73
	ds_read_b128 v[144:147], v64
	ds_read_b128 v[148:151], v112
	s_waitcnt vmcnt(9) lgkmcnt(2)
	v_mfma_f32_32x32x16_f16 v[48:63], v[152:155], v[100:103], v[48:63]
	v_mfma_f32_32x32x16_f16 v[16:31], v[156:159], v[100:103], v[16:31]
	s_waitcnt vmcnt(8)
	v_mfma_f32_32x32x16_f16 v[32:47], v[152:155], v[104:107], v[32:47]
	v_mfma_f32_32x32x16_f16 v[0:15], v[156:159], v[104:107], v[0:15]
	s_and_b32 s15, s13, 63
	s_lshl_b32 s15, s15, 5
	s_add_i32 s13, s13, 1
	v_add_u32_e32 v64, s15, v72
	v_add_u32_e32 v112, s15, v73
	ds_read_b128 v[152:155], v64
	ds_read_b128 v[156:159], v112
	s_waitcnt vmcnt(7) lgkmcnt(2)
	v_mfma_f32_32x32x16_f16 v[48:63], v[144:147], v[108:111], v[48:63]
	v_mfma_f32_32x32x16_f16 v[16:31], v[148:151], v[108:111], v[16:31]
	s_waitcnt vmcnt(6)
	v_mfma_f32_32x32x16_f16 v[32:47], v[144:147], v[116:119], v[32:47]
	v_mfma_f32_32x32x16_f16 v[0:15], v[148:151], v[116:119], v[0:15]
	s_and_b32 s15, s13, 63
	s_lshl_b32 s15, s15, 5
	s_add_i32 s13, s13, 1
	v_add_u32_e32 v64, s15, v72
	v_add_u32_e32 v112, s15, v73
	ds_read_b128 v[144:147], v64
	ds_read_b128 v[148:151], v112
	s_waitcnt vmcnt(5) lgkmcnt(2)
	v_mfma_f32_32x32x16_f16 v[48:63], v[152:155], v[120:123], v[48:63]
	v_mfma_f32_32x32x16_f16 v[16:31], v[156:159], v[120:123], v[16:31]
	s_waitcnt vmcnt(4)
	v_mfma_f32_32x32x16_f16 v[32:47], v[152:155], v[124:127], v[32:47]
	v_mfma_f32_32x32x16_f16 v[0:15], v[156:159], v[124:127], v[0:15]
	s_and_b32 s15, s13, 63
	s_lshl_b32 s15, s15, 5
	s_add_i32 s13, s13, 1
	v_add_u32_e32 v64, s15, v72
	v_add_u32_e32 v112, s15, v73
	ds_read_b128 v[152:155], v64
	ds_read_b128 v[156:159], v112
	s_waitcnt vmcnt(3) lgkmcnt(2)
	v_mfma_f32_32x32x16_f16 v[48:63], v[144:147], v[128:131], v[48:63]
	v_mfma_f32_32x32x16_f16 v[16:31], v[148:151], v[128:131], v[16:31]
	s_waitcnt vmcnt(2)
	v_mfma_f32_32x32x16_f16 v[32:47], v[144:147], v[132:135], v[32:47]
	v_mfma_f32_32x32x16_f16 v[0:15], v[148:151], v[132:135], v[0:15]
	s_waitcnt vmcnt(1) lgkmcnt(0)
	v_mfma_f32_32x32x16_f16 v[48:63], v[152:155], v[136:139], v[48:63]
	v_mfma_f32_32x32x16_f16 v[16:31], v[156:159], v[136:139], v[16:31]
	s_waitcnt vmcnt(0)
	v_mfma_f32_32x32x16_f16 v[32:47], v[152:155], v[140:143], v[32:47]
	v_mfma_f32_32x32x16_f16 v[0:15], v[156:159], v[140:143], v[0:15]
	s_nop 7
	s_nop 3
	s_andn2_b64 vcc, exec, s[8:9]
	s_mov_b64 s[12:13], -1
	s_cbranch_vccnz .LBB0_252
	v_mov_b32_e32 v64, v176
	s_lshl_b32 s0, s35, 11
	v_lshlrev_b32_e32 v64, 3, v64
	s_add_i32 s0, s0, s37
	v_and_b32_e32 v64, 0x1f8, v64
	v_or_b32_e32 v74, s0, v64
	v_ashrrev_i32_e32 v75, 31, v74
	v_cvt_pk_f16_f32 v68, v48, v49
	v_cvt_pk_f16_f32 v69, v50, v51
	v_cvt_pk_f16_f32 v70, v52, v53
	v_cvt_pk_f16_f32 v71, v54, v55
	v_lshl_add_u64 v[74:75], v[74:75], 1, s[6:7]
	global_store_dwordx4 v[74:75], v[68:71], off
	s_addk_i32 s0, 0x4000
	s_mov_b64 s[12:13], 0
	v_cvt_pk_f16_f32 v68, v56, v57
	v_cvt_pk_f16_f32 v69, v58, v59
	v_cvt_pk_f16_f32 v70, v60, v61
	v_cvt_pk_f16_f32 v71, v62, v63
	global_store_dwordx4 v[74:75], v[68:71], off offset:1024
	s_nop 1
	v_cvt_pk_f16_f32 v68, v32, v33
	v_cvt_pk_f16_f32 v69, v34, v35
	v_cvt_pk_f16_f32 v70, v36, v37
	v_cvt_pk_f16_f32 v71, v38, v39
	global_store_dwordx4 v[74:75], v[68:71], off offset:2048
	s_nop 1
	v_cvt_pk_f16_f32 v68, v40, v41
	v_cvt_pk_f16_f32 v69, v42, v43
	v_cvt_pk_f16_f32 v70, v44, v45
	v_cvt_pk_f16_f32 v71, v46, v47
	global_store_dwordx4 v[74:75], v[68:71], off offset:3072
	v_or_b32_e32 v74, s0, v64
	v_ashrrev_i32_e32 v75, 31, v74
	v_cvt_pk_f16_f32 v68, v16, v17
	v_cvt_pk_f16_f32 v69, v18, v19
	v_cvt_pk_f16_f32 v70, v20, v21
	v_cvt_pk_f16_f32 v71, v22, v23
	v_lshl_add_u64 v[74:75], v[74:75], 1, s[6:7]
	global_store_dwordx4 v[74:75], v[68:71], off
	s_lshl_b32 s0, s35, 6
	s_nop 0
	v_cvt_pk_f16_f32 v68, v24, v25
	v_cvt_pk_f16_f32 v69, v26, v27
	v_cvt_pk_f16_f32 v70, v28, v29
	v_cvt_pk_f16_f32 v71, v30, v31
	global_store_dwordx4 v[74:75], v[68:71], off offset:1024
	s_nop 1
	v_cvt_pk_f16_f32 v68, v0, v1
	v_cvt_pk_f16_f32 v69, v2, v3
	v_cvt_pk_f16_f32 v70, v4, v5
	v_cvt_pk_f16_f32 v71, v6, v7
	global_store_dwordx4 v[74:75], v[68:71], off offset:2048
	s_nop 1
	v_cvt_pk_f16_f32 v68, v8, v9
	v_cvt_pk_f16_f32 v69, v10, v11
	v_cvt_pk_f16_f32 v70, v12, v13
	v_cvt_pk_f16_f32 v71, v14, v15
	global_store_dwordx4 v[74:75], v[68:71], off offset:3072

; #define MFMA32(a, b, c) __builtin_amdgcn_mfma_f32_32x32x16_f16((a), (b), (c), 0, 0, 0)
; DI int crow(int i, int h) { return (i & 3) + 8 * (i >> 2) + 4 * h; }
; template <int HD, int BIAS, bool FULL>
; DI void attn_block(const bf16_t* Kb, int ktb, const bf16_t* Vb, int vtb, int koff, int kpos0, int qp, float slope, const float* rel,
;                    const bf16x8 (&qf)[HD / 16], f32x16 (&o)[HD / 32], float& m, float& l) {
;     ...
;     bf16x8 kreg[NKT][KSQ];
; #pragma unroll
;     for (int kt = 0; kt < NKT; ++kt)
; #pragma unroll
;         for (int ks = 0; ks < KSQ; ++ks) kreg[kt][ks] = *(const bf16x8*)(Kb + (size_t)kt * ktb + ks * 512 + lane * 8);
;     constexpr int NS = FULL ? 4 : 1;
;     bf16x8 vreg[DT][NS];
;     auto loadV = [&]() {
; #pragma unroll
;         for (int si = 0; si < NS; ++si)
; #pragma unroll
;             for (int dt = 0; dt < DT; ++dt) { const int s = FULL ? si : s0; vreg[dt][si] = *(const bf16x8*)(Vb + (size_t)(s >> 1) * vtb + dt * 1024 + (s & 1) * 512 + lane * 8); }
;     };
;     if (VTOP) loadV();
;     __builtin_amdgcn_sched_barrier(0);
;     f32x16 st[NKT];
; #pragma unroll
;     for (int kt = 0; kt < NKT; ++kt) {
; #pragma unroll
;         for (int i = 0; i < 16; ++i) st[kt][i] = 0.f;
; #pragma unroll
;         for (int ks = 0; ks < KSQ; ++ks) st[kt] = MFMA32(kreg[kt][ks], qf[ks], st[kt]);
;     }
;     __builtin_amdgcn_sched_barrier(0);
;     if (!VTOP) loadV();
;     float mx = -1e30f;
; #pragma unroll
;     for (int kt = 0; kt < NKT; ++kt)
; #pragma unroll
;         for (int i = 0; i < 16; ++i) {
;             const int key = kt * 32 + crow(i, h);
;             float s = st[kt][i];
;             const int dk = dq + (kt * 32 + (i & 3) + 8 * (i >> 2));
;             if (BIAS == 1) s -= slope * (float)(dk < 0 ? -dk : dk);
;             if (BIAS == 2) { int d = dk < -256 ? -256 : (dk > 256 ? 256 : dk); s += rel[d + 256]; }
;             if (!FULL) { if (key < kbeg || key >= kend) s = -1e30f; }
;             st[kt][i] = s; mx = fmaxf(mx, s);
.LBB0_329:
	v_mov_b32_e32 v0, v176
	s_add_u32 s28, s2, s0
	v_lshrrev_b32_e32 v34, 3, v0
	v_and_b32_e32 v0, 63, v0
	v_lshlrev_b32_e32 v0, 4, v0
	s_addc_u32 s29, s3, s1
	v_lshl_add_u64 v[50:51], s[28:29], 0, v[0:1]
	s_mov_b32 s28, 0x18406000
	v_add_co_u32_e32 v46, vcc, s28, v50
	s_mov_b32 s28, 0x1840e000
	s_nop 0
	v_addc_co_u32_e32 v47, vcc, 0, v51, vcc
	v_and_b32_e32 v34, 4, v34
	v_add_co_u32_e32 v52, vcc, s28, v50
	s_waitcnt vmcnt(4)
	v_add_u32_e32 v120, v118, v34
	v_addc_co_u32_e32 v53, vcc, 0, v51, vcc
	s_mov_b32 s28, 0x18806000
	global_load_dwordx4 v[34:37], v[46:47], off
	global_load_dwordx4 v[38:41], v[46:47], off offset:1024
	global_load_dwordx4 v[42:45], v[46:47], off offset:2048
	s_nop 0
	global_load_dwordx4 v[46:49], v[46:47], off offset:3072
	s_nop 0
	global_load_dwordx4 v[122:125], v[52:53], off
	global_load_dwordx4 v[126:129], v[52:53], off offset:1024
	global_load_dwordx4 v[130:133], v[52:53], off offset:2048
	global_load_dwordx4 v[134:137], v[52:53], off offset:3072
	v_add_co_u32_e32 v52, vcc, s28, v50
	s_mov_b32 s28, 0x1880e000
	s_nop 0
	v_addc_co_u32_e32 v53, vcc, 0, v51, vcc
	v_add_co_u32_e32 v50, vcc, s28, v50
	global_load_dwordx4 v[110:113], v[52:53], off
	global_load_dwordx4 v[102:105], v[52:53], off offset:1024
	global_load_dwordx4 v[106:109], v[52:53], off offset:2048
	global_load_dwordx4 v[98:101], v[52:53], off offset:3072
	v_addc_co_u32_e32 v51, vcc, 0, v51, vcc
	global_load_dwordx4 v[94:97], v[50:51], off
	global_load_dwordx4 v[86:89], v[50:51], off offset:1024
	global_load_dwordx4 v[90:93], v[50:51], off offset:2048
	global_load_dwordx4 v[82:85], v[50:51], off offset:3072
	v_mov_b32_e32 v121, v58
	v_mov_b32_e32 v119, v59
	s_waitcnt vmcnt(15)
	v_mfma_f32_32x32x16_f16 v[50:65], v[34:37], v[78:81], 0
	s_waitcnt vmcnt(14)
	v_mfma_f32_32x32x16_f16 v[50:65], v[38:41], v[74:77], v[50:65]
	s_waitcnt vmcnt(13)
	v_mfma_f32_32x32x16_f16 v[50:65], v[42:45], v[66:69], v[50:65]
	s_waitcnt vmcnt(12)
	v_mfma_f32_32x32x16_f16 v[50:65], v[46:49], v[70:73], v[50:65]
	s_waitcnt vmcnt(11)
	v_mfma_f32_32x32x16_f16 v[34:49], v[122:125], v[78:81], 0
	s_waitcnt vmcnt(10)
	v_mfma_f32_32x32x16_f16 v[34:49], v[126:129], v[74:77], v[34:49]
	s_waitcnt vmcnt(9)
	v_mfma_f32_32x32x16_f16 v[34:49], v[130:133], v[66:69], v[34:49]
	s_waitcnt vmcnt(8)
	v_mfma_f32_32x32x16_f16 v[34:49], v[134:137], v[70:73], v[34:49]
	v_add_u32_e32 v142, 2, v120
	v_med3_i32 v142, v142, s45, v186
	v_lshl_add_u32 v142, v142, 2, s61
	ds_read_b32 v142, v142 offset:1024
	v_med3_i32 v143, v120, s45, v186
	v_lshl_add_u32 v143, v143, 2, s61
	ds_read_b32 v143, v143 offset:1024
	v_add_u32_e32 v144, 3, v120
	v_med3_i32 v144, v144, s45, v186
	v_lshl_add_u32 v144, v144, 2, s61
	ds_read_b32 v144, v144 offset:1024
	v_add_u32_e32 v145, 8, v120
	v_med3_i32 v145, v145, s45, v186
	v_lshl_add_u32 v145, v145, 2, s61
	ds_read_b32 v145, v145 offset:1024
	v_add_u32_e32 v146, 9, v120
	v_med3_i32 v146, v146, s45, v186
	v_lshl_add_u32 v146, v146, 2, s61
	ds_read_b32 v146, v146 offset:1024
	v_add_u32_e32 v147, 10, v120
	v_med3_i32 v147, v147, s45, v186
	v_lshl_add_u32 v147, v147, 2, s61
	ds_read_b32 v147, v147 offset:1024
	v_add_u32_e32 v148, 11, v120
	v_med3_i32 v148, v148, s45, v186
	v_lshl_add_u32 v148, v148, 2, s61
	ds_read_b32 v148, v148 offset:1024
	v_add_u32_e32 v149, 16, v120
	v_med3_i32 v149, v149, s45, v186
	v_lshl_add_u32 v149, v149, 2, s61
	ds_read_b32 v149, v149 offset:1024
	v_add_u32_e32 v150, 17, v120
	v_med3_i32 v150, v150, s45, v186
	v_lshl_add_u32 v150, v150, 2, s61
	ds_read_b32 v150, v150 offset:1024
	v_add_u32_e32 v151, 1, v120
	v_med3_i32 v151, v151, s45, v186
	v_lshl_add_u32 v151, v151, 2, s61
	v_add_u32_e32 v152, 18, v120
	v_med3_i32 v152, v152, s45, v186
	v_lshl_add_u32 v152, v152, 2, s61
	ds_read_b32 v151, v151 offset:1024
	ds_read_b32 v152, v152 offset:1024
	v_add_u32_e32 v153, 19, v120
	v_med3_i32 v153, v153, s45, v186
	v_lshl_add_u32 v153, v153, 2, s61
	ds_read_b32 v153, v153 offset:1024
	v_add_u32_e32 v154, 24, v120
	v_med3_i32 v154, v154, s45, v186
	v_lshl_add_u32 v154, v154, 2, s61
	ds_read_b32 v154, v154 offset:1024
	v_add_u32_e32 v155, 25, v120
	v_med3_i32 v155, v155, s45, v186
	v_lshl_add_u32 v155, v155, 2, s61
	ds_read_b32 v155, v155 offset:1024
	v_add_u32_e32 v156, 26, v120
	v_med3_i32 v156, v156, s45, v186
	v_lshl_add_u32 v156, v156, 2, s61
	ds_read_b32 v156, v156 offset:1024
	v_add_u32_e32 v157, 27, v120
	v_med3_i32 v157, v157, s45, v186
	v_lshl_add_u32 v157, v157, 2, s61
	ds_read_b32 v157, v157 offset:1024
	v_add_u32_e32 v158, 32, v120
	v_med3_i32 v158, v158, s45, v186
	v_lshl_add_u32 v158, v158, 2, s61
	ds_read_b32 v158, v158 offset:1024
	v_add_u32_e32 v159, 33, v120
	v_med3_i32 v159, v159, s45, v186
	v_lshl_add_u32 v159, v159, 2, s61
	ds_read_b32 v159, v159 offset:1024
	v_add_u32_e32 v160, 34, v120
	v_med3_i32 v160, v160, s45, v186
	v_lshl_add_u32 v160, v160, 2, s61
	ds_read_b32 v160, v160 offset:1024
	v_add_u32_e32 v161, 35, v120
	v_med3_i32 v161, v161, s45, v186
	v_lshl_add_u32 v161, v161, 2, s61
	ds_read_b32 v161, v161 offset:1024
	v_add_u32_e32 v162, 40, v120
	v_med3_i32 v162, v162, s45, v186
	v_lshl_add_u32 v162, v162, 2, s61
	ds_read_b32 v162, v162 offset:1024
	v_add_u32_e32 v163, 41, v120
	v_med3_i32 v163, v163, s45, v186
	v_lshl_add_u32 v163, v163, 2, s61
	ds_read_b32 v163, v163 offset:1024
	v_add_u32_e32 v164, 42, v120
	v_med3_i32 v164, v164, s45, v186
	v_lshl_add_u32 v164, v164, 2, s61
	ds_read_b32 v164, v164 offset:1024
	v_add_u32_e32 v165, 43, v120
	v_med3_i32 v165, v165, s45, v186
	v_lshl_add_u32 v165, v165, 2, s61
	ds_read_b32 v165, v165 offset:1024
	v_add_u32_e32 v166, 48, v120
	v_med3_i32 v166, v166, s45, v186
	v_lshl_add_u32 v166, v166, 2, s61
	ds_read_b32 v166, v166 offset:1024
	v_add_u32_e32 v167, 49, v120
	v_med3_i32 v167, v167, s45, v186
	v_lshl_add_u32 v167, v167, 2, s61
	ds_read_b32 v167, v167 offset:1024
	v_add_u32_e32 v168, 50, v120
	v_med3_i32 v168, v168, s45, v186
	v_lshl_add_u32 v168, v168, 2, s61
	ds_read_b32 v168, v168 offset:1024
	v_add_u32_e32 v169, 51, v120
	v_med3_i32 v169, v169, s45, v186
	v_lshl_add_u32 v169, v169, 2, s61
	ds_read_b32 v169, v169 offset:1024
	v_add_u32_e32 v170, 56, v120
	v_med3_i32 v170, v170, s45, v186
	v_lshl_add_u32 v170, v170, 2, s61
	ds_read_b32 v170, v170 offset:1024
	v_add_u32_e32 v171, 57, v120
	v_med3_i32 v171, v171, s45, v186
	v_lshl_add_u32 v171, v171, 2, s61
	ds_read_b32 v171, v171 offset:1024
	v_add_u32_e32 v172, 58, v120
	v_med3_i32 v172, v172, s45, v186
	v_lshl_add_u32 v172, v172, 2, s61
	ds_read_b32 v172, v172 offset:1024
	v_add_u32_e32 v173, 59, v120
	v_med3_i32 v173, v173, s45, v186
	v_lshl_add_u32 v173, v173, 2, s61
	ds_read_b32 v173, v173 offset:1024
	s_waitcnt lgkmcnt(0)
; #define MFMA32(a, b, c) __builtin_amdgcn_mfma_f32_32x32x16_f16((a), (b), (c), 0, 0, 0)
; DI int crow(int i, int h) { return (i & 3) + 8 * (i >> 2) + 4 * h; }
; template <int HD, int BIAS, bool FULL>
; DI void attn_block(const bf16_t* Kb, int ktb, const bf16_t* Vb, int vtb, int koff, int kpos0, int qp, float slope, const float* rel,
;                    const bf16x8 (&qf)[HD / 16], f32x16 (&o)[HD / 32], float& m, float& l) {
;     ...
;     for (int kt = 0; kt < NKT; ++kt)
; #pragma unroll
;         for (int i = 0; i < 16; ++i) {
;             const int key = kt * 32 + crow(i, h);
;             float s = st[kt][i];
;             const int dk = dq + (kt * 32 + (i & 3) + 8 * (i >> 2));
;             if (BIAS == 1) s -= slope * (float)(dk < 0 ? -dk : dk);
;             if (BIAS == 2) { int d = dk < -256 ? -256 : (dk > 256 ? 256 : dk); s += rel[d + 256]; }
;             if (!FULL) { if (key < kbeg || key >= kend) s = -1e30f; }
;             st[kt][i] = s; mx = fmaxf(mx, s);
;         }
;     mx = fmaxf(mx, __shfl_xor(mx, 32));
;     const float mn = fmaxf(m, mx);
;     const float alpha = __builtin_amdgcn_exp2f((m - mn) * LOG2E);
;     m = mn;
;     float ps = 0.f;
; #pragma unroll
;     for (int kt = 0; kt < NKT; ++kt)
; #pragma unroll
;         for (int i = 0; i < 16; ++i) { const float pv = __builtin_amdgcn_exp2f((st[kt][i] - mn) * LOG2E); st[kt][i] = pv; ps += pv; }
;     l = l * alpha + ps;
; #pragma unroll
;     for (int dt = 0; dt < DT; ++dt)
; #pragma unroll
;         for (int i = 0; i < 16; ++i) o[dt][i] *= alpha;
; #pragma unroll
;     for (int si = 0; si < NS; ++si) {
;         u32x4 pw;
;         if (FULL) { const int kt = si >> 1, b0 = (si & 1) * 8; pw = (u32x4){pk2(st[kt][b0], st[kt][b0 + 1]), pk2(st[kt][b0 + 2], st[kt][b0 + 3]), pk2(st[kt][b0 + 4], st[kt][b0 + 5]), pk2(st[kt][b0 + 6], st[kt][b0 + 7])}; }
;         else {
;             const u32x4 lo = {pk2(st[0][0], st[0][1]), pk2(st[0][2], st[0][3]), pk2(st[0][4], st[0][5]), pk2(st[0][6], st[0][7])};
;             const u32x4 hi = {pk2(st[0][8], st[0][9]), pk2(st[0][10], st[0][11]), pk2(st[0][12], st[0][13]), pk2(st[0][14], st[0][15])};
;             pw = (s0 & 1) ? hi : lo;
;         }
;         const bf16x8 pf = __builtin_bit_cast(bf16x8, pw);
; #pragma unroll
;         for (int dt = 0; dt < DT; ++dt) o[dt] = MFMA32(vreg[dt][si], pf, o[dt]);
	v_cmp_lt_i32_e32 vcc, v188, v189
	v_add_f32_e32 v52, v52, v142
	s_add_u32 s0, s0, 0x10000
	s_addc_u32 s1, s1, 0
	v_add_u32_e32 v118, 64, v118
	s_cmp_eq_u32 s0, 0x80000
	v_add_f32_e32 v53, v53, v144
	v_add_f32_e32 v54, v54, v145
	v_add_f32_e32 v55, v55, v146
	v_add_f32_e32 v56, v56, v147
	v_add_f32_e32 v57, v57, v148
	v_add_f32_e32 v122, v58, v149
	v_add_f32_e32 v50, v50, v143
	v_add_f32_e32 v59, v59, v150
	v_add_f32_e32 v51, v51, v151
	v_add_f32_e32 v60, v60, v152
	v_max3_f32 v0, v50, s46, v51
	v_max3_f32 v0, v0, v52, v53
	v_max3_f32 v0, v0, v54, v55
	v_max3_f32 v0, v0, v56, v57
	v_add_f32_e32 v61, v61, v153
	v_max3_f32 v0, v0, v122, v59
	v_max3_f32 v0, v0, v60, v61
	v_add_f32_e32 v62, v62, v154
	v_add_f32_e32 v63, v63, v155
	v_max3_f32 v0, v0, v62, v63
	v_add_f32_e32 v64, v64, v156
	v_add_f32_e32 v65, v65, v157
	v_max3_f32 v0, v0, v64, v65
	v_add_f32_e32 v34, v34, v158
	v_add_f32_e32 v35, v35, v159
	v_max3_f32 v0, v0, v34, v35
	v_add_f32_e32 v36, v36, v160
	v_add_f32_e32 v37, v37, v161
	v_max3_f32 v0, v0, v36, v37
	v_add_f32_e32 v38, v38, v162
	v_add_f32_e32 v39, v39, v163
	v_max3_f32 v0, v0, v38, v39
	v_add_f32_e32 v40, v40, v164
	v_add_f32_e32 v41, v41, v165
	v_max3_f32 v0, v0, v40, v41
	v_add_f32_e32 v42, v42, v166
	v_add_f32_e32 v43, v43, v167
	v_max3_f32 v0, v0, v42, v43
	v_add_f32_e32 v44, v44, v168
	v_add_f32_e32 v45, v45, v169
	v_max3_f32 v0, v0, v44, v45
	v_add_f32_e32 v46, v46, v170
	v_add_f32_e32 v47, v47, v171
	v_max3_f32 v0, v0, v46, v47
	v_add_f32_e32 v48, v48, v172
	v_add_f32_e32 v49, v49, v173
	v_max3_f32 v58, v0, v48, v49
	v_cndmask_b32_e32 v0, v187, v188, vcc
	v_lshlrev_b32_e32 v0, 2, v0
	ds_bpermute_b32 v120, v0, v58
	s_waitcnt lgkmcnt(0)
	v_max3_f32 v58, v121, v58, v120
	v_sub_f32_e32 v50, v50, v58
	v_mul_f32_e32 v50, 0x3fb8aa3b, v50
	v_sub_f32_e32 v51, v51, v58
	v_exp_f32_e32 v50, v50
	v_mul_f32_e32 v51, 0x3fb8aa3b, v51
	v_sub_f32_e32 v52, v52, v58
	v_exp_f32_e32 v51, v51
	v_mul_f32_e32 v52, 0x3fb8aa3b, v52
	v_sub_f32_e32 v53, v53, v58
	v_sub_f32_e32 v35, v35, v58
	v_exp_f32_e32 v52, v52
	v_mul_f32_e32 v53, 0x3fb8aa3b, v53
	v_sub_f32_e32 v54, v54, v58
	v_mul_f32_e32 v35, 0x3fb8aa3b, v35
	v_exp_f32_e32 v53, v53
	v_mul_f32_e32 v54, 0x3fb8aa3b, v54
	v_sub_f32_e32 v55, v55, v58
	v_exp_f32_e32 v124, v35
	v_sub_f32_e32 v35, v36, v58
	v_sub_f32_e32 v120, v121, v58
	v_add_f32_e32 v121, 0, v50
	v_exp_f32_e32 v54, v54
	v_mul_f32_e32 v55, 0x3fb8aa3b, v55
	v_sub_f32_e32 v56, v56, v58
	v_mul_f32_e32 v35, 0x3fb8aa3b, v35
	v_add_f32_e32 v121, v51, v121
	v_exp_f32_e32 v55, v55
	v_mul_f32_e32 v56, 0x3fb8aa3b, v56
	v_sub_f32_e32 v57, v57, v58
	v_exp_f32_e32 v125, v35
	v_sub_f32_e32 v35, v37, v58
	v_add_f32_e32 v121, v52, v121
	v_exp_f32_e32 v56, v56
	v_mul_f32_e32 v57, 0x3fb8aa3b, v57
	v_sub_f32_e32 v122, v122, v58
	v_mul_f32_e32 v35, 0x3fb8aa3b, v35
	v_add_f32_e32 v121, v53, v121
	v_exp_f32_e32 v57, v57
	v_mul_f32_e32 v122, 0x3fb8aa3b, v122
	v_sub_f32_e32 v59, v59, v58
	v_exp_f32_e32 v126, v35
	v_sub_f32_e32 v35, v38, v58
	v_add_f32_e32 v121, v54, v121
	v_exp_f32_e32 v122, v122
	v_mul_f32_e32 v59, 0x3fb8aa3b, v59
	v_sub_f32_e32 v60, v60, v58
	v_mul_f32_e32 v35, 0x3fb8aa3b, v35
	v_add_f32_e32 v121, v55, v121
	v_exp_f32_e32 v123, v59
	v_mul_f32_e32 v60, 0x3fb8aa3b, v60
	v_sub_f32_e32 v61, v61, v58
	v_exp_f32_e32 v38, v35
	v_sub_f32_e32 v35, v39, v58
	v_add_f32_e32 v121, v56, v121
	v_exp_f32_e32 v60, v60
	v_mul_f32_e32 v61, 0x3fb8aa3b, v61
	v_sub_f32_e32 v62, v62, v58
	v_mul_f32_e32 v35, 0x3fb8aa3b, v35
	v_add_f32_e32 v121, v57, v121
	v_exp_f32_e32 v61, v61
	v_mul_f32_e32 v62, 0x3fb8aa3b, v62
	v_sub_f32_e32 v63, v63, v58
	v_exp_f32_e32 v39, v35
	v_sub_f32_e32 v35, v40, v58
	v_add_f32_e32 v121, v122, v121
	v_exp_f32_e32 v62, v62
	v_mul_f32_e32 v63, 0x3fb8aa3b, v63
	v_sub_f32_e32 v64, v64, v58
	v_mul_f32_e32 v35, 0x3fb8aa3b, v35
	v_add_f32_e32 v59, v123, v121
	v_exp_f32_e32 v63, v63
	v_mul_f32_e32 v64, 0x3fb8aa3b, v64
	v_sub_f32_e32 v65, v65, v58
	v_exp_f32_e32 v40, v35
	v_sub_f32_e32 v35, v41, v58
	v_add_f32_e32 v59, v60, v59
	v_exp_f32_e32 v64, v64
	v_mul_f32_e32 v65, 0x3fb8aa3b, v65
	v_sub_f32_e32 v34, v34, v58
	v_mul_f32_e32 v35, 0x3fb8aa3b, v35
	v_add_f32_e32 v59, v61, v59
	v_exp_f32_e32 v65, v65
	v_mul_f32_e32 v34, 0x3fb8aa3b, v34
	v_exp_f32_e32 v41, v35
	v_sub_f32_e32 v35, v42, v58
	v_add_f32_e32 v59, v62, v59
	v_exp_f32_e32 v121, v34
	v_mul_f32_e32 v35, 0x3fb8aa3b, v35
	v_add_f32_e32 v59, v63, v59
	v_exp_f32_e32 v42, v35
	v_sub_f32_e32 v35, v43, v58
	v_add_f32_e32 v59, v64, v59
	v_mul_f32_e32 v35, 0x3fb8aa3b, v35
	v_add_f32_e32 v59, v65, v59
	v_exp_f32_e32 v43, v35
	v_sub_f32_e32 v35, v44, v58
	v_add_f32_e32 v34, v121, v59
	v_mul_f32_e32 v35, 0x3fb8aa3b, v35
	v_add_f32_e32 v34, v124, v34
	v_exp_f32_e32 v44, v35
	v_sub_f32_e32 v35, v45, v58
	v_add_f32_e32 v34, v125, v34
	v_mul_f32_e32 v35, 0x3fb8aa3b, v35
	v_add_f32_e32 v34, v126, v34
	v_exp_f32_e32 v45, v35
	v_sub_f32_e32 v35, v46, v58
	v_add_f32_e32 v34, v38, v34
	v_mul_f32_e32 v35, 0x3fb8aa3b, v35
	v_add_f32_e32 v34, v39, v34
	v_exp_f32_e32 v46, v35
	v_sub_f32_e32 v35, v47, v58
	v_add_f32_e32 v34, v40, v34
	v_mul_f32_e32 v35, 0x3fb8aa3b, v35
	v_add_f32_e32 v34, v41, v34
	v_exp_f32_e32 v47, v35
	v_sub_f32_e32 v35, v48, v58
	v_add_f32_e32 v34, v42, v34
	v_mul_f32_e32 v35, 0x3fb8aa3b, v35
	v_add_f32_e32 v34, v43, v34
	v_exp_f32_e32 v48, v35
	v_sub_f32_e32 v35, v49, v58
	v_add_f32_e32 v34, v44, v34
	v_mul_f32_e32 v35, 0x3fb8aa3b, v35
	v_add_f32_e32 v34, v45, v34
	v_exp_f32_e32 v49, v35
	v_add_f32_e32 v34, v46, v34
	v_add_f32_e32 v34, v47, v34
	v_mul_f32_e32 v120, 0x3fb8aa3b, v120
	v_add_f32_e32 v34, v48, v34
	v_add_f32_e32 v59, v49, v34
	v_exp_f32_e32 v34, v120
	v_cvt_pk_f16_f32 v36, v54, v55
	v_cvt_pk_f16_f32 v37, v56, v57
	v_fmac_f32_e32 v59, v119, v34
	v_pk_mul_f32 v[2:3], v[2:3], v[34:35] op_sel_hi:[1,0]
	v_pk_mul_f32 v[4:5], v[4:5], v[34:35] op_sel_hi:[1,0]
	v_pk_mul_f32 v[6:7], v[6:7], v[34:35] op_sel_hi:[1,0]
	v_pk_mul_f32 v[8:9], v[8:9], v[34:35] op_sel_hi:[1,0]
	v_pk_mul_f32 v[10:11], v[10:11], v[34:35] op_sel_hi:[1,0]
	v_pk_mul_f32 v[12:13], v[12:13], v[34:35] op_sel_hi:[1,0]
	v_pk_mul_f32 v[14:15], v[14:15], v[34:35] op_sel_hi:[1,0]
	v_pk_mul_f32 v[16:17], v[16:17], v[34:35] op_sel_hi:[1,0]
	v_pk_mul_f32 v[18:19], v[18:19], v[34:35] op_sel_hi:[1,0]
	v_pk_mul_f32 v[20:21], v[20:21], v[34:35] op_sel_hi:[1,0]
	v_pk_mul_f32 v[22:23], v[22:23], v[34:35] op_sel_hi:[1,0]
	v_pk_mul_f32 v[24:25], v[24:25], v[34:35] op_sel_hi:[1,0]
	v_pk_mul_f32 v[26:27], v[26:27], v[34:35] op_sel_hi:[1,0]
	v_pk_mul_f32 v[28:29], v[28:29], v[34:35] op_sel_hi:[1,0]
	v_pk_mul_f32 v[30:31], v[30:31], v[34:35] op_sel_hi:[1,0]
	v_pk_mul_f32 v[32:33], v[32:33], v[34:35] op_sel_hi:[1,0]
	v_cvt_pk_f16_f32 v34, v50, v51
	v_cvt_pk_f16_f32 v35, v52, v53
	s_waitcnt vmcnt(7)
; template <int HD, int BIAS, bool FULL>
; DI void attn_block(const bf16_t* Kb, int ktb, const bf16_t* Vb, int vtb, int koff, int kpos0, int qp, float slope, const float* rel,
;                    const bf16x8 (&qf)[HD / 16], f32x16 (&o)[HD / 32], float& m, float& l) {
;     ...
;     bf16x8 kreg[NKT][KSQ];
; #pragma unroll
;     for (int kt = 0; kt < NKT; ++kt)
; #pragma unroll
;         for (int ks = 0; ks < KSQ; ++ks) kreg[kt][ks] = *(const bf16x8*)(Kb + (size_t)kt * ktb + ks * 512 + lane * 8);
;     constexpr int NS = FULL ? 4 : 1;
;     bf16x8 vreg[DT][NS];
;     auto loadV = [&]() {
; #pragma unroll
;         for (int si = 0; si < NS; ++si)
; #pragma unroll
;             for (int dt = 0; dt < DT; ++dt) { const int s = FULL ? si : s0; vreg[dt][si] = *(const bf16x8*)(Vb + (size_t)(s >> 1) * vtb + dt * 1024 + (s & 1) * 512 + lane * 8); }
;     };
;     if (VTOP) loadV();
;     __builtin_amdgcn_sched_barrier(0);
;     f32x16 st[NKT];
; #pragma unroll
;     for (int kt = 0; kt < NKT; ++kt) {
; #pragma unroll
;         for (int i = 0; i < 16; ++i) st[kt][i] = 0.f;
; #pragma unroll
;         for (int ks = 0; ks < KSQ; ++ks) st[kt] = MFMA32(kreg[kt][ks], qf[ks], st[kt]);
;     }
;     __builtin_amdgcn_sched_barrier(0);
;     if (!VTOP) loadV();
;     float mx = -1e30f;
; #pragma unroll
;     for (int kt = 0; kt < NKT; ++kt)
; #pragma unroll
;         for (int i = 0; i < 16; ++i) {
;             const int key = kt * 32 + crow(i, h);
;             float s = st[kt][i];
;             const int dk = dq + (kt * 32 + (i & 3) + 8 * (i >> 2));
;     ...
;     for (int si = 0; si < NS; ++si) {
;         u32x4 pw;
;         if (FULL) { const int kt = si >> 1, b0 = (si & 1) * 8; pw = (u32x4){pk2(st[kt][b0], st[kt][b0 + 1]), pk2(st[kt][b0 + 2], st[kt][b0 + 3]), pk2(st[kt][b0 + 4], st[kt][b0 + 5]), pk2(st[kt][b0 + 6], st[kt][b0 + 7])}; }
;         else {
;             const u32x4 lo = {pk2(st[0][0], st[0][1]), pk2(st[0][2], st[0][3]), pk2(st[0][4], st[0][5]), pk2(st[0][6], st[0][7])};
;             const u32x4 hi = {pk2(st[0][8], st[0][9]), pk2(st[0][10], st[0][11]), pk2(st[0][12], st[0][13]), pk2(st[0][14], st[0][15])};
;             pw = (s0 & 1) ? hi : lo;
;         }
;         const bf16x8 pf = __builtin_bit_cast(bf16x8, pw);
; #pragma unroll
;         for (int dt = 0; dt < DT; ++dt) o[dt] = MFMA32(vreg[dt][si], pf, o[dt]);
;     }
; }
	s_nop 0
	v_mfma_f32_32x32x16_f16 v[2:17], v[110:113], v[34:37], v[2:17]
	s_waitcnt vmcnt(5)
	v_mfma_f32_32x32x16_f16 v[18:33], v[106:109], v[34:37], v[18:33]
	v_cvt_pk_f16_f32 v34, v122, v123
	v_cvt_pk_f16_f32 v35, v60, v61
	v_cvt_pk_f16_f32 v36, v62, v63
	v_cvt_pk_f16_f32 v37, v64, v65
	s_nop 1
	v_mfma_f32_32x32x16_f16 v[2:17], v[102:105], v[34:37], v[2:17]
	s_waitcnt vmcnt(4)
	v_mfma_f32_32x32x16_f16 v[18:33], v[98:101], v[34:37], v[18:33]
	v_cvt_pk_f16_f32 v34, v121, v124
	v_cvt_pk_f16_f32 v35, v125, v126
	v_cvt_pk_f16_f32 v36, v38, v39
	v_cvt_pk_f16_f32 v37, v40, v41
	s_waitcnt vmcnt(3)
	s_nop 0
	v_mfma_f32_32x32x16_f16 v[2:17], v[94:97], v[34:37], v[2:17]
	s_waitcnt vmcnt(1)
	v_mfma_f32_32x32x16_f16 v[18:33], v[90:93], v[34:37], v[18:33]
	v_cvt_pk_f16_f32 v34, v42, v43
	v_cvt_pk_f16_f32 v35, v44, v45
	v_cvt_pk_f16_f32 v36, v46, v47
	v_cvt_pk_f16_f32 v37, v48, v49
	s_nop 1
	v_mfma_f32_32x32x16_f16 v[2:17], v[86:89], v[34:37], v[2:17]
	s_waitcnt vmcnt(0)
	v_mfma_f32_32x32x16_f16 v[18:33], v[82:85], v[34:37], v[18:33]
	s_cbranch_scc0 .LBB0_329
	v_mov_b32_e32 v34, v176
	s_lshl_b32 s0, s96, 10
	v_lshrrev_b32_e32 v35, 3, v34
	v_and_b32_e32 v63, 4, v35
	v_or_b32_e32 v35, s97, v117
	v_lshlrev_b32_e32 v34, 4, v34
	v_sub_u32_e32 v62, v63, v35
	v_and_b32_e32 v38, 0x3f0, v34
	global_load_dwordx4 v[34:37], v38, s[66:67]
	global_load_dwordx4 v[82:85], v38, s[66:67] offset:1024
	global_load_dwordx4 v[86:89], v38, s[66:67] offset:2048
	global_load_dwordx4 v[90:93], v38, s[66:67] offset:3072
	s_add_u32 s0, s57, s0
	s_addc_u32 s1, s60, 0
	global_load_dwordx4 v[50:53], v38, s[0:1]
	global_load_dwordx4 v[54:57], v38, s[0:1] offset:2048
	s_waitcnt vmcnt(5)
	v_mfma_f32_32x32x16_f16 v[34:49], v[34:37], v[78:81], 0
	s_waitcnt vmcnt(4)
	v_mfma_f32_32x32x16_f16 v[34:49], v[82:85], v[74:77], v[34:49]
	s_waitcnt vmcnt(3)
	v_mfma_f32_32x32x16_f16 v[34:49], v[86:89], v[66:69], v[34:49]
	s_waitcnt vmcnt(2)
	v_mfma_f32_32x32x16_f16 v[34:49], v[90:93], v[70:73], v[34:49]
	v_cmp_gt_u32_e64 s[0:1], s97, v63
	v_cmp_le_u32_e32 vcc, s97, v63
	v_mov_b32_e32 v60, 0xf149f2ca
	v_mov_b32_e32 v61, 0xf149f2ca
	s_and_saveexec_b64 s[2:3], vcc
	s_cbranch_execz .LBB0_332
	v_med3_i32 v61, v62, s45, v186
	v_lshl_add_u32 v61, v61, 2, s61
	ds_read_b32 v61, v61 offset:1024
	s_waitcnt lgkmcnt(0)
	s_nop 1
	v_add_f32_e32 v61, v34, v61

; #define MFMA32(a, b, c) __builtin_amdgcn_mfma_f32_32x32x16_f16((a), (b), (c), 0, 0, 0)
; DI int crow(int i, int h) { return (i & 3) + 8 * (i >> 2) + 4 * h; }
; template <int HD, int BIAS, bool FULL>
; DI void attn_block(const bf16_t* Kb, int ktb, const bf16_t* Vb, int vtb, int koff, int kpos0, int qp, float slope, const float* rel,
;                    const bf16x8 (&qf)[HD / 16], f32x16 (&o)[HD / 32], float& m, float& l) {
;     ...
;     bf16x8 kreg[NKT][KSQ];
; #pragma unroll
;     for (int kt = 0; kt < NKT; ++kt)
; #pragma unroll
;         for (int ks = 0; ks < KSQ; ++ks) kreg[kt][ks] = *(const bf16x8*)(Kb + (size_t)kt * ktb + ks * 512 + lane * 8);
;     constexpr int NS = FULL ? 4 : 1;
;     bf16x8 vreg[DT][NS];
;     auto loadV = [&]() {
; #pragma unroll
;         for (int si = 0; si < NS; ++si)
; #pragma unroll
;             for (int dt = 0; dt < DT; ++dt) { const int s = FULL ? si : s0; vreg[dt][si] = *(const bf16x8*)(Vb + (size_t)(s >> 1) * vtb + dt * 1024 + (s & 1) * 512 + lane * 8); }
;     };
;     if (VTOP) loadV();
;     __builtin_amdgcn_sched_barrier(0);
;     f32x16 st[NKT];
; #pragma unroll
;     for (int kt = 0; kt < NKT; ++kt) {
; #pragma unroll
;         for (int i = 0; i < 16; ++i) st[kt][i] = 0.f;
; #pragma unroll
;         for (int ks = 0; ks < KSQ; ++ks) st[kt] = MFMA32(kreg[kt][ks], qf[ks], st[kt]);
;     }
;     __builtin_amdgcn_sched_barrier(0);
;     if (!VTOP) loadV();
;     float mx = -1e30f;
; #pragma unroll
;     for (int kt = 0; kt < NKT; ++kt)
; #pragma unroll
;         for (int i = 0; i < 16; ++i) {
;             const int key = kt * 32 + crow(i, h);
;             float s = st[kt][i];
;             const int dk = dq + (kt * 32 + (i & 3) + 8 * (i >> 2));
;             if (BIAS == 1) s -= slope * (float)(dk < 0 ? -dk : dk);
;             if (BIAS == 2) { int d = dk < -256 ? -256 : (dk > 256 ? 256 : dk); s += rel[d + 256]; }
;             if (!FULL) { if (key < kbeg || key >= kend) s = -1e30f; }
;             st[kt][i] = s; mx = fmaxf(mx, s);
.LBB0_362:
	v_mov_b32_e32 v0, v176
	s_mov_b32 s29, 0x1020000
	v_lshrrev_b32_e32 v34, 3, v0
	v_and_b32_e32 v0, 63, v0
	v_and_b32_e32 v34, 4, v34
	v_lshlrev_b32_e32 v0, 4, v0
	s_waitcnt vmcnt(4)
	v_add_u32_e32 v120, v115, v34
	v_lshl_add_u64 v[34:35], s[0:1], 0, v[0:1]
	v_add_co_u32_e32 v50, vcc, s22, v34
	global_load_dwordx4 v[38:41], v0, s[0:1]
	global_load_dwordx4 v[42:45], v0, s[0:1] offset:1024
	global_load_dwordx4 v[46:49], v0, s[0:1] offset:2048
	global_load_dwordx4 v[122:125], v0, s[0:1] offset:3072
	v_addc_co_u32_e32 v51, vcc, 0, v35, vcc
	global_load_dwordx4 v[126:129], v[50:51], off
	global_load_dwordx4 v[130:133], v[50:51], off offset:1024
	global_load_dwordx4 v[134:137], v[50:51], off offset:2048
	global_load_dwordx4 v[138:141], v[50:51], off offset:3072
	v_add_co_u32_e32 v50, vcc, s29, v34
	s_mov_b32 s29, 0x1028000
	s_nop 0
	v_addc_co_u32_e32 v51, vcc, 0, v35, vcc
	v_add_co_u32_e32 v34, vcc, s29, v34
	global_load_dwordx4 v[102:105], v[50:51], off
	global_load_dwordx4 v[90:93], v[50:51], off offset:1024
	global_load_dwordx4 v[110:113], v[50:51], off offset:2048
	global_load_dwordx4 v[94:97], v[50:51], off offset:3072
	v_addc_co_u32_e32 v35, vcc, 0, v35, vcc
	global_load_dwordx4 v[98:101], v[34:35], off
	global_load_dwordx4 v[82:85], v[34:35], off offset:1024
	global_load_dwordx4 v[106:109], v[34:35], off offset:2048
	global_load_dwordx4 v[86:89], v[34:35], off offset:3072
	v_mov_b32_e32 v119, v36
	s_waitcnt vmcnt(15)
	v_mfma_f32_32x32x16_f16 v[50:65], v[38:41], v[66:69], 0
	s_waitcnt vmcnt(14)
	v_mfma_f32_32x32x16_f16 v[50:65], v[42:45], v[70:73], v[50:65]
	s_waitcnt vmcnt(13)
	v_mfma_f32_32x32x16_f16 v[50:65], v[46:49], v[74:77], v[50:65]
	s_waitcnt vmcnt(11)
	v_mfma_f32_32x32x16_f16 v[34:49], v[126:129], v[66:69], 0
	s_waitcnt vmcnt(10)
	v_mfma_f32_32x32x16_f16 v[34:49], v[130:133], v[70:73], v[34:49]
	s_waitcnt vmcnt(9)
	v_mfma_f32_32x32x16_f16 v[34:49], v[134:137], v[74:77], v[34:49]
	s_waitcnt vmcnt(8)
	v_mfma_f32_32x32x16_f16 v[34:49], v[138:141], v[78:81], v[34:49]
	v_mfma_f32_32x32x16_f16 v[50:65], v[122:125], v[78:81], v[50:65]
	v_add_u32_e32 v142, 2, v120
	v_med3_i32 v142, v142, s45, v186
	v_lshl_add_u32 v142, v142, 2, s3
	ds_read_b32 v142, v142 offset:1024
	v_med3_i32 v143, v120, s45, v186
	v_lshl_add_u32 v143, v143, 2, s3
	ds_read_b32 v143, v143 offset:1024
	v_add_u32_e32 v144, 3, v120
	v_med3_i32 v144, v144, s45, v186
	v_lshl_add_u32 v144, v144, 2, s3
	ds_read_b32 v144, v144 offset:1024
	v_add_u32_e32 v145, 8, v120
	v_med3_i32 v145, v145, s45, v186
	v_lshl_add_u32 v145, v145, 2, s3
	ds_read_b32 v145, v145 offset:1024
	v_add_u32_e32 v146, 9, v120
	v_med3_i32 v146, v146, s45, v186
	v_lshl_add_u32 v146, v146, 2, s3
	ds_read_b32 v146, v146 offset:1024
	v_add_u32_e32 v147, 10, v120
	v_med3_i32 v147, v147, s45, v186
	v_lshl_add_u32 v147, v147, 2, s3
	ds_read_b32 v147, v147 offset:1024
	v_add_u32_e32 v148, 11, v120
	v_med3_i32 v148, v148, s45, v186
	v_lshl_add_u32 v148, v148, 2, s3
	ds_read_b32 v148, v148 offset:1024
	v_add_u32_e32 v149, 16, v120
	v_med3_i32 v149, v149, s45, v186
	v_lshl_add_u32 v149, v149, 2, s3
	ds_read_b32 v149, v149 offset:1024
	v_add_u32_e32 v150, 17, v120
	v_med3_i32 v150, v150, s45, v186
	v_lshl_add_u32 v150, v150, 2, s3
	ds_read_b32 v150, v150 offset:1024
	v_add_u32_e32 v151, 18, v120
	v_med3_i32 v151, v151, s45, v186
	v_lshl_add_u32 v151, v151, 2, s3
	ds_read_b32 v151, v151 offset:1024
	v_add_u32_e32 v152, 19, v120
	v_med3_i32 v152, v152, s45, v186
	v_lshl_add_u32 v152, v152, 2, s3
	ds_read_b32 v152, v152 offset:1024
	v_add_u32_e32 v153, 24, v120
	v_med3_i32 v153, v153, s45, v186
	v_lshl_add_u32 v153, v153, 2, s3
	ds_read_b32 v153, v153 offset:1024
	v_add_u32_e32 v154, 25, v120
	v_med3_i32 v154, v154, s45, v186
	v_lshl_add_u32 v154, v154, 2, s3
	ds_read_b32 v154, v154 offset:1024
	v_add_u32_e32 v155, 26, v120
	v_med3_i32 v155, v155, s45, v186
	v_lshl_add_u32 v155, v155, 2, s3
	ds_read_b32 v155, v155 offset:1024
	v_add_u32_e32 v156, 27, v120
	v_med3_i32 v156, v156, s45, v186
	v_lshl_add_u32 v156, v156, 2, s3
	ds_read_b32 v156, v156 offset:1024
	v_add_u32_e32 v157, 32, v120
	v_med3_i32 v157, v157, s45, v186
	v_lshl_add_u32 v157, v157, 2, s3
	ds_read_b32 v157, v157 offset:1024
	v_add_u32_e32 v158, 33, v120
	v_med3_i32 v158, v158, s45, v186
	v_lshl_add_u32 v158, v158, 2, s3
	ds_read_b32 v158, v158 offset:1024
	v_add_u32_e32 v159, 1, v120
	v_med3_i32 v159, v159, s45, v186
	v_lshl_add_u32 v159, v159, 2, s3
	v_add_u32_e32 v160, 34, v120
	v_med3_i32 v160, v160, s45, v186
	v_lshl_add_u32 v160, v160, 2, s3
	ds_read_b32 v159, v159 offset:1024
	ds_read_b32 v160, v160 offset:1024
	v_add_u32_e32 v161, 35, v120
	v_med3_i32 v161, v161, s45, v186
	v_lshl_add_u32 v161, v161, 2, s3
	ds_read_b32 v161, v161 offset:1024
	v_add_u32_e32 v162, 40, v120
	v_med3_i32 v162, v162, s45, v186
	v_lshl_add_u32 v162, v162, 2, s3
	ds_read_b32 v162, v162 offset:1024
	v_add_u32_e32 v163, 41, v120
	v_med3_i32 v163, v163, s45, v186
	v_lshl_add_u32 v163, v163, 2, s3
	ds_read_b32 v163, v163 offset:1024
	v_add_u32_e32 v164, 42, v120
	v_med3_i32 v164, v164, s45, v186
	v_lshl_add_u32 v164, v164, 2, s3
	ds_read_b32 v164, v164 offset:1024
	v_add_u32_e32 v165, 43, v120
	v_med3_i32 v165, v165, s45, v186
	v_lshl_add_u32 v165, v165, 2, s3
	ds_read_b32 v165, v165 offset:1024
	v_add_u32_e32 v166, 48, v120
	v_med3_i32 v166, v166, s45, v186
	v_lshl_add_u32 v166, v166, 2, s3
	ds_read_b32 v166, v166 offset:1024
	v_add_u32_e32 v167, 49, v120
	v_med3_i32 v167, v167, s45, v186
	v_lshl_add_u32 v167, v167, 2, s3
	ds_read_b32 v167, v167 offset:1024
	v_add_u32_e32 v168, 50, v120
	v_med3_i32 v168, v168, s45, v186
	v_lshl_add_u32 v168, v168, 2, s3
	ds_read_b32 v168, v168 offset:1024
	v_add_u32_e32 v169, 51, v120
	v_med3_i32 v169, v169, s45, v186
	v_lshl_add_u32 v169, v169, 2, s3
	ds_read_b32 v169, v169 offset:1024
	v_add_u32_e32 v170, 56, v120
	v_med3_i32 v170, v170, s45, v186
	v_lshl_add_u32 v170, v170, 2, s3
	ds_read_b32 v170, v170 offset:1024
	v_add_u32_e32 v171, 57, v120
	v_med3_i32 v171, v171, s45, v186
	v_lshl_add_u32 v171, v171, 2, s3
	ds_read_b32 v171, v171 offset:1024
	v_add_u32_e32 v172, 58, v120
	v_med3_i32 v172, v172, s45, v186
	v_lshl_add_u32 v172, v172, 2, s3
	ds_read_b32 v172, v172 offset:1024
	v_add_u32_e32 v173, 59, v120
	v_med3_i32 v173, v173, s45, v186
	v_lshl_add_u32 v173, v173, 2, s3
	ds_read_b32 v173, v173 offset:1024
	s_waitcnt lgkmcnt(0)
; DI int crow(int i, int h) { return (i & 3) + 8 * (i >> 2) + 4 * h; }
; template <int HD, int BIAS, bool FULL>
; DI void attn_block(const bf16_t* Kb, int ktb, const bf16_t* Vb, int vtb, int koff, int kpos0, int qp, float slope, const float* rel,
;                    const bf16x8 (&qf)[HD / 16], f32x16 (&o)[HD / 32], float& m, float& l) {
;     ...
;     for (int kt = 0; kt < NKT; ++kt)
; #pragma unroll
;         for (int i = 0; i < 16; ++i) {
;             const int key = kt * 32 + crow(i, h);
;             float s = st[kt][i];
;             const int dk = dq + (kt * 32 + (i & 3) + 8 * (i >> 2));
;             if (BIAS == 1) s -= slope * (float)(dk < 0 ? -dk : dk);
;             if (BIAS == 2) { int d = dk < -256 ? -256 : (dk > 256 ? 256 : dk); s += rel[d + 256]; }
;             if (!FULL) { if (key < kbeg || key >= kend) s = -1e30f; }
;             st[kt][i] = s; mx = fmaxf(mx, s);
;         }
;     mx = fmaxf(mx, __shfl_xor(mx, 32));
;     const float mn = fmaxf(m, mx);
	s_add_i32 s28, s28, 1
	s_nop 2
	v_add_f32_e32 v52, v52, v142
	s_add_u32 s0, s0, 0x10000
	s_addc_u32 s1, s1, 0
	v_add_u32_e32 v115, 64, v115
	s_cmp_lg_u32 s73, s28
	v_add_f32_e32 v53, v53, v144
	v_add_f32_e32 v54, v54, v145
	v_add_f32_e32 v55, v55, v146
	v_add_f32_e32 v56, v56, v147
	v_add_f32_e32 v57, v57, v148
	v_add_f32_e32 v58, v58, v149
	v_add_f32_e32 v59, v59, v150
	v_add_f32_e32 v60, v60, v151
	v_add_f32_e32 v61, v61, v152
	v_add_f32_e32 v62, v62, v153
	v_add_f32_e32 v63, v63, v154
	v_add_f32_e32 v64, v64, v155
	v_add_f32_e32 v65, v65, v156
	v_add_f32_e32 v121, v34, v157
	v_add_f32_e32 v50, v50, v143
	v_add_f32_e32 v122, v35, v158
	v_add_f32_e32 v51, v51, v159
	v_add_f32_e32 v36, v36, v160
	v_max3_f32 v0, v50, s46, v51
	v_max3_f32 v0, v0, v52, v53
	v_max3_f32 v0, v0, v54, v55
	v_max3_f32 v0, v0, v56, v57
	v_add_f32_e32 v123, v37, v161
	v_max3_f32 v0, v0, v58, v59
	v_max3_f32 v0, v0, v60, v61
	v_max3_f32 v0, v0, v62, v63
	v_max3_f32 v0, v0, v64, v65
	v_add_f32_e32 v38, v38, v162
	v_max3_f32 v0, v0, v121, v122
	v_max3_f32 v0, v0, v36, v123
	v_add_f32_e32 v39, v39, v163
	v_max3_f32 v0, v0, v38, v39
	v_add_f32_e32 v40, v40, v164
	v_add_f32_e32 v41, v41, v165
	v_max3_f32 v0, v0, v40, v41
	v_add_f32_e32 v42, v42, v166
	v_add_f32_e32 v43, v43, v167
	v_max3_f32 v0, v0, v42, v43
	v_add_f32_e32 v44, v44, v168
	v_add_f32_e32 v45, v45, v169
	v_max3_f32 v0, v0, v44, v45
	v_add_f32_e32 v46, v46, v170
	v_add_f32_e32 v47, v47, v171
	v_max3_f32 v0, v0, v46, v47
	v_add_f32_e32 v48, v48, v172
	v_add_f32_e32 v49, v49, v173
	v_max3_f32 v37, v0, v48, v49
	v_mbcnt_hi_u32_b32 v0, -1, v178
	v_and_b32_e32 v35, 64, v0
	v_xor_b32_e32 v34, 32, v0
	v_add_u32_e32 v35, 64, v35
	v_cmp_lt_i32_e32 vcc, v34, v35
	s_nop 1
	v_cndmask_b32_e32 v120, v0, v34, vcc
	v_lshlrev_b32_e32 v120, 2, v120
	ds_bpermute_b32 v120, v120, v37
	s_waitcnt lgkmcnt(0)
; #define MFMA32(a, b, c) __builtin_amdgcn_mfma_f32_32x32x16_f16((a), (b), (c), 0, 0, 0)
; DI unsigned pk2(float lo, float hi) { f32x2 v = {lo, hi}; bf2_t b = __builtin_convertvector(v, bf2_t); return __builtin_bit_cast(unsigned, b); }
; template <int HD, int BIAS, bool FULL>
; DI void attn_block(const bf16_t* Kb, int ktb, const bf16_t* Vb, int vtb, int koff, int kpos0, int qp, float slope, const float* rel,
;                    const bf16x8 (&qf)[HD / 16], f32x16 (&o)[HD / 32], float& m, float& l) {
;     ...
;     const float mn = fmaxf(m, mx);
;     const float alpha = __builtin_amdgcn_exp2f((m - mn) * LOG2E);
;     m = mn;
;     float ps = 0.f;
; #pragma unroll
;     for (int kt = 0; kt < NKT; ++kt)
; #pragma unroll
;         for (int i = 0; i < 16; ++i) { const float pv = __builtin_amdgcn_exp2f((st[kt][i] - mn) * LOG2E); st[kt][i] = pv; ps += pv; }
;     l = l * alpha + ps;
; #pragma unroll
;     for (int dt = 0; dt < DT; ++dt)
; #pragma unroll
;         for (int i = 0; i < 16; ++i) o[dt][i] *= alpha;
; #pragma unroll
;     for (int si = 0; si < NS; ++si) {
;         u32x4 pw;
;         if (FULL) { const int kt = si >> 1, b0 = (si & 1) * 8; pw = (u32x4){pk2(st[kt][b0], st[kt][b0 + 1]), pk2(st[kt][b0 + 2], st[kt][b0 + 3]), pk2(st[kt][b0 + 4], st[kt][b0 + 5]), pk2(st[kt][b0 + 6], st[kt][b0 + 7])}; }
;         else {
;             const u32x4 lo = {pk2(st[0][0], st[0][1]), pk2(st[0][2], st[0][3]), pk2(st[0][4], st[0][5]), pk2(st[0][6], st[0][7])};
;             const u32x4 hi = {pk2(st[0][8], st[0][9]), pk2(st[0][10], st[0][11]), pk2(st[0][12], st[0][13]), pk2(st[0][14], st[0][15])};
;             pw = (s0 & 1) ? hi : lo;
;         }
;         const bf16x8 pf = __builtin_bit_cast(bf16x8, pw);
; #pragma unroll
;         for (int dt = 0; dt < DT; ++dt) o[dt] = MFMA32(vreg[dt][si], pf, o[dt]);
;     }
; }
	v_max3_f32 v37, v118, v37, v120
	v_sub_f32_e32 v50, v50, v37
	v_mul_f32_e32 v50, 0x3fb8aa3b, v50
	v_sub_f32_e32 v51, v51, v37
	v_exp_f32_e32 v50, v50
	v_mul_f32_e32 v51, 0x3fb8aa3b, v51
	v_sub_f32_e32 v52, v52, v37
	v_exp_f32_e32 v51, v51
	v_mul_f32_e32 v52, 0x3fb8aa3b, v52
	v_sub_f32_e32 v53, v53, v37
	v_exp_f32_e32 v52, v52
	v_mul_f32_e32 v53, 0x3fb8aa3b, v53
	v_sub_f32_e32 v54, v54, v37
	v_exp_f32_e32 v53, v53
	v_mul_f32_e32 v54, 0x3fb8aa3b, v54
	v_sub_f32_e32 v55, v55, v37
	v_add_f32_e32 v120, 0, v50
	v_exp_f32_e32 v54, v54
	v_mul_f32_e32 v55, 0x3fb8aa3b, v55
	v_sub_f32_e32 v56, v56, v37
	v_add_f32_e32 v120, v51, v120
	v_exp_f32_e32 v55, v55
	v_mul_f32_e32 v56, 0x3fb8aa3b, v56
	v_sub_f32_e32 v57, v57, v37
	v_add_f32_e32 v120, v52, v120
	v_exp_f32_e32 v56, v56
	v_mul_f32_e32 v57, 0x3fb8aa3b, v57
	v_sub_f32_e32 v58, v58, v37
	v_add_f32_e32 v120, v53, v120
	v_exp_f32_e32 v57, v57
	v_mul_f32_e32 v58, 0x3fb8aa3b, v58
	v_sub_f32_e32 v59, v59, v37
	v_add_f32_e32 v120, v54, v120
	v_exp_f32_e32 v58, v58
	v_mul_f32_e32 v59, 0x3fb8aa3b, v59
	v_sub_f32_e32 v60, v60, v37
	v_add_f32_e32 v120, v55, v120
	v_exp_f32_e32 v59, v59
	v_mul_f32_e32 v60, 0x3fb8aa3b, v60
	v_sub_f32_e32 v61, v61, v37
	v_add_f32_e32 v120, v56, v120
	v_exp_f32_e32 v60, v60
	v_mul_f32_e32 v61, 0x3fb8aa3b, v61
	v_sub_f32_e32 v62, v62, v37
	v_add_f32_e32 v120, v57, v120
	v_exp_f32_e32 v61, v61
	v_mul_f32_e32 v62, 0x3fb8aa3b, v62
	v_sub_f32_e32 v63, v63, v37
	v_add_f32_e32 v120, v58, v120
	v_exp_f32_e32 v62, v62
	v_mul_f32_e32 v63, 0x3fb8aa3b, v63
	v_sub_f32_e32 v64, v64, v37
	v_add_f32_e32 v120, v59, v120
	v_exp_f32_e32 v63, v63
	v_mul_f32_e32 v64, 0x3fb8aa3b, v64
	v_sub_f32_e32 v65, v65, v37
	v_add_f32_e32 v120, v60, v120
	v_exp_f32_e32 v64, v64
	v_mul_f32_e32 v65, 0x3fb8aa3b, v65
	v_sub_f32_e32 v121, v121, v37
	v_add_f32_e32 v120, v61, v120
	v_exp_f32_e32 v65, v65
	v_mul_f32_e32 v121, 0x3fb8aa3b, v121
	v_sub_f32_e32 v122, v122, v37
	v_add_f32_e32 v120, v62, v120
	v_exp_f32_e32 v121, v121
	v_mul_f32_e32 v122, 0x3fb8aa3b, v122
	v_sub_f32_e32 v36, v36, v37
	v_add_f32_e32 v120, v63, v120
	v_exp_f32_e32 v122, v122
	v_mul_f32_e32 v36, 0x3fb8aa3b, v36
	v_add_f32_e32 v120, v64, v120
	v_exp_f32_e32 v124, v36
	v_add_f32_e32 v120, v65, v120
	v_add_f32_e32 v120, v121, v120
	v_sub_f32_e32 v38, v38, v37
	v_add_f32_e32 v120, v122, v120
	v_mul_f32_e32 v38, 0x3fb8aa3b, v38
	v_add_f32_e32 v36, v124, v120
	v_sub_f32_e32 v120, v123, v37
	v_exp_f32_e32 v123, v38
	v_sub_f32_e32 v38, v39, v37
	v_mul_f32_e32 v38, 0x3fb8aa3b, v38
	v_exp_f32_e32 v125, v38
	v_sub_f32_e32 v38, v40, v37
	v_mul_f32_e32 v38, 0x3fb8aa3b, v38
	v_exp_f32_e32 v126, v38
	v_sub_f32_e32 v38, v41, v37
	v_mul_f32_e32 v38, 0x3fb8aa3b, v38
	v_exp_f32_e32 v127, v38
	v_sub_f32_e32 v38, v42, v37
	v_mul_f32_e32 v38, 0x3fb8aa3b, v38
	v_exp_f32_e32 v42, v38
	v_sub_f32_e32 v38, v43, v37
	v_mul_f32_e32 v120, 0x3fb8aa3b, v120
	v_mul_f32_e32 v38, 0x3fb8aa3b, v38
	v_exp_f32_e32 v120, v120
	v_exp_f32_e32 v43, v38
	v_sub_f32_e32 v38, v44, v37
	v_mul_f32_e32 v38, 0x3fb8aa3b, v38
	v_exp_f32_e32 v44, v38
	v_sub_f32_e32 v38, v45, v37
	v_mul_f32_e32 v38, 0x3fb8aa3b, v38
	v_add_f32_e32 v36, v120, v36
	v_exp_f32_e32 v45, v38
	v_sub_f32_e32 v38, v46, v37
	v_add_f32_e32 v36, v123, v36
	v_mul_f32_e32 v38, 0x3fb8aa3b, v38
	v_add_f32_e32 v36, v125, v36
	v_exp_f32_e32 v46, v38
	v_sub_f32_e32 v38, v47, v37
	v_add_f32_e32 v36, v126, v36
	v_mul_f32_e32 v38, 0x3fb8aa3b, v38
	v_add_f32_e32 v36, v127, v36
	v_exp_f32_e32 v47, v38
	v_sub_f32_e32 v38, v48, v37
	v_add_f32_e32 v36, v42, v36
	v_mul_f32_e32 v38, 0x3fb8aa3b, v38
	v_add_f32_e32 v36, v43, v36
	v_exp_f32_e32 v48, v38
	v_sub_f32_e32 v38, v49, v37
	v_sub_f32_e32 v118, v118, v37
	v_add_f32_e32 v36, v44, v36
	v_mul_f32_e32 v38, 0x3fb8aa3b, v38
	v_mul_f32_e32 v118, 0x3fb8aa3b, v118
	v_add_f32_e32 v36, v45, v36
	v_exp_f32_e32 v49, v38
	v_add_f32_e32 v36, v46, v36
	v_exp_f32_e32 v38, v118
	v_add_f32_e32 v36, v47, v36
	v_add_f32_e32 v36, v48, v36
	v_add_f32_e32 v36, v49, v36
	v_fmac_f32_e32 v36, v119, v38
	v_pk_mul_f32 v[18:19], v[18:19], v[38:39] op_sel_hi:[1,0]
	v_pk_mul_f32 v[20:21], v[20:21], v[38:39] op_sel_hi:[1,0]
	v_pk_mul_f32 v[22:23], v[22:23], v[38:39] op_sel_hi:[1,0]
	v_pk_mul_f32 v[24:25], v[24:25], v[38:39] op_sel_hi:[1,0]
	v_pk_mul_f32 v[26:27], v[26:27], v[38:39] op_sel_hi:[1,0]
	v_pk_mul_f32 v[28:29], v[28:29], v[38:39] op_sel_hi:[1,0]
	v_pk_mul_f32 v[30:31], v[30:31], v[38:39] op_sel_hi:[1,0]
	v_pk_mul_f32 v[32:33], v[32:33], v[38:39] op_sel_hi:[1,0]
	v_pk_mul_f32 v[2:3], v[2:3], v[38:39] op_sel_hi:[1,0]
	v_pk_mul_f32 v[4:5], v[4:5], v[38:39] op_sel_hi:[1,0]
	v_pk_mul_f32 v[6:7], v[6:7], v[38:39] op_sel_hi:[1,0]
	v_pk_mul_f32 v[8:9], v[8:9], v[38:39] op_sel_hi:[1,0]
	v_pk_mul_f32 v[10:11], v[10:11], v[38:39] op_sel_hi:[1,0]
	v_pk_mul_f32 v[12:13], v[12:13], v[38:39] op_sel_hi:[1,0]
	v_pk_mul_f32 v[14:15], v[14:15], v[38:39] op_sel_hi:[1,0]
	v_pk_mul_f32 v[16:17], v[16:17], v[38:39] op_sel_hi:[1,0]
	v_cvt_pk_f16_f32 v38, v50, v51
	v_cvt_pk_f16_f32 v39, v52, v53
	v_cvt_pk_f16_f32 v40, v54, v55
	v_cvt_pk_f16_f32 v41, v56, v57
	v_mov_b32_e32 v118, v37
	s_waitcnt vmcnt(7)
	v_mfma_f32_32x32x16_f16 v[18:33], v[102:105], v[38:41], v[18:33]
	s_waitcnt vmcnt(5)
	v_mfma_f32_32x32x16_f16 v[2:17], v[110:113], v[38:41], v[2:17]
	v_cvt_pk_f16_f32 v38, v58, v59
	v_cvt_pk_f16_f32 v39, v60, v61
	v_cvt_pk_f16_f32 v40, v62, v63
	v_cvt_pk_f16_f32 v41, v64, v65
	s_nop 1
	v_mfma_f32_32x32x16_f16 v[18:33], v[90:93], v[38:41], v[18:33]
	s_waitcnt vmcnt(4)
	v_mfma_f32_32x32x16_f16 v[2:17], v[94:97], v[38:41], v[2:17]
	v_cvt_pk_f16_f32 v38, v121, v122
	v_cvt_pk_f16_f32 v39, v124, v120
	v_cvt_pk_f16_f32 v40, v123, v125
	v_cvt_pk_f16_f32 v41, v126, v127
	s_waitcnt vmcnt(3)
	s_nop 0
	v_mfma_f32_32x32x16_f16 v[18:33], v[98:101], v[38:41], v[18:33]
	s_waitcnt vmcnt(1)
	v_mfma_f32_32x32x16_f16 v[2:17], v[106:109], v[38:41], v[2:17]
	v_cvt_pk_f16_f32 v38, v42, v43
	v_cvt_pk_f16_f32 v39, v44, v45
	v_cvt_pk_f16_f32 v40, v46, v47
	v_cvt_pk_f16_f32 v41, v48, v49
	s_nop 1
	v_mfma_f32_32x32x16_f16 v[18:33], v[82:85], v[38:41], v[18:33]
	s_waitcnt vmcnt(0)
	v_mfma_f32_32x32x16_f16 v[2:17], v[86:89], v[38:41], v[2:17]
	s_cbranch_scc1 .LBB0_362

; DI int otid() { int t = threadIdx.x; asm volatile("" : "+v"(t)); return t; }
; DI bf16_t cv1(float x) { return (bf16_t)(pk2(x, 0.f) & 0xffffu); }
; DI int crow(int i, int h) { return (i & 3) + 8 * (i >> 2) + 4 * h; }
; template <int MT> DI void st_bf16(bf16_t* base, int ld, int d2, int col0, const f32x16 (&acc)[MT][NT]) {
;     const int lane = otid() & 63, r = lane & 31, h = lane >> 5;
; #pragma unroll
;     for (int mi = 0; mi < MT; ++mi)
; #pragma unroll
;         for (int nj = 0; nj < NT; ++nj)
; #pragma unroll
;             for (int i = 0; i < 16; ++i) base[(mi * 32 + crow(i, h) + (mi == 2 ? d2 : 0)) * ld + col0 + nj * 32 + r] = cv1(acc[mi][nj][i]);
; }
.LBB0_426:
	s_and_saveexec_b64 s[8:9], s[4:5]
	s_cbranch_execz .LBB0_428
	s_waitcnt vmcnt(0)
	v_lshrrev_b32_e32 v0, 6, v0
	v_and_b32_e32 v98, 31, v176
	v_lshrrev_b32_e32 v99, 3, v176
	v_and_b32_e32 v99, 4, v99
	v_mul_u32_u24_e32 v99, 0x2c00, v99
	v_lshl_add_u32 v100, v98, 1, v99
	v_lshl_add_u32 v100, v0, 7, v100
	v_add_u32_e32 v101, 0x2800, v100
	v_cvt_f16_f32_e32 v105, v82
	global_store_short v101, v105, s[6:7]
	v_cvt_f16_f32_e32 v106, v66
	global_store_short v101, v106, s[6:7] offset:64
	v_add_u32_e32 v102, 0x5400, v100
	v_cvt_f16_f32_e32 v107, v83
	global_store_short v102, v107, s[6:7]
	v_cvt_f16_f32_e32 v108, v67
	global_store_short v102, v108, s[6:7] offset:64
	v_add_u32_e32 v103, 0x8000, v100
	v_cvt_f16_f32_e32 v109, v84
	global_store_short v103, v109, s[6:7]
	v_cvt_f16_f32_e32 v110, v68
	global_store_short v103, v110, s[6:7] offset:64
	v_add_u32_e32 v104, 0xac00, v100
	v_cvt_f16_f32_e32 v111, v85
	global_store_short v104, v111, s[6:7]
	v_cvt_f16_f32_e32 v112, v69
	global_store_short v104, v112, s[6:7] offset:64
	v_add_u32_e32 v101, 0x18800, v100
	v_cvt_f16_f32_e32 v105, v86
	global_store_short v101, v105, s[6:7]
	v_cvt_f16_f32_e32 v106, v70
	global_store_short v101, v106, s[6:7] offset:64
	v_add_u32_e32 v102, 0x1b400, v100
	v_cvt_f16_f32_e32 v107, v87
	global_store_short v102, v107, s[6:7]
	v_cvt_f16_f32_e32 v108, v71
	global_store_short v102, v108, s[6:7] offset:64
	v_add_u32_e32 v103, 0x1e000, v100
	v_cvt_f16_f32_e32 v109, v88
	global_store_short v103, v109, s[6:7]
	v_cvt_f16_f32_e32 v110, v72
	global_store_short v103, v110, s[6:7] offset:64
	v_add_u32_e32 v104, 0x20c00, v100
	v_cvt_f16_f32_e32 v111, v89
	global_store_short v104, v111, s[6:7]
	v_cvt_f16_f32_e32 v112, v73
	global_store_short v104, v112, s[6:7] offset:64
	v_add_u32_e32 v101, 0x2e800, v100
	v_cvt_f16_f32_e32 v105, v90
	global_store_short v101, v105, s[6:7]
	v_cvt_f16_f32_e32 v106, v74
	global_store_short v101, v106, s[6:7] offset:64
	v_add_u32_e32 v102, 0x31400, v100
	v_cvt_f16_f32_e32 v107, v91
	global_store_short v102, v107, s[6:7]
	v_cvt_f16_f32_e32 v108, v75
	global_store_short v102, v108, s[6:7] offset:64
	v_add_u32_e32 v103, 0x34000, v100
	v_cvt_f16_f32_e32 v109, v92
	global_store_short v103, v109, s[6:7]
	v_cvt_f16_f32_e32 v110, v76
	global_store_short v103, v110, s[6:7] offset:64
	v_add_u32_e32 v104, 0x36c00, v100
	v_cvt_f16_f32_e32 v111, v93
	global_store_short v104, v111, s[6:7]
	v_cvt_f16_f32_e32 v112, v77
	global_store_short v104, v112, s[6:7] offset:64
	v_add_u32_e32 v101, 0x44800, v100
	v_cvt_f16_f32_e32 v105, v94
	global_store_short v101, v105, s[6:7]
	v_cvt_f16_f32_e32 v106, v78
	global_store_short v101, v106, s[6:7] offset:64
	v_add_u32_e32 v102, 0x47400, v100
	v_cvt_f16_f32_e32 v107, v95
	global_store_short v102, v107, s[6:7]
	v_cvt_f16_f32_e32 v108, v79
	global_store_short v102, v108, s[6:7] offset:64
	v_add_u32_e32 v103, 0x4a000, v100
	v_cvt_f16_f32_e32 v109, v96
	global_store_short v103, v109, s[6:7]
	v_cvt_f16_f32_e32 v110, v80
	global_store_short v103, v110, s[6:7] offset:64
	v_add_u32_e32 v104, 0x4cc00, v100
	v_cvt_f16_f32_e32 v111, v97
	global_store_short v104, v111, s[6:7]
	v_cvt_f16_f32_e32 v112, v81
	global_store_short v104, v112, s[6:7] offset:64
	v_add_u32_e32 v101, 0x5a800, v100
	v_cvt_f16_f32_e32 v105, v50
	global_store_short v101, v105, s[6:7]
	v_cvt_f16_f32_e32 v106, v34
	global_store_short v101, v106, s[6:7] offset:64
	v_add_u32_e32 v102, 0x5d400, v100
	v_cvt_f16_f32_e32 v107, v51
	global_store_short v102, v107, s[6:7]
	v_cvt_f16_f32_e32 v108, v35
	global_store_short v102, v108, s[6:7] offset:64
	v_add_u32_e32 v103, 0x60000, v100
	v_cvt_f16_f32_e32 v109, v52
	global_store_short v103, v109, s[6:7]
	v_cvt_f16_f32_e32 v110, v36
	global_store_short v103, v110, s[6:7] offset:64
	v_add_u32_e32 v104, 0x62c00, v100
	v_cvt_f16_f32_e32 v111, v53
	global_store_short v104, v111, s[6:7]
	v_cvt_f16_f32_e32 v112, v37
	global_store_short v104, v112, s[6:7] offset:64
	v_add_u32_e32 v101, 0x70800, v100
	v_cvt_f16_f32_e32 v105, v54
	global_store_short v101, v105, s[6:7]
	v_cvt_f16_f32_e32 v106, v38
	global_store_short v101, v106, s[6:7] offset:64
	v_add_u32_e32 v102, 0x73400, v100
	v_cvt_f16_f32_e32 v107, v55
	global_store_short v102, v107, s[6:7]
	v_cvt_f16_f32_e32 v108, v39
	global_store_short v102, v108, s[6:7] offset:64
	v_add_u32_e32 v103, 0x76000, v100
	v_cvt_f16_f32_e32 v109, v56
	global_store_short v103, v109, s[6:7]
	v_cvt_f16_f32_e32 v110, v40
	global_store_short v103, v110, s[6:7] offset:64
	v_add_u32_e32 v104, 0x78c00, v100
	v_cvt_f16_f32_e32 v111, v57
; DI int otid() { int t = threadIdx.x; asm volatile("" : "+v"(t)); return t; }
; DI bf16_t cv1(float x) { return (bf16_t)(pk2(x, 0.f) & 0xffffu); }
; DI int crow(int i, int h) { return (i & 3) + 8 * (i >> 2) + 4 * h; }
; template <int MT> DI void st_bf16(bf16_t* base, int ld, int d2, int col0, const f32x16 (&acc)[MT][NT]) {
;     const int lane = otid() & 63, r = lane & 31, h = lane >> 5;
; #pragma unroll
;     for (int mi = 0; mi < MT; ++mi)
; #pragma unroll
;         for (int nj = 0; nj < NT; ++nj)
; #pragma unroll
;             for (int i = 0; i < 16; ++i) base[(mi * 32 + crow(i, h) + (mi == 2 ? d2 : 0)) * ld + col0 + nj * 32 + r] = cv1(acc[mi][nj][i]);
; }
	global_store_short v104, v111, s[6:7]
	v_cvt_f16_f32_e32 v112, v41
	global_store_short v104, v112, s[6:7] offset:64
	v_add_u32_e32 v101, 0x86800, v100
	v_cvt_f16_f32_e32 v105, v58
	global_store_short v101, v105, s[6:7]
	v_cvt_f16_f32_e32 v106, v42
	global_store_short v101, v106, s[6:7] offset:64
	v_add_u32_e32 v102, 0x89400, v100
	v_cvt_f16_f32_e32 v107, v59
	global_store_short v102, v107, s[6:7]
	v_cvt_f16_f32_e32 v108, v43
	global_store_short v102, v108, s[6:7] offset:64
	v_add_u32_e32 v103, 0x8c000, v100
	v_cvt_f16_f32_e32 v109, v60
	global_store_short v103, v109, s[6:7]
	v_cvt_f16_f32_e32 v110, v44
	global_store_short v103, v110, s[6:7] offset:64
	v_add_u32_e32 v104, 0x8ec00, v100
	v_cvt_f16_f32_e32 v111, v61
	global_store_short v104, v111, s[6:7]
	v_cvt_f16_f32_e32 v112, v45
	global_store_short v104, v112, s[6:7] offset:64
	v_add_u32_e32 v101, 0x9c800, v100
	v_cvt_f16_f32_e32 v105, v62
	global_store_short v101, v105, s[6:7]
	v_cvt_f16_f32_e32 v106, v46
	global_store_short v101, v106, s[6:7] offset:64
	v_add_u32_e32 v102, 0x9f400, v100
	v_cvt_f16_f32_e32 v107, v63
	global_store_short v102, v107, s[6:7]
	v_cvt_f16_f32_e32 v108, v47
	global_store_short v102, v108, s[6:7] offset:64
	v_add_u32_e32 v103, 0xa2000, v100
	v_cvt_f16_f32_e32 v109, v64
	global_store_short v103, v109, s[6:7]
	v_cvt_f16_f32_e32 v110, v48
	global_store_short v103, v110, s[6:7] offset:64
	v_add_u32_e32 v104, 0xa4c00, v100
	v_cvt_f16_f32_e32 v111, v65
	global_store_short v104, v111, s[6:7]
	v_cvt_f16_f32_e32 v112, v49
	global_store_short v104, v112, s[6:7] offset:64
	s_sub_i32 s100, 0x4000, s62
	s_mul_i32 s101, s100, 0x2c00
	v_add_u32_e32 v99, s101, v100
	v_add_u32_e32 v101, 0x2800, v99
	v_cvt_f16_f32_e32 v105, v18
	global_store_short v101, v105, s[6:7]
	v_cvt_f16_f32_e32 v106, v2
	global_store_short v101, v106, s[6:7] offset:64
	v_add_u32_e32 v102, 0x5400, v99
	v_cvt_f16_f32_e32 v107, v19
	global_store_short v102, v107, s[6:7]
	v_cvt_f16_f32_e32 v108, v3
	global_store_short v102, v108, s[6:7] offset:64
	v_add_u32_e32 v103, 0x8000, v99
	v_cvt_f16_f32_e32 v109, v20
	global_store_short v103, v109, s[6:7]
	v_cvt_f16_f32_e32 v110, v4
	global_store_short v103, v110, s[6:7] offset:64
	v_add_u32_e32 v104, 0xac00, v99
	v_cvt_f16_f32_e32 v111, v21
	global_store_short v104, v111, s[6:7]
	v_cvt_f16_f32_e32 v112, v5
	global_store_short v104, v112, s[6:7] offset:64
	v_add_u32_e32 v101, 0x18800, v99
	v_cvt_f16_f32_e32 v105, v22
	global_store_short v101, v105, s[6:7]
	v_cvt_f16_f32_e32 v106, v6
	global_store_short v101, v106, s[6:7] offset:64
	v_add_u32_e32 v102, 0x1b400, v99
	v_cvt_f16_f32_e32 v107, v23
	global_store_short v102, v107, s[6:7]
	v_cvt_f16_f32_e32 v108, v7
	global_store_short v102, v108, s[6:7] offset:64
	v_add_u32_e32 v103, 0x1e000, v99
	v_cvt_f16_f32_e32 v109, v24
	global_store_short v103, v109, s[6:7]
	v_cvt_f16_f32_e32 v110, v8
	global_store_short v103, v110, s[6:7] offset:64
	v_add_u32_e32 v104, 0x20c00, v99
	v_cvt_f16_f32_e32 v111, v25
	global_store_short v104, v111, s[6:7]
	v_cvt_f16_f32_e32 v112, v9
	global_store_short v104, v112, s[6:7] offset:64
	v_add_u32_e32 v101, 0x2e800, v99
	v_cvt_f16_f32_e32 v105, v26
	global_store_short v101, v105, s[6:7]
	v_cvt_f16_f32_e32 v106, v10
	global_store_short v101, v106, s[6:7] offset:64
	v_add_u32_e32 v102, 0x31400, v99
	v_cvt_f16_f32_e32 v107, v27
	global_store_short v102, v107, s[6:7]
	v_cvt_f16_f32_e32 v108, v11
	global_store_short v102, v108, s[6:7] offset:64
	v_add_u32_e32 v103, 0x34000, v99
	v_cvt_f16_f32_e32 v109, v28
	global_store_short v103, v109, s[6:7]
	v_cvt_f16_f32_e32 v110, v12
	global_store_short v103, v110, s[6:7] offset:64
	v_add_u32_e32 v104, 0x36c00, v99
	v_cvt_f16_f32_e32 v111, v29
	global_store_short v104, v111, s[6:7]
	v_cvt_f16_f32_e32 v112, v13
	global_store_short v104, v112, s[6:7] offset:64
	v_add_u32_e32 v101, 0x44800, v99
	v_cvt_f16_f32_e32 v105, v30
	global_store_short v101, v105, s[6:7]
	v_cvt_f16_f32_e32 v106, v14
	global_store_short v101, v106, s[6:7] offset:64
	v_add_u32_e32 v102, 0x47400, v99
	v_cvt_f16_f32_e32 v107, v31
	global_store_short v102, v107, s[6:7]
	v_cvt_f16_f32_e32 v108, v15
	global_store_short v102, v108, s[6:7] offset:64
	v_add_u32_e32 v103, 0x4a000, v99
	v_cvt_f16_f32_e32 v109, v32
	global_store_short v103, v109, s[6:7]
	v_cvt_f16_f32_e32 v110, v16
	global_store_short v103, v110, s[6:7] offset:64
	v_add_u32_e32 v104, 0x4cc00, v99
	v_cvt_f16_f32_e32 v111, v33
	global_store_short v104, v111, s[6:7]
	v_cvt_f16_f32_e32 v112, v17
	global_store_short v104, v112, s[6:7] offset:64

; DI int otid() { int t = threadIdx.x; asm volatile("" : "+v"(t)); return t; }
; DI bf16_t cv1(float x) { return (bf16_t)(pk2(x, 0.f) & 0xffffu); }
; DI int crow(int i, int h) { return (i & 3) + 8 * (i >> 2) + 4 * h; }
; template <int MT> DI void st_bf16(bf16_t* base, int ld, int d2, int col0, const f32x16 (&acc)[MT][NT]) {
;     const int lane = otid() & 63, r = lane & 31, h = lane >> 5;
; #pragma unroll
;     for (int mi = 0; mi < MT; ++mi)
; #pragma unroll
;         for (int nj = 0; nj < NT; ++nj)
; #pragma unroll
;             for (int i = 0; i < 16; ++i) base[(mi * 32 + crow(i, h) + (mi == 2 ? d2 : 0)) * ld + col0 + nj * 32 + r] = cv1(acc[mi][nj][i]);
; }
;     DI void operator()(int unit, const f32x16 (&acc)[MT][NT]) const {
;         st_bf16<MT>(priv, PRIVW, d2, unit * UW, acc);
.LBB0_469:
	s_and_saveexec_b64 s[56:57], s[4:5]
	s_cbranch_execz .LBB0_458
	s_waitcnt vmcnt(0)
	v_and_b32_e32 v2, 31, v176
	v_lshrrev_b32_e32 v3, 3, v176
	v_and_b32_e32 v3, 4, v3
	v_mul_u32_u24_e32 v3, 0x2c00, v3
	v_lshl_add_u32 v4, v2, 1, v3
	v_lshl_add_u32 v4, v233, 7, v4
	v_add_u32_e32 v5, 0, v4
	v_cvt_f16_f32_e32 v116, v96
	global_store_short v5, v116, s[6:7]
	v_cvt_f16_f32_e32 v117, v80
	global_store_short v5, v117, s[6:7] offset:64
	v_add_u32_e32 v112, 0x2c00, v4
	v_cvt_f16_f32_e32 v118, v97
	global_store_short v112, v118, s[6:7]
	v_cvt_f16_f32_e32 v119, v81
	global_store_short v112, v119, s[6:7] offset:64
	v_add_u32_e32 v113, 0x5800, v4
	v_cvt_f16_f32_e32 v120, v98
	global_store_short v113, v120, s[6:7]
	v_cvt_f16_f32_e32 v121, v82
	global_store_short v113, v121, s[6:7] offset:64
	v_add_u32_e32 v114, 0x8400, v4
	v_cvt_f16_f32_e32 v122, v99
	global_store_short v114, v122, s[6:7]
	v_cvt_f16_f32_e32 v123, v83
	global_store_short v114, v123, s[6:7] offset:64
	v_add_u32_e32 v5, 0x16000, v4
	v_cvt_f16_f32_e32 v116, v100
	global_store_short v5, v116, s[6:7]
	v_cvt_f16_f32_e32 v117, v84
	global_store_short v5, v117, s[6:7] offset:64
	v_add_u32_e32 v112, 0x18c00, v4
	v_cvt_f16_f32_e32 v118, v101
	global_store_short v112, v118, s[6:7]
	v_cvt_f16_f32_e32 v119, v85
	global_store_short v112, v119, s[6:7] offset:64
	v_add_u32_e32 v113, 0x1b800, v4
	v_cvt_f16_f32_e32 v120, v102
	global_store_short v113, v120, s[6:7]
	v_cvt_f16_f32_e32 v121, v86
	global_store_short v113, v121, s[6:7] offset:64
	v_add_u32_e32 v114, 0x1e400, v4
	v_cvt_f16_f32_e32 v122, v103
	global_store_short v114, v122, s[6:7]
	v_cvt_f16_f32_e32 v123, v87
	global_store_short v114, v123, s[6:7] offset:64
	v_add_u32_e32 v5, 0x2c000, v4
	v_cvt_f16_f32_e32 v116, v104
	global_store_short v5, v116, s[6:7]
	v_cvt_f16_f32_e32 v117, v88
	global_store_short v5, v117, s[6:7] offset:64
	v_add_u32_e32 v112, 0x2ec00, v4
	v_cvt_f16_f32_e32 v118, v105
	global_store_short v112, v118, s[6:7]
	v_cvt_f16_f32_e32 v119, v89
	global_store_short v112, v119, s[6:7] offset:64
	v_add_u32_e32 v113, 0x31800, v4
	v_cvt_f16_f32_e32 v120, v106
	global_store_short v113, v120, s[6:7]
	v_cvt_f16_f32_e32 v121, v90
	global_store_short v113, v121, s[6:7] offset:64
	v_add_u32_e32 v114, 0x34400, v4
	v_cvt_f16_f32_e32 v122, v107
	global_store_short v114, v122, s[6:7]
	v_cvt_f16_f32_e32 v123, v91
	global_store_short v114, v123, s[6:7] offset:64
	v_add_u32_e32 v5, 0x42000, v4
	v_cvt_f16_f32_e32 v116, v108
	global_store_short v5, v116, s[6:7]
	v_cvt_f16_f32_e32 v117, v92
	global_store_short v5, v117, s[6:7] offset:64
	v_add_u32_e32 v112, 0x44c00, v4
	v_cvt_f16_f32_e32 v118, v109
	global_store_short v112, v118, s[6:7]
	v_cvt_f16_f32_e32 v119, v93
	global_store_short v112, v119, s[6:7] offset:64
	v_add_u32_e32 v113, 0x47800, v4
	v_cvt_f16_f32_e32 v120, v110
	global_store_short v113, v120, s[6:7]
	v_cvt_f16_f32_e32 v121, v94
	global_store_short v113, v121, s[6:7] offset:64
	v_add_u32_e32 v114, 0x4a400, v4
	v_cvt_f16_f32_e32 v122, v111
	global_store_short v114, v122, s[6:7]
	v_cvt_f16_f32_e32 v123, v95
	global_store_short v114, v123, s[6:7] offset:64
	v_add_u32_e32 v5, 0x58000, v4
	v_cvt_f16_f32_e32 v116, v64
	global_store_short v5, v116, s[6:7]
	v_cvt_f16_f32_e32 v117, v48
	global_store_short v5, v117, s[6:7] offset:64
	v_add_u32_e32 v112, 0x5ac00, v4
	v_cvt_f16_f32_e32 v118, v65
	global_store_short v112, v118, s[6:7]
	v_cvt_f16_f32_e32 v119, v49
	global_store_short v112, v119, s[6:7] offset:64
	v_add_u32_e32 v113, 0x5d800, v4
	v_cvt_f16_f32_e32 v120, v66
	global_store_short v113, v120, s[6:7]
	v_cvt_f16_f32_e32 v121, v50
	global_store_short v113, v121, s[6:7] offset:64
	v_add_u32_e32 v114, 0x60400, v4
	v_cvt_f16_f32_e32 v122, v67
	global_store_short v114, v122, s[6:7]
	v_cvt_f16_f32_e32 v123, v51
	global_store_short v114, v123, s[6:7] offset:64
	v_add_u32_e32 v5, 0x6e000, v4
	v_cvt_f16_f32_e32 v116, v68
	global_store_short v5, v116, s[6:7]
	v_cvt_f16_f32_e32 v117, v52
	global_store_short v5, v117, s[6:7] offset:64
	v_add_u32_e32 v112, 0x70c00, v4
	v_cvt_f16_f32_e32 v118, v69
	global_store_short v112, v118, s[6:7]
	v_cvt_f16_f32_e32 v119, v53
	global_store_short v112, v119, s[6:7] offset:64
	v_add_u32_e32 v113, 0x73800, v4
	v_cvt_f16_f32_e32 v120, v70
	global_store_short v113, v120, s[6:7]
	v_cvt_f16_f32_e32 v121, v54
	global_store_short v113, v121, s[6:7] offset:64
	v_add_u32_e32 v114, 0x76400, v4
	v_cvt_f16_f32_e32 v122, v71
	global_store_short v114, v122, s[6:7]
	v_cvt_f16_f32_e32 v123, v55
	global_store_short v114, v123, s[6:7] offset:64
	v_add_u32_e32 v5, 0x84000, v4
	v_cvt_f16_f32_e32 v116, v72
	global_store_short v5, v116, s[6:7]
	v_cvt_f16_f32_e32 v117, v56
; DI int otid() { int t = threadIdx.x; asm volatile("" : "+v"(t)); return t; }
; DI bf16_t cv1(float x) { return (bf16_t)(pk2(x, 0.f) & 0xffffu); }
; DI int crow(int i, int h) { return (i & 3) + 8 * (i >> 2) + 4 * h; }
; template <int MT> DI void st_bf16(bf16_t* base, int ld, int d2, int col0, const f32x16 (&acc)[MT][NT]) {
;     const int lane = otid() & 63, r = lane & 31, h = lane >> 5;
; #pragma unroll
;     for (int mi = 0; mi < MT; ++mi)
; #pragma unroll
;         for (int nj = 0; nj < NT; ++nj)
; #pragma unroll
;             for (int i = 0; i < 16; ++i) base[(mi * 32 + crow(i, h) + (mi == 2 ? d2 : 0)) * ld + col0 + nj * 32 + r] = cv1(acc[mi][nj][i]);
; }
;     DI void operator()(int unit, const f32x16 (&acc)[MT][NT]) const {
;     ...
; #pragma unroll
;         for (int mi = 1; mi < MT; ++mi)
; #pragma unroll
;             for (int nj = 0; nj < NT; ++nj)
; #pragma unroll
;                 for (int i = 0; i < 16; ++i) {
;                     const int lr = mi * 32 + crow(i, h), c = unit * UW + nj * 32 + r;
;                     if (mi == 1) { if (lr >= 62) { halo[(lr - 62) * DFF2 + c] = acc[mi][nj][i]; if (pconv) pconv[(lr - 62) * DFF2 + c] = acc[mi][nj][i]; } }
;                     else if ((lr & 15) >= 14) sconv[(((lr - 64) >> 4) * 2 + ((lr & 15) - 14)) * DFF2 + c] = acc[mi][nj][i];
;                 }
	global_store_short v5, v117, s[6:7] offset:64
	v_add_u32_e32 v112, 0x86c00, v4
	v_cvt_f16_f32_e32 v118, v73
	global_store_short v112, v118, s[6:7]
	v_cvt_f16_f32_e32 v119, v57
	global_store_short v112, v119, s[6:7] offset:64
	v_add_u32_e32 v113, 0x89800, v4
	v_cvt_f16_f32_e32 v120, v74
	global_store_short v113, v120, s[6:7]
	v_cvt_f16_f32_e32 v121, v58
	global_store_short v113, v121, s[6:7] offset:64
	v_add_u32_e32 v114, 0x8c400, v4
	v_cvt_f16_f32_e32 v122, v75
	global_store_short v114, v122, s[6:7]
	v_cvt_f16_f32_e32 v123, v59
	global_store_short v114, v123, s[6:7] offset:64
	v_add_u32_e32 v5, 0x9a000, v4
	v_cvt_f16_f32_e32 v116, v76
	global_store_short v5, v116, s[6:7]
	v_cvt_f16_f32_e32 v117, v60
	global_store_short v5, v117, s[6:7] offset:64
	v_add_u32_e32 v112, 0x9cc00, v4
	v_cvt_f16_f32_e32 v118, v77
	global_store_short v112, v118, s[6:7]
	v_cvt_f16_f32_e32 v119, v61
	global_store_short v112, v119, s[6:7] offset:64
	v_add_u32_e32 v113, 0x9f800, v4
	v_cvt_f16_f32_e32 v120, v78
	global_store_short v113, v120, s[6:7]
	v_cvt_f16_f32_e32 v121, v62
	global_store_short v113, v121, s[6:7] offset:64
	v_add_u32_e32 v114, 0xa2400, v4
	v_cvt_f16_f32_e32 v122, v79
	global_store_short v114, v122, s[6:7]
	v_cvt_f16_f32_e32 v123, v63
	global_store_short v114, v123, s[6:7] offset:64
	s_mul_i32 s101, s59, 0x2c00
	v_add_u32_e32 v3, s101, v4
	v_add_u32_e32 v5, 0, v3
	v_cvt_f16_f32_e32 v116, v32
	global_store_short v5, v116, s[6:7]
	v_cvt_f16_f32_e32 v117, v16
	global_store_short v5, v117, s[6:7] offset:64
	v_add_u32_e32 v112, 0x2c00, v3
	v_cvt_f16_f32_e32 v118, v33
	global_store_short v112, v118, s[6:7]
	v_cvt_f16_f32_e32 v119, v17
	global_store_short v112, v119, s[6:7] offset:64
	v_add_u32_e32 v113, 0x5800, v3
	v_cvt_f16_f32_e32 v120, v34
	global_store_short v113, v120, s[6:7]
	v_cvt_f16_f32_e32 v121, v18
	global_store_short v113, v121, s[6:7] offset:64
	v_add_u32_e32 v114, 0x8400, v3
	v_cvt_f16_f32_e32 v122, v35
	global_store_short v114, v122, s[6:7]
	v_cvt_f16_f32_e32 v123, v19
	global_store_short v114, v123, s[6:7] offset:64
	v_add_u32_e32 v5, 0x16000, v3
	v_cvt_f16_f32_e32 v116, v36
	global_store_short v5, v116, s[6:7]
	v_cvt_f16_f32_e32 v117, v20
	global_store_short v5, v117, s[6:7] offset:64
	v_add_u32_e32 v112, 0x18c00, v3
	v_cvt_f16_f32_e32 v118, v37
	global_store_short v112, v118, s[6:7]
	v_cvt_f16_f32_e32 v119, v21
	global_store_short v112, v119, s[6:7] offset:64
	v_add_u32_e32 v113, 0x1b800, v3
	v_cvt_f16_f32_e32 v120, v38
	global_store_short v113, v120, s[6:7]
	v_cvt_f16_f32_e32 v121, v22
	global_store_short v113, v121, s[6:7] offset:64
	v_add_u32_e32 v114, 0x1e400, v3
	v_cvt_f16_f32_e32 v122, v39
	global_store_short v114, v122, s[6:7]
	v_cvt_f16_f32_e32 v123, v23
	global_store_short v114, v123, s[6:7] offset:64
	v_add_u32_e32 v5, 0x2c000, v3
	v_cvt_f16_f32_e32 v116, v40
	global_store_short v5, v116, s[6:7]
	v_cvt_f16_f32_e32 v117, v24
	global_store_short v5, v117, s[6:7] offset:64
	v_add_u32_e32 v112, 0x2ec00, v3
	v_cvt_f16_f32_e32 v118, v41
	global_store_short v112, v118, s[6:7]
	v_cvt_f16_f32_e32 v119, v25
	global_store_short v112, v119, s[6:7] offset:64
	v_add_u32_e32 v113, 0x31800, v3
	v_cvt_f16_f32_e32 v120, v42
	global_store_short v113, v120, s[6:7]
	v_cvt_f16_f32_e32 v121, v26
	global_store_short v113, v121, s[6:7] offset:64
	v_add_u32_e32 v114, 0x34400, v3
	v_cvt_f16_f32_e32 v122, v43
	global_store_short v114, v122, s[6:7]
	v_cvt_f16_f32_e32 v123, v27
	global_store_short v114, v123, s[6:7] offset:64
	v_add_u32_e32 v5, 0x42000, v3
	v_cvt_f16_f32_e32 v116, v44
	global_store_short v5, v116, s[6:7]
	v_cvt_f16_f32_e32 v117, v28
	global_store_short v5, v117, s[6:7] offset:64
	v_add_u32_e32 v112, 0x44c00, v3
	v_cvt_f16_f32_e32 v118, v45
	global_store_short v112, v118, s[6:7]
	v_cvt_f16_f32_e32 v119, v29
	global_store_short v112, v119, s[6:7] offset:64
	v_add_u32_e32 v113, 0x47800, v3
	v_cvt_f16_f32_e32 v120, v46
	global_store_short v113, v120, s[6:7]
	v_cvt_f16_f32_e32 v121, v30
	global_store_short v113, v121, s[6:7] offset:64
	v_add_u32_e32 v114, 0x4a400, v3
	v_cvt_f16_f32_e32 v122, v47
	global_store_short v114, v122, s[6:7]
	v_cvt_f16_f32_e32 v123, v31
	global_store_short v114, v123, s[6:7] offset:64
	v_lshlrev_b32_e32 v0, 6, v233
	v_mov_b32_e32 v3, v176
	s_nop 0
	v_lshrrev_b32_e32 v2, 3, v3
	v_and_b32_e32 v4, 4, v2
	v_and_or_b32 v2, v3, 31, v0
	v_and_b32_e32 v3, 32, v3
	v_add_u32_e32 v5, 0xfffaac00, v2
	v_or_b32_e32 v0, 58, v4
	v_cmp_ne_u32_e32 vcc, 0, v3
	s_and_saveexec_b64 s[0:1], vcc
	s_cbranch_execz .LBB0_472
	v_mad_u32_u24 v6, v0, s44, v5
	v_ashrrev_i32_e32 v7, 31, v6
	v_lshl_add_u64 v[6:7], v[6:7], 2, s[8:9]
	global_store_dword v[6:7], v78, off

; #define MFMA32(a, b, c) __builtin_amdgcn_mfma_f32_32x32x16_f16((a), (b), (c), 0, 0, 0)
; DI int crow(int i, int h) { return (i & 3) + 8 * (i >> 2) + 4 * h; }
; template <int HD, int BIAS, bool FULL>
; DI void attn_block(const bf16_t* Kb, int ktb, const bf16_t* Vb, int vtb, int koff, int kpos0, int qp, float slope, const float* rel,
;                    const bf16x8 (&qf)[HD / 16], f32x16 (&o)[HD / 32], float& m, float& l) {
;     ...
;     bf16x8 kreg[NKT][KSQ];
; #pragma unroll
;     for (int kt = 0; kt < NKT; ++kt)
; #pragma unroll
;         for (int ks = 0; ks < KSQ; ++ks) kreg[kt][ks] = *(const bf16x8*)(Kb + (size_t)kt * ktb + ks * 512 + lane * 8);
;     constexpr int NS = FULL ? 4 : 1;
;     bf16x8 vreg[DT][NS];
;     auto loadV = [&]() {
; #pragma unroll
;         for (int si = 0; si < NS; ++si)
; #pragma unroll
;             for (int dt = 0; dt < DT; ++dt) { const int s = FULL ? si : s0; vreg[dt][si] = *(const bf16x8*)(Vb + (size_t)(s >> 1) * vtb + dt * 1024 + (s & 1) * 512 + lane * 8); }
;     };
;     if (VTOP) loadV();
;     __builtin_amdgcn_sched_barrier(0);
;     f32x16 st[NKT];
; #pragma unroll
;     for (int kt = 0; kt < NKT; ++kt) {
; #pragma unroll
;         for (int i = 0; i < 16; ++i) st[kt][i] = 0.f;
; #pragma unroll
;         for (int ks = 0; ks < KSQ; ++ks) st[kt] = MFMA32(kreg[kt][ks], qf[ks], st[kt]);
;     }
;     __builtin_amdgcn_sched_barrier(0);
;     if (!VTOP) loadV();
;     float mx = -1e30f;
; #pragma unroll
;     for (int kt = 0; kt < NKT; ++kt)
; #pragma unroll
;         for (int i = 0; i < 16; ++i) {
;             const int key = kt * 32 + crow(i, h);
;             float s = st[kt][i];
;             const int dk = dq + (kt * 32 + (i & 3) + 8 * (i >> 2));
;             if (BIAS == 1) s -= slope * (float)(dk < 0 ? -dk : dk);
;             if (BIAS == 2) { int d = dk < -256 ? -256 : (dk > 256 ? 256 : dk); s += rel[d + 256]; }
;             if (!FULL) { if (key < kbeg || key >= kend) s = -1e30f; }
;             st[kt][i] = s; mx = fmaxf(mx, s);
.LBB0_497:
	v_mov_b32_e32 v0, v176
	s_add_u32 s68, s3, s4
	v_lshrrev_b32_e32 v35, 3, v0
	v_and_b32_e32 v0, 63, v0
	v_lshlrev_b32_e32 v0, 4, v0
	s_addc_u32 s69, s64, s5
	v_lshl_add_u64 v[48:49], s[68:69], 0, v[0:1]
	s_mov_b32 s68, 0x155b0000
	v_and_b32_e32 v35, 4, v35
	v_add_co_u32_e32 v50, vcc, s68, v48
	v_add_u32_e32 v119, v116, v35
	s_nop 0
	v_addc_co_u32_e32 v51, vcc, 0, v49, vcc
	s_mov_b32 s68, 0x155b8000
	global_load_dwordx4 v[36:39], v[50:51], off
	global_load_dwordx4 v[40:43], v[50:51], off offset:1024
	global_load_dwordx4 v[44:47], v[50:51], off offset:2048
	global_load_dwordx4 v[120:123], v[50:51], off offset:3072
	v_add_co_u32_e32 v50, vcc, s68, v48
	s_mov_b32 s68, 0x165d0000
	s_nop 0
	v_addc_co_u32_e32 v51, vcc, 0, v49, vcc
	global_load_dwordx4 v[124:127], v[50:51], off
	global_load_dwordx4 v[128:131], v[50:51], off offset:1024
	global_load_dwordx4 v[132:135], v[50:51], off offset:2048
	global_load_dwordx4 v[136:139], v[50:51], off offset:3072
	v_add_co_u32_e32 v50, vcc, s68, v48
	s_mov_b32 s68, 0x165d8000
	s_nop 0
	v_addc_co_u32_e32 v51, vcc, 0, v49, vcc
	v_add_co_u32_e32 v48, vcc, s68, v48
	global_load_dwordx4 v[102:105], v[50:51], off
	global_load_dwordx4 v[90:93], v[50:51], off offset:1024
	global_load_dwordx4 v[110:113], v[50:51], off offset:2048
	global_load_dwordx4 v[94:97], v[50:51], off offset:3072
	v_addc_co_u32_e32 v49, vcc, 0, v49, vcc
	global_load_dwordx4 v[98:101], v[48:49], off
	global_load_dwordx4 v[82:85], v[48:49], off offset:1024
	global_load_dwordx4 v[106:109], v[48:49], off offset:2048
	global_load_dwordx4 v[86:89], v[48:49], off offset:3072
	v_mov_b32_e32 v118, v34
	s_waitcnt vmcnt(15)
	v_mfma_f32_32x32x16_f16 v[50:65], v[36:39], v[66:69], 0
	s_waitcnt vmcnt(14)
	v_mfma_f32_32x32x16_f16 v[50:65], v[40:43], v[70:73], v[50:65]
	s_waitcnt vmcnt(13)
	v_mfma_f32_32x32x16_f16 v[50:65], v[44:47], v[74:77], v[50:65]
	s_waitcnt vmcnt(11)
	v_mfma_f32_32x32x16_f16 v[34:49], v[124:127], v[66:69], 0
	s_waitcnt vmcnt(10)
	v_mfma_f32_32x32x16_f16 v[34:49], v[128:131], v[70:73], v[34:49]
	s_waitcnt vmcnt(9)
	v_mfma_f32_32x32x16_f16 v[34:49], v[132:135], v[74:77], v[34:49]
	s_waitcnt vmcnt(8)
	v_mfma_f32_32x32x16_f16 v[34:49], v[136:139], v[78:81], v[34:49]
	v_mfma_f32_32x32x16_f16 v[50:65], v[120:123], v[78:81], v[50:65]
	v_add_u32_e32 v142, 2, v119
	v_med3_i32 v142, v142, s45, v186
	v_lshl_add_u32 v142, v142, 2, s67
	ds_read_b32 v142, v142 offset:1024
	v_med3_i32 v143, v119, s45, v186
	v_lshl_add_u32 v143, v143, 2, s67
	ds_read_b32 v143, v143 offset:1024
	v_add_u32_e32 v144, 3, v119
	v_med3_i32 v144, v144, s45, v186
	v_lshl_add_u32 v144, v144, 2, s67
	ds_read_b32 v144, v144 offset:1024
	v_add_u32_e32 v145, 8, v119
	v_med3_i32 v145, v145, s45, v186
	v_lshl_add_u32 v145, v145, 2, s67
	ds_read_b32 v145, v145 offset:1024
	v_add_u32_e32 v146, 9, v119
	v_med3_i32 v146, v146, s45, v186
	v_lshl_add_u32 v146, v146, 2, s67
	ds_read_b32 v146, v146 offset:1024
	v_add_u32_e32 v147, 10, v119
	v_med3_i32 v147, v147, s45, v186
	v_lshl_add_u32 v147, v147, 2, s67
	ds_read_b32 v147, v147 offset:1024
	v_add_u32_e32 v148, 11, v119
	v_med3_i32 v148, v148, s45, v186
	v_lshl_add_u32 v148, v148, 2, s67
	ds_read_b32 v148, v148 offset:1024
	v_add_u32_e32 v149, 16, v119
	v_med3_i32 v149, v149, s45, v186
	v_lshl_add_u32 v149, v149, 2, s67
	ds_read_b32 v149, v149 offset:1024
	v_add_u32_e32 v150, 17, v119
	v_med3_i32 v150, v150, s45, v186
	v_lshl_add_u32 v150, v150, 2, s67
	ds_read_b32 v150, v150 offset:1024
	v_add_u32_e32 v151, 18, v119
	v_med3_i32 v151, v151, s45, v186
	v_lshl_add_u32 v151, v151, 2, s67
	ds_read_b32 v151, v151 offset:1024
	v_add_u32_e32 v152, 19, v119
	v_med3_i32 v152, v152, s45, v186
	v_lshl_add_u32 v152, v152, 2, s67
	ds_read_b32 v152, v152 offset:1024
	v_add_u32_e32 v153, 24, v119
	v_med3_i32 v153, v153, s45, v186
	v_lshl_add_u32 v153, v153, 2, s67
	ds_read_b32 v153, v153 offset:1024
	v_add_u32_e32 v154, 25, v119
	v_med3_i32 v154, v154, s45, v186
	v_lshl_add_u32 v154, v154, 2, s67
	ds_read_b32 v154, v154 offset:1024
	v_add_u32_e32 v155, 26, v119
	v_med3_i32 v155, v155, s45, v186
	v_lshl_add_u32 v155, v155, 2, s67
	ds_read_b32 v155, v155 offset:1024
	v_add_u32_e32 v156, 27, v119
	v_med3_i32 v156, v156, s45, v186
	v_lshl_add_u32 v156, v156, 2, s67
	ds_read_b32 v156, v156 offset:1024
	v_add_u32_e32 v157, 32, v119
	v_med3_i32 v157, v157, s45, v186
	v_lshl_add_u32 v157, v157, 2, s67
	ds_read_b32 v157, v157 offset:1024
	v_add_u32_e32 v158, 33, v119
	v_med3_i32 v158, v158, s45, v186
	v_lshl_add_u32 v158, v158, 2, s67
	ds_read_b32 v158, v158 offset:1024
	v_add_u32_e32 v159, 34, v119
	v_med3_i32 v159, v159, s45, v186
	v_lshl_add_u32 v159, v159, 2, s67
	ds_read_b32 v159, v159 offset:1024
	v_add_u32_e32 v160, 1, v119
	v_med3_i32 v160, v160, s45, v186
	v_lshl_add_u32 v160, v160, 2, s67
	v_add_u32_e32 v161, 35, v119
	v_med3_i32 v161, v161, s45, v186
	v_lshl_add_u32 v161, v161, 2, s67
	ds_read_b32 v160, v160 offset:1024
	ds_read_b32 v161, v161 offset:1024
	v_add_u32_e32 v162, 40, v119
	v_med3_i32 v162, v162, s45, v186
	v_lshl_add_u32 v162, v162, 2, s67
	ds_read_b32 v162, v162 offset:1024
	v_add_u32_e32 v163, 41, v119
	v_med3_i32 v163, v163, s45, v186
	v_lshl_add_u32 v163, v163, 2, s67
	ds_read_b32 v163, v163 offset:1024
	v_add_u32_e32 v164, 42, v119
	v_med3_i32 v164, v164, s45, v186
	v_lshl_add_u32 v164, v164, 2, s67
	ds_read_b32 v164, v164 offset:1024
	v_add_u32_e32 v165, 43, v119
	v_med3_i32 v165, v165, s45, v186
	v_lshl_add_u32 v165, v165, 2, s67
	ds_read_b32 v165, v165 offset:1024
	v_add_u32_e32 v166, 48, v119
	v_med3_i32 v166, v166, s45, v186
	v_lshl_add_u32 v166, v166, 2, s67
	ds_read_b32 v166, v166 offset:1024
	v_add_u32_e32 v167, 49, v119
	v_med3_i32 v167, v167, s45, v186
	v_lshl_add_u32 v167, v167, 2, s67
	ds_read_b32 v167, v167 offset:1024
	v_add_u32_e32 v168, 50, v119
	v_med3_i32 v168, v168, s45, v186
	v_lshl_add_u32 v168, v168, 2, s67
	ds_read_b32 v168, v168 offset:1024
	v_add_u32_e32 v169, 51, v119
	v_med3_i32 v169, v169, s45, v186
	v_lshl_add_u32 v169, v169, 2, s67
	ds_read_b32 v169, v169 offset:1024
	v_add_u32_e32 v170, 56, v119
	v_med3_i32 v170, v170, s45, v186
	v_lshl_add_u32 v170, v170, 2, s67
	ds_read_b32 v170, v170 offset:1024
	v_add_u32_e32 v171, 57, v119
	v_med3_i32 v171, v171, s45, v186
	v_lshl_add_u32 v171, v171, 2, s67
	ds_read_b32 v171, v171 offset:1024
	v_add_u32_e32 v172, 58, v119
	v_med3_i32 v172, v172, s45, v186
	v_lshl_add_u32 v172, v172, 2, s67
	ds_read_b32 v172, v172 offset:1024
	v_add_u32_e32 v173, 59, v119
	v_med3_i32 v173, v173, s45, v186
	v_lshl_add_u32 v173, v173, 2, s67
	ds_read_b32 v173, v173 offset:1024
	s_waitcnt lgkmcnt(0)
; DI int crow(int i, int h) { return (i & 3) + 8 * (i >> 2) + 4 * h; }
; template <int HD, int BIAS, bool FULL>
; DI void attn_block(const bf16_t* Kb, int ktb, const bf16_t* Vb, int vtb, int koff, int kpos0, int qp, float slope, const float* rel,
;                    const bf16x8 (&qf)[HD / 16], f32x16 (&o)[HD / 32], float& m, float& l) {
;     ...
;     for (int kt = 0; kt < NKT; ++kt)
; #pragma unroll
;         for (int i = 0; i < 16; ++i) {
;             const int key = kt * 32 + crow(i, h);
;             float s = st[kt][i];
;             const int dk = dq + (kt * 32 + (i & 3) + 8 * (i >> 2));
;             if (BIAS == 1) s -= slope * (float)(dk < 0 ? -dk : dk);
;             if (BIAS == 2) { int d = dk < -256 ? -256 : (dk > 256 ? 256 : dk); s += rel[d + 256]; }
;             if (!FULL) { if (key < kbeg || key >= kend) s = -1e30f; }
;             st[kt][i] = s; mx = fmaxf(mx, s);
;         }
;     mx = fmaxf(mx, __shfl_xor(mx, 32));
;     const float mn = fmaxf(m, mx);
	v_cmp_lt_i32_e32 vcc, v188, v189
	s_nop 2
	v_add_f32_e32 v52, v52, v142
	s_add_u32 s4, s4, 0x10000
	s_addc_u32 s5, s5, 0
	v_add_u32_e32 v116, 64, v116
	s_cmp_lg_u32 s1, s4
	v_add_f32_e32 v53, v53, v144
	v_add_f32_e32 v54, v54, v145
	v_add_f32_e32 v55, v55, v146
	v_add_f32_e32 v56, v56, v147
	v_add_f32_e32 v57, v57, v148
	v_add_f32_e32 v58, v58, v149
	v_add_f32_e32 v59, v59, v150
	v_add_f32_e32 v60, v60, v151
	v_add_f32_e32 v61, v61, v152
	v_add_f32_e32 v62, v62, v153
	v_add_f32_e32 v63, v63, v154
	v_add_f32_e32 v64, v64, v155
	v_add_f32_e32 v65, v65, v156
	v_add_f32_e32 v34, v34, v157
	v_add_f32_e32 v120, v35, v158
	v_add_f32_e32 v50, v50, v143
	v_add_f32_e32 v36, v36, v159
	v_add_f32_e32 v51, v51, v160
	v_add_f32_e32 v37, v37, v161
	v_max3_f32 v0, v50, s46, v51
	v_max3_f32 v0, v0, v52, v53
	v_max3_f32 v0, v0, v54, v55
	v_max3_f32 v0, v0, v56, v57
	v_add_f32_e32 v38, v38, v162
	v_max3_f32 v0, v0, v58, v59
	v_max3_f32 v0, v0, v60, v61
	v_max3_f32 v0, v0, v62, v63
	v_max3_f32 v0, v0, v64, v65
	v_add_f32_e32 v39, v39, v163
	v_max3_f32 v0, v0, v34, v120
	v_max3_f32 v0, v0, v36, v37
	v_max3_f32 v0, v0, v38, v39
	v_add_f32_e32 v40, v40, v164
	v_add_f32_e32 v41, v41, v165
	v_max3_f32 v0, v0, v40, v41
	v_add_f32_e32 v42, v42, v166
	v_add_f32_e32 v43, v43, v167
	v_max3_f32 v0, v0, v42, v43
	v_add_f32_e32 v44, v44, v168
	v_add_f32_e32 v45, v45, v169
	v_max3_f32 v0, v0, v44, v45
	v_add_f32_e32 v46, v46, v170
	v_add_f32_e32 v47, v47, v171
	v_max3_f32 v0, v0, v46, v47
	v_add_f32_e32 v48, v48, v172
	v_add_f32_e32 v49, v49, v173
	v_max3_f32 v35, v0, v48, v49
	v_cndmask_b32_e32 v0, v187, v188, vcc
	v_lshlrev_b32_e32 v0, 2, v0
	ds_bpermute_b32 v119, v0, v35
	s_waitcnt lgkmcnt(0)
; #define MFMA32(a, b, c) __builtin_amdgcn_mfma_f32_32x32x16_f16((a), (b), (c), 0, 0, 0)
; DI unsigned pk2(float lo, float hi) { f32x2 v = {lo, hi}; bf2_t b = __builtin_convertvector(v, bf2_t); return __builtin_bit_cast(unsigned, b); }
; template <int HD, int BIAS, bool FULL>
; DI void attn_block(const bf16_t* Kb, int ktb, const bf16_t* Vb, int vtb, int koff, int kpos0, int qp, float slope, const float* rel,
;                    const bf16x8 (&qf)[HD / 16], f32x16 (&o)[HD / 32], float& m, float& l) {
;     ...
;     const float mn = fmaxf(m, mx);
;     const float alpha = __builtin_amdgcn_exp2f((m - mn) * LOG2E);
;     m = mn;
;     float ps = 0.f;
; #pragma unroll
;     for (int kt = 0; kt < NKT; ++kt)
; #pragma unroll
;         for (int i = 0; i < 16; ++i) { const float pv = __builtin_amdgcn_exp2f((st[kt][i] - mn) * LOG2E); st[kt][i] = pv; ps += pv; }
;     l = l * alpha + ps;
; #pragma unroll
;     for (int dt = 0; dt < DT; ++dt)
; #pragma unroll
;         for (int i = 0; i < 16; ++i) o[dt][i] *= alpha;
; #pragma unroll
;     for (int si = 0; si < NS; ++si) {
;         u32x4 pw;
;         if (FULL) { const int kt = si >> 1, b0 = (si & 1) * 8; pw = (u32x4){pk2(st[kt][b0], st[kt][b0 + 1]), pk2(st[kt][b0 + 2], st[kt][b0 + 3]), pk2(st[kt][b0 + 4], st[kt][b0 + 5]), pk2(st[kt][b0 + 6], st[kt][b0 + 7])}; }
;         else {
;             const u32x4 lo = {pk2(st[0][0], st[0][1]), pk2(st[0][2], st[0][3]), pk2(st[0][4], st[0][5]), pk2(st[0][6], st[0][7])};
;             const u32x4 hi = {pk2(st[0][8], st[0][9]), pk2(st[0][10], st[0][11]), pk2(st[0][12], st[0][13]), pk2(st[0][14], st[0][15])};
;             pw = (s0 & 1) ? hi : lo;
;         }
;         const bf16x8 pf = __builtin_bit_cast(bf16x8, pw);
; #pragma unroll
;         for (int dt = 0; dt < DT; ++dt) o[dt] = MFMA32(vreg[dt][si], pf, o[dt]);
;     }
; }
; template <int HD, int BIAS> ...
;     ...
;     for (int blk = 0; blk < nb1; ++blk)
;         attn_block<HD, BIAS, true>(K1 + (size_t)(2 * blk) * ktb1, ktb1, V1 + (size_t)(2 * blk) * vtb1, vtb1, 0, pos1 + blk * 64, qp, slope, rel, qf, o, m, l);
;     if (nb2) attn_block<HD, BIAS, false>(K2, 0, V2, 0, koff2, pos2 - koff2, qp, slope, rel, qf, o, m, l);
;     const float lt = l + __shfl_xor(l, 32);
;     const float inv = 1.f / lt;
	v_max3_f32 v35, v117, v35, v119
	v_sub_f32_e32 v50, v50, v35
	v_mul_f32_e32 v50, 0x3fb8aa3b, v50
	v_sub_f32_e32 v51, v51, v35
	v_exp_f32_e32 v50, v50
	v_mul_f32_e32 v51, 0x3fb8aa3b, v51
	v_sub_f32_e32 v52, v52, v35
	v_exp_f32_e32 v51, v51
	v_mul_f32_e32 v52, 0x3fb8aa3b, v52
	v_sub_f32_e32 v53, v53, v35
	v_exp_f32_e32 v52, v52
	v_mul_f32_e32 v53, 0x3fb8aa3b, v53
	v_sub_f32_e32 v54, v54, v35
	v_exp_f32_e32 v53, v53
	v_mul_f32_e32 v54, 0x3fb8aa3b, v54
	v_sub_f32_e32 v55, v55, v35
	v_add_f32_e32 v119, 0, v50
	v_exp_f32_e32 v54, v54
	v_mul_f32_e32 v55, 0x3fb8aa3b, v55
	v_sub_f32_e32 v56, v56, v35
	v_add_f32_e32 v119, v51, v119
	v_exp_f32_e32 v55, v55
	v_mul_f32_e32 v56, 0x3fb8aa3b, v56
	v_sub_f32_e32 v57, v57, v35
	v_add_f32_e32 v119, v52, v119
	v_exp_f32_e32 v56, v56
	v_mul_f32_e32 v57, 0x3fb8aa3b, v57
	v_sub_f32_e32 v58, v58, v35
	v_add_f32_e32 v119, v53, v119
	v_exp_f32_e32 v57, v57
	v_mul_f32_e32 v58, 0x3fb8aa3b, v58
	v_sub_f32_e32 v59, v59, v35
	v_add_f32_e32 v119, v54, v119
	v_exp_f32_e32 v58, v58
	v_mul_f32_e32 v59, 0x3fb8aa3b, v59
	v_sub_f32_e32 v60, v60, v35
	v_add_f32_e32 v119, v55, v119
	v_exp_f32_e32 v59, v59
	v_mul_f32_e32 v60, 0x3fb8aa3b, v60
	v_sub_f32_e32 v61, v61, v35
	v_add_f32_e32 v119, v56, v119
	v_exp_f32_e32 v60, v60
	v_mul_f32_e32 v61, 0x3fb8aa3b, v61
	v_sub_f32_e32 v62, v62, v35
	v_add_f32_e32 v119, v57, v119
	v_exp_f32_e32 v61, v61
	v_mul_f32_e32 v62, 0x3fb8aa3b, v62
	v_sub_f32_e32 v63, v63, v35
	v_add_f32_e32 v119, v58, v119
	v_exp_f32_e32 v62, v62
	v_mul_f32_e32 v63, 0x3fb8aa3b, v63
	v_sub_f32_e32 v64, v64, v35
	v_add_f32_e32 v119, v59, v119
	v_exp_f32_e32 v63, v63
	v_mul_f32_e32 v64, 0x3fb8aa3b, v64
	v_sub_f32_e32 v65, v65, v35
	v_add_f32_e32 v119, v60, v119
	v_exp_f32_e32 v64, v64
	v_mul_f32_e32 v65, 0x3fb8aa3b, v65
	v_sub_f32_e32 v34, v34, v35
	v_add_f32_e32 v119, v61, v119
	v_exp_f32_e32 v65, v65
	v_mul_f32_e32 v34, 0x3fb8aa3b, v34
	v_add_f32_e32 v119, v62, v119
	v_exp_f32_e32 v121, v34
	v_add_f32_e32 v119, v63, v119
	v_add_f32_e32 v119, v64, v119
	v_sub_f32_e32 v36, v36, v35
	v_add_f32_e32 v119, v65, v119
	v_mul_f32_e32 v36, 0x3fb8aa3b, v36
	v_add_f32_e32 v34, v121, v119
	v_sub_f32_e32 v119, v120, v35
	v_exp_f32_e32 v120, v36
	v_sub_f32_e32 v36, v37, v35
	v_mul_f32_e32 v36, 0x3fb8aa3b, v36
	v_exp_f32_e32 v122, v36
	v_sub_f32_e32 v36, v38, v35
	v_mul_f32_e32 v36, 0x3fb8aa3b, v36
	v_exp_f32_e32 v123, v36
	v_sub_f32_e32 v36, v39, v35
	v_mul_f32_e32 v36, 0x3fb8aa3b, v36
	v_exp_f32_e32 v124, v36
	v_sub_f32_e32 v36, v40, v35
	v_mul_f32_e32 v36, 0x3fb8aa3b, v36
	v_exp_f32_e32 v40, v36
	v_sub_f32_e32 v36, v41, v35
	v_mul_f32_e32 v36, 0x3fb8aa3b, v36
	v_exp_f32_e32 v41, v36
	v_sub_f32_e32 v36, v42, v35
	v_mul_f32_e32 v119, 0x3fb8aa3b, v119
	v_mul_f32_e32 v36, 0x3fb8aa3b, v36
	v_exp_f32_e32 v119, v119
	v_exp_f32_e32 v42, v36
	v_sub_f32_e32 v36, v43, v35
	v_mul_f32_e32 v36, 0x3fb8aa3b, v36
	v_exp_f32_e32 v43, v36
	v_sub_f32_e32 v36, v44, v35
	v_mul_f32_e32 v36, 0x3fb8aa3b, v36
	v_add_f32_e32 v34, v119, v34
	v_exp_f32_e32 v44, v36
	v_sub_f32_e32 v36, v45, v35
	v_add_f32_e32 v34, v120, v34
	v_mul_f32_e32 v36, 0x3fb8aa3b, v36
	v_add_f32_e32 v34, v122, v34
	v_exp_f32_e32 v45, v36
	v_sub_f32_e32 v36, v46, v35
	v_add_f32_e32 v34, v123, v34
	v_mul_f32_e32 v36, 0x3fb8aa3b, v36
	v_add_f32_e32 v34, v124, v34
	v_exp_f32_e32 v46, v36
	v_sub_f32_e32 v36, v47, v35
	v_add_f32_e32 v34, v40, v34
	v_mul_f32_e32 v36, 0x3fb8aa3b, v36
	v_add_f32_e32 v34, v41, v34
	v_exp_f32_e32 v47, v36
	v_sub_f32_e32 v36, v48, v35
	v_add_f32_e32 v34, v42, v34
	v_mul_f32_e32 v36, 0x3fb8aa3b, v36
	v_add_f32_e32 v34, v43, v34
	v_exp_f32_e32 v48, v36
	v_sub_f32_e32 v36, v49, v35
	v_sub_f32_e32 v117, v117, v35
	v_add_f32_e32 v34, v44, v34
	v_mul_f32_e32 v36, 0x3fb8aa3b, v36
	v_mul_f32_e32 v117, 0x3fb8aa3b, v117
	v_add_f32_e32 v34, v45, v34
	v_exp_f32_e32 v49, v36
	v_add_f32_e32 v34, v46, v34
	v_exp_f32_e32 v36, v117
	v_add_f32_e32 v34, v47, v34
	v_add_f32_e32 v34, v48, v34
	v_add_f32_e32 v34, v49, v34
	v_fmac_f32_e32 v34, v118, v36
	v_pk_mul_f32 v[18:19], v[18:19], v[36:37] op_sel_hi:[1,0]
	v_pk_mul_f32 v[20:21], v[20:21], v[36:37] op_sel_hi:[1,0]
	v_pk_mul_f32 v[22:23], v[22:23], v[36:37] op_sel_hi:[1,0]
	v_pk_mul_f32 v[24:25], v[24:25], v[36:37] op_sel_hi:[1,0]
	v_pk_mul_f32 v[26:27], v[26:27], v[36:37] op_sel_hi:[1,0]
	v_pk_mul_f32 v[28:29], v[28:29], v[36:37] op_sel_hi:[1,0]
	v_pk_mul_f32 v[30:31], v[30:31], v[36:37] op_sel_hi:[1,0]
	v_pk_mul_f32 v[32:33], v[32:33], v[36:37] op_sel_hi:[1,0]
	v_pk_mul_f32 v[2:3], v[2:3], v[36:37] op_sel_hi:[1,0]
	v_pk_mul_f32 v[4:5], v[4:5], v[36:37] op_sel_hi:[1,0]
	v_pk_mul_f32 v[6:7], v[6:7], v[36:37] op_sel_hi:[1,0]
	v_pk_mul_f32 v[8:9], v[8:9], v[36:37] op_sel_hi:[1,0]
	v_pk_mul_f32 v[10:11], v[10:11], v[36:37] op_sel_hi:[1,0]
	v_pk_mul_f32 v[12:13], v[12:13], v[36:37] op_sel_hi:[1,0]
	v_pk_mul_f32 v[14:15], v[14:15], v[36:37] op_sel_hi:[1,0]
	v_pk_mul_f32 v[16:17], v[16:17], v[36:37] op_sel_hi:[1,0]
	v_cvt_pk_f16_f32 v36, v50, v51
	v_cvt_pk_f16_f32 v37, v52, v53
	v_cvt_pk_f16_f32 v38, v54, v55
	v_cvt_pk_f16_f32 v39, v56, v57
	v_mov_b32_e32 v117, v35
	s_waitcnt vmcnt(7)
	v_mfma_f32_32x32x16_f16 v[18:33], v[102:105], v[36:39], v[18:33]
	s_waitcnt vmcnt(5)
	v_mfma_f32_32x32x16_f16 v[2:17], v[110:113], v[36:39], v[2:17]
	v_cvt_pk_f16_f32 v36, v58, v59
	v_cvt_pk_f16_f32 v37, v60, v61
	v_cvt_pk_f16_f32 v38, v62, v63
	v_cvt_pk_f16_f32 v39, v64, v65
	s_nop 1
	v_mfma_f32_32x32x16_f16 v[18:33], v[90:93], v[36:39], v[18:33]
	s_waitcnt vmcnt(4)
	v_mfma_f32_32x32x16_f16 v[2:17], v[94:97], v[36:39], v[2:17]
	v_cvt_pk_f16_f32 v36, v121, v119
	v_cvt_pk_f16_f32 v37, v120, v122
	v_cvt_pk_f16_f32 v38, v123, v124
	v_cvt_pk_f16_f32 v39, v40, v41
	s_waitcnt vmcnt(3)
	s_nop 0
	v_mfma_f32_32x32x16_f16 v[18:33], v[98:101], v[36:39], v[18:33]
	s_waitcnt vmcnt(1)
	v_mfma_f32_32x32x16_f16 v[2:17], v[106:109], v[36:39], v[2:17]
	v_cvt_pk_f16_f32 v36, v42, v43
	v_cvt_pk_f16_f32 v37, v44, v45
	v_cvt_pk_f16_f32 v38, v46, v47
	v_cvt_pk_f16_f32 v39, v48, v49
	s_nop 1
	v_mfma_f32_32x32x16_f16 v[18:33], v[82:85], v[36:39], v[18:33]
	s_waitcnt vmcnt(0)
	v_mfma_f32_32x32x16_f16 v[2:17], v[86:89], v[36:39], v[2:17]
	s_cbranch_scc1 .LBB0_497
	ds_bpermute_b32 v35, v0, v34
	s_lshl_b32 s2, s2, 1
	s_add_u32 s2, s8, s2
	v_lshlrev_b32_e32 v0, 1, v114
	s_addc_u32 s3, s9, 0
	s_waitcnt lgkmcnt(0)
	v_add_f32_e32 v36, v34, v35
	v_lshl_add_u64 v[34:35], s[2:3], 0, v[0:1]
	s_mov_b64 s[2:3], 0
	s_movk_i32 s17, 0x810
	s_movk_i32 s64, 0x3fff

; #define MFMA32(a, b, c) __builtin_amdgcn_mfma_f32_32x32x16_f16((a), (b), (c), 0, 0, 0)
; template <int K, class Epi>
; DI void gemm64_res(const bf16_t* A, int lda, const bf16_t* Wp, int NU, unsigned char* lds, const Epi& epi) {
;     ...
;     const unsigned char* ab = lds + r * LD + 16 * h;
; #pragma unroll 1
;     for (int unit = wave; unit < NU; unit += NWAVE) {
;         const u32x4* bp = Bw + (size_t)(unit * NT) * 64 + lane;
;         f32x16 acc[2][NT];
; #pragma unroll
;         for (int mi = 0; mi < 2; ++mi)
; #pragma unroll
;             for (int nj = 0; nj < NT; ++nj)
; #pragma unroll
;                 for (int i = 0; i < 16; ++i) acc[mi][nj][i] = 0.f;
;         u32x4 bq[PD][NT];
; #pragma unroll
;         for (int s = 0; s < PD; ++s)
; #pragma unroll
;             for (int j = 0; j < NT; ++j) bq[s][j] = bp[(size_t)((s + rot) & (KS - 1)) * kstr + j * 64];
; #pragma unroll 1
;         for (int kk = 0; kk < KS; kk += PD) {
; #pragma unroll
;             for (int s = 0; s < PD; ++s) {
;                 const int ks = kk + s, ksr = (ks + rot) & (KS - 1);
;                 const bf16x8 a0 = *(const bf16x8*)(ab + ksr * 32), a1 = *(const bf16x8*)(ab + 32 * LD + ksr * 32);
; #pragma unroll
;                 for (int j = 0; j < NT; ++j) { acc[0][j] = MFMA32(a0, __builtin_bit_cast(bf16x8, bq[s][j]), acc[0][j]); acc[1][j] = MFMA32(a1, __builtin_bit_cast(bf16x8, bq[s][j]), acc[1][j]); }
;                 int nk = ks + PD; nk = nk < KS ? nk : KS - 1; nk = (nk + rot) & (KS - 1);
; #pragma unroll
;                 for (int j = 0; j < NT; ++j) bq[s][j] = bp[(size_t)nk * kstr + j * 64];
;             }
.LBB0_505:
	s_lshl_b32 s2, s1, 1
	s_ashr_i32 s3, s2, 31
	s_lshl_b64 s[2:3], s[2:3], 10
	v_mov_b32_e32 v2, 0
	v_lshl_add_u64 v[68:69], v[66:67], 0, s[2:3]
	s_mov_b32 s2, -4
	v_readlane_b32 s3, v254, 45
	s_mov_b32 s4, s85
	v_readlane_b32 s7, v253, 29
	s_mov_b32 s6, s9
	s_mov_b32 s5, s87
	v_mov_b32_e32 v3, v2
	v_mov_b32_e32 v4, v2
	v_mov_b32_e32 v5, v2
	v_mov_b32_e32 v6, v2
	v_mov_b32_e32 v7, v2
	v_mov_b32_e32 v8, v2
	v_mov_b32_e32 v9, v2
	v_mov_b32_e32 v10, v2
	v_mov_b32_e32 v11, v2
	v_mov_b32_e32 v12, v2
	v_mov_b32_e32 v13, v2
	v_mov_b32_e32 v14, v2
	v_mov_b32_e32 v15, v2
	v_mov_b32_e32 v16, v2
	v_mov_b32_e32 v17, v2
	v_mov_b32_e32 v18, v2
	v_mov_b32_e32 v19, v2
	v_mov_b32_e32 v20, v2
	v_mov_b32_e32 v21, v2
	v_mov_b32_e32 v22, v2
	v_mov_b32_e32 v23, v2
	v_mov_b32_e32 v24, v2
	v_mov_b32_e32 v25, v2
	v_mov_b32_e32 v26, v2
	v_mov_b32_e32 v27, v2
	v_mov_b32_e32 v28, v2
	v_mov_b32_e32 v29, v2
	v_mov_b32_e32 v30, v2
	v_mov_b32_e32 v31, v2
	v_mov_b32_e32 v32, v2
	v_mov_b32_e32 v33, v2
	v_mov_b32_e32 v34, v2
	v_mov_b32_e32 v35, v2
	v_mov_b32_e32 v36, v2
	v_mov_b32_e32 v37, v2
	v_mov_b32_e32 v38, v2
	v_mov_b32_e32 v39, v2
	v_mov_b32_e32 v40, v2
	v_mov_b32_e32 v41, v2
	v_mov_b32_e32 v42, v2
	v_mov_b32_e32 v43, v2
	v_mov_b32_e32 v44, v2
	v_mov_b32_e32 v45, v2
	v_mov_b32_e32 v46, v2
	v_mov_b32_e32 v47, v2
	v_mov_b32_e32 v48, v2
	v_mov_b32_e32 v49, v2
	v_mov_b32_e32 v50, v2
	v_mov_b32_e32 v51, v2
	v_mov_b32_e32 v52, v2
	v_mov_b32_e32 v53, v2
	v_mov_b32_e32 v54, v2
	v_mov_b32_e32 v55, v2
	v_mov_b32_e32 v56, v2
	v_mov_b32_e32 v57, v2
	v_mov_b32_e32 v58, v2
	v_mov_b32_e32 v59, v2
	v_mov_b32_e32 v60, v2
	v_mov_b32_e32 v61, v2
	v_mov_b32_e32 v62, v2
	v_mov_b32_e32 v63, v2
	v_mov_b32_e32 v64, v2
	v_mov_b32_e32 v65, v2
	v_readlane_b32 s2, v254, 45
	s_nop 3
	s_lshr_b32 s2, s2, 5
	s_mov_b32 s101, 0
	s_mov_b32 s4, s2
	s_and_b32 s5, s4, 31
	s_add_i32 s4, s4, 1
	s_mul_i32 s100, s5, 0x8000
	v_lshl_add_u64 v[70:71], v[68:69], 0, s[100:101]
	global_load_dwordx4 v[72:75], v[70:71], off
	global_load_dwordx4 v[76:79], v[70:71], off offset:1024
	s_and_b32 s5, s4, 31
	s_add_i32 s4, s4, 1
	s_mul_i32 s100, s5, 0x8000
	v_lshl_add_u64 v[70:71], v[68:69], 0, s[100:101]
	global_load_dwordx4 v[80:83], v[70:71], off
	global_load_dwordx4 v[84:87], v[70:71], off offset:1024
	s_and_b32 s5, s4, 31
	s_add_i32 s4, s4, 1
	s_mul_i32 s100, s5, 0x8000
	v_lshl_add_u64 v[70:71], v[68:69], 0, s[100:101]
	global_load_dwordx4 v[88:91], v[70:71], off
	global_load_dwordx4 v[92:95], v[70:71], off offset:1024
	s_and_b32 s5, s4, 31
	s_add_i32 s4, s4, 1
	s_mul_i32 s100, s5, 0x8000
	v_lshl_add_u64 v[70:71], v[68:69], 0, s[100:101]
	global_load_dwordx4 v[96:99], v[70:71], off
	global_load_dwordx4 v[100:103], v[70:71], off offset:1024
	s_and_b32 s5, s4, 31
	s_add_i32 s4, s4, 1
	s_mul_i32 s100, s5, 0x8000
	v_lshl_add_u64 v[70:71], v[68:69], 0, s[100:101]
	global_load_dwordx4 v[104:107], v[70:71], off
	global_load_dwordx4 v[108:111], v[70:71], off offset:1024
	s_and_b32 s5, s4, 31
	s_add_i32 s4, s4, 1
	s_mul_i32 s100, s5, 0x8000
	v_lshl_add_u64 v[70:71], v[68:69], 0, s[100:101]
	global_load_dwordx4 v[112:115], v[70:71], off
	global_load_dwordx4 v[116:119], v[70:71], off offset:1024
	s_and_b32 s5, s4, 31
	s_add_i32 s4, s4, 1
	s_mul_i32 s100, s5, 0x8000
	v_lshl_add_u64 v[70:71], v[68:69], 0, s[100:101]
	global_load_dwordx4 v[120:123], v[70:71], off
	global_load_dwordx4 v[128:131], v[70:71], off offset:1024
	s_and_b32 s5, s4, 31
	s_add_i32 s4, s4, 1
	s_mul_i32 s100, s5, 0x8000
	v_lshl_add_u64 v[70:71], v[68:69], 0, s[100:101]
	global_load_dwordx4 v[132:135], v[70:71], off
	global_load_dwordx4 v[136:139], v[70:71], off offset:1024
	s_mov_b32 s3, s2
	s_and_b32 s5, s3, 31
	s_lshl_b32 s5, s5, 5
	s_add_i32 s3, s3, 1
	v_add_u32_e32 v125, s5, v124
	ds_read_b128 v[140:143], v125
	ds_read_b128 v[144:147], v125 offset:33280
	s_mov_b32 s6, 3
.Lkoa2_loop:
	s_and_b32 s5, s3, 31
	s_lshl_b32 s5, s5, 5
	s_add_i32 s3, s3, 1
	v_add_u32_e32 v125, s5, v124
	ds_read_b128 v[148:151], v125
	ds_read_b128 v[152:155], v125 offset:33280
	s_waitcnt vmcnt(15) lgkmcnt(2)
	v_mfma_f32_32x32x16_f16 v[50:65], v[140:143], v[72:75], v[50:65]
	v_mfma_f32_32x32x16_f16 v[18:33], v[144:147], v[72:75], v[18:33]
	s_waitcnt vmcnt(14)
	v_mfma_f32_32x32x16_f16 v[34:49], v[140:143], v[76:79], v[34:49]
	v_mfma_f32_32x32x16_f16 v[2:17], v[144:147], v[76:79], v[2:17]
	s_and_b32 s5, s4, 31
	s_add_i32 s4, s4, 1
	s_mul_i32 s100, s5, 0x8000
	v_lshl_add_u64 v[70:71], v[68:69], 0, s[100:101]
	global_load_dwordx4 v[72:75], v[70:71], off
	global_load_dwordx4 v[76:79], v[70:71], off offset:1024
	s_and_b32 s5, s3, 31
	s_lshl_b32 s5, s5, 5
	s_add_i32 s3, s3, 1
	v_add_u32_e32 v125, s5, v124
	ds_read_b128 v[140:143], v125
	ds_read_b128 v[144:147], v125 offset:33280
	s_waitcnt vmcnt(15) lgkmcnt(2)
	v_mfma_f32_32x32x16_f16 v[50:65], v[148:151], v[80:83], v[50:65]
	v_mfma_f32_32x32x16_f16 v[18:33], v[152:155], v[80:83], v[18:33]
	s_waitcnt vmcnt(14)
	v_mfma_f32_32x32x16_f16 v[34:49], v[148:151], v[84:87], v[34:49]
	v_mfma_f32_32x32x16_f16 v[2:17], v[152:155], v[84:87], v[2:17]
	s_and_b32 s5, s4, 31
	s_add_i32 s4, s4, 1
	s_mul_i32 s100, s5, 0x8000
	v_lshl_add_u64 v[70:71], v[68:69], 0, s[100:101]
	global_load_dwordx4 v[80:83], v[70:71], off
	global_load_dwordx4 v[84:87], v[70:71], off offset:1024
	s_and_b32 s5, s3, 31
	s_lshl_b32 s5, s5, 5
	s_add_i32 s3, s3, 1
	v_add_u32_e32 v125, s5, v124
	ds_read_b128 v[148:151], v125
	ds_read_b128 v[152:155], v125 offset:33280
	s_waitcnt vmcnt(15) lgkmcnt(2)
	v_mfma_f32_32x32x16_f16 v[50:65], v[140:143], v[88:91], v[50:65]
	v_mfma_f32_32x32x16_f16 v[18:33], v[144:147], v[88:91], v[18:33]
	s_waitcnt vmcnt(14)
; #define MFMA32(a, b, c) __builtin_amdgcn_mfma_f32_32x32x16_f16((a), (b), (c), 0, 0, 0)
; template <int K, class Epi>
; DI void gemm64_res(const bf16_t* A, int lda, const bf16_t* Wp, int NU, unsigned char* lds, const Epi& epi) {
;     ...
;         for (int kk = 0; kk < KS; kk += PD) {
; #pragma unroll
;             for (int s = 0; s < PD; ++s) {
;                 const int ks = kk + s, ksr = (ks + rot) & (KS - 1);
;                 const bf16x8 a0 = *(const bf16x8*)(ab + ksr * 32), a1 = *(const bf16x8*)(ab + 32 * LD + ksr * 32);
; #pragma unroll
;                 for (int j = 0; j < NT; ++j) { acc[0][j] = MFMA32(a0, __builtin_bit_cast(bf16x8, bq[s][j]), acc[0][j]); acc[1][j] = MFMA32(a1, __builtin_bit_cast(bf16x8, bq[s][j]), acc[1][j]); }
;                 int nk = ks + PD; nk = nk < KS ? nk : KS - 1; nk = (nk + rot) & (KS - 1);
; #pragma unroll
;                 for (int j = 0; j < NT; ++j) bq[s][j] = bp[(size_t)nk * kstr + j * 64];
;             }
	v_mfma_f32_32x32x16_f16 v[34:49], v[140:143], v[92:95], v[34:49]
	v_mfma_f32_32x32x16_f16 v[2:17], v[144:147], v[92:95], v[2:17]
	s_and_b32 s5, s4, 31
	s_add_i32 s4, s4, 1
	s_mul_i32 s100, s5, 0x8000
	v_lshl_add_u64 v[70:71], v[68:69], 0, s[100:101]
	global_load_dwordx4 v[88:91], v[70:71], off
	global_load_dwordx4 v[92:95], v[70:71], off offset:1024
	s_and_b32 s5, s3, 31
	s_lshl_b32 s5, s5, 5
	s_add_i32 s3, s3, 1
	v_add_u32_e32 v125, s5, v124
	ds_read_b128 v[140:143], v125
	ds_read_b128 v[144:147], v125 offset:33280
	s_waitcnt vmcnt(15) lgkmcnt(2)
	v_mfma_f32_32x32x16_f16 v[50:65], v[148:151], v[96:99], v[50:65]
	v_mfma_f32_32x32x16_f16 v[18:33], v[152:155], v[96:99], v[18:33]
	s_waitcnt vmcnt(14)
	v_mfma_f32_32x32x16_f16 v[34:49], v[148:151], v[100:103], v[34:49]
	v_mfma_f32_32x32x16_f16 v[2:17], v[152:155], v[100:103], v[2:17]
	s_and_b32 s5, s4, 31
	s_add_i32 s4, s4, 1
	s_mul_i32 s100, s5, 0x8000
	v_lshl_add_u64 v[70:71], v[68:69], 0, s[100:101]
	global_load_dwordx4 v[96:99], v[70:71], off
	global_load_dwordx4 v[100:103], v[70:71], off offset:1024
	s_and_b32 s5, s3, 31
	s_lshl_b32 s5, s5, 5
	s_add_i32 s3, s3, 1
	v_add_u32_e32 v125, s5, v124
	ds_read_b128 v[148:151], v125
	ds_read_b128 v[152:155], v125 offset:33280
	s_waitcnt vmcnt(15) lgkmcnt(2)
	v_mfma_f32_32x32x16_f16 v[50:65], v[140:143], v[104:107], v[50:65]
	v_mfma_f32_32x32x16_f16 v[18:33], v[144:147], v[104:107], v[18:33]
	s_waitcnt vmcnt(14)
	v_mfma_f32_32x32x16_f16 v[34:49], v[140:143], v[108:111], v[34:49]
	v_mfma_f32_32x32x16_f16 v[2:17], v[144:147], v[108:111], v[2:17]
	s_and_b32 s5, s4, 31
	s_add_i32 s4, s4, 1
	s_mul_i32 s100, s5, 0x8000
	v_lshl_add_u64 v[70:71], v[68:69], 0, s[100:101]
	global_load_dwordx4 v[104:107], v[70:71], off
	global_load_dwordx4 v[108:111], v[70:71], off offset:1024
	s_and_b32 s5, s3, 31
	s_lshl_b32 s5, s5, 5
	s_add_i32 s3, s3, 1
	v_add_u32_e32 v125, s5, v124
	ds_read_b128 v[140:143], v125
	ds_read_b128 v[144:147], v125 offset:33280
	s_waitcnt vmcnt(15) lgkmcnt(2)
	v_mfma_f32_32x32x16_f16 v[50:65], v[148:151], v[112:115], v[50:65]
	v_mfma_f32_32x32x16_f16 v[18:33], v[152:155], v[112:115], v[18:33]
	s_waitcnt vmcnt(14)
	v_mfma_f32_32x32x16_f16 v[34:49], v[148:151], v[116:119], v[34:49]
	v_mfma_f32_32x32x16_f16 v[2:17], v[152:155], v[116:119], v[2:17]
	s_and_b32 s5, s4, 31
	s_add_i32 s4, s4, 1
	s_mul_i32 s100, s5, 0x8000
	v_lshl_add_u64 v[70:71], v[68:69], 0, s[100:101]
	global_load_dwordx4 v[112:115], v[70:71], off
	global_load_dwordx4 v[116:119], v[70:71], off offset:1024
	s_and_b32 s5, s3, 31
	s_lshl_b32 s5, s5, 5
	s_add_i32 s3, s3, 1
	v_add_u32_e32 v125, s5, v124
	ds_read_b128 v[148:151], v125
	ds_read_b128 v[152:155], v125 offset:33280
	s_waitcnt vmcnt(15) lgkmcnt(2)
	v_mfma_f32_32x32x16_f16 v[50:65], v[140:143], v[120:123], v[50:65]
	v_mfma_f32_32x32x16_f16 v[18:33], v[144:147], v[120:123], v[18:33]
	s_waitcnt vmcnt(14)
	v_mfma_f32_32x32x16_f16 v[34:49], v[140:143], v[128:131], v[34:49]
	v_mfma_f32_32x32x16_f16 v[2:17], v[144:147], v[128:131], v[2:17]
	s_and_b32 s5, s4, 31
	s_add_i32 s4, s4, 1
	s_mul_i32 s100, s5, 0x8000
	v_lshl_add_u64 v[70:71], v[68:69], 0, s[100:101]
	global_load_dwordx4 v[120:123], v[70:71], off
	global_load_dwordx4 v[128:131], v[70:71], off offset:1024
	s_and_b32 s5, s3, 31
	s_lshl_b32 s5, s5, 5
	s_add_i32 s3, s3, 1
	v_add_u32_e32 v125, s5, v124
	ds_read_b128 v[140:143], v125
	ds_read_b128 v[144:147], v125 offset:33280
	s_waitcnt vmcnt(15) lgkmcnt(2)
	v_mfma_f32_32x32x16_f16 v[50:65], v[148:151], v[132:135], v[50:65]
	v_mfma_f32_32x32x16_f16 v[18:33], v[152:155], v[132:135], v[18:33]
	s_waitcnt vmcnt(14)
	v_mfma_f32_32x32x16_f16 v[34:49], v[148:151], v[136:139], v[34:49]
	v_mfma_f32_32x32x16_f16 v[2:17], v[152:155], v[136:139], v[2:17]
	s_and_b32 s5, s4, 31
	s_add_i32 s4, s4, 1
	s_mul_i32 s100, s5, 0x8000
	v_lshl_add_u64 v[70:71], v[68:69], 0, s[100:101]
	global_load_dwordx4 v[132:135], v[70:71], off
	global_load_dwordx4 v[136:139], v[70:71], off offset:1024
	s_add_i32 s6, s6, -1
	s_cmp_lg_u32 s6, 0
	s_cbranch_scc1 .Lkoa2_loop
	s_and_b32 s5, s3, 31
	s_lshl_b32 s5, s5, 5
	s_add_i32 s3, s3, 1
	v_add_u32_e32 v125, s5, v124
	ds_read_b128 v[148:151], v125
	ds_read_b128 v[152:155], v125 offset:33280
	s_waitcnt vmcnt(15) lgkmcnt(2)
	v_mfma_f32_32x32x16_f16 v[50:65], v[140:143], v[72:75], v[50:65]
	v_mfma_f32_32x32x16_f16 v[18:33], v[144:147], v[72:75], v[18:33]
	s_waitcnt vmcnt(14)
	v_mfma_f32_32x32x16_f16 v[34:49], v[140:143], v[76:79], v[34:49]
	v_mfma_f32_32x32x16_f16 v[2:17], v[144:147], v[76:79], v[2:17]
	s_and_b32 s5, s3, 31
	s_lshl_b32 s5, s5, 5
	s_add_i32 s3, s3, 1
	v_add_u32_e32 v125, s5, v124
	ds_read_b128 v[140:143], v125
	ds_read_b128 v[144:147], v125 offset:33280
	s_waitcnt vmcnt(13) lgkmcnt(2)
	v_mfma_f32_32x32x16_f16 v[50:65], v[148:151], v[80:83], v[50:65]
	v_mfma_f32_32x32x16_f16 v[18:33], v[152:155], v[80:83], v[18:33]
	s_waitcnt vmcnt(12)
	v_mfma_f32_32x32x16_f16 v[34:49], v[148:151], v[84:87], v[34:49]
	v_mfma_f32_32x32x16_f16 v[2:17], v[152:155], v[84:87], v[2:17]
	s_and_b32 s5, s3, 31
	s_lshl_b32 s5, s5, 5
	s_add_i32 s3, s3, 1
	v_add_u32_e32 v125, s5, v124
	ds_read_b128 v[148:151], v125
	ds_read_b128 v[152:155], v125 offset:33280
	s_waitcnt vmcnt(11) lgkmcnt(2)
	v_mfma_f32_32x32x16_f16 v[50:65], v[140:143], v[88:91], v[50:65]
	v_mfma_f32_32x32x16_f16 v[18:33], v[144:147], v[88:91], v[18:33]
	s_waitcnt vmcnt(10)
	v_mfma_f32_32x32x16_f16 v[34:49], v[140:143], v[92:95], v[34:49]
	v_mfma_f32_32x32x16_f16 v[2:17], v[144:147], v[92:95], v[2:17]
	s_and_b32 s5, s3, 31
	s_lshl_b32 s5, s5, 5
	s_add_i32 s3, s3, 1
	v_add_u32_e32 v125, s5, v124
	ds_read_b128 v[140:143], v125
	ds_read_b128 v[144:147], v125 offset:33280
	s_waitcnt vmcnt(9) lgkmcnt(2)
; #define MFMA32(a, b, c) __builtin_amdgcn_mfma_f32_32x32x16_f16((a), (b), (c), 0, 0, 0)
; DI int otid() { int t = threadIdx.x; asm volatile("" : "+v"(t)); return t; }
; DI bf16_t cv1(float x) { return (bf16_t)(pk2(x, 0.f) & 0xffffu); }
; DI float bf2f(bf16_t v) { return (float)__builtin_bit_cast(_Float16, v); }
; DI int crow(int i, int h) { return (i & 3) + 8 * (i >> 2) + 4 * h; }
; template <int K, class Epi>
; DI void gemm64_res(const bf16_t* A, int lda, const bf16_t* Wp, int NU, unsigned char* lds, const Epi& epi) {
;     ...
; #pragma unroll 1
;         for (int kk = 0; kk < KS; kk += PD) {
; #pragma unroll
;             for (int s = 0; s < PD; ++s) {
;                 const int ks = kk + s, ksr = (ks + rot) & (KS - 1);
;                 const bf16x8 a0 = *(const bf16x8*)(ab + ksr * 32), a1 = *(const bf16x8*)(ab + 32 * LD + ksr * 32);
; #pragma unroll
;                 for (int j = 0; j < NT; ++j) { acc[0][j] = MFMA32(a0, __builtin_bit_cast(bf16x8, bq[s][j]), acc[0][j]); acc[1][j] = MFMA32(a1, __builtin_bit_cast(bf16x8, bq[s][j]), acc[1][j]); }
;                 int nk = ks + PD; nk = nk < KS ? nk : KS - 1; nk = (nk + rot) & (KS - 1);
; #pragma unroll
;                 for (int j = 0; j < NT; ++j) bq[s][j] = bp[(size_t)nk * kstr + j * 64];
;             }
;         }
;     DI void operator()(int unit, const f32x16 (&acc)[MT][NT]) const {
;         const int lane = otid() & 63, r = lane & 31, h = lane >> 5;
; #pragma unroll
;         for (int mi = 0; mi < MT; ++mi)
; #pragma unroll
;             for (int nj = 0; nj < NT; ++nj)
; #pragma unroll
;                 for (int i = 0; i < 16; ++i) {
;                     bf16_t* rowp = priv + (mi * 32 + crow(i, h) + (mi == 2 ? d2 : 0)) * PRIVW; const int c = unit * UW + nj * 32 + r;
;                     float v = bf2f(rowp[gcol + c]) * acc[mi][nj][i];
;                     if (SECOND) v += bf2f(rowp[PC_M + c]);
;                     rowp[PC_M + c] = cv1(v);
	v_mfma_f32_32x32x16_f16 v[50:65], v[148:151], v[96:99], v[50:65]
	v_mfma_f32_32x32x16_f16 v[18:33], v[152:155], v[96:99], v[18:33]
	s_waitcnt vmcnt(8)
	v_mfma_f32_32x32x16_f16 v[34:49], v[148:151], v[100:103], v[34:49]
	v_mfma_f32_32x32x16_f16 v[2:17], v[152:155], v[100:103], v[2:17]
	s_and_b32 s5, s3, 31
	s_lshl_b32 s5, s5, 5
	s_add_i32 s3, s3, 1
	v_add_u32_e32 v125, s5, v124
	ds_read_b128 v[148:151], v125
	ds_read_b128 v[152:155], v125 offset:33280
	s_waitcnt vmcnt(7) lgkmcnt(2)
	v_mfma_f32_32x32x16_f16 v[50:65], v[140:143], v[104:107], v[50:65]
	v_mfma_f32_32x32x16_f16 v[18:33], v[144:147], v[104:107], v[18:33]
	s_waitcnt vmcnt(6)
	v_mfma_f32_32x32x16_f16 v[34:49], v[140:143], v[108:111], v[34:49]
	v_mfma_f32_32x32x16_f16 v[2:17], v[144:147], v[108:111], v[2:17]
	s_and_b32 s5, s3, 31
	s_lshl_b32 s5, s5, 5
	s_add_i32 s3, s3, 1
	v_add_u32_e32 v125, s5, v124
	ds_read_b128 v[140:143], v125
	ds_read_b128 v[144:147], v125 offset:33280
	s_waitcnt vmcnt(5) lgkmcnt(2)
	v_mfma_f32_32x32x16_f16 v[50:65], v[148:151], v[112:115], v[50:65]
	v_mfma_f32_32x32x16_f16 v[18:33], v[152:155], v[112:115], v[18:33]
	s_waitcnt vmcnt(4)
	v_mfma_f32_32x32x16_f16 v[34:49], v[148:151], v[116:119], v[34:49]
	v_mfma_f32_32x32x16_f16 v[2:17], v[152:155], v[116:119], v[2:17]
	s_and_b32 s5, s3, 31
	s_lshl_b32 s5, s5, 5
	s_add_i32 s3, s3, 1
	v_add_u32_e32 v125, s5, v124
	ds_read_b128 v[148:151], v125
	ds_read_b128 v[152:155], v125 offset:33280
	s_waitcnt vmcnt(3) lgkmcnt(2)
	v_mfma_f32_32x32x16_f16 v[50:65], v[140:143], v[120:123], v[50:65]
	v_mfma_f32_32x32x16_f16 v[18:33], v[144:147], v[120:123], v[18:33]
	s_waitcnt vmcnt(2)
	v_mfma_f32_32x32x16_f16 v[34:49], v[140:143], v[128:131], v[34:49]
	v_mfma_f32_32x32x16_f16 v[2:17], v[144:147], v[128:131], v[2:17]
	s_waitcnt vmcnt(1) lgkmcnt(0)
	v_mfma_f32_32x32x16_f16 v[50:65], v[148:151], v[132:135], v[50:65]
	v_mfma_f32_32x32x16_f16 v[18:33], v[152:155], v[132:135], v[18:33]
	s_waitcnt vmcnt(0)
	v_mfma_f32_32x32x16_f16 v[34:49], v[148:151], v[136:139], v[34:49]
	v_mfma_f32_32x32x16_f16 v[2:17], v[152:155], v[136:139], v[2:17]
	s_nop 7
	s_nop 3
	s_waitcnt vmcnt(0)
	v_and_b32_e32 v68, 31, v176
	v_lshrrev_b32_e32 v69, 3, v176
	v_and_b32_e32 v69, 4, v69
	v_mul_u32_u24_e32 v69, 0x2c00, v69
	v_lshl_add_u32 v70, v68, 1, v69
	v_lshl_add_u32 v70, s1, 7, v70
	v_add_u32_e32 v71, 0x1400, v70
	global_load_ushort v87, v71, s[34:35] offset:-3072
	global_load_ushort v88, v71, s[34:35] offset:-3008
	v_add_u32_e32 v72, 0x4000, v70
	global_load_ushort v89, v72, s[34:35] offset:-3072
	global_load_ushort v90, v72, s[34:35] offset:-3008
	v_add_u32_e32 v73, 0x6c00, v70
	global_load_ushort v91, v73, s[34:35] offset:-3072
	global_load_ushort v92, v73, s[34:35] offset:-3008
	v_add_u32_e32 v74, 0x9800, v70
	global_load_ushort v93, v74, s[34:35] offset:-3072
	global_load_ushort v94, v74, s[34:35] offset:-3008
	v_add_u32_e32 v75, 0x17400, v70
	global_load_ushort v95, v75, s[34:35] offset:-3072
	global_load_ushort v96, v75, s[34:35] offset:-3008
	v_add_u32_e32 v76, 0x1a000, v70
	global_load_ushort v97, v76, s[34:35] offset:-3072
	global_load_ushort v98, v76, s[34:35] offset:-3008
	v_add_u32_e32 v77, 0x1cc00, v70
	global_load_ushort v99, v77, s[34:35] offset:-3072
	global_load_ushort v100, v77, s[34:35] offset:-3008
	v_add_u32_e32 v78, 0x1f800, v70
	global_load_ushort v101, v78, s[34:35] offset:-3072
	global_load_ushort v102, v78, s[34:35] offset:-3008
	v_add_u32_e32 v79, 0x2d400, v70
	global_load_ushort v103, v79, s[34:35] offset:-3072
	global_load_ushort v104, v79, s[34:35] offset:-3008
	v_add_u32_e32 v80, 0x30000, v70
	global_load_ushort v105, v80, s[34:35] offset:-3072
	global_load_ushort v106, v80, s[34:35] offset:-3008
	v_add_u32_e32 v81, 0x32c00, v70
	global_load_ushort v107, v81, s[34:35] offset:-3072
	global_load_ushort v108, v81, s[34:35] offset:-3008
	v_add_u32_e32 v82, 0x35800, v70
	global_load_ushort v109, v82, s[34:35] offset:-3072
	global_load_ushort v110, v82, s[34:35] offset:-3008
	v_add_u32_e32 v83, 0x43400, v70
	global_load_ushort v111, v83, s[34:35] offset:-3072
	global_load_ushort v112, v83, s[34:35] offset:-3008
	v_add_u32_e32 v84, 0x46000, v70
	global_load_ushort v113, v84, s[34:35] offset:-3072
	global_load_ushort v114, v84, s[34:35] offset:-3008
	v_add_u32_e32 v85, 0x48c00, v70
	global_load_ushort v116, v85, s[34:35] offset:-3072
	global_load_ushort v117, v85, s[34:35] offset:-3008
	v_add_u32_e32 v86, 0x4b800, v70
	global_load_ushort v118, v86, s[34:35] offset:-3072
	global_load_ushort v119, v86, s[34:35] offset:-3008
	s_waitcnt vmcnt(0)
; DI int otid() { int t = threadIdx.x; asm volatile("" : "+v"(t)); return t; }
; DI bf16_t cv1(float x) { return (bf16_t)(pk2(x, 0.f) & 0xffffu); }
; DI float bf2f(bf16_t v) { return (float)__builtin_bit_cast(_Float16, v); }
; DI int crow(int i, int h) { return (i & 3) + 8 * (i >> 2) + 4 * h; }
;     DI void operator()(int unit, const f32x16 (&acc)[MT][NT]) const {
;         const int lane = otid() & 63, r = lane & 31, h = lane >> 5;
; #pragma unroll
;         for (int mi = 0; mi < MT; ++mi)
; #pragma unroll
;             for (int nj = 0; nj < NT; ++nj)
; #pragma unroll
;                 for (int i = 0; i < 16; ++i) {
;                     bf16_t* rowp = priv + (mi * 32 + crow(i, h) + (mi == 2 ? d2 : 0)) * PRIVW; const int c = unit * UW + nj * 32 + r;
;                     float v = bf2f(rowp[gcol + c]) * acc[mi][nj][i];
;                     if (SECOND) v += bf2f(rowp[PC_M + c]);
;                     rowp[PC_M + c] = cv1(v);
;                     if (i == 15) __builtin_amdgcn_sched_barrier(0);
	v_fma_mixlo_f16 v87, v50, v87, 0 op_sel_hi:[0,1,0]
	global_store_short v71, v87, s[34:35] offset:3072
	v_fma_mixlo_f16 v88, v34, v88, 0 op_sel_hi:[0,1,0]
	global_store_short v71, v88, s[34:35] offset:3136
	v_fma_mixlo_f16 v89, v51, v89, 0 op_sel_hi:[0,1,0]
	global_store_short v72, v89, s[34:35] offset:3072
	v_fma_mixlo_f16 v90, v35, v90, 0 op_sel_hi:[0,1,0]
	global_store_short v72, v90, s[34:35] offset:3136
	v_fma_mixlo_f16 v91, v52, v91, 0 op_sel_hi:[0,1,0]
	global_store_short v73, v91, s[34:35] offset:3072
	v_fma_mixlo_f16 v92, v36, v92, 0 op_sel_hi:[0,1,0]
	global_store_short v73, v92, s[34:35] offset:3136
	v_fma_mixlo_f16 v93, v53, v93, 0 op_sel_hi:[0,1,0]
	global_store_short v74, v93, s[34:35] offset:3072
	v_fma_mixlo_f16 v94, v37, v94, 0 op_sel_hi:[0,1,0]
	global_store_short v74, v94, s[34:35] offset:3136
	v_fma_mixlo_f16 v95, v54, v95, 0 op_sel_hi:[0,1,0]
	global_store_short v75, v95, s[34:35] offset:3072
	v_fma_mixlo_f16 v96, v38, v96, 0 op_sel_hi:[0,1,0]
	global_store_short v75, v96, s[34:35] offset:3136
	v_fma_mixlo_f16 v97, v55, v97, 0 op_sel_hi:[0,1,0]
	global_store_short v76, v97, s[34:35] offset:3072
	v_fma_mixlo_f16 v98, v39, v98, 0 op_sel_hi:[0,1,0]
	global_store_short v76, v98, s[34:35] offset:3136
	v_fma_mixlo_f16 v99, v56, v99, 0 op_sel_hi:[0,1,0]
	global_store_short v77, v99, s[34:35] offset:3072
	v_fma_mixlo_f16 v100, v40, v100, 0 op_sel_hi:[0,1,0]
	global_store_short v77, v100, s[34:35] offset:3136
	v_fma_mixlo_f16 v101, v57, v101, 0 op_sel_hi:[0,1,0]
	global_store_short v78, v101, s[34:35] offset:3072
	v_fma_mixlo_f16 v102, v41, v102, 0 op_sel_hi:[0,1,0]
	global_store_short v78, v102, s[34:35] offset:3136
	v_fma_mixlo_f16 v103, v58, v103, 0 op_sel_hi:[0,1,0]
	global_store_short v79, v103, s[34:35] offset:3072
	v_fma_mixlo_f16 v104, v42, v104, 0 op_sel_hi:[0,1,0]
	global_store_short v79, v104, s[34:35] offset:3136
	v_fma_mixlo_f16 v105, v59, v105, 0 op_sel_hi:[0,1,0]
	global_store_short v80, v105, s[34:35] offset:3072
	v_fma_mixlo_f16 v106, v43, v106, 0 op_sel_hi:[0,1,0]
	global_store_short v80, v106, s[34:35] offset:3136
	v_fma_mixlo_f16 v107, v60, v107, 0 op_sel_hi:[0,1,0]
	global_store_short v81, v107, s[34:35] offset:3072
	v_fma_mixlo_f16 v108, v44, v108, 0 op_sel_hi:[0,1,0]
	global_store_short v81, v108, s[34:35] offset:3136
	v_fma_mixlo_f16 v109, v61, v109, 0 op_sel_hi:[0,1,0]
	global_store_short v82, v109, s[34:35] offset:3072
	v_fma_mixlo_f16 v110, v45, v110, 0 op_sel_hi:[0,1,0]
	global_store_short v82, v110, s[34:35] offset:3136
	v_fma_mixlo_f16 v111, v62, v111, 0 op_sel_hi:[0,1,0]
	global_store_short v83, v111, s[34:35] offset:3072
	v_fma_mixlo_f16 v112, v46, v112, 0 op_sel_hi:[0,1,0]
	global_store_short v83, v112, s[34:35] offset:3136
	v_fma_mixlo_f16 v113, v63, v113, 0 op_sel_hi:[0,1,0]
	global_store_short v84, v113, s[34:35] offset:3072
	v_fma_mixlo_f16 v114, v47, v114, 0 op_sel_hi:[0,1,0]
	global_store_short v84, v114, s[34:35] offset:3136
	v_fma_mixlo_f16 v116, v64, v116, 0 op_sel_hi:[0,1,0]
	global_store_short v85, v116, s[34:35] offset:3072
	v_fma_mixlo_f16 v117, v48, v117, 0 op_sel_hi:[0,1,0]
	global_store_short v85, v117, s[34:35] offset:3136
	v_fma_mixlo_f16 v118, v65, v118, 0 op_sel_hi:[0,1,0]
	global_store_short v86, v118, s[34:35] offset:3072
	v_fma_mixlo_f16 v119, v49, v119, 0 op_sel_hi:[0,1,0]
	global_store_short v86, v119, s[34:35] offset:3136
	v_add_u32_e32 v71, 0x59400, v70
	global_load_ushort v87, v71, s[34:35] offset:-3072
	global_load_ushort v88, v71, s[34:35] offset:-3008
	v_add_u32_e32 v72, 0x5c000, v70
	global_load_ushort v89, v72, s[34:35] offset:-3072
	global_load_ushort v90, v72, s[34:35] offset:-3008
	v_add_u32_e32 v73, 0x5ec00, v70
	global_load_ushort v91, v73, s[34:35] offset:-3072
	global_load_ushort v92, v73, s[34:35] offset:-3008
	v_add_u32_e32 v74, 0x61800, v70
	global_load_ushort v93, v74, s[34:35] offset:-3072
	global_load_ushort v94, v74, s[34:35] offset:-3008
	v_add_u32_e32 v75, 0x6f400, v70
	global_load_ushort v95, v75, s[34:35] offset:-3072
	global_load_ushort v96, v75, s[34:35] offset:-3008
	v_add_u32_e32 v76, 0x72000, v70
	global_load_ushort v97, v76, s[34:35] offset:-3072
	global_load_ushort v98, v76, s[34:35] offset:-3008
	v_add_u32_e32 v77, 0x74c00, v70
	global_load_ushort v99, v77, s[34:35] offset:-3072
	global_load_ushort v100, v77, s[34:35] offset:-3008
	v_add_u32_e32 v78, 0x77800, v70
	global_load_ushort v101, v78, s[34:35] offset:-3072
	global_load_ushort v102, v78, s[34:35] offset:-3008
	v_add_u32_e32 v79, 0x85400, v70
	global_load_ushort v103, v79, s[34:35] offset:-3072
	global_load_ushort v104, v79, s[34:35] offset:-3008
	v_add_u32_e32 v80, 0x88000, v70
	global_load_ushort v105, v80, s[34:35] offset:-3072
	global_load_ushort v106, v80, s[34:35] offset:-3008
	v_add_u32_e32 v81, 0x8ac00, v70
	global_load_ushort v107, v81, s[34:35] offset:-3072
	global_load_ushort v108, v81, s[34:35] offset:-3008
	v_add_u32_e32 v82, 0x8d800, v70
	global_load_ushort v109, v82, s[34:35] offset:-3072
	global_load_ushort v110, v82, s[34:35] offset:-3008
	v_add_u32_e32 v83, 0x9b400, v70
	global_load_ushort v111, v83, s[34:35] offset:-3072
	global_load_ushort v112, v83, s[34:35] offset:-3008
	v_add_u32_e32 v84, 0x9e000, v70
	global_load_ushort v113, v84, s[34:35] offset:-3072
	global_load_ushort v114, v84, s[34:35] offset:-3008
	v_add_u32_e32 v85, 0xa0c00, v70
	global_load_ushort v116, v85, s[34:35] offset:-3072
	global_load_ushort v117, v85, s[34:35] offset:-3008
	v_add_u32_e32 v86, 0xa3800, v70
	global_load_ushort v118, v86, s[34:35] offset:-3072
	global_load_ushort v119, v86, s[34:35] offset:-3008
	s_waitcnt vmcnt(0)
; DI int otid() { int t = threadIdx.x; asm volatile("" : "+v"(t)); return t; }
; DI bf16_t cv1(float x) { return (bf16_t)(pk2(x, 0.f) & 0xffffu); }
; DI float bf2f(bf16_t v) { return (float)__builtin_bit_cast(_Float16, v); }
; DI int crow(int i, int h) { return (i & 3) + 8 * (i >> 2) + 4 * h; }
;     DI void operator()(int unit, const f32x16 (&acc)[MT][NT]) const {
;         const int lane = otid() & 63, r = lane & 31, h = lane >> 5;
; #pragma unroll
;         for (int mi = 0; mi < MT; ++mi)
; #pragma unroll
;             for (int nj = 0; nj < NT; ++nj)
; #pragma unroll
;                 for (int i = 0; i < 16; ++i) {
;                     bf16_t* rowp = priv + (mi * 32 + crow(i, h) + (mi == 2 ? d2 : 0)) * PRIVW; const int c = unit * UW + nj * 32 + r;
;                     float v = bf2f(rowp[gcol + c]) * acc[mi][nj][i];
;                     if (SECOND) v += bf2f(rowp[PC_M + c]);
;                     rowp[PC_M + c] = cv1(v);
;                     if (i == 15) __builtin_amdgcn_sched_barrier(0);
	v_fma_mixlo_f16 v87, v18, v87, 0 op_sel_hi:[0,1,0]
	global_store_short v71, v87, s[34:35] offset:3072
	v_fma_mixlo_f16 v88, v2, v88, 0 op_sel_hi:[0,1,0]
	global_store_short v71, v88, s[34:35] offset:3136
	v_fma_mixlo_f16 v89, v19, v89, 0 op_sel_hi:[0,1,0]
	global_store_short v72, v89, s[34:35] offset:3072
	v_fma_mixlo_f16 v90, v3, v90, 0 op_sel_hi:[0,1,0]
	global_store_short v72, v90, s[34:35] offset:3136
	v_fma_mixlo_f16 v91, v20, v91, 0 op_sel_hi:[0,1,0]
	global_store_short v73, v91, s[34:35] offset:3072
	v_fma_mixlo_f16 v92, v4, v92, 0 op_sel_hi:[0,1,0]
	global_store_short v73, v92, s[34:35] offset:3136
	v_fma_mixlo_f16 v93, v21, v93, 0 op_sel_hi:[0,1,0]
	global_store_short v74, v93, s[34:35] offset:3072
	v_fma_mixlo_f16 v94, v5, v94, 0 op_sel_hi:[0,1,0]
	global_store_short v74, v94, s[34:35] offset:3136
	v_fma_mixlo_f16 v95, v22, v95, 0 op_sel_hi:[0,1,0]
	global_store_short v75, v95, s[34:35] offset:3072
	v_fma_mixlo_f16 v96, v6, v96, 0 op_sel_hi:[0,1,0]
	global_store_short v75, v96, s[34:35] offset:3136
	v_fma_mixlo_f16 v97, v23, v97, 0 op_sel_hi:[0,1,0]
	global_store_short v76, v97, s[34:35] offset:3072
	v_fma_mixlo_f16 v98, v7, v98, 0 op_sel_hi:[0,1,0]
	global_store_short v76, v98, s[34:35] offset:3136
	v_fma_mixlo_f16 v99, v24, v99, 0 op_sel_hi:[0,1,0]
	global_store_short v77, v99, s[34:35] offset:3072
	v_fma_mixlo_f16 v100, v8, v100, 0 op_sel_hi:[0,1,0]
	global_store_short v77, v100, s[34:35] offset:3136
	v_fma_mixlo_f16 v101, v25, v101, 0 op_sel_hi:[0,1,0]
	global_store_short v78, v101, s[34:35] offset:3072
	v_fma_mixlo_f16 v102, v9, v102, 0 op_sel_hi:[0,1,0]
	global_store_short v78, v102, s[34:35] offset:3136
	v_fma_mixlo_f16 v103, v26, v103, 0 op_sel_hi:[0,1,0]
	global_store_short v79, v103, s[34:35] offset:3072
	v_fma_mixlo_f16 v104, v10, v104, 0 op_sel_hi:[0,1,0]
	global_store_short v79, v104, s[34:35] offset:3136
	v_fma_mixlo_f16 v105, v27, v105, 0 op_sel_hi:[0,1,0]
	global_store_short v80, v105, s[34:35] offset:3072
	v_fma_mixlo_f16 v106, v11, v106, 0 op_sel_hi:[0,1,0]
	global_store_short v80, v106, s[34:35] offset:3136
	v_fma_mixlo_f16 v107, v28, v107, 0 op_sel_hi:[0,1,0]
	global_store_short v81, v107, s[34:35] offset:3072
	v_fma_mixlo_f16 v108, v12, v108, 0 op_sel_hi:[0,1,0]
	global_store_short v81, v108, s[34:35] offset:3136
	v_fma_mixlo_f16 v109, v29, v109, 0 op_sel_hi:[0,1,0]
	global_store_short v82, v109, s[34:35] offset:3072
	v_fma_mixlo_f16 v110, v13, v110, 0 op_sel_hi:[0,1,0]
	global_store_short v82, v110, s[34:35] offset:3136
	v_fma_mixlo_f16 v111, v30, v111, 0 op_sel_hi:[0,1,0]
	global_store_short v83, v111, s[34:35] offset:3072
	v_fma_mixlo_f16 v112, v14, v112, 0 op_sel_hi:[0,1,0]
	global_store_short v83, v112, s[34:35] offset:3136
	v_fma_mixlo_f16 v113, v31, v113, 0 op_sel_hi:[0,1,0]
	global_store_short v84, v113, s[34:35] offset:3072
	v_fma_mixlo_f16 v114, v15, v114, 0 op_sel_hi:[0,1,0]
	global_store_short v84, v114, s[34:35] offset:3136
	v_fma_mixlo_f16 v116, v32, v116, 0 op_sel_hi:[0,1,0]
	global_store_short v85, v116, s[34:35] offset:3072
	v_fma_mixlo_f16 v117, v16, v117, 0 op_sel_hi:[0,1,0]
	global_store_short v85, v117, s[34:35] offset:3136
	v_fma_mixlo_f16 v118, v33, v118, 0 op_sel_hi:[0,1,0]
	global_store_short v86, v118, s[34:35] offset:3072
	v_fma_mixlo_f16 v119, v17, v119, 0 op_sel_hi:[0,1,0]
	global_store_short v86, v119, s[34:35] offset:3136
	s_waitcnt vmcnt(0)
	s_add_i32 s2, s1, 8
	s_cmp_lt_i32 s1, 8
	s_mov_b32 s1, s2
	s_cbranch_scc1 .LBB0_505
	s_movk_i32 s17, 0x810
	s_movk_i32 s64, 0x3fff

; #define MFMA32(a, b, c) __builtin_amdgcn_mfma_f32_32x32x16_f16((a), (b), (c), 0, 0, 0)
; template <int K, class Epi>
; DI void gemm64_res(const bf16_t* A, int lda, const bf16_t* Wp, int NU, unsigned char* lds, const Epi& epi) {
;     ...
;     for (int unit = wave; unit < NU; unit += NWAVE) {
;         const u32x4* bp = Bw + (size_t)(unit * NT) * 64 + lane;
;         f32x16 acc[2][NT];
; #pragma unroll
;         for (int mi = 0; mi < 2; ++mi)
; #pragma unroll
;             for (int nj = 0; nj < NT; ++nj)
; #pragma unroll
;                 for (int i = 0; i < 16; ++i) acc[mi][nj][i] = 0.f;
;         u32x4 bq[PD][NT];
; #pragma unroll
;         for (int s = 0; s < PD; ++s)
; #pragma unroll
;             for (int j = 0; j < NT; ++j) bq[s][j] = bp[(size_t)((s + rot) & (KS - 1)) * kstr + j * 64];
; #pragma unroll 1
;         for (int kk = 0; kk < KS; kk += PD) {
; #pragma unroll
;             for (int s = 0; s < PD; ++s) {
;                 const int ks = kk + s, ksr = (ks + rot) & (KS - 1);
;                 const bf16x8 a0 = *(const bf16x8*)(ab + ksr * 32), a1 = *(const bf16x8*)(ab + 32 * LD + ksr * 32);
; #pragma unroll
;                 for (int j = 0; j < NT; ++j) { acc[0][j] = MFMA32(a0, __builtin_bit_cast(bf16x8, bq[s][j]), acc[0][j]); acc[1][j] = MFMA32(a1, __builtin_bit_cast(bf16x8, bq[s][j]), acc[1][j]); }
;                 int nk = ks + PD; nk = nk < KS ? nk : KS - 1; nk = (nk + rot) & (KS - 1);
; #pragma unroll
;                 for (int j = 0; j < NT; ++j) bq[s][j] = bp[(size_t)nk * kstr + j * 64];
;             }
;         }
.LBB0_511:
	s_lshl_b32 s2, s1, 1
	s_ashr_i32 s3, s2, 31
	s_lshl_b64 s[2:3], s[2:3], 10
	v_mov_b32_e32 v2, 0
	v_lshl_add_u64 v[68:69], v[66:67], 0, s[2:3]
	s_mov_b32 s2, -4
	v_readlane_b32 s3, v254, 45
	s_mov_b32 s4, s85
	v_readlane_b32 s7, v253, 29
	s_mov_b32 s6, s9
	s_mov_b32 s5, s87
	v_mov_b32_e32 v3, v2
	v_mov_b32_e32 v4, v2
	v_mov_b32_e32 v5, v2
	v_mov_b32_e32 v6, v2
	v_mov_b32_e32 v7, v2
	v_mov_b32_e32 v8, v2
	v_mov_b32_e32 v9, v2
	v_mov_b32_e32 v10, v2
	v_mov_b32_e32 v11, v2
	v_mov_b32_e32 v12, v2
	v_mov_b32_e32 v13, v2
	v_mov_b32_e32 v14, v2
	v_mov_b32_e32 v15, v2
	v_mov_b32_e32 v16, v2
	v_mov_b32_e32 v17, v2
	v_mov_b32_e32 v18, v2
	v_mov_b32_e32 v19, v2
	v_mov_b32_e32 v20, v2
	v_mov_b32_e32 v21, v2
	v_mov_b32_e32 v22, v2
	v_mov_b32_e32 v23, v2
	v_mov_b32_e32 v24, v2
	v_mov_b32_e32 v25, v2
	v_mov_b32_e32 v26, v2
	v_mov_b32_e32 v27, v2
	v_mov_b32_e32 v28, v2
	v_mov_b32_e32 v29, v2
	v_mov_b32_e32 v30, v2
	v_mov_b32_e32 v31, v2
	v_mov_b32_e32 v32, v2
	v_mov_b32_e32 v33, v2
	v_mov_b32_e32 v34, v2
	v_mov_b32_e32 v35, v2
	v_mov_b32_e32 v36, v2
	v_mov_b32_e32 v37, v2
	v_mov_b32_e32 v38, v2
	v_mov_b32_e32 v39, v2
	v_mov_b32_e32 v40, v2
	v_mov_b32_e32 v41, v2
	v_mov_b32_e32 v42, v2
	v_mov_b32_e32 v43, v2
	v_mov_b32_e32 v44, v2
	v_mov_b32_e32 v45, v2
	v_mov_b32_e32 v46, v2
	v_mov_b32_e32 v47, v2
	v_mov_b32_e32 v48, v2
	v_mov_b32_e32 v49, v2
	v_mov_b32_e32 v50, v2
	v_mov_b32_e32 v51, v2
	v_mov_b32_e32 v52, v2
	v_mov_b32_e32 v53, v2
	v_mov_b32_e32 v54, v2
	v_mov_b32_e32 v55, v2
	v_mov_b32_e32 v56, v2
	v_mov_b32_e32 v57, v2
	v_mov_b32_e32 v58, v2
	v_mov_b32_e32 v59, v2
	v_mov_b32_e32 v60, v2
	v_mov_b32_e32 v61, v2
	v_mov_b32_e32 v62, v2
	v_mov_b32_e32 v63, v2
	v_mov_b32_e32 v64, v2
	v_mov_b32_e32 v65, v2
	v_readlane_b32 s2, v254, 45
	s_nop 3
	s_lshr_b32 s2, s2, 5
	s_mov_b32 s101, 0
	s_mov_b32 s4, s2
	s_and_b32 s5, s4, 31
	s_add_i32 s4, s4, 1
	s_mul_i32 s100, s5, 0x8000
	v_lshl_add_u64 v[70:71], v[68:69], 0, s[100:101]
	global_load_dwordx4 v[72:75], v[70:71], off
	global_load_dwordx4 v[76:79], v[70:71], off offset:1024
	s_and_b32 s5, s4, 31
	s_add_i32 s4, s4, 1
	s_mul_i32 s100, s5, 0x8000
	v_lshl_add_u64 v[70:71], v[68:69], 0, s[100:101]
	global_load_dwordx4 v[80:83], v[70:71], off
	global_load_dwordx4 v[84:87], v[70:71], off offset:1024
	s_and_b32 s5, s4, 31
	s_add_i32 s4, s4, 1
	s_mul_i32 s100, s5, 0x8000
	v_lshl_add_u64 v[70:71], v[68:69], 0, s[100:101]
	global_load_dwordx4 v[88:91], v[70:71], off
	global_load_dwordx4 v[92:95], v[70:71], off offset:1024
	s_and_b32 s5, s4, 31
	s_add_i32 s4, s4, 1
	s_mul_i32 s100, s5, 0x8000
	v_lshl_add_u64 v[70:71], v[68:69], 0, s[100:101]
	global_load_dwordx4 v[96:99], v[70:71], off
	global_load_dwordx4 v[100:103], v[70:71], off offset:1024
	s_and_b32 s5, s4, 31
	s_add_i32 s4, s4, 1
	s_mul_i32 s100, s5, 0x8000
	v_lshl_add_u64 v[70:71], v[68:69], 0, s[100:101]
	global_load_dwordx4 v[104:107], v[70:71], off
	global_load_dwordx4 v[108:111], v[70:71], off offset:1024
	s_and_b32 s5, s4, 31
	s_add_i32 s4, s4, 1
	s_mul_i32 s100, s5, 0x8000
	v_lshl_add_u64 v[70:71], v[68:69], 0, s[100:101]
	global_load_dwordx4 v[112:115], v[70:71], off
	global_load_dwordx4 v[116:119], v[70:71], off offset:1024
	s_and_b32 s5, s4, 31
	s_add_i32 s4, s4, 1
	s_mul_i32 s100, s5, 0x8000
	v_lshl_add_u64 v[70:71], v[68:69], 0, s[100:101]
	global_load_dwordx4 v[120:123], v[70:71], off
	global_load_dwordx4 v[124:127], v[70:71], off offset:1024
	s_and_b32 s5, s4, 31
	s_add_i32 s4, s4, 1
	s_mul_i32 s100, s5, 0x8000
	v_lshl_add_u64 v[70:71], v[68:69], 0, s[100:101]
	global_load_dwordx4 v[132:135], v[70:71], off
	global_load_dwordx4 v[136:139], v[70:71], off offset:1024
	s_mov_b32 s3, s2
	s_and_b32 s5, s3, 31
	s_lshl_b32 s5, s5, 5
	s_add_i32 s3, s3, 1
	v_add_u32_e32 v129, s5, v128
	ds_read_b128 v[140:143], v129
	ds_read_b128 v[144:147], v129 offset:33280
	s_mov_b32 s6, 3
.Lkob2_loop:
	s_and_b32 s5, s3, 31
	s_lshl_b32 s5, s5, 5
	s_add_i32 s3, s3, 1
	v_add_u32_e32 v129, s5, v128
	ds_read_b128 v[148:151], v129
	ds_read_b128 v[152:155], v129 offset:33280
	s_waitcnt vmcnt(15) lgkmcnt(2)
	v_mfma_f32_32x32x16_f16 v[50:65], v[140:143], v[72:75], v[50:65]
	v_mfma_f32_32x32x16_f16 v[18:33], v[144:147], v[72:75], v[18:33]
	s_waitcnt vmcnt(14)
	v_mfma_f32_32x32x16_f16 v[34:49], v[140:143], v[76:79], v[34:49]
	v_mfma_f32_32x32x16_f16 v[2:17], v[144:147], v[76:79], v[2:17]
	s_and_b32 s5, s4, 31
	s_add_i32 s4, s4, 1
	s_mul_i32 s100, s5, 0x8000
	v_lshl_add_u64 v[70:71], v[68:69], 0, s[100:101]
	global_load_dwordx4 v[72:75], v[70:71], off
	global_load_dwordx4 v[76:79], v[70:71], off offset:1024
	s_and_b32 s5, s3, 31
	s_lshl_b32 s5, s5, 5
	s_add_i32 s3, s3, 1
	v_add_u32_e32 v129, s5, v128
	ds_read_b128 v[140:143], v129
	ds_read_b128 v[144:147], v129 offset:33280
	s_waitcnt vmcnt(15) lgkmcnt(2)
	v_mfma_f32_32x32x16_f16 v[50:65], v[148:151], v[80:83], v[50:65]
	v_mfma_f32_32x32x16_f16 v[18:33], v[152:155], v[80:83], v[18:33]
	s_waitcnt vmcnt(14)
	v_mfma_f32_32x32x16_f16 v[34:49], v[148:151], v[84:87], v[34:49]
	v_mfma_f32_32x32x16_f16 v[2:17], v[152:155], v[84:87], v[2:17]
	s_and_b32 s5, s4, 31
	s_add_i32 s4, s4, 1
	s_mul_i32 s100, s5, 0x8000
	v_lshl_add_u64 v[70:71], v[68:69], 0, s[100:101]
	global_load_dwordx4 v[80:83], v[70:71], off
	global_load_dwordx4 v[84:87], v[70:71], off offset:1024
	s_and_b32 s5, s3, 31
	s_lshl_b32 s5, s5, 5
	s_add_i32 s3, s3, 1
	v_add_u32_e32 v129, s5, v128
	ds_read_b128 v[148:151], v129
	ds_read_b128 v[152:155], v129 offset:33280
	s_waitcnt vmcnt(15) lgkmcnt(2)
	v_mfma_f32_32x32x16_f16 v[50:65], v[140:143], v[88:91], v[50:65]
	v_mfma_f32_32x32x16_f16 v[18:33], v[144:147], v[88:91], v[18:33]
	s_waitcnt vmcnt(14)
; #define MFMA32(a, b, c) __builtin_amdgcn_mfma_f32_32x32x16_f16((a), (b), (c), 0, 0, 0)
; template <int K, class Epi>
; DI void gemm64_res(const bf16_t* A, int lda, const bf16_t* Wp, int NU, unsigned char* lds, const Epi& epi) {
;     ...
; #pragma unroll 1
;         for (int kk = 0; kk < KS; kk += PD) {
; #pragma unroll
;             for (int s = 0; s < PD; ++s) {
;                 const int ks = kk + s, ksr = (ks + rot) & (KS - 1);
;                 const bf16x8 a0 = *(const bf16x8*)(ab + ksr * 32), a1 = *(const bf16x8*)(ab + 32 * LD + ksr * 32);
; #pragma unroll
;                 for (int j = 0; j < NT; ++j) { acc[0][j] = MFMA32(a0, __builtin_bit_cast(bf16x8, bq[s][j]), acc[0][j]); acc[1][j] = MFMA32(a1, __builtin_bit_cast(bf16x8, bq[s][j]), acc[1][j]); }
;                 int nk = ks + PD; nk = nk < KS ? nk : KS - 1; nk = (nk + rot) & (KS - 1);
; #pragma unroll
;                 for (int j = 0; j < NT; ++j) bq[s][j] = bp[(size_t)nk * kstr + j * 64];
;             }
;         }
	v_mfma_f32_32x32x16_f16 v[34:49], v[140:143], v[92:95], v[34:49]
	v_mfma_f32_32x32x16_f16 v[2:17], v[144:147], v[92:95], v[2:17]
	s_and_b32 s5, s4, 31
	s_add_i32 s4, s4, 1
	s_mul_i32 s100, s5, 0x8000
	v_lshl_add_u64 v[70:71], v[68:69], 0, s[100:101]
	global_load_dwordx4 v[88:91], v[70:71], off
	global_load_dwordx4 v[92:95], v[70:71], off offset:1024
	s_and_b32 s5, s3, 31
	s_lshl_b32 s5, s5, 5
	s_add_i32 s3, s3, 1
	v_add_u32_e32 v129, s5, v128
	ds_read_b128 v[140:143], v129
	ds_read_b128 v[144:147], v129 offset:33280
	s_waitcnt vmcnt(15) lgkmcnt(2)
	v_mfma_f32_32x32x16_f16 v[50:65], v[148:151], v[96:99], v[50:65]
	v_mfma_f32_32x32x16_f16 v[18:33], v[152:155], v[96:99], v[18:33]
	s_waitcnt vmcnt(14)
	v_mfma_f32_32x32x16_f16 v[34:49], v[148:151], v[100:103], v[34:49]
	v_mfma_f32_32x32x16_f16 v[2:17], v[152:155], v[100:103], v[2:17]
	s_and_b32 s5, s4, 31
	s_add_i32 s4, s4, 1
	s_mul_i32 s100, s5, 0x8000
	v_lshl_add_u64 v[70:71], v[68:69], 0, s[100:101]
	global_load_dwordx4 v[96:99], v[70:71], off
	global_load_dwordx4 v[100:103], v[70:71], off offset:1024
	s_and_b32 s5, s3, 31
	s_lshl_b32 s5, s5, 5
	s_add_i32 s3, s3, 1
	v_add_u32_e32 v129, s5, v128
	ds_read_b128 v[148:151], v129
	ds_read_b128 v[152:155], v129 offset:33280
	s_waitcnt vmcnt(15) lgkmcnt(2)
	v_mfma_f32_32x32x16_f16 v[50:65], v[140:143], v[104:107], v[50:65]
	v_mfma_f32_32x32x16_f16 v[18:33], v[144:147], v[104:107], v[18:33]
	s_waitcnt vmcnt(14)
	v_mfma_f32_32x32x16_f16 v[34:49], v[140:143], v[108:111], v[34:49]
	v_mfma_f32_32x32x16_f16 v[2:17], v[144:147], v[108:111], v[2:17]
	s_and_b32 s5, s4, 31
	s_add_i32 s4, s4, 1
	s_mul_i32 s100, s5, 0x8000
	v_lshl_add_u64 v[70:71], v[68:69], 0, s[100:101]
	global_load_dwordx4 v[104:107], v[70:71], off
	global_load_dwordx4 v[108:111], v[70:71], off offset:1024
	s_and_b32 s5, s3, 31
	s_lshl_b32 s5, s5, 5
	s_add_i32 s3, s3, 1
	v_add_u32_e32 v129, s5, v128
	ds_read_b128 v[140:143], v129
	ds_read_b128 v[144:147], v129 offset:33280
	s_waitcnt vmcnt(15) lgkmcnt(2)
	v_mfma_f32_32x32x16_f16 v[50:65], v[148:151], v[112:115], v[50:65]
	v_mfma_f32_32x32x16_f16 v[18:33], v[152:155], v[112:115], v[18:33]
	s_waitcnt vmcnt(14)
	v_mfma_f32_32x32x16_f16 v[34:49], v[148:151], v[116:119], v[34:49]
	v_mfma_f32_32x32x16_f16 v[2:17], v[152:155], v[116:119], v[2:17]
	s_and_b32 s5, s4, 31
	s_add_i32 s4, s4, 1
	s_mul_i32 s100, s5, 0x8000
	v_lshl_add_u64 v[70:71], v[68:69], 0, s[100:101]
	global_load_dwordx4 v[112:115], v[70:71], off
	global_load_dwordx4 v[116:119], v[70:71], off offset:1024
	s_and_b32 s5, s3, 31
	s_lshl_b32 s5, s5, 5
	s_add_i32 s3, s3, 1
	v_add_u32_e32 v129, s5, v128
	ds_read_b128 v[148:151], v129
	ds_read_b128 v[152:155], v129 offset:33280
	s_waitcnt vmcnt(15) lgkmcnt(2)
	v_mfma_f32_32x32x16_f16 v[50:65], v[140:143], v[120:123], v[50:65]
	v_mfma_f32_32x32x16_f16 v[18:33], v[144:147], v[120:123], v[18:33]
	s_waitcnt vmcnt(14)
	v_mfma_f32_32x32x16_f16 v[34:49], v[140:143], v[124:127], v[34:49]
	v_mfma_f32_32x32x16_f16 v[2:17], v[144:147], v[124:127], v[2:17]
	s_and_b32 s5, s4, 31
	s_add_i32 s4, s4, 1
	s_mul_i32 s100, s5, 0x8000
	v_lshl_add_u64 v[70:71], v[68:69], 0, s[100:101]
	global_load_dwordx4 v[120:123], v[70:71], off
	global_load_dwordx4 v[124:127], v[70:71], off offset:1024
	s_and_b32 s5, s3, 31
	s_lshl_b32 s5, s5, 5
	s_add_i32 s3, s3, 1
	v_add_u32_e32 v129, s5, v128
	ds_read_b128 v[140:143], v129
	ds_read_b128 v[144:147], v129 offset:33280
	s_waitcnt vmcnt(15) lgkmcnt(2)
	v_mfma_f32_32x32x16_f16 v[50:65], v[148:151], v[132:135], v[50:65]
	v_mfma_f32_32x32x16_f16 v[18:33], v[152:155], v[132:135], v[18:33]
	s_waitcnt vmcnt(14)
	v_mfma_f32_32x32x16_f16 v[34:49], v[148:151], v[136:139], v[34:49]
	v_mfma_f32_32x32x16_f16 v[2:17], v[152:155], v[136:139], v[2:17]
	s_and_b32 s5, s4, 31
	s_add_i32 s4, s4, 1
	s_mul_i32 s100, s5, 0x8000
	v_lshl_add_u64 v[70:71], v[68:69], 0, s[100:101]
	global_load_dwordx4 v[132:135], v[70:71], off
	global_load_dwordx4 v[136:139], v[70:71], off offset:1024
	s_add_i32 s6, s6, -1
	s_cmp_lg_u32 s6, 0
	s_cbranch_scc1 .Lkob2_loop
	s_and_b32 s5, s3, 31
	s_lshl_b32 s5, s5, 5
	s_add_i32 s3, s3, 1
	v_add_u32_e32 v129, s5, v128
	ds_read_b128 v[148:151], v129
	ds_read_b128 v[152:155], v129 offset:33280
	s_waitcnt vmcnt(15) lgkmcnt(2)
	v_mfma_f32_32x32x16_f16 v[50:65], v[140:143], v[72:75], v[50:65]
	v_mfma_f32_32x32x16_f16 v[18:33], v[144:147], v[72:75], v[18:33]
	s_waitcnt vmcnt(14)
	v_mfma_f32_32x32x16_f16 v[34:49], v[140:143], v[76:79], v[34:49]
	v_mfma_f32_32x32x16_f16 v[2:17], v[144:147], v[76:79], v[2:17]
	s_and_b32 s5, s3, 31
	s_lshl_b32 s5, s5, 5
	s_add_i32 s3, s3, 1
	v_add_u32_e32 v129, s5, v128
	ds_read_b128 v[140:143], v129
	ds_read_b128 v[144:147], v129 offset:33280
	s_waitcnt vmcnt(13) lgkmcnt(2)
	v_mfma_f32_32x32x16_f16 v[50:65], v[148:151], v[80:83], v[50:65]
	v_mfma_f32_32x32x16_f16 v[18:33], v[152:155], v[80:83], v[18:33]
	s_waitcnt vmcnt(12)
	v_mfma_f32_32x32x16_f16 v[34:49], v[148:151], v[84:87], v[34:49]
	v_mfma_f32_32x32x16_f16 v[2:17], v[152:155], v[84:87], v[2:17]
	s_and_b32 s5, s3, 31
	s_lshl_b32 s5, s5, 5
	s_add_i32 s3, s3, 1
	v_add_u32_e32 v129, s5, v128
	ds_read_b128 v[148:151], v129
	ds_read_b128 v[152:155], v129 offset:33280
	s_waitcnt vmcnt(11) lgkmcnt(2)
	v_mfma_f32_32x32x16_f16 v[50:65], v[140:143], v[88:91], v[50:65]
	v_mfma_f32_32x32x16_f16 v[18:33], v[144:147], v[88:91], v[18:33]
	s_waitcnt vmcnt(10)
	v_mfma_f32_32x32x16_f16 v[34:49], v[140:143], v[92:95], v[34:49]
	v_mfma_f32_32x32x16_f16 v[2:17], v[144:147], v[92:95], v[2:17]
	s_and_b32 s5, s3, 31
	s_lshl_b32 s5, s5, 5
	s_add_i32 s3, s3, 1
	v_add_u32_e32 v129, s5, v128
	ds_read_b128 v[140:143], v129
	ds_read_b128 v[144:147], v129 offset:33280
	s_waitcnt vmcnt(9) lgkmcnt(2)
; #define MFMA32(a, b, c) __builtin_amdgcn_mfma_f32_32x32x16_f16((a), (b), (c), 0, 0, 0)
; DI int otid() { int t = threadIdx.x; asm volatile("" : "+v"(t)); return t; }
; DI bf16_t cv1(float x) { return (bf16_t)(pk2(x, 0.f) & 0xffffu); }
; DI float bf2f(bf16_t v) { return (float)__builtin_bit_cast(_Float16, v); }
; DI int crow(int i, int h) { return (i & 3) + 8 * (i >> 2) + 4 * h; }
; template <int K, class Epi>
; DI void gemm64_res(const bf16_t* A, int lda, const bf16_t* Wp, int NU, unsigned char* lds, const Epi& epi) {
;     ...
; #pragma unroll 1
;         for (int kk = 0; kk < KS; kk += PD) {
; #pragma unroll
;             for (int s = 0; s < PD; ++s) {
;                 const int ks = kk + s, ksr = (ks + rot) & (KS - 1);
;                 const bf16x8 a0 = *(const bf16x8*)(ab + ksr * 32), a1 = *(const bf16x8*)(ab + 32 * LD + ksr * 32);
; #pragma unroll
;                 for (int j = 0; j < NT; ++j) { acc[0][j] = MFMA32(a0, __builtin_bit_cast(bf16x8, bq[s][j]), acc[0][j]); acc[1][j] = MFMA32(a1, __builtin_bit_cast(bf16x8, bq[s][j]), acc[1][j]); }
;                 int nk = ks + PD; nk = nk < KS ? nk : KS - 1; nk = (nk + rot) & (KS - 1);
; #pragma unroll
;                 for (int j = 0; j < NT; ++j) bq[s][j] = bp[(size_t)nk * kstr + j * 64];
;             }
;         }
;     DI void operator()(int unit, const f32x16 (&acc)[MT][NT]) const {
;         const int lane = otid() & 63, r = lane & 31, h = lane >> 5;
; #pragma unroll
;         for (int mi = 0; mi < MT; ++mi)
; #pragma unroll
;             for (int nj = 0; nj < NT; ++nj)
; #pragma unroll
;                 for (int i = 0; i < 16; ++i) {
;                     bf16_t* rowp = priv + (mi * 32 + crow(i, h) + (mi == 2 ? d2 : 0)) * PRIVW; const int c = unit * UW + nj * 32 + r;
;                     float v = bf2f(rowp[gcol + c]) * acc[mi][nj][i];
;                     if (SECOND) v += bf2f(rowp[PC_M + c]);
;                     rowp[PC_M + c] = cv1(v);
	v_mfma_f32_32x32x16_f16 v[50:65], v[148:151], v[96:99], v[50:65]
	v_mfma_f32_32x32x16_f16 v[18:33], v[152:155], v[96:99], v[18:33]
	s_waitcnt vmcnt(8)
	v_mfma_f32_32x32x16_f16 v[34:49], v[148:151], v[100:103], v[34:49]
	v_mfma_f32_32x32x16_f16 v[2:17], v[152:155], v[100:103], v[2:17]
	s_and_b32 s5, s3, 31
	s_lshl_b32 s5, s5, 5
	s_add_i32 s3, s3, 1
	v_add_u32_e32 v129, s5, v128
	ds_read_b128 v[148:151], v129
	ds_read_b128 v[152:155], v129 offset:33280
	s_waitcnt vmcnt(7) lgkmcnt(2)
	v_mfma_f32_32x32x16_f16 v[50:65], v[140:143], v[104:107], v[50:65]
	v_mfma_f32_32x32x16_f16 v[18:33], v[144:147], v[104:107], v[18:33]
	s_waitcnt vmcnt(6)
	v_mfma_f32_32x32x16_f16 v[34:49], v[140:143], v[108:111], v[34:49]
	v_mfma_f32_32x32x16_f16 v[2:17], v[144:147], v[108:111], v[2:17]
	s_and_b32 s5, s3, 31
	s_lshl_b32 s5, s5, 5
	s_add_i32 s3, s3, 1
	v_add_u32_e32 v129, s5, v128
	ds_read_b128 v[140:143], v129
	ds_read_b128 v[144:147], v129 offset:33280
	s_waitcnt vmcnt(5) lgkmcnt(2)
	v_mfma_f32_32x32x16_f16 v[50:65], v[148:151], v[112:115], v[50:65]
	v_mfma_f32_32x32x16_f16 v[18:33], v[152:155], v[112:115], v[18:33]
	s_waitcnt vmcnt(4)
	v_mfma_f32_32x32x16_f16 v[34:49], v[148:151], v[116:119], v[34:49]
	v_mfma_f32_32x32x16_f16 v[2:17], v[152:155], v[116:119], v[2:17]
	s_and_b32 s5, s3, 31
	s_lshl_b32 s5, s5, 5
	s_add_i32 s3, s3, 1
	v_add_u32_e32 v129, s5, v128
	ds_read_b128 v[148:151], v129
	ds_read_b128 v[152:155], v129 offset:33280
	s_waitcnt vmcnt(3) lgkmcnt(2)
	v_mfma_f32_32x32x16_f16 v[50:65], v[140:143], v[120:123], v[50:65]
	v_mfma_f32_32x32x16_f16 v[18:33], v[144:147], v[120:123], v[18:33]
	s_waitcnt vmcnt(2)
	v_mfma_f32_32x32x16_f16 v[34:49], v[140:143], v[124:127], v[34:49]
	v_mfma_f32_32x32x16_f16 v[2:17], v[144:147], v[124:127], v[2:17]
	s_waitcnt vmcnt(1) lgkmcnt(0)
	v_mfma_f32_32x32x16_f16 v[50:65], v[148:151], v[132:135], v[50:65]
	v_mfma_f32_32x32x16_f16 v[18:33], v[152:155], v[132:135], v[18:33]
	s_waitcnt vmcnt(0)
	v_mfma_f32_32x32x16_f16 v[34:49], v[148:151], v[136:139], v[34:49]
	v_mfma_f32_32x32x16_f16 v[2:17], v[152:155], v[136:139], v[2:17]
	s_nop 7
	s_nop 3
	s_waitcnt vmcnt(0)
	v_and_b32_e32 v68, 31, v176
	v_lshrrev_b32_e32 v69, 3, v176
	v_and_b32_e32 v69, 4, v69
	v_mul_u32_u24_e32 v69, 0x2c00, v69
	v_lshl_add_u32 v70, v68, 1, v69
	v_lshl_add_u32 v70, s1, 7, v70
	v_add_u32_e32 v71, 0x1800, v70
	global_load_ushort v87, v71, s[34:35] offset:-2048
	global_load_ushort v120, v71, s[34:35] offset:2048
	global_load_ushort v88, v71, s[34:35] offset:-1984
	global_load_ushort v121, v71, s[34:35] offset:2112
	v_add_u32_e32 v72, 0x4400, v70
	global_load_ushort v89, v72, s[34:35] offset:-2048
	global_load_ushort v122, v72, s[34:35] offset:2048
	global_load_ushort v90, v72, s[34:35] offset:-1984
	global_load_ushort v123, v72, s[34:35] offset:2112
	v_add_u32_e32 v73, 0x7000, v70
	global_load_ushort v91, v73, s[34:35] offset:-2048
	global_load_ushort v124, v73, s[34:35] offset:2048
	global_load_ushort v92, v73, s[34:35] offset:-1984
	global_load_ushort v125, v73, s[34:35] offset:2112
	v_add_u32_e32 v74, 0x9c00, v70
	global_load_ushort v93, v74, s[34:35] offset:-2048
	global_load_ushort v126, v74, s[34:35] offset:2048
	global_load_ushort v94, v74, s[34:35] offset:-1984
	global_load_ushort v127, v74, s[34:35] offset:2112
	v_add_u32_e32 v75, 0x17800, v70
	global_load_ushort v95, v75, s[34:35] offset:-2048
	global_load_ushort v129, v75, s[34:35] offset:2048
	global_load_ushort v96, v75, s[34:35] offset:-1984
	global_load_ushort v130, v75, s[34:35] offset:2112
	v_add_u32_e32 v76, 0x1a400, v70
	global_load_ushort v97, v76, s[34:35] offset:-2048
	global_load_ushort v131, v76, s[34:35] offset:2048
	global_load_ushort v98, v76, s[34:35] offset:-1984
	global_load_ushort v132, v76, s[34:35] offset:2112
	v_add_u32_e32 v77, 0x1d000, v70
	global_load_ushort v99, v77, s[34:35] offset:-2048
	global_load_ushort v133, v77, s[34:35] offset:2048
	global_load_ushort v100, v77, s[34:35] offset:-1984
	global_load_ushort v134, v77, s[34:35] offset:2112
	v_add_u32_e32 v78, 0x1fc00, v70
	global_load_ushort v101, v78, s[34:35] offset:-2048
	global_load_ushort v135, v78, s[34:35] offset:2048
	global_load_ushort v102, v78, s[34:35] offset:-1984
	global_load_ushort v136, v78, s[34:35] offset:2112
	v_add_u32_e32 v79, 0x2d800, v70
	global_load_ushort v103, v79, s[34:35] offset:-2048
	global_load_ushort v137, v79, s[34:35] offset:2048
	global_load_ushort v104, v79, s[34:35] offset:-1984
	global_load_ushort v138, v79, s[34:35] offset:2112
	v_add_u32_e32 v80, 0x30400, v70
	global_load_ushort v105, v80, s[34:35] offset:-2048
	global_load_ushort v139, v80, s[34:35] offset:2048
	global_load_ushort v106, v80, s[34:35] offset:-1984
	global_load_ushort v140, v80, s[34:35] offset:2112
	v_add_u32_e32 v81, 0x33000, v70
	global_load_ushort v107, v81, s[34:35] offset:-2048
	global_load_ushort v141, v81, s[34:35] offset:2048
	global_load_ushort v108, v81, s[34:35] offset:-1984
	global_load_ushort v142, v81, s[34:35] offset:2112
	v_add_u32_e32 v82, 0x35c00, v70
	global_load_ushort v109, v82, s[34:35] offset:-2048
	global_load_ushort v143, v82, s[34:35] offset:2048
	global_load_ushort v110, v82, s[34:35] offset:-1984
	global_load_ushort v144, v82, s[34:35] offset:2112
	v_add_u32_e32 v83, 0x43800, v70
	global_load_ushort v111, v83, s[34:35] offset:-2048
	global_load_ushort v145, v83, s[34:35] offset:2048
	global_load_ushort v112, v83, s[34:35] offset:-1984
	global_load_ushort v146, v83, s[34:35] offset:2112
	v_add_u32_e32 v84, 0x46400, v70
	global_load_ushort v113, v84, s[34:35] offset:-2048
	global_load_ushort v147, v84, s[34:35] offset:2048
	global_load_ushort v114, v84, s[34:35] offset:-1984
	global_load_ushort v148, v84, s[34:35] offset:2112
	v_add_u32_e32 v85, 0x49000, v70
	global_load_ushort v116, v85, s[34:35] offset:-2048
	global_load_ushort v149, v85, s[34:35] offset:2048
	global_load_ushort v117, v85, s[34:35] offset:-1984
	global_load_ushort v150, v85, s[34:35] offset:2112
	v_add_u32_e32 v86, 0x4bc00, v70
	global_load_ushort v118, v86, s[34:35] offset:-2048
	global_load_ushort v151, v86, s[34:35] offset:2048
	global_load_ushort v119, v86, s[34:35] offset:-1984
	global_load_ushort v152, v86, s[34:35] offset:2112
	s_waitcnt vmcnt(0)
; DI int otid() { int t = threadIdx.x; asm volatile("" : "+v"(t)); return t; }
; DI bf16_t cv1(float x) { return (bf16_t)(pk2(x, 0.f) & 0xffffu); }
; DI float bf2f(bf16_t v) { return (float)__builtin_bit_cast(_Float16, v); }
; DI int crow(int i, int h) { return (i & 3) + 8 * (i >> 2) + 4 * h; }
;     DI void operator()(int unit, const f32x16 (&acc)[MT][NT]) const {
;         const int lane = otid() & 63, r = lane & 31, h = lane >> 5;
; #pragma unroll
;         for (int mi = 0; mi < MT; ++mi)
; #pragma unroll
;             for (int nj = 0; nj < NT; ++nj)
; #pragma unroll
;                 for (int i = 0; i < 16; ++i) {
;                     bf16_t* rowp = priv + (mi * 32 + crow(i, h) + (mi == 2 ? d2 : 0)) * PRIVW; const int c = unit * UW + nj * 32 + r;
;                     float v = bf2f(rowp[gcol + c]) * acc[mi][nj][i];
;                     if (SECOND) v += bf2f(rowp[PC_M + c]);
;                     rowp[PC_M + c] = cv1(v);
	v_fma_mixlo_f16 v87, v50, v87, v120 op_sel_hi:[0,1,1]
	global_store_short v71, v87, s[34:35] offset:2048
	v_fma_mixlo_f16 v88, v34, v88, v121 op_sel_hi:[0,1,1]
	global_store_short v71, v88, s[34:35] offset:2112
	v_fma_mixlo_f16 v89, v51, v89, v122 op_sel_hi:[0,1,1]
	global_store_short v72, v89, s[34:35] offset:2048
	v_fma_mixlo_f16 v90, v35, v90, v123 op_sel_hi:[0,1,1]
	global_store_short v72, v90, s[34:35] offset:2112
	v_fma_mixlo_f16 v91, v52, v91, v124 op_sel_hi:[0,1,1]
	global_store_short v73, v91, s[34:35] offset:2048
	v_fma_mixlo_f16 v92, v36, v92, v125 op_sel_hi:[0,1,1]
	global_store_short v73, v92, s[34:35] offset:2112
	v_fma_mixlo_f16 v93, v53, v93, v126 op_sel_hi:[0,1,1]
	global_store_short v74, v93, s[34:35] offset:2048
	v_fma_mixlo_f16 v94, v37, v94, v127 op_sel_hi:[0,1,1]
	global_store_short v74, v94, s[34:35] offset:2112
	v_fma_mixlo_f16 v95, v54, v95, v129 op_sel_hi:[0,1,1]
	global_store_short v75, v95, s[34:35] offset:2048
	v_fma_mixlo_f16 v96, v38, v96, v130 op_sel_hi:[0,1,1]
	global_store_short v75, v96, s[34:35] offset:2112
	v_fma_mixlo_f16 v97, v55, v97, v131 op_sel_hi:[0,1,1]
	global_store_short v76, v97, s[34:35] offset:2048
	v_fma_mixlo_f16 v98, v39, v98, v132 op_sel_hi:[0,1,1]
	global_store_short v76, v98, s[34:35] offset:2112
	v_fma_mixlo_f16 v99, v56, v99, v133 op_sel_hi:[0,1,1]
	global_store_short v77, v99, s[34:35] offset:2048
	v_fma_mixlo_f16 v100, v40, v100, v134 op_sel_hi:[0,1,1]
	global_store_short v77, v100, s[34:35] offset:2112
	v_fma_mixlo_f16 v101, v57, v101, v135 op_sel_hi:[0,1,1]
	global_store_short v78, v101, s[34:35] offset:2048
	v_fma_mixlo_f16 v102, v41, v102, v136 op_sel_hi:[0,1,1]
	global_store_short v78, v102, s[34:35] offset:2112
	v_fma_mixlo_f16 v103, v58, v103, v137 op_sel_hi:[0,1,1]
	global_store_short v79, v103, s[34:35] offset:2048
	v_fma_mixlo_f16 v104, v42, v104, v138 op_sel_hi:[0,1,1]
	global_store_short v79, v104, s[34:35] offset:2112
	v_fma_mixlo_f16 v105, v59, v105, v139 op_sel_hi:[0,1,1]
	global_store_short v80, v105, s[34:35] offset:2048
	v_fma_mixlo_f16 v106, v43, v106, v140 op_sel_hi:[0,1,1]
	global_store_short v80, v106, s[34:35] offset:2112
	v_fma_mixlo_f16 v107, v60, v107, v141 op_sel_hi:[0,1,1]
	global_store_short v81, v107, s[34:35] offset:2048
	v_fma_mixlo_f16 v108, v44, v108, v142 op_sel_hi:[0,1,1]
	global_store_short v81, v108, s[34:35] offset:2112
	v_fma_mixlo_f16 v109, v61, v109, v143 op_sel_hi:[0,1,1]
	global_store_short v82, v109, s[34:35] offset:2048
	v_fma_mixlo_f16 v110, v45, v110, v144 op_sel_hi:[0,1,1]
	global_store_short v82, v110, s[34:35] offset:2112
	v_fma_mixlo_f16 v111, v62, v111, v145 op_sel_hi:[0,1,1]
	global_store_short v83, v111, s[34:35] offset:2048
	v_fma_mixlo_f16 v112, v46, v112, v146 op_sel_hi:[0,1,1]
	global_store_short v83, v112, s[34:35] offset:2112
	v_fma_mixlo_f16 v113, v63, v113, v147 op_sel_hi:[0,1,1]
	global_store_short v84, v113, s[34:35] offset:2048
	v_fma_mixlo_f16 v114, v47, v114, v148 op_sel_hi:[0,1,1]
	global_store_short v84, v114, s[34:35] offset:2112
	v_fma_mixlo_f16 v116, v64, v116, v149 op_sel_hi:[0,1,1]
	global_store_short v85, v116, s[34:35] offset:2048
	v_fma_mixlo_f16 v117, v48, v117, v150 op_sel_hi:[0,1,1]
	global_store_short v85, v117, s[34:35] offset:2112
	v_fma_mixlo_f16 v118, v65, v118, v151 op_sel_hi:[0,1,1]
	global_store_short v86, v118, s[34:35] offset:2048
	v_fma_mixlo_f16 v119, v49, v119, v152 op_sel_hi:[0,1,1]
	global_store_short v86, v119, s[34:35] offset:2112
	v_add_u32_e32 v71, 0x59800, v70
	global_load_ushort v87, v71, s[34:35] offset:-2048
	global_load_ushort v120, v71, s[34:35] offset:2048
	global_load_ushort v88, v71, s[34:35] offset:-1984
	global_load_ushort v121, v71, s[34:35] offset:2112
	v_add_u32_e32 v72, 0x5c400, v70
	global_load_ushort v89, v72, s[34:35] offset:-2048
	global_load_ushort v122, v72, s[34:35] offset:2048
	global_load_ushort v90, v72, s[34:35] offset:-1984
	global_load_ushort v123, v72, s[34:35] offset:2112
	v_add_u32_e32 v73, 0x5f000, v70
	global_load_ushort v91, v73, s[34:35] offset:-2048
	global_load_ushort v124, v73, s[34:35] offset:2048
	global_load_ushort v92, v73, s[34:35] offset:-1984
	global_load_ushort v125, v73, s[34:35] offset:2112
	v_add_u32_e32 v74, 0x61c00, v70
	global_load_ushort v93, v74, s[34:35] offset:-2048
	global_load_ushort v126, v74, s[34:35] offset:2048
	global_load_ushort v94, v74, s[34:35] offset:-1984
	global_load_ushort v127, v74, s[34:35] offset:2112
	v_add_u32_e32 v75, 0x6f800, v70
	global_load_ushort v95, v75, s[34:35] offset:-2048
	global_load_ushort v129, v75, s[34:35] offset:2048
	global_load_ushort v96, v75, s[34:35] offset:-1984
	global_load_ushort v130, v75, s[34:35] offset:2112
	v_add_u32_e32 v76, 0x72400, v70
	global_load_ushort v97, v76, s[34:35] offset:-2048
	global_load_ushort v131, v76, s[34:35] offset:2048
	global_load_ushort v98, v76, s[34:35] offset:-1984
	global_load_ushort v132, v76, s[34:35] offset:2112
	v_add_u32_e32 v77, 0x75000, v70
	global_load_ushort v99, v77, s[34:35] offset:-2048
	global_load_ushort v133, v77, s[34:35] offset:2048
	global_load_ushort v100, v77, s[34:35] offset:-1984
	global_load_ushort v134, v77, s[34:35] offset:2112
	v_add_u32_e32 v78, 0x77c00, v70
	global_load_ushort v101, v78, s[34:35] offset:-2048
	global_load_ushort v135, v78, s[34:35] offset:2048
	global_load_ushort v102, v78, s[34:35] offset:-1984
	global_load_ushort v136, v78, s[34:35] offset:2112
	v_add_u32_e32 v79, 0x85800, v70
	global_load_ushort v103, v79, s[34:35] offset:-2048
; DI int otid() { int t = threadIdx.x; asm volatile("" : "+v"(t)); return t; }
; DI bf16_t cv1(float x) { return (bf16_t)(pk2(x, 0.f) & 0xffffu); }
; DI float bf2f(bf16_t v) { return (float)__builtin_bit_cast(_Float16, v); }
; DI int crow(int i, int h) { return (i & 3) + 8 * (i >> 2) + 4 * h; }
;     DI void operator()(int unit, const f32x16 (&acc)[MT][NT]) const {
;         const int lane = otid() & 63, r = lane & 31, h = lane >> 5;
; #pragma unroll
;         for (int mi = 0; mi < MT; ++mi)
; #pragma unroll
;             for (int nj = 0; nj < NT; ++nj)
; #pragma unroll
;                 for (int i = 0; i < 16; ++i) {
;                     bf16_t* rowp = priv + (mi * 32 + crow(i, h) + (mi == 2 ? d2 : 0)) * PRIVW; const int c = unit * UW + nj * 32 + r;
;                     float v = bf2f(rowp[gcol + c]) * acc[mi][nj][i];
;                     if (SECOND) v += bf2f(rowp[PC_M + c]);
;                     rowp[PC_M + c] = cv1(v);
;                     if (i == 15) __builtin_amdgcn_sched_barrier(0);
	global_load_ushort v137, v79, s[34:35] offset:2048
	global_load_ushort v104, v79, s[34:35] offset:-1984
	global_load_ushort v138, v79, s[34:35] offset:2112
	v_add_u32_e32 v80, 0x88400, v70
	global_load_ushort v105, v80, s[34:35] offset:-2048
	global_load_ushort v139, v80, s[34:35] offset:2048
	global_load_ushort v106, v80, s[34:35] offset:-1984
	global_load_ushort v140, v80, s[34:35] offset:2112
	v_add_u32_e32 v81, 0x8b000, v70
	global_load_ushort v107, v81, s[34:35] offset:-2048
	global_load_ushort v141, v81, s[34:35] offset:2048
	global_load_ushort v108, v81, s[34:35] offset:-1984
	global_load_ushort v142, v81, s[34:35] offset:2112
	v_add_u32_e32 v82, 0x8dc00, v70
	global_load_ushort v109, v82, s[34:35] offset:-2048
	global_load_ushort v143, v82, s[34:35] offset:2048
	global_load_ushort v110, v82, s[34:35] offset:-1984
	global_load_ushort v144, v82, s[34:35] offset:2112
	v_add_u32_e32 v83, 0x9b800, v70
	global_load_ushort v111, v83, s[34:35] offset:-2048
	global_load_ushort v145, v83, s[34:35] offset:2048
	global_load_ushort v112, v83, s[34:35] offset:-1984
	global_load_ushort v146, v83, s[34:35] offset:2112
	v_add_u32_e32 v84, 0x9e400, v70
	global_load_ushort v113, v84, s[34:35] offset:-2048
	global_load_ushort v147, v84, s[34:35] offset:2048
	global_load_ushort v114, v84, s[34:35] offset:-1984
	global_load_ushort v148, v84, s[34:35] offset:2112
	v_add_u32_e32 v85, 0xa1000, v70
	global_load_ushort v116, v85, s[34:35] offset:-2048
	global_load_ushort v149, v85, s[34:35] offset:2048
	global_load_ushort v117, v85, s[34:35] offset:-1984
	global_load_ushort v150, v85, s[34:35] offset:2112
	v_add_u32_e32 v86, 0xa3c00, v70
	global_load_ushort v118, v86, s[34:35] offset:-2048
	global_load_ushort v151, v86, s[34:35] offset:2048
	global_load_ushort v119, v86, s[34:35] offset:-1984
	global_load_ushort v152, v86, s[34:35] offset:2112
	s_waitcnt vmcnt(0)
	v_fma_mixlo_f16 v87, v18, v87, v120 op_sel_hi:[0,1,1]
	global_store_short v71, v87, s[34:35] offset:2048
	v_fma_mixlo_f16 v88, v2, v88, v121 op_sel_hi:[0,1,1]
	global_store_short v71, v88, s[34:35] offset:2112
	v_fma_mixlo_f16 v89, v19, v89, v122 op_sel_hi:[0,1,1]
	global_store_short v72, v89, s[34:35] offset:2048
	v_fma_mixlo_f16 v90, v3, v90, v123 op_sel_hi:[0,1,1]
	global_store_short v72, v90, s[34:35] offset:2112
	v_fma_mixlo_f16 v91, v20, v91, v124 op_sel_hi:[0,1,1]
	global_store_short v73, v91, s[34:35] offset:2048
	v_fma_mixlo_f16 v92, v4, v92, v125 op_sel_hi:[0,1,1]
	global_store_short v73, v92, s[34:35] offset:2112
	v_fma_mixlo_f16 v93, v21, v93, v126 op_sel_hi:[0,1,1]
	global_store_short v74, v93, s[34:35] offset:2048
	v_fma_mixlo_f16 v94, v5, v94, v127 op_sel_hi:[0,1,1]
	global_store_short v74, v94, s[34:35] offset:2112
	v_fma_mixlo_f16 v95, v22, v95, v129 op_sel_hi:[0,1,1]
	global_store_short v75, v95, s[34:35] offset:2048
	v_fma_mixlo_f16 v96, v6, v96, v130 op_sel_hi:[0,1,1]
	global_store_short v75, v96, s[34:35] offset:2112
	v_fma_mixlo_f16 v97, v23, v97, v131 op_sel_hi:[0,1,1]
	global_store_short v76, v97, s[34:35] offset:2048
	v_fma_mixlo_f16 v98, v7, v98, v132 op_sel_hi:[0,1,1]
	global_store_short v76, v98, s[34:35] offset:2112
	v_fma_mixlo_f16 v99, v24, v99, v133 op_sel_hi:[0,1,1]
	global_store_short v77, v99, s[34:35] offset:2048
	v_fma_mixlo_f16 v100, v8, v100, v134 op_sel_hi:[0,1,1]
	global_store_short v77, v100, s[34:35] offset:2112
	v_fma_mixlo_f16 v101, v25, v101, v135 op_sel_hi:[0,1,1]
	global_store_short v78, v101, s[34:35] offset:2048
	v_fma_mixlo_f16 v102, v9, v102, v136 op_sel_hi:[0,1,1]
	global_store_short v78, v102, s[34:35] offset:2112
	v_fma_mixlo_f16 v103, v26, v103, v137 op_sel_hi:[0,1,1]
	global_store_short v79, v103, s[34:35] offset:2048
	v_fma_mixlo_f16 v104, v10, v104, v138 op_sel_hi:[0,1,1]
	global_store_short v79, v104, s[34:35] offset:2112
	v_fma_mixlo_f16 v105, v27, v105, v139 op_sel_hi:[0,1,1]
	global_store_short v80, v105, s[34:35] offset:2048
	v_fma_mixlo_f16 v106, v11, v106, v140 op_sel_hi:[0,1,1]
	global_store_short v80, v106, s[34:35] offset:2112
	v_fma_mixlo_f16 v107, v28, v107, v141 op_sel_hi:[0,1,1]
	global_store_short v81, v107, s[34:35] offset:2048
	v_fma_mixlo_f16 v108, v12, v108, v142 op_sel_hi:[0,1,1]
	global_store_short v81, v108, s[34:35] offset:2112
	v_fma_mixlo_f16 v109, v29, v109, v143 op_sel_hi:[0,1,1]
	global_store_short v82, v109, s[34:35] offset:2048
	v_fma_mixlo_f16 v110, v13, v110, v144 op_sel_hi:[0,1,1]
	global_store_short v82, v110, s[34:35] offset:2112
	v_fma_mixlo_f16 v111, v30, v111, v145 op_sel_hi:[0,1,1]
	global_store_short v83, v111, s[34:35] offset:2048
	v_fma_mixlo_f16 v112, v14, v112, v146 op_sel_hi:[0,1,1]
	global_store_short v83, v112, s[34:35] offset:2112
	v_fma_mixlo_f16 v113, v31, v113, v147 op_sel_hi:[0,1,1]
	global_store_short v84, v113, s[34:35] offset:2048
	v_fma_mixlo_f16 v114, v15, v114, v148 op_sel_hi:[0,1,1]
	global_store_short v84, v114, s[34:35] offset:2112
	v_fma_mixlo_f16 v116, v32, v116, v149 op_sel_hi:[0,1,1]
	global_store_short v85, v116, s[34:35] offset:2048
	v_fma_mixlo_f16 v117, v16, v117, v150 op_sel_hi:[0,1,1]
	global_store_short v85, v117, s[34:35] offset:2112
	v_fma_mixlo_f16 v118, v33, v118, v151 op_sel_hi:[0,1,1]
	global_store_short v86, v118, s[34:35] offset:2048
	v_fma_mixlo_f16 v119, v17, v119, v152 op_sel_hi:[0,1,1]
	global_store_short v86, v119, s[34:35] offset:2112
	s_waitcnt vmcnt(0)
	s_add_i32 s2, s1, 8
	s_cmp_lt_i32 s1, 8
	s_mov_b32 s1, s2
	s_cbranch_scc1 .LBB0_511
	s_movk_i32 s17, 0x810
	s_movk_i32 s64, 0x3fff

; #define MFMA32(a, b, c) __builtin_amdgcn_mfma_f32_32x32x16_f16((a), (b), (c), 0, 0, 0)
; template <int K, class Epi>
; DI void gemm64_res(const bf16_t* A, int lda, const bf16_t* Wp, int NU, unsigned char* lds, const Epi& epi) {
;     ...
;     for (int unit = wave; unit < NU; unit += NWAVE) {
;         const u32x4* bp = Bw + (size_t)(unit * NT) * 64 + lane;
;         f32x16 acc[2][NT];
; #pragma unroll
;         for (int mi = 0; mi < 2; ++mi)
; #pragma unroll
;             for (int nj = 0; nj < NT; ++nj)
; #pragma unroll
;                 for (int i = 0; i < 16; ++i) acc[mi][nj][i] = 0.f;
;         u32x4 bq[PD][NT];
; #pragma unroll
;         for (int s = 0; s < PD; ++s)
; #pragma unroll
;             for (int j = 0; j < NT; ++j) bq[s][j] = bp[(size_t)((s + rot) & (KS - 1)) * kstr + j * 64];
; #pragma unroll 1
;         for (int kk = 0; kk < KS; kk += PD) {
; #pragma unroll
;             for (int s = 0; s < PD; ++s) {
;                 const int ks = kk + s, ksr = (ks + rot) & (KS - 1);
;                 const bf16x8 a0 = *(const bf16x8*)(ab + ksr * 32), a1 = *(const bf16x8*)(ab + 32 * LD + ksr * 32);
; #pragma unroll
;                 for (int j = 0; j < NT; ++j) { acc[0][j] = MFMA32(a0, __builtin_bit_cast(bf16x8, bq[s][j]), acc[0][j]); acc[1][j] = MFMA32(a1, __builtin_bit_cast(bf16x8, bq[s][j]), acc[1][j]); }
;                 int nk = ks + PD; nk = nk < KS ? nk : KS - 1; nk = (nk + rot) & (KS - 1);
; #pragma unroll
;                 for (int j = 0; j < NT; ++j) bq[s][j] = bp[(size_t)nk * kstr + j * 64];
;             }
;         }
.LBB0_517:
	s_lshl_b32 s2, s29, 1
	s_ashr_i32 s3, s2, 31
	s_lshl_b64 s[2:3], s[2:3], 10
	v_lshl_add_u64 v[68:69], v[66:67], 0, s[2:3]
	v_readlane_b32 s2, v255, 16
	v_readlane_b32 s3, v255, 17
	s_mov_b32 s6, s2
	s_mov_b32 s3, s65
	v_writelane_b32 v255, s6, 16
	v_lshl_add_u64 v[2:3], v[68:69], 0, s[2:3]
	s_mov_b64 s[2:3], 0x8400
	v_writelane_b32 v255, s7, 17
	v_lshl_add_u64 v[70:71], v[2:3], 0, s[2:3]
	v_mov_b32_e32 v2, 0
	v_readlane_b32 s2, v253, 31
	v_readlane_b32 s3, v255, 15
	s_mov_b32 s37, -4
	v_readlane_b32 s31, v254, 46
	v_readlane_b32 s52, v253, 32
	s_mov_b32 s6, s2
	v_readlane_b32 s2, v253, 30
	s_mov_b32 s8, s3
	v_mov_b32_e32 v3, v2
	v_mov_b32_e32 v4, v2
	v_mov_b32_e32 v5, v2
	v_mov_b32_e32 v6, v2
	v_mov_b32_e32 v7, v2
	v_mov_b32_e32 v8, v2
	v_mov_b32_e32 v9, v2
	v_mov_b32_e32 v10, v2
	v_mov_b32_e32 v11, v2
	v_mov_b32_e32 v12, v2
	v_mov_b32_e32 v13, v2
	v_mov_b32_e32 v14, v2
	v_mov_b32_e32 v15, v2
	v_mov_b32_e32 v16, v2
	v_mov_b32_e32 v17, v2
	v_mov_b32_e32 v18, v2
	v_mov_b32_e32 v19, v2
	v_mov_b32_e32 v20, v2
	v_mov_b32_e32 v21, v2
	v_mov_b32_e32 v22, v2
	v_mov_b32_e32 v23, v2
	v_mov_b32_e32 v24, v2
	v_mov_b32_e32 v25, v2
	v_mov_b32_e32 v26, v2
	v_mov_b32_e32 v27, v2
	v_mov_b32_e32 v28, v2
	v_mov_b32_e32 v29, v2
	v_mov_b32_e32 v30, v2
	v_mov_b32_e32 v31, v2
	v_mov_b32_e32 v32, v2
	v_mov_b32_e32 v33, v2
	v_mov_b32_e32 v34, v2
	v_mov_b32_e32 v35, v2
	v_mov_b32_e32 v36, v2
	v_mov_b32_e32 v37, v2
	v_mov_b32_e32 v38, v2
	v_mov_b32_e32 v39, v2
	v_mov_b32_e32 v40, v2
	v_mov_b32_e32 v41, v2
	v_mov_b32_e32 v42, v2
	v_mov_b32_e32 v43, v2
	v_mov_b32_e32 v44, v2
	v_mov_b32_e32 v45, v2
	v_mov_b32_e32 v46, v2
	v_mov_b32_e32 v47, v2
	v_mov_b32_e32 v48, v2
	v_mov_b32_e32 v49, v2
	v_mov_b32_e32 v50, v2
	v_mov_b32_e32 v51, v2
	v_mov_b32_e32 v52, v2
	v_mov_b32_e32 v53, v2
	v_mov_b32_e32 v54, v2
	v_mov_b32_e32 v55, v2
	v_mov_b32_e32 v56, v2
	v_mov_b32_e32 v57, v2
	v_mov_b32_e32 v58, v2
	v_mov_b32_e32 v59, v2
	v_mov_b32_e32 v60, v2
	v_mov_b32_e32 v61, v2
	v_mov_b32_e32 v62, v2
	v_mov_b32_e32 v63, v2
	v_mov_b32_e32 v64, v2
	v_mov_b32_e32 v65, v2
	v_readlane_b32 s2, v254, 48
	s_nop 3
	s_mov_b32 s101, 0
	s_mov_b32 s6, s2
	s_and_b32 s8, s6, 63
	s_add_i32 s6, s6, 1
	s_mul_i32 s100, s8, 0x8000
	v_lshl_add_u64 v[74:75], v[68:69], 0, s[100:101]
	global_load_dwordx4 v[76:79], v[74:75], off
	global_load_dwordx4 v[80:83], v[74:75], off offset:1024
	s_and_b32 s8, s6, 63
	s_add_i32 s6, s6, 1
	s_mul_i32 s100, s8, 0x8000
	v_lshl_add_u64 v[74:75], v[68:69], 0, s[100:101]
	global_load_dwordx4 v[84:87], v[74:75], off
	global_load_dwordx4 v[88:91], v[74:75], off offset:1024
	s_and_b32 s8, s6, 63
	s_add_i32 s6, s6, 1
	s_mul_i32 s100, s8, 0x8000
	v_lshl_add_u64 v[74:75], v[68:69], 0, s[100:101]
	global_load_dwordx4 v[92:95], v[74:75], off
	global_load_dwordx4 v[96:99], v[74:75], off offset:1024
	s_and_b32 s8, s6, 63
	s_add_i32 s6, s6, 1
	s_mul_i32 s100, s8, 0x8000
	v_lshl_add_u64 v[74:75], v[68:69], 0, s[100:101]
	global_load_dwordx4 v[100:103], v[74:75], off
	global_load_dwordx4 v[104:107], v[74:75], off offset:1024
	s_and_b32 s8, s6, 63
	s_add_i32 s6, s6, 1
	s_mul_i32 s100, s8, 0x8000
	v_lshl_add_u64 v[74:75], v[68:69], 0, s[100:101]
	global_load_dwordx4 v[108:111], v[74:75], off
	global_load_dwordx4 v[116:119], v[74:75], off offset:1024
	s_and_b32 s8, s6, 63
	s_add_i32 s6, s6, 1
	s_mul_i32 s100, s8, 0x8000
	v_lshl_add_u64 v[74:75], v[68:69], 0, s[100:101]
	global_load_dwordx4 v[120:123], v[74:75], off
	global_load_dwordx4 v[124:127], v[74:75], off offset:1024
	s_and_b32 s8, s6, 63
	s_add_i32 s6, s6, 1
	s_mul_i32 s100, s8, 0x8000
	v_lshl_add_u64 v[74:75], v[68:69], 0, s[100:101]
	global_load_dwordx4 v[128:131], v[74:75], off
	global_load_dwordx4 v[132:135], v[74:75], off offset:1024
	s_and_b32 s8, s6, 63
	s_add_i32 s6, s6, 1
	s_mul_i32 s100, s8, 0x8000
	v_lshl_add_u64 v[74:75], v[68:69], 0, s[100:101]
	global_load_dwordx4 v[136:139], v[74:75], off
	global_load_dwordx4 v[140:143], v[74:75], off offset:1024
	s_mov_b32 s3, s2
	s_and_b32 s8, s3, 63
	s_lshl_b32 s8, s8, 5
	s_add_i32 s3, s3, 1
	v_add_u32_e32 v73, s8, v0
	v_add_u32_e32 v112, s8, v72
	ds_read_b128 v[144:147], v73
	ds_read_b128 v[148:151], v112
	s_mov_b32 s9, 7
.Lkout2_loop:
	s_and_b32 s8, s3, 63
	s_lshl_b32 s8, s8, 5
	s_add_i32 s3, s3, 1
	v_add_u32_e32 v73, s8, v0
	v_add_u32_e32 v112, s8, v72
	ds_read_b128 v[152:155], v73
	ds_read_b128 v[156:159], v112
	s_waitcnt vmcnt(15) lgkmcnt(2)
	v_mfma_f32_32x32x16_f16 v[50:65], v[144:147], v[76:79], v[50:65]
	v_mfma_f32_32x32x16_f16 v[18:33], v[148:151], v[76:79], v[18:33]
	s_waitcnt vmcnt(14)
	v_mfma_f32_32x32x16_f16 v[34:49], v[144:147], v[80:83], v[34:49]
	v_mfma_f32_32x32x16_f16 v[2:17], v[148:151], v[80:83], v[2:17]
	s_and_b32 s8, s6, 63
	s_add_i32 s6, s6, 1
	s_mul_i32 s100, s8, 0x8000
	v_lshl_add_u64 v[74:75], v[68:69], 0, s[100:101]
	global_load_dwordx4 v[76:79], v[74:75], off
	global_load_dwordx4 v[80:83], v[74:75], off offset:1024
	s_and_b32 s8, s3, 63
	s_lshl_b32 s8, s8, 5
	s_add_i32 s3, s3, 1
	v_add_u32_e32 v73, s8, v0
	v_add_u32_e32 v112, s8, v72
	ds_read_b128 v[144:147], v73
	ds_read_b128 v[148:151], v112
	s_waitcnt vmcnt(15) lgkmcnt(2)
	v_mfma_f32_32x32x16_f16 v[50:65], v[152:155], v[84:87], v[50:65]
	v_mfma_f32_32x32x16_f16 v[18:33], v[156:159], v[84:87], v[18:33]
	s_waitcnt vmcnt(14)
	v_mfma_f32_32x32x16_f16 v[34:49], v[152:155], v[88:91], v[34:49]
	v_mfma_f32_32x32x16_f16 v[2:17], v[156:159], v[88:91], v[2:17]
	s_and_b32 s8, s6, 63
	s_add_i32 s6, s6, 1
	s_mul_i32 s100, s8, 0x8000
	v_lshl_add_u64 v[74:75], v[68:69], 0, s[100:101]
	global_load_dwordx4 v[84:87], v[74:75], off
	global_load_dwordx4 v[88:91], v[74:75], off offset:1024
	s_and_b32 s8, s3, 63
	s_lshl_b32 s8, s8, 5
	s_add_i32 s3, s3, 1
	v_add_u32_e32 v73, s8, v0
	v_add_u32_e32 v112, s8, v72
	ds_read_b128 v[152:155], v73
	ds_read_b128 v[156:159], v112
	s_waitcnt vmcnt(15) lgkmcnt(2)
; #define MFMA32(a, b, c) __builtin_amdgcn_mfma_f32_32x32x16_f16((a), (b), (c), 0, 0, 0)
; template <int K, class Epi>
; DI void gemm64_res(const bf16_t* A, int lda, const bf16_t* Wp, int NU, unsigned char* lds, const Epi& epi) {
;     ...
; #pragma unroll 1
;         for (int kk = 0; kk < KS; kk += PD) {
; #pragma unroll
;             for (int s = 0; s < PD; ++s) {
;                 const int ks = kk + s, ksr = (ks + rot) & (KS - 1);
;                 const bf16x8 a0 = *(const bf16x8*)(ab + ksr * 32), a1 = *(const bf16x8*)(ab + 32 * LD + ksr * 32);
; #pragma unroll
;                 for (int j = 0; j < NT; ++j) { acc[0][j] = MFMA32(a0, __builtin_bit_cast(bf16x8, bq[s][j]), acc[0][j]); acc[1][j] = MFMA32(a1, __builtin_bit_cast(bf16x8, bq[s][j]), acc[1][j]); }
;                 int nk = ks + PD; nk = nk < KS ? nk : KS - 1; nk = (nk + rot) & (KS - 1);
; #pragma unroll
;                 for (int j = 0; j < NT; ++j) bq[s][j] = bp[(size_t)nk * kstr + j * 64];
;             }
;         }
	v_mfma_f32_32x32x16_f16 v[50:65], v[144:147], v[92:95], v[50:65]
	v_mfma_f32_32x32x16_f16 v[18:33], v[148:151], v[92:95], v[18:33]
	s_waitcnt vmcnt(14)
	v_mfma_f32_32x32x16_f16 v[34:49], v[144:147], v[96:99], v[34:49]
	v_mfma_f32_32x32x16_f16 v[2:17], v[148:151], v[96:99], v[2:17]
	s_and_b32 s8, s6, 63
	s_add_i32 s6, s6, 1
	s_mul_i32 s100, s8, 0x8000
	v_lshl_add_u64 v[74:75], v[68:69], 0, s[100:101]
	global_load_dwordx4 v[92:95], v[74:75], off
	global_load_dwordx4 v[96:99], v[74:75], off offset:1024
	s_and_b32 s8, s3, 63
	s_lshl_b32 s8, s8, 5
	s_add_i32 s3, s3, 1
	v_add_u32_e32 v73, s8, v0
	v_add_u32_e32 v112, s8, v72
	ds_read_b128 v[144:147], v73
	ds_read_b128 v[148:151], v112
	s_waitcnt vmcnt(15) lgkmcnt(2)
	v_mfma_f32_32x32x16_f16 v[50:65], v[152:155], v[100:103], v[50:65]
	v_mfma_f32_32x32x16_f16 v[18:33], v[156:159], v[100:103], v[18:33]
	s_waitcnt vmcnt(14)
	v_mfma_f32_32x32x16_f16 v[34:49], v[152:155], v[104:107], v[34:49]
	v_mfma_f32_32x32x16_f16 v[2:17], v[156:159], v[104:107], v[2:17]
	s_and_b32 s8, s6, 63
	s_add_i32 s6, s6, 1
	s_mul_i32 s100, s8, 0x8000
	v_lshl_add_u64 v[74:75], v[68:69], 0, s[100:101]
	global_load_dwordx4 v[100:103], v[74:75], off
	global_load_dwordx4 v[104:107], v[74:75], off offset:1024
	s_and_b32 s8, s3, 63
	s_lshl_b32 s8, s8, 5
	s_add_i32 s3, s3, 1
	v_add_u32_e32 v73, s8, v0
	v_add_u32_e32 v112, s8, v72
	ds_read_b128 v[152:155], v73
	ds_read_b128 v[156:159], v112
	s_waitcnt vmcnt(15) lgkmcnt(2)
	v_mfma_f32_32x32x16_f16 v[50:65], v[144:147], v[108:111], v[50:65]
	v_mfma_f32_32x32x16_f16 v[18:33], v[148:151], v[108:111], v[18:33]
	s_waitcnt vmcnt(14)
	v_mfma_f32_32x32x16_f16 v[34:49], v[144:147], v[116:119], v[34:49]
	v_mfma_f32_32x32x16_f16 v[2:17], v[148:151], v[116:119], v[2:17]
	s_and_b32 s8, s6, 63
	s_add_i32 s6, s6, 1
	s_mul_i32 s100, s8, 0x8000
	v_lshl_add_u64 v[74:75], v[68:69], 0, s[100:101]
	global_load_dwordx4 v[108:111], v[74:75], off
	global_load_dwordx4 v[116:119], v[74:75], off offset:1024
	s_and_b32 s8, s3, 63
	s_lshl_b32 s8, s8, 5
	s_add_i32 s3, s3, 1
	v_add_u32_e32 v73, s8, v0
	v_add_u32_e32 v112, s8, v72
	ds_read_b128 v[144:147], v73
	ds_read_b128 v[148:151], v112
	s_waitcnt vmcnt(15) lgkmcnt(2)
	v_mfma_f32_32x32x16_f16 v[50:65], v[152:155], v[120:123], v[50:65]
	v_mfma_f32_32x32x16_f16 v[18:33], v[156:159], v[120:123], v[18:33]
	s_waitcnt vmcnt(14)
	v_mfma_f32_32x32x16_f16 v[34:49], v[152:155], v[124:127], v[34:49]
	v_mfma_f32_32x32x16_f16 v[2:17], v[156:159], v[124:127], v[2:17]
	s_and_b32 s8, s6, 63
	s_add_i32 s6, s6, 1
	s_mul_i32 s100, s8, 0x8000
	v_lshl_add_u64 v[74:75], v[68:69], 0, s[100:101]
	global_load_dwordx4 v[120:123], v[74:75], off
	global_load_dwordx4 v[124:127], v[74:75], off offset:1024
	s_and_b32 s8, s3, 63
	s_lshl_b32 s8, s8, 5
	s_add_i32 s3, s3, 1
	v_add_u32_e32 v73, s8, v0
	v_add_u32_e32 v112, s8, v72
	ds_read_b128 v[152:155], v73
	ds_read_b128 v[156:159], v112
	s_waitcnt vmcnt(15) lgkmcnt(2)
	v_mfma_f32_32x32x16_f16 v[50:65], v[144:147], v[128:131], v[50:65]
	v_mfma_f32_32x32x16_f16 v[18:33], v[148:151], v[128:131], v[18:33]
	s_waitcnt vmcnt(14)
	v_mfma_f32_32x32x16_f16 v[34:49], v[144:147], v[132:135], v[34:49]
	v_mfma_f32_32x32x16_f16 v[2:17], v[148:151], v[132:135], v[2:17]
	s_and_b32 s8, s6, 63
	s_add_i32 s6, s6, 1
	s_mul_i32 s100, s8, 0x8000
	v_lshl_add_u64 v[74:75], v[68:69], 0, s[100:101]
	global_load_dwordx4 v[128:131], v[74:75], off
	global_load_dwordx4 v[132:135], v[74:75], off offset:1024
	s_and_b32 s8, s3, 63
	s_lshl_b32 s8, s8, 5
	s_add_i32 s3, s3, 1
	v_add_u32_e32 v73, s8, v0
	v_add_u32_e32 v112, s8, v72
	ds_read_b128 v[144:147], v73
	ds_read_b128 v[148:151], v112
	s_waitcnt vmcnt(15) lgkmcnt(2)
	v_mfma_f32_32x32x16_f16 v[50:65], v[152:155], v[136:139], v[50:65]
	v_mfma_f32_32x32x16_f16 v[18:33], v[156:159], v[136:139], v[18:33]
	s_waitcnt vmcnt(14)
	v_mfma_f32_32x32x16_f16 v[34:49], v[152:155], v[140:143], v[34:49]
	v_mfma_f32_32x32x16_f16 v[2:17], v[156:159], v[140:143], v[2:17]
	s_and_b32 s8, s6, 63
	s_add_i32 s6, s6, 1
	s_mul_i32 s100, s8, 0x8000
	v_lshl_add_u64 v[74:75], v[68:69], 0, s[100:101]
	global_load_dwordx4 v[136:139], v[74:75], off
	global_load_dwordx4 v[140:143], v[74:75], off offset:1024
	s_add_i32 s9, s9, -1
	s_cmp_lg_u32 s9, 0
	s_cbranch_scc1 .Lkout2_loop
; #define MFMA32(a, b, c) __builtin_amdgcn_mfma_f32_32x32x16_f16((a), (b), (c), 0, 0, 0)
; DI int otid() { int t = threadIdx.x; asm volatile("" : "+v"(t)); return t; }
; DI int crow(int i, int h) { return (i & 3) + 8 * (i >> 2) + 4 * h; }
; template <int K, class Epi>
; DI void gemm64_res(const bf16_t* A, int lda, const bf16_t* Wp, int NU, unsigned char* lds, const Epi& epi) {
;     ...
; #pragma unroll 1
;         for (int kk = 0; kk < KS; kk += PD) {
; #pragma unroll
;             for (int s = 0; s < PD; ++s) {
;                 const int ks = kk + s, ksr = (ks + rot) & (KS - 1);
;                 const bf16x8 a0 = *(const bf16x8*)(ab + ksr * 32), a1 = *(const bf16x8*)(ab + 32 * LD + ksr * 32);
; #pragma unroll
;                 for (int j = 0; j < NT; ++j) { acc[0][j] = MFMA32(a0, __builtin_bit_cast(bf16x8, bq[s][j]), acc[0][j]); acc[1][j] = MFMA32(a1, __builtin_bit_cast(bf16x8, bq[s][j]), acc[1][j]); }
;                 int nk = ks + PD; nk = nk < KS ? nk : KS - 1; nk = (nk + rot) & (KS - 1);
; #pragma unroll
;                 for (int j = 0; j < NT; ++j) bq[s][j] = bp[(size_t)nk * kstr + j * 64];
;             }
;         }
;     DI void operator()(int unit, const f32x16 (&acc)[MT][NT]) const {
;         const int lane = otid() & 63, r = lane & 31, h = lane >> 5;
; #pragma unroll
;         for (int mi = 0; mi < MT; ++mi)
; #pragma unroll
;             for (int nj = 0; nj < NT; ++nj)
; #pragma unroll
;                 for (int i = 0; i < 16; ++i) { float* q = x + ((mi * 32 + crow(i, h) + (mi == 2 ? d2 : 0)) * DM + unit * UW + nj * 32 + r); *q = *q + acc[mi][nj][i]; if (i == 15) __builtin_amdgcn_sched_barrier(0); }
	s_and_b32 s8, s3, 63
	s_lshl_b32 s8, s8, 5
	s_add_i32 s3, s3, 1
	v_add_u32_e32 v73, s8, v0
	v_add_u32_e32 v112, s8, v72
	ds_read_b128 v[152:155], v73
	ds_read_b128 v[156:159], v112
	s_waitcnt vmcnt(15) lgkmcnt(2)
	v_mfma_f32_32x32x16_f16 v[50:65], v[144:147], v[76:79], v[50:65]
	v_mfma_f32_32x32x16_f16 v[18:33], v[148:151], v[76:79], v[18:33]
	s_waitcnt vmcnt(14)
	v_mfma_f32_32x32x16_f16 v[34:49], v[144:147], v[80:83], v[34:49]
	v_mfma_f32_32x32x16_f16 v[2:17], v[148:151], v[80:83], v[2:17]
	s_and_b32 s8, s3, 63
	s_lshl_b32 s8, s8, 5
	s_add_i32 s3, s3, 1
	v_add_u32_e32 v73, s8, v0
	v_add_u32_e32 v112, s8, v72
	ds_read_b128 v[144:147], v73
	ds_read_b128 v[148:151], v112
	s_waitcnt vmcnt(13) lgkmcnt(2)
	v_mfma_f32_32x32x16_f16 v[50:65], v[152:155], v[84:87], v[50:65]
	v_mfma_f32_32x32x16_f16 v[18:33], v[156:159], v[84:87], v[18:33]
	s_waitcnt vmcnt(12)
	v_mfma_f32_32x32x16_f16 v[34:49], v[152:155], v[88:91], v[34:49]
	v_mfma_f32_32x32x16_f16 v[2:17], v[156:159], v[88:91], v[2:17]
	s_and_b32 s8, s3, 63
	s_lshl_b32 s8, s8, 5
	s_add_i32 s3, s3, 1
	v_add_u32_e32 v73, s8, v0
	v_add_u32_e32 v112, s8, v72
	ds_read_b128 v[152:155], v73
	ds_read_b128 v[156:159], v112
	s_waitcnt vmcnt(11) lgkmcnt(2)
	v_mfma_f32_32x32x16_f16 v[50:65], v[144:147], v[92:95], v[50:65]
	v_mfma_f32_32x32x16_f16 v[18:33], v[148:151], v[92:95], v[18:33]
	s_waitcnt vmcnt(10)
	v_mfma_f32_32x32x16_f16 v[34:49], v[144:147], v[96:99], v[34:49]
	v_mfma_f32_32x32x16_f16 v[2:17], v[148:151], v[96:99], v[2:17]
	s_and_b32 s8, s3, 63
	s_lshl_b32 s8, s8, 5
	s_add_i32 s3, s3, 1
	v_add_u32_e32 v73, s8, v0
	v_add_u32_e32 v112, s8, v72
	ds_read_b128 v[144:147], v73
	ds_read_b128 v[148:151], v112
	s_waitcnt vmcnt(9) lgkmcnt(2)
	v_mfma_f32_32x32x16_f16 v[50:65], v[152:155], v[100:103], v[50:65]
	v_mfma_f32_32x32x16_f16 v[18:33], v[156:159], v[100:103], v[18:33]
	s_waitcnt vmcnt(8)
	v_mfma_f32_32x32x16_f16 v[34:49], v[152:155], v[104:107], v[34:49]
	v_mfma_f32_32x32x16_f16 v[2:17], v[156:159], v[104:107], v[2:17]
	s_and_b32 s8, s3, 63
	s_lshl_b32 s8, s8, 5
	s_add_i32 s3, s3, 1
	v_add_u32_e32 v73, s8, v0
	v_add_u32_e32 v112, s8, v72
	ds_read_b128 v[152:155], v73
	ds_read_b128 v[156:159], v112
	s_waitcnt vmcnt(7) lgkmcnt(2)
	v_mfma_f32_32x32x16_f16 v[50:65], v[144:147], v[108:111], v[50:65]
	v_mfma_f32_32x32x16_f16 v[18:33], v[148:151], v[108:111], v[18:33]
	s_waitcnt vmcnt(6)
	v_mfma_f32_32x32x16_f16 v[34:49], v[144:147], v[116:119], v[34:49]
	v_mfma_f32_32x32x16_f16 v[2:17], v[148:151], v[116:119], v[2:17]
	s_and_b32 s8, s3, 63
	s_lshl_b32 s8, s8, 5
	s_add_i32 s3, s3, 1
	v_add_u32_e32 v73, s8, v0
	v_add_u32_e32 v112, s8, v72
	ds_read_b128 v[144:147], v73
	ds_read_b128 v[148:151], v112
	s_waitcnt vmcnt(5) lgkmcnt(2)
	v_mfma_f32_32x32x16_f16 v[50:65], v[152:155], v[120:123], v[50:65]
	v_mfma_f32_32x32x16_f16 v[18:33], v[156:159], v[120:123], v[18:33]
	s_waitcnt vmcnt(4)
	v_mfma_f32_32x32x16_f16 v[34:49], v[152:155], v[124:127], v[34:49]
	v_mfma_f32_32x32x16_f16 v[2:17], v[156:159], v[124:127], v[2:17]
	s_and_b32 s8, s3, 63
	s_lshl_b32 s8, s8, 5
	s_add_i32 s3, s3, 1
	v_add_u32_e32 v73, s8, v0
	v_add_u32_e32 v112, s8, v72
	ds_read_b128 v[152:155], v73
	ds_read_b128 v[156:159], v112
	s_waitcnt vmcnt(3) lgkmcnt(2)
	v_mfma_f32_32x32x16_f16 v[50:65], v[144:147], v[128:131], v[50:65]
	v_mfma_f32_32x32x16_f16 v[18:33], v[148:151], v[128:131], v[18:33]
	s_waitcnt vmcnt(2)
	v_mfma_f32_32x32x16_f16 v[34:49], v[144:147], v[132:135], v[34:49]
	v_mfma_f32_32x32x16_f16 v[2:17], v[148:151], v[132:135], v[2:17]
	s_waitcnt vmcnt(1) lgkmcnt(0)
	v_mfma_f32_32x32x16_f16 v[50:65], v[152:155], v[136:139], v[50:65]
	v_mfma_f32_32x32x16_f16 v[18:33], v[156:159], v[136:139], v[18:33]
	s_waitcnt vmcnt(0)
	v_mfma_f32_32x32x16_f16 v[34:49], v[152:155], v[140:143], v[34:49]
	v_mfma_f32_32x32x16_f16 v[2:17], v[156:159], v[140:143], v[2:17]
	s_nop 7
	s_nop 3
	s_waitcnt vmcnt(0)
	v_and_b32_e32 v68, 31, v176
	v_lshlrev_b32_e32 v69, 9, v176
	v_and_b32_e32 v69, 0x4000, v69
	v_lshl_or_b32 v70, v68, 2, v69
	v_lshl_add_u32 v70, s29, 8, v70
	v_add_u32_e32 v71, 0x1000, v70
	global_load_dword v80, v71, s[0:1] offset:-4096
	global_load_dword v81, v71, s[0:1] offset:-3968
	global_load_dword v82, v71, s[0:1] offset:0
	global_load_dword v83, v71, s[0:1] offset:128
	v_add_u32_e32 v73, 0x3000, v70
	global_load_dword v84, v73, s[0:1] offset:-4096
	global_load_dword v85, v73, s[0:1] offset:-3968
	global_load_dword v86, v73, s[0:1] offset:0
	global_load_dword v87, v73, s[0:1] offset:128
	v_add_u32_e32 v74, 0x9000, v70
	global_load_dword v88, v74, s[0:1] offset:-4096
	global_load_dword v89, v74, s[0:1] offset:-3968
	global_load_dword v90, v74, s[0:1] offset:0
	global_load_dword v91, v74, s[0:1] offset:128
	v_add_u32_e32 v75, 0xb000, v70
	global_load_dword v92, v75, s[0:1] offset:-4096
	global_load_dword v93, v75, s[0:1] offset:-3968
	global_load_dword v94, v75, s[0:1] offset:0
	global_load_dword v95, v75, s[0:1] offset:128
	v_add_u32_e32 v76, 0x11000, v70
	global_load_dword v96, v76, s[0:1] offset:-4096
	global_load_dword v97, v76, s[0:1] offset:-3968
	global_load_dword v98, v76, s[0:1] offset:0
	global_load_dword v99, v76, s[0:1] offset:128
	v_add_u32_e32 v77, 0x13000, v70
	global_load_dword v100, v77, s[0:1] offset:-4096
	global_load_dword v101, v77, s[0:1] offset:-3968
	global_load_dword v102, v77, s[0:1] offset:0
	global_load_dword v103, v77, s[0:1] offset:128
	v_add_u32_e32 v78, 0x19000, v70
	global_load_dword v104, v78, s[0:1] offset:-4096
	global_load_dword v105, v78, s[0:1] offset:-3968
	global_load_dword v106, v78, s[0:1] offset:0
	global_load_dword v107, v78, s[0:1] offset:128
	v_add_u32_e32 v79, 0x1b000, v70
	global_load_dword v108, v79, s[0:1] offset:-4096
	global_load_dword v109, v79, s[0:1] offset:-3968
	global_load_dword v110, v79, s[0:1] offset:0
	global_load_dword v111, v79, s[0:1] offset:128
	s_waitcnt vmcnt(0)
; DI int otid() { int t = threadIdx.x; asm volatile("" : "+v"(t)); return t; }
; DI int crow(int i, int h) { return (i & 3) + 8 * (i >> 2) + 4 * h; }
;     DI void operator()(int unit, const f32x16 (&acc)[MT][NT]) const {
;         const int lane = otid() & 63, r = lane & 31, h = lane >> 5;
; #pragma unroll
;         for (int mi = 0; mi < MT; ++mi)
; #pragma unroll
;             for (int nj = 0; nj < NT; ++nj)
; #pragma unroll
;                 for (int i = 0; i < 16; ++i) { float* q = x + ((mi * 32 + crow(i, h) + (mi == 2 ? d2 : 0)) * DM + unit * UW + nj * 32 + r); *q = *q + acc[mi][nj][i]; if (i == 15) __builtin_amdgcn_sched_barrier(0); }
;     }
	v_add_f32_e32 v80, v50, v80
	global_store_dword v71, v80, s[0:1] offset:-4096
	v_add_f32_e32 v81, v34, v81
	global_store_dword v71, v81, s[0:1] offset:-3968
	v_add_f32_e32 v82, v51, v82
	global_store_dword v71, v82, s[0:1] offset:0
	v_add_f32_e32 v83, v35, v83
	global_store_dword v71, v83, s[0:1] offset:128
	v_add_f32_e32 v84, v52, v84
	global_store_dword v73, v84, s[0:1] offset:-4096
	v_add_f32_e32 v85, v36, v85
	global_store_dword v73, v85, s[0:1] offset:-3968
	v_add_f32_e32 v86, v53, v86
	global_store_dword v73, v86, s[0:1] offset:0
	v_add_f32_e32 v87, v37, v87
	global_store_dword v73, v87, s[0:1] offset:128
	v_add_f32_e32 v88, v54, v88
	global_store_dword v74, v88, s[0:1] offset:-4096
	v_add_f32_e32 v89, v38, v89
	global_store_dword v74, v89, s[0:1] offset:-3968
	v_add_f32_e32 v90, v55, v90
	global_store_dword v74, v90, s[0:1] offset:0
	v_add_f32_e32 v91, v39, v91
	global_store_dword v74, v91, s[0:1] offset:128
	v_add_f32_e32 v92, v56, v92
	global_store_dword v75, v92, s[0:1] offset:-4096
	v_add_f32_e32 v93, v40, v93
	global_store_dword v75, v93, s[0:1] offset:-3968
	v_add_f32_e32 v94, v57, v94
	global_store_dword v75, v94, s[0:1] offset:0
	v_add_f32_e32 v95, v41, v95
	global_store_dword v75, v95, s[0:1] offset:128
	v_add_f32_e32 v96, v58, v96
	global_store_dword v76, v96, s[0:1] offset:-4096
	v_add_f32_e32 v97, v42, v97
	global_store_dword v76, v97, s[0:1] offset:-3968
	v_add_f32_e32 v98, v59, v98
	global_store_dword v76, v98, s[0:1] offset:0
	v_add_f32_e32 v99, v43, v99
	global_store_dword v76, v99, s[0:1] offset:128
	v_add_f32_e32 v100, v60, v100
	global_store_dword v77, v100, s[0:1] offset:-4096
	v_add_f32_e32 v101, v44, v101
	global_store_dword v77, v101, s[0:1] offset:-3968
	v_add_f32_e32 v102, v61, v102
	global_store_dword v77, v102, s[0:1] offset:0
	v_add_f32_e32 v103, v45, v103
	global_store_dword v77, v103, s[0:1] offset:128
	v_add_f32_e32 v104, v62, v104
	global_store_dword v78, v104, s[0:1] offset:-4096
	v_add_f32_e32 v105, v46, v105
	global_store_dword v78, v105, s[0:1] offset:-3968
	v_add_f32_e32 v106, v63, v106
	global_store_dword v78, v106, s[0:1] offset:0
	v_add_f32_e32 v107, v47, v107
	global_store_dword v78, v107, s[0:1] offset:128
	v_add_f32_e32 v108, v64, v108
	global_store_dword v79, v108, s[0:1] offset:-4096
	v_add_f32_e32 v109, v48, v109
	global_store_dword v79, v109, s[0:1] offset:-3968
	v_add_f32_e32 v110, v65, v110
	global_store_dword v79, v110, s[0:1] offset:0
	v_add_f32_e32 v111, v49, v111
	global_store_dword v79, v111, s[0:1] offset:128
	v_add_u32_e32 v71, 0x21000, v70
	global_load_dword v80, v71, s[0:1] offset:-4096
	global_load_dword v81, v71, s[0:1] offset:-3968
	global_load_dword v82, v71, s[0:1] offset:0
	global_load_dword v83, v71, s[0:1] offset:128
	v_add_u32_e32 v73, 0x23000, v70
	global_load_dword v84, v73, s[0:1] offset:-4096
	global_load_dword v85, v73, s[0:1] offset:-3968
	global_load_dword v86, v73, s[0:1] offset:0
	global_load_dword v87, v73, s[0:1] offset:128
	v_add_u32_e32 v74, 0x29000, v70
	global_load_dword v88, v74, s[0:1] offset:-4096
	global_load_dword v89, v74, s[0:1] offset:-3968
	global_load_dword v90, v74, s[0:1] offset:0
	global_load_dword v91, v74, s[0:1] offset:128
	v_add_u32_e32 v75, 0x2b000, v70
	global_load_dword v92, v75, s[0:1] offset:-4096
	global_load_dword v93, v75, s[0:1] offset:-3968
	global_load_dword v94, v75, s[0:1] offset:0
	global_load_dword v95, v75, s[0:1] offset:128
	v_add_u32_e32 v76, 0x31000, v70
	global_load_dword v96, v76, s[0:1] offset:-4096
	global_load_dword v97, v76, s[0:1] offset:-3968
	global_load_dword v98, v76, s[0:1] offset:0
	global_load_dword v99, v76, s[0:1] offset:128
	v_add_u32_e32 v77, 0x33000, v70
	global_load_dword v100, v77, s[0:1] offset:-4096
	global_load_dword v101, v77, s[0:1] offset:-3968
	global_load_dword v102, v77, s[0:1] offset:0
	global_load_dword v103, v77, s[0:1] offset:128
	v_add_u32_e32 v78, 0x39000, v70
	global_load_dword v104, v78, s[0:1] offset:-4096
	global_load_dword v105, v78, s[0:1] offset:-3968
	global_load_dword v106, v78, s[0:1] offset:0
	global_load_dword v107, v78, s[0:1] offset:128
	v_add_u32_e32 v79, 0x3b000, v70
	global_load_dword v108, v79, s[0:1] offset:-4096
	global_load_dword v109, v79, s[0:1] offset:-3968
	global_load_dword v110, v79, s[0:1] offset:0
	global_load_dword v111, v79, s[0:1] offset:128
	s_waitcnt vmcnt(0)
	v_add_f32_e32 v80, v18, v80
	global_store_dword v71, v80, s[0:1] offset:-4096
	v_add_f32_e32 v81, v2, v81
	global_store_dword v71, v81, s[0:1] offset:-3968
	v_add_f32_e32 v82, v19, v82
	global_store_dword v71, v82, s[0:1] offset:0
	v_add_f32_e32 v83, v3, v83
	global_store_dword v71, v83, s[0:1] offset:128
	v_add_f32_e32 v84, v20, v84
	global_store_dword v73, v84, s[0:1] offset:-4096
	v_add_f32_e32 v85, v4, v85
	global_store_dword v73, v85, s[0:1] offset:-3968
	v_add_f32_e32 v86, v21, v86
	global_store_dword v73, v86, s[0:1] offset:0
	v_add_f32_e32 v87, v5, v87
	global_store_dword v73, v87, s[0:1] offset:128
	v_add_f32_e32 v88, v22, v88
	global_store_dword v74, v88, s[0:1] offset:-4096
	v_add_f32_e32 v89, v6, v89
	global_store_dword v74, v89, s[0:1] offset:-3968
	v_add_f32_e32 v90, v23, v90
	global_store_dword v74, v90, s[0:1] offset:0
	v_add_f32_e32 v91, v7, v91
	global_store_dword v74, v91, s[0:1] offset:128
	v_add_f32_e32 v92, v24, v92
	global_store_dword v75, v92, s[0:1] offset:-4096
	v_add_f32_e32 v93, v8, v93
	global_store_dword v75, v93, s[0:1] offset:-3968
	v_add_f32_e32 v94, v25, v94
	global_store_dword v75, v94, s[0:1] offset:0
	v_add_f32_e32 v95, v9, v95
	global_store_dword v75, v95, s[0:1] offset:128
	v_add_f32_e32 v96, v26, v96
	global_store_dword v76, v96, s[0:1] offset:-4096
	v_add_f32_e32 v97, v10, v97
	global_store_dword v76, v97, s[0:1] offset:-3968
	v_add_f32_e32 v98, v27, v98
	global_store_dword v76, v98, s[0:1] offset:0
	v_add_f32_e32 v99, v11, v99
	global_store_dword v76, v99, s[0:1] offset:128
	v_add_f32_e32 v100, v28, v100
	global_store_dword v77, v100, s[0:1] offset:-4096
	v_add_f32_e32 v101, v12, v101
	global_store_dword v77, v101, s[0:1] offset:-3968
	v_add_f32_e32 v102, v29, v102
	global_store_dword v77, v102, s[0:1] offset:0
	v_add_f32_e32 v103, v13, v103
	global_store_dword v77, v103, s[0:1] offset:128
	v_add_f32_e32 v104, v30, v104
	global_store_dword v78, v104, s[0:1] offset:-4096
	v_add_f32_e32 v105, v14, v105
	global_store_dword v78, v105, s[0:1] offset:-3968
	v_add_f32_e32 v106, v31, v106
	global_store_dword v78, v106, s[0:1] offset:0
	v_add_f32_e32 v107, v15, v107
	global_store_dword v78, v107, s[0:1] offset:128
	v_add_f32_e32 v108, v32, v108
	global_store_dword v79, v108, s[0:1] offset:-4096
	v_add_f32_e32 v109, v16, v109
	global_store_dword v79, v109, s[0:1] offset:-3968
	v_add_f32_e32 v110, v33, v110
	global_store_dword v79, v110, s[0:1] offset:0
	v_add_f32_e32 v111, v17, v111
	global_store_dword v79, v111, s[0:1] offset:128
	s_waitcnt vmcnt(0)
	s_add_i32 s2, s29, 8
	s_cmp_lt_i32 s29, 8
	s_mov_b32 s29, s2
	s_cbranch_scc1 .LBB0_517
	s_movk_i32 s17, 0x810
	s_movk_i32 s64, 0x3fff

; #define MFMA32(a, b, c) __builtin_amdgcn_mfma_f32_32x32x16_f16((a), (b), (c), 0, 0, 0)
; template <int K, class Epi>
; DI void gemm64_res(const bf16_t* A, int lda, const bf16_t* Wp, int NU, unsigned char* lds, const Epi& epi) {
;     ...
;     for (int unit = wave; unit < NU; unit += NWAVE) {
;         const u32x4* bp = Bw + (size_t)(unit * NT) * 64 + lane;
;         f32x16 acc[2][NT];
; #pragma unroll
;         for (int mi = 0; mi < 2; ++mi)
; #pragma unroll
;             for (int nj = 0; nj < NT; ++nj)
; #pragma unroll
;                 for (int i = 0; i < 16; ++i) acc[mi][nj][i] = 0.f;
;         u32x4 bq[PD][NT];
; #pragma unroll
;         for (int s = 0; s < PD; ++s)
; #pragma unroll
;             for (int j = 0; j < NT; ++j) bq[s][j] = bp[(size_t)((s + rot) & (KS - 1)) * kstr + j * 64];
; #pragma unroll 1
;         for (int kk = 0; kk < KS; kk += PD) {
; #pragma unroll
;             for (int s = 0; s < PD; ++s) {
;                 const int ks = kk + s, ksr = (ks + rot) & (KS - 1);
;                 const bf16x8 a0 = *(const bf16x8*)(ab + ksr * 32), a1 = *(const bf16x8*)(ab + 32 * LD + ksr * 32);
; #pragma unroll
;                 for (int j = 0; j < NT; ++j) { acc[0][j] = MFMA32(a0, __builtin_bit_cast(bf16x8, bq[s][j]), acc[0][j]); acc[1][j] = MFMA32(a1, __builtin_bit_cast(bf16x8, bq[s][j]), acc[1][j]); }
;                 int nk = ks + PD; nk = nk < KS ? nk : KS - 1; nk = (nk + rot) & (KS - 1);
; #pragma unroll
;                 for (int j = 0; j < NT; ++j) bq[s][j] = bp[(size_t)nk * kstr + j * 64];
;             }
;         }
.LBB0_523:
	s_lshl_b32 s2, s29, 1
	s_ashr_i32 s3, s2, 31
	s_lshl_b64 s[2:3], s[2:3], 10
	v_lshl_add_u64 v[68:69], v[66:67], 0, s[2:3]
	v_readlane_b32 s2, v255, 19
	v_readlane_b32 s3, v255, 20
	s_mov_b32 s6, s2
	s_mov_b32 s3, s65
	v_writelane_b32 v255, s6, 19
	v_lshl_add_u64 v[2:3], v[68:69], 0, s[2:3]
	s_mov_b64 s[2:3], 0x4400
	v_writelane_b32 v255, s7, 20
	v_lshl_add_u64 v[70:71], v[2:3], 0, s[2:3]
	v_mov_b32_e32 v2, 0
	v_readlane_b32 s2, v253, 34
	v_readlane_b32 s3, v255, 18
	s_mov_b32 s37, -4
	v_readlane_b32 s31, v254, 46
	v_readlane_b32 s52, v253, 35
	s_mov_b32 s6, s2
	v_readlane_b32 s2, v253, 33
	s_mov_b32 s8, s3
	v_mov_b32_e32 v3, v2
	v_mov_b32_e32 v4, v2
	v_mov_b32_e32 v5, v2
	v_mov_b32_e32 v6, v2
	v_mov_b32_e32 v7, v2
	v_mov_b32_e32 v8, v2
	v_mov_b32_e32 v9, v2
	v_mov_b32_e32 v10, v2
	v_mov_b32_e32 v11, v2
	v_mov_b32_e32 v12, v2
	v_mov_b32_e32 v13, v2
	v_mov_b32_e32 v14, v2
	v_mov_b32_e32 v15, v2
	v_mov_b32_e32 v16, v2
	v_mov_b32_e32 v17, v2
	v_mov_b32_e32 v18, v2
	v_mov_b32_e32 v19, v2
	v_mov_b32_e32 v20, v2
	v_mov_b32_e32 v21, v2
	v_mov_b32_e32 v22, v2
	v_mov_b32_e32 v23, v2
	v_mov_b32_e32 v24, v2
	v_mov_b32_e32 v25, v2
	v_mov_b32_e32 v26, v2
	v_mov_b32_e32 v27, v2
	v_mov_b32_e32 v28, v2
	v_mov_b32_e32 v29, v2
	v_mov_b32_e32 v30, v2
	v_mov_b32_e32 v31, v2
	v_mov_b32_e32 v32, v2
	v_mov_b32_e32 v33, v2
	v_mov_b32_e32 v34, v2
	v_mov_b32_e32 v35, v2
	v_mov_b32_e32 v36, v2
	v_mov_b32_e32 v37, v2
	v_mov_b32_e32 v38, v2
	v_mov_b32_e32 v39, v2
	v_mov_b32_e32 v40, v2
	v_mov_b32_e32 v41, v2
	v_mov_b32_e32 v42, v2
	v_mov_b32_e32 v43, v2
	v_mov_b32_e32 v44, v2
	v_mov_b32_e32 v45, v2
	v_mov_b32_e32 v46, v2
	v_mov_b32_e32 v47, v2
	v_mov_b32_e32 v48, v2
	v_mov_b32_e32 v49, v2
	v_mov_b32_e32 v50, v2
	v_mov_b32_e32 v51, v2
	v_mov_b32_e32 v52, v2
	v_mov_b32_e32 v53, v2
	v_mov_b32_e32 v54, v2
	v_mov_b32_e32 v55, v2
	v_mov_b32_e32 v56, v2
	v_mov_b32_e32 v57, v2
	v_mov_b32_e32 v58, v2
	v_mov_b32_e32 v59, v2
	v_mov_b32_e32 v60, v2
	v_mov_b32_e32 v61, v2
	v_mov_b32_e32 v62, v2
	v_mov_b32_e32 v63, v2
	v_mov_b32_e32 v64, v2
	v_mov_b32_e32 v65, v2
	v_readlane_b32 s2, v254, 48
	s_nop 3
	s_mov_b32 s101, 0
	s_mov_b32 s6, s2
	s_and_b32 s8, s6, 63
	s_add_i32 s6, s6, 1
	s_mul_i32 s100, s8, 0x4000
	v_lshl_add_u64 v[74:75], v[68:69], 0, s[100:101]
	global_load_dwordx4 v[76:79], v[74:75], off
	global_load_dwordx4 v[80:83], v[74:75], off offset:1024
	s_and_b32 s8, s6, 63
	s_add_i32 s6, s6, 1
	s_mul_i32 s100, s8, 0x4000
	v_lshl_add_u64 v[74:75], v[68:69], 0, s[100:101]
	global_load_dwordx4 v[84:87], v[74:75], off
	global_load_dwordx4 v[88:91], v[74:75], off offset:1024
	s_and_b32 s8, s6, 63
	s_add_i32 s6, s6, 1
	s_mul_i32 s100, s8, 0x4000
	v_lshl_add_u64 v[74:75], v[68:69], 0, s[100:101]
	global_load_dwordx4 v[92:95], v[74:75], off
	global_load_dwordx4 v[96:99], v[74:75], off offset:1024
	s_and_b32 s8, s6, 63
	s_add_i32 s6, s6, 1
	s_mul_i32 s100, s8, 0x4000
	v_lshl_add_u64 v[74:75], v[68:69], 0, s[100:101]
	global_load_dwordx4 v[100:103], v[74:75], off
	global_load_dwordx4 v[104:107], v[74:75], off offset:1024
	s_and_b32 s8, s6, 63
	s_add_i32 s6, s6, 1
	s_mul_i32 s100, s8, 0x4000
	v_lshl_add_u64 v[74:75], v[68:69], 0, s[100:101]
	global_load_dwordx4 v[108:111], v[74:75], off
	global_load_dwordx4 v[116:119], v[74:75], off offset:1024
	s_and_b32 s8, s6, 63
	s_add_i32 s6, s6, 1
	s_mul_i32 s100, s8, 0x4000
	v_lshl_add_u64 v[74:75], v[68:69], 0, s[100:101]
	global_load_dwordx4 v[120:123], v[74:75], off
	global_load_dwordx4 v[124:127], v[74:75], off offset:1024
	s_and_b32 s8, s6, 63
	s_add_i32 s6, s6, 1
	s_mul_i32 s100, s8, 0x4000
	v_lshl_add_u64 v[74:75], v[68:69], 0, s[100:101]
	global_load_dwordx4 v[128:131], v[74:75], off
	global_load_dwordx4 v[132:135], v[74:75], off offset:1024
	s_and_b32 s8, s6, 63
	s_add_i32 s6, s6, 1
	s_mul_i32 s100, s8, 0x4000
	v_lshl_add_u64 v[74:75], v[68:69], 0, s[100:101]
	global_load_dwordx4 v[136:139], v[74:75], off
	global_load_dwordx4 v[140:143], v[74:75], off offset:1024
	s_mov_b32 s3, s2
	s_and_b32 s8, s3, 63
	s_lshl_b32 s8, s8, 5
	s_add_i32 s3, s3, 1
	v_add_u32_e32 v73, s8, v0
	v_add_u32_e32 v112, s8, v72
	ds_read_b128 v[144:147], v73
	ds_read_b128 v[148:151], v112
	s_mov_b32 s9, 7
.Lkxq2_loop:
	s_and_b32 s8, s3, 63
	s_lshl_b32 s8, s8, 5
	s_add_i32 s3, s3, 1
	v_add_u32_e32 v73, s8, v0
	v_add_u32_e32 v112, s8, v72
	ds_read_b128 v[152:155], v73
	ds_read_b128 v[156:159], v112
	s_waitcnt vmcnt(15) lgkmcnt(2)
	v_mfma_f32_32x32x16_f16 v[50:65], v[144:147], v[76:79], v[50:65]
	v_mfma_f32_32x32x16_f16 v[18:33], v[148:151], v[76:79], v[18:33]
	s_waitcnt vmcnt(14)
	v_mfma_f32_32x32x16_f16 v[34:49], v[144:147], v[80:83], v[34:49]
	v_mfma_f32_32x32x16_f16 v[2:17], v[148:151], v[80:83], v[2:17]
	s_and_b32 s8, s6, 63
	s_add_i32 s6, s6, 1
	s_mul_i32 s100, s8, 0x4000
	v_lshl_add_u64 v[74:75], v[68:69], 0, s[100:101]
	global_load_dwordx4 v[76:79], v[74:75], off
	global_load_dwordx4 v[80:83], v[74:75], off offset:1024
	s_and_b32 s8, s3, 63
	s_lshl_b32 s8, s8, 5
	s_add_i32 s3, s3, 1
	v_add_u32_e32 v73, s8, v0
	v_add_u32_e32 v112, s8, v72
	ds_read_b128 v[144:147], v73
	ds_read_b128 v[148:151], v112
	s_waitcnt vmcnt(15) lgkmcnt(2)
	v_mfma_f32_32x32x16_f16 v[50:65], v[152:155], v[84:87], v[50:65]
	v_mfma_f32_32x32x16_f16 v[18:33], v[156:159], v[84:87], v[18:33]
	s_waitcnt vmcnt(14)
	v_mfma_f32_32x32x16_f16 v[34:49], v[152:155], v[88:91], v[34:49]
	v_mfma_f32_32x32x16_f16 v[2:17], v[156:159], v[88:91], v[2:17]
	s_and_b32 s8, s6, 63
	s_add_i32 s6, s6, 1
	s_mul_i32 s100, s8, 0x4000
	v_lshl_add_u64 v[74:75], v[68:69], 0, s[100:101]
	global_load_dwordx4 v[84:87], v[74:75], off
	global_load_dwordx4 v[88:91], v[74:75], off offset:1024
	s_and_b32 s8, s3, 63
	s_lshl_b32 s8, s8, 5
	s_add_i32 s3, s3, 1
	v_add_u32_e32 v73, s8, v0
	v_add_u32_e32 v112, s8, v72
	ds_read_b128 v[152:155], v73
	ds_read_b128 v[156:159], v112
	s_waitcnt vmcnt(15) lgkmcnt(2)
; #define MFMA32(a, b, c) __builtin_amdgcn_mfma_f32_32x32x16_f16((a), (b), (c), 0, 0, 0)
; template <int K, class Epi>
; DI void gemm64_res(const bf16_t* A, int lda, const bf16_t* Wp, int NU, unsigned char* lds, const Epi& epi) {
;     ...
; #pragma unroll 1
;         for (int kk = 0; kk < KS; kk += PD) {
; #pragma unroll
;             for (int s = 0; s < PD; ++s) {
;                 const int ks = kk + s, ksr = (ks + rot) & (KS - 1);
;                 const bf16x8 a0 = *(const bf16x8*)(ab + ksr * 32), a1 = *(const bf16x8*)(ab + 32 * LD + ksr * 32);
; #pragma unroll
;                 for (int j = 0; j < NT; ++j) { acc[0][j] = MFMA32(a0, __builtin_bit_cast(bf16x8, bq[s][j]), acc[0][j]); acc[1][j] = MFMA32(a1, __builtin_bit_cast(bf16x8, bq[s][j]), acc[1][j]); }
;                 int nk = ks + PD; nk = nk < KS ? nk : KS - 1; nk = (nk + rot) & (KS - 1);
; #pragma unroll
;                 for (int j = 0; j < NT; ++j) bq[s][j] = bp[(size_t)nk * kstr + j * 64];
;             }
;         }
	v_mfma_f32_32x32x16_f16 v[50:65], v[144:147], v[92:95], v[50:65]
	v_mfma_f32_32x32x16_f16 v[18:33], v[148:151], v[92:95], v[18:33]
	s_waitcnt vmcnt(14)
	v_mfma_f32_32x32x16_f16 v[34:49], v[144:147], v[96:99], v[34:49]
	v_mfma_f32_32x32x16_f16 v[2:17], v[148:151], v[96:99], v[2:17]
	s_and_b32 s8, s6, 63
	s_add_i32 s6, s6, 1
	s_mul_i32 s100, s8, 0x4000
	v_lshl_add_u64 v[74:75], v[68:69], 0, s[100:101]
	global_load_dwordx4 v[92:95], v[74:75], off
	global_load_dwordx4 v[96:99], v[74:75], off offset:1024
	s_and_b32 s8, s3, 63
	s_lshl_b32 s8, s8, 5
	s_add_i32 s3, s3, 1
	v_add_u32_e32 v73, s8, v0
	v_add_u32_e32 v112, s8, v72
	ds_read_b128 v[144:147], v73
	ds_read_b128 v[148:151], v112
	s_waitcnt vmcnt(15) lgkmcnt(2)
	v_mfma_f32_32x32x16_f16 v[50:65], v[152:155], v[100:103], v[50:65]
	v_mfma_f32_32x32x16_f16 v[18:33], v[156:159], v[100:103], v[18:33]
	s_waitcnt vmcnt(14)
	v_mfma_f32_32x32x16_f16 v[34:49], v[152:155], v[104:107], v[34:49]
	v_mfma_f32_32x32x16_f16 v[2:17], v[156:159], v[104:107], v[2:17]
	s_and_b32 s8, s6, 63
	s_add_i32 s6, s6, 1
	s_mul_i32 s100, s8, 0x4000
	v_lshl_add_u64 v[74:75], v[68:69], 0, s[100:101]
	global_load_dwordx4 v[100:103], v[74:75], off
	global_load_dwordx4 v[104:107], v[74:75], off offset:1024
	s_and_b32 s8, s3, 63
	s_lshl_b32 s8, s8, 5
	s_add_i32 s3, s3, 1
	v_add_u32_e32 v73, s8, v0
	v_add_u32_e32 v112, s8, v72
	ds_read_b128 v[152:155], v73
	ds_read_b128 v[156:159], v112
	s_waitcnt vmcnt(15) lgkmcnt(2)
	v_mfma_f32_32x32x16_f16 v[50:65], v[144:147], v[108:111], v[50:65]
	v_mfma_f32_32x32x16_f16 v[18:33], v[148:151], v[108:111], v[18:33]
	s_waitcnt vmcnt(14)
	v_mfma_f32_32x32x16_f16 v[34:49], v[144:147], v[116:119], v[34:49]
	v_mfma_f32_32x32x16_f16 v[2:17], v[148:151], v[116:119], v[2:17]
	s_and_b32 s8, s6, 63
	s_add_i32 s6, s6, 1
	s_mul_i32 s100, s8, 0x4000
	v_lshl_add_u64 v[74:75], v[68:69], 0, s[100:101]
	global_load_dwordx4 v[108:111], v[74:75], off
	global_load_dwordx4 v[116:119], v[74:75], off offset:1024
	s_and_b32 s8, s3, 63
	s_lshl_b32 s8, s8, 5
	s_add_i32 s3, s3, 1
	v_add_u32_e32 v73, s8, v0
	v_add_u32_e32 v112, s8, v72
	ds_read_b128 v[144:147], v73
	ds_read_b128 v[148:151], v112
	s_waitcnt vmcnt(15) lgkmcnt(2)
	v_mfma_f32_32x32x16_f16 v[50:65], v[152:155], v[120:123], v[50:65]
	v_mfma_f32_32x32x16_f16 v[18:33], v[156:159], v[120:123], v[18:33]
	s_waitcnt vmcnt(14)
	v_mfma_f32_32x32x16_f16 v[34:49], v[152:155], v[124:127], v[34:49]
	v_mfma_f32_32x32x16_f16 v[2:17], v[156:159], v[124:127], v[2:17]
	s_and_b32 s8, s6, 63
	s_add_i32 s6, s6, 1
	s_mul_i32 s100, s8, 0x4000
	v_lshl_add_u64 v[74:75], v[68:69], 0, s[100:101]
	global_load_dwordx4 v[120:123], v[74:75], off
	global_load_dwordx4 v[124:127], v[74:75], off offset:1024
	s_and_b32 s8, s3, 63
	s_lshl_b32 s8, s8, 5
	s_add_i32 s3, s3, 1
	v_add_u32_e32 v73, s8, v0
	v_add_u32_e32 v112, s8, v72
	ds_read_b128 v[152:155], v73
	ds_read_b128 v[156:159], v112
	s_waitcnt vmcnt(15) lgkmcnt(2)
	v_mfma_f32_32x32x16_f16 v[50:65], v[144:147], v[128:131], v[50:65]
	v_mfma_f32_32x32x16_f16 v[18:33], v[148:151], v[128:131], v[18:33]
	s_waitcnt vmcnt(14)
	v_mfma_f32_32x32x16_f16 v[34:49], v[144:147], v[132:135], v[34:49]
	v_mfma_f32_32x32x16_f16 v[2:17], v[148:151], v[132:135], v[2:17]
	s_and_b32 s8, s6, 63
	s_add_i32 s6, s6, 1
	s_mul_i32 s100, s8, 0x4000
	v_lshl_add_u64 v[74:75], v[68:69], 0, s[100:101]
	global_load_dwordx4 v[128:131], v[74:75], off
	global_load_dwordx4 v[132:135], v[74:75], off offset:1024
	s_and_b32 s8, s3, 63
	s_lshl_b32 s8, s8, 5
	s_add_i32 s3, s3, 1
	v_add_u32_e32 v73, s8, v0
	v_add_u32_e32 v112, s8, v72
	ds_read_b128 v[144:147], v73
	ds_read_b128 v[148:151], v112
	s_waitcnt vmcnt(15) lgkmcnt(2)
	v_mfma_f32_32x32x16_f16 v[50:65], v[152:155], v[136:139], v[50:65]
	v_mfma_f32_32x32x16_f16 v[18:33], v[156:159], v[136:139], v[18:33]
	s_waitcnt vmcnt(14)
	v_mfma_f32_32x32x16_f16 v[34:49], v[152:155], v[140:143], v[34:49]
	v_mfma_f32_32x32x16_f16 v[2:17], v[156:159], v[140:143], v[2:17]
	s_and_b32 s8, s6, 63
	s_add_i32 s6, s6, 1
	s_mul_i32 s100, s8, 0x4000
	v_lshl_add_u64 v[74:75], v[68:69], 0, s[100:101]
	global_load_dwordx4 v[136:139], v[74:75], off
	global_load_dwordx4 v[140:143], v[74:75], off offset:1024
	s_add_i32 s9, s9, -1
	s_cmp_lg_u32 s9, 0
	s_cbranch_scc1 .Lkxq2_loop
; #define MFMA32(a, b, c) __builtin_amdgcn_mfma_f32_32x32x16_f16((a), (b), (c), 0, 0, 0)
; DI int otid() { int t = threadIdx.x; asm volatile("" : "+v"(t)); return t; }
; DI bf16_t cv1(float x) { return (bf16_t)(pk2(x, 0.f) & 0xffffu); }
; DI int crow(int i, int h) { return (i & 3) + 8 * (i >> 2) + 4 * h; }
; template <int K, class Epi>
; DI void gemm64_res(const bf16_t* A, int lda, const bf16_t* Wp, int NU, unsigned char* lds, const Epi& epi) {
;     ...
; #pragma unroll 1
;         for (int kk = 0; kk < KS; kk += PD) {
; #pragma unroll
;             for (int s = 0; s < PD; ++s) {
;                 const int ks = kk + s, ksr = (ks + rot) & (KS - 1);
;                 const bf16x8 a0 = *(const bf16x8*)(ab + ksr * 32), a1 = *(const bf16x8*)(ab + 32 * LD + ksr * 32);
; #pragma unroll
;                 for (int j = 0; j < NT; ++j) { acc[0][j] = MFMA32(a0, __builtin_bit_cast(bf16x8, bq[s][j]), acc[0][j]); acc[1][j] = MFMA32(a1, __builtin_bit_cast(bf16x8, bq[s][j]), acc[1][j]); }
;                 int nk = ks + PD; nk = nk < KS ? nk : KS - 1; nk = (nk + rot) & (KS - 1);
; #pragma unroll
;                 for (int j = 0; j < NT; ++j) bq[s][j] = bp[(size_t)nk * kstr + j * 64];
;             }
;         }
; template <int MT> DI void st_bf16(bf16_t* base, int ld, int d2, int col0, const f32x16 (&acc)[MT][NT]) {
;     const int lane = otid() & 63, r = lane & 31, h = lane >> 5;
; #pragma unroll
;     for (int mi = 0; mi < MT; ++mi)
; #pragma unroll
;         for (int nj = 0; nj < NT; ++nj)
; #pragma unroll
;             for (int i = 0; i < 16; ++i) base[(mi * 32 + crow(i, h) + (mi == 2 ? d2 : 0)) * ld + col0 + nj * 32 + r] = cv1(acc[mi][nj][i]);
; }
	s_and_b32 s8, s3, 63
	s_lshl_b32 s8, s8, 5
	s_add_i32 s3, s3, 1
	v_add_u32_e32 v73, s8, v0
	v_add_u32_e32 v112, s8, v72
	ds_read_b128 v[152:155], v73
	ds_read_b128 v[156:159], v112
	s_waitcnt vmcnt(15) lgkmcnt(2)
	v_mfma_f32_32x32x16_f16 v[50:65], v[144:147], v[76:79], v[50:65]
	v_mfma_f32_32x32x16_f16 v[18:33], v[148:151], v[76:79], v[18:33]
	s_waitcnt vmcnt(14)
	v_mfma_f32_32x32x16_f16 v[34:49], v[144:147], v[80:83], v[34:49]
	v_mfma_f32_32x32x16_f16 v[2:17], v[148:151], v[80:83], v[2:17]
	s_and_b32 s8, s3, 63
	s_lshl_b32 s8, s8, 5
	s_add_i32 s3, s3, 1
	v_add_u32_e32 v73, s8, v0
	v_add_u32_e32 v112, s8, v72
	ds_read_b128 v[144:147], v73
	ds_read_b128 v[148:151], v112
	s_waitcnt vmcnt(13) lgkmcnt(2)
	v_mfma_f32_32x32x16_f16 v[50:65], v[152:155], v[84:87], v[50:65]
	v_mfma_f32_32x32x16_f16 v[18:33], v[156:159], v[84:87], v[18:33]
	s_waitcnt vmcnt(12)
	v_mfma_f32_32x32x16_f16 v[34:49], v[152:155], v[88:91], v[34:49]
	v_mfma_f32_32x32x16_f16 v[2:17], v[156:159], v[88:91], v[2:17]
	s_and_b32 s8, s3, 63
	s_lshl_b32 s8, s8, 5
	s_add_i32 s3, s3, 1
	v_add_u32_e32 v73, s8, v0
	v_add_u32_e32 v112, s8, v72
	ds_read_b128 v[152:155], v73
	ds_read_b128 v[156:159], v112
	s_waitcnt vmcnt(11) lgkmcnt(2)
	v_mfma_f32_32x32x16_f16 v[50:65], v[144:147], v[92:95], v[50:65]
	v_mfma_f32_32x32x16_f16 v[18:33], v[148:151], v[92:95], v[18:33]
	s_waitcnt vmcnt(10)
	v_mfma_f32_32x32x16_f16 v[34:49], v[144:147], v[96:99], v[34:49]
	v_mfma_f32_32x32x16_f16 v[2:17], v[148:151], v[96:99], v[2:17]
	s_and_b32 s8, s3, 63
	s_lshl_b32 s8, s8, 5
	s_add_i32 s3, s3, 1
	v_add_u32_e32 v73, s8, v0
	v_add_u32_e32 v112, s8, v72
	ds_read_b128 v[144:147], v73
	ds_read_b128 v[148:151], v112
	s_waitcnt vmcnt(9) lgkmcnt(2)
	v_mfma_f32_32x32x16_f16 v[50:65], v[152:155], v[100:103], v[50:65]
	v_mfma_f32_32x32x16_f16 v[18:33], v[156:159], v[100:103], v[18:33]
	s_waitcnt vmcnt(8)
	v_mfma_f32_32x32x16_f16 v[34:49], v[152:155], v[104:107], v[34:49]
	v_mfma_f32_32x32x16_f16 v[2:17], v[156:159], v[104:107], v[2:17]
	s_and_b32 s8, s3, 63
	s_lshl_b32 s8, s8, 5
	s_add_i32 s3, s3, 1
	v_add_u32_e32 v73, s8, v0
	v_add_u32_e32 v112, s8, v72
	ds_read_b128 v[152:155], v73
	ds_read_b128 v[156:159], v112
	s_waitcnt vmcnt(7) lgkmcnt(2)
	v_mfma_f32_32x32x16_f16 v[50:65], v[144:147], v[108:111], v[50:65]
	v_mfma_f32_32x32x16_f16 v[18:33], v[148:151], v[108:111], v[18:33]
	s_waitcnt vmcnt(6)
	v_mfma_f32_32x32x16_f16 v[34:49], v[144:147], v[116:119], v[34:49]
	v_mfma_f32_32x32x16_f16 v[2:17], v[148:151], v[116:119], v[2:17]
	s_and_b32 s8, s3, 63
	s_lshl_b32 s8, s8, 5
	s_add_i32 s3, s3, 1
	v_add_u32_e32 v73, s8, v0
	v_add_u32_e32 v112, s8, v72
	ds_read_b128 v[144:147], v73
	ds_read_b128 v[148:151], v112
	s_waitcnt vmcnt(5) lgkmcnt(2)
	v_mfma_f32_32x32x16_f16 v[50:65], v[152:155], v[120:123], v[50:65]
	v_mfma_f32_32x32x16_f16 v[18:33], v[156:159], v[120:123], v[18:33]
	s_waitcnt vmcnt(4)
	v_mfma_f32_32x32x16_f16 v[34:49], v[152:155], v[124:127], v[34:49]
	v_mfma_f32_32x32x16_f16 v[2:17], v[156:159], v[124:127], v[2:17]
	s_and_b32 s8, s3, 63
	s_lshl_b32 s8, s8, 5
	s_add_i32 s3, s3, 1
	v_add_u32_e32 v73, s8, v0
	v_add_u32_e32 v112, s8, v72
	ds_read_b128 v[152:155], v73
	ds_read_b128 v[156:159], v112
	s_waitcnt vmcnt(3) lgkmcnt(2)
	v_mfma_f32_32x32x16_f16 v[50:65], v[144:147], v[128:131], v[50:65]
	v_mfma_f32_32x32x16_f16 v[18:33], v[148:151], v[128:131], v[18:33]
	s_waitcnt vmcnt(2)
	v_mfma_f32_32x32x16_f16 v[34:49], v[144:147], v[132:135], v[34:49]
	v_mfma_f32_32x32x16_f16 v[2:17], v[148:151], v[132:135], v[2:17]
	s_waitcnt vmcnt(1) lgkmcnt(0)
	v_mfma_f32_32x32x16_f16 v[50:65], v[152:155], v[136:139], v[50:65]
	v_mfma_f32_32x32x16_f16 v[18:33], v[156:159], v[136:139], v[18:33]
	s_waitcnt vmcnt(0)
	v_mfma_f32_32x32x16_f16 v[34:49], v[152:155], v[140:143], v[34:49]
	v_mfma_f32_32x32x16_f16 v[2:17], v[156:159], v[140:143], v[2:17]
	s_nop 7
	s_nop 3
	s_lshl_b32 s2, s29, 6
	v_mov_b32_e32 v68, v176
	s_addk_i32 s2, 0x1400
	s_nop 2
	v_cvt_f16_f32_e32 v50, v50
	v_lshrrev_b32_e32 v69, 3, v68
	v_and_b32_e32 v70, 4, v69
	v_and_or_b32 v71, v68, 31, s2
	v_mad_u32_u24 v68, v70, s44, v71
	v_ashrrev_i32_e32 v69, 31, v68
	v_lshl_add_u64 v[68:69], v[68:69], 1, s[34:35]
	global_store_short v[68:69], v50, off
	v_cvt_f16_f32_e32 v68, v51
	v_mad_u32_u24 v69, v70, s44, s44
	v_add_u32_e32 v50, v69, v71
	v_ashrrev_i32_e32 v51, 31, v50
	v_lshl_add_u64 v[50:51], v[50:51], 1, s[34:35]
	global_store_short v[50:51], v68, off
	v_cvt_f16_f32_e32 v52, v52
	v_mad_u32_u24 v68, v70, s44, v191
	v_add_u32_e32 v50, v68, v71
	v_ashrrev_i32_e32 v51, 31, v50
	v_lshl_add_u64 v[50:51], v[50:51], 1, s[34:35]
	global_store_short v[50:51], v52, off
	v_cvt_f16_f32_e32 v52, v53
	v_mad_u32_u24 v53, v70, s44, v192
	v_add_u32_e32 v50, v53, v71
	v_ashrrev_i32_e32 v51, 31, v50
	v_lshl_add_u64 v[50:51], v[50:51], 1, s[34:35]
	global_store_short v[50:51], v52, off
	v_cvt_f16_f32_e32 v52, v54
	v_mad_u32_u24 v54, v70, s44, v193
	v_add_u32_e32 v50, v54, v71
	v_ashrrev_i32_e32 v51, 31, v50
	v_lshl_add_u64 v[50:51], v[50:51], 1, s[34:35]
	global_store_short v[50:51], v52, off
	v_cvt_f16_f32_e32 v52, v55
	v_mad_u32_u24 v55, v70, s44, v194
	v_add_u32_e32 v50, v55, v71
	v_ashrrev_i32_e32 v51, 31, v50
	v_lshl_add_u64 v[50:51], v[50:51], 1, s[34:35]
	global_store_short v[50:51], v52, off
	v_cvt_f16_f32_e32 v52, v56
	v_mad_u32_u24 v56, v70, s44, v195
	v_add_u32_e32 v50, v56, v71
	v_ashrrev_i32_e32 v51, 31, v50
	v_lshl_add_u64 v[50:51], v[50:51], 1, s[34:35]
	global_store_short v[50:51], v52, off
	v_cvt_f16_f32_e32 v52, v57
	v_mad_u32_u24 v57, v70, s44, v196
	v_add_u32_e32 v50, v57, v71
	v_ashrrev_i32_e32 v51, 31, v50
	v_lshl_add_u64 v[50:51], v[50:51], 1, s[34:35]
; DI int otid() { int t = threadIdx.x; asm volatile("" : "+v"(t)); return t; }
; DI bf16_t cv1(float x) { return (bf16_t)(pk2(x, 0.f) & 0xffffu); }
; DI int crow(int i, int h) { return (i & 3) + 8 * (i >> 2) + 4 * h; }
; template <int MT> DI void st_bf16(bf16_t* base, int ld, int d2, int col0, const f32x16 (&acc)[MT][NT]) {
;     const int lane = otid() & 63, r = lane & 31, h = lane >> 5;
; #pragma unroll
;     for (int mi = 0; mi < MT; ++mi)
; #pragma unroll
;         for (int nj = 0; nj < NT; ++nj)
; #pragma unroll
;             for (int i = 0; i < 16; ++i) base[(mi * 32 + crow(i, h) + (mi == 2 ? d2 : 0)) * ld + col0 + nj * 32 + r] = cv1(acc[mi][nj][i]);
; }
	global_store_short v[50:51], v52, off
	v_cvt_f16_f32_e32 v52, v58
	v_mad_u32_u24 v58, v70, s44, v197
	v_add_u32_e32 v50, v58, v71
	v_ashrrev_i32_e32 v51, 31, v50
	v_lshl_add_u64 v[50:51], v[50:51], 1, s[34:35]
	global_store_short v[50:51], v52, off
	v_cvt_f16_f32_e32 v52, v59
	v_mad_u32_u24 v59, v70, s44, v198
	v_add_u32_e32 v50, v59, v71
	v_ashrrev_i32_e32 v51, 31, v50
	v_lshl_add_u64 v[50:51], v[50:51], 1, s[34:35]
	global_store_short v[50:51], v52, off
	v_cvt_f16_f32_e32 v52, v60
	v_mad_u32_u24 v60, v70, s44, v199
	v_add_u32_e32 v50, v60, v71
	v_ashrrev_i32_e32 v51, 31, v50
	v_lshl_add_u64 v[50:51], v[50:51], 1, s[34:35]
	global_store_short v[50:51], v52, off
	v_cvt_f16_f32_e32 v52, v61
	v_mad_u32_u24 v61, v70, s44, v200
	v_add_u32_e32 v50, v61, v71
	v_ashrrev_i32_e32 v51, 31, v50
	v_lshl_add_u64 v[50:51], v[50:51], 1, s[34:35]
	global_store_short v[50:51], v52, off
	v_cvt_f16_f32_e32 v52, v62
	v_mad_u32_u24 v62, v70, s44, v201
	v_add_u32_e32 v50, v62, v71
	v_ashrrev_i32_e32 v51, 31, v50
	v_lshl_add_u64 v[50:51], v[50:51], 1, s[34:35]
	global_store_short v[50:51], v52, off
	v_cvt_f16_f32_e32 v52, v63
	v_mad_u32_u24 v63, v70, s44, v202
	v_add_u32_e32 v50, v63, v71
	v_ashrrev_i32_e32 v51, 31, v50
	v_lshl_add_u64 v[50:51], v[50:51], 1, s[34:35]
	global_store_short v[50:51], v52, off
	v_cvt_f16_f32_e32 v52, v64
	v_mad_u32_u24 v64, v70, s44, v203
	v_add_u32_e32 v50, v64, v71
	v_ashrrev_i32_e32 v51, 31, v50
	v_lshl_add_u64 v[50:51], v[50:51], 1, s[34:35]
	global_store_short v[50:51], v52, off
	v_cvt_f16_f32_e32 v52, v65
	v_mad_u32_u24 v65, v70, s44, v204
	v_add_u32_e32 v50, v65, v71
	v_ashrrev_i32_e32 v51, 31, v50
	v_lshl_add_u64 v[50:51], v[50:51], 1, s[34:35]
	global_store_short v[50:51], v52, off
	v_or_b32_e32 v52, 32, v71
	v_cvt_f16_f32_e32 v34, v34
	v_mad_u32_u24 v50, v70, s44, v52
	v_ashrrev_i32_e32 v51, 31, v50
	v_lshl_add_u64 v[50:51], v[50:51], 1, s[34:35]
	global_store_short v[50:51], v34, off
	v_cvt_f16_f32_e32 v50, v35
	v_add_u32_e32 v34, v69, v52
	v_ashrrev_i32_e32 v35, 31, v34
	v_lshl_add_u64 v[34:35], v[34:35], 1, s[34:35]
	v_cvt_f16_f32_e32 v36, v36
	global_store_short v[34:35], v50, off
	v_add_u32_e32 v34, v68, v52
	v_ashrrev_i32_e32 v35, 31, v34
	v_lshl_add_u64 v[34:35], v[34:35], 1, s[34:35]
	global_store_short v[34:35], v36, off
	v_cvt_f16_f32_e32 v36, v37
	v_add_u32_e32 v34, v53, v52
	v_ashrrev_i32_e32 v35, 31, v34
	v_lshl_add_u64 v[34:35], v[34:35], 1, s[34:35]
	global_store_short v[34:35], v36, off
	v_cvt_f16_f32_e32 v36, v38
	v_add_u32_e32 v34, v54, v52
	v_ashrrev_i32_e32 v35, 31, v34
	v_lshl_add_u64 v[34:35], v[34:35], 1, s[34:35]
	global_store_short v[34:35], v36, off
	v_cvt_f16_f32_e32 v36, v39
	v_add_u32_e32 v34, v55, v52
	v_ashrrev_i32_e32 v35, 31, v34
	v_lshl_add_u64 v[34:35], v[34:35], 1, s[34:35]
	global_store_short v[34:35], v36, off
	v_cvt_f16_f32_e32 v36, v40
	v_add_u32_e32 v34, v56, v52
	v_ashrrev_i32_e32 v35, 31, v34
	v_lshl_add_u64 v[34:35], v[34:35], 1, s[34:35]
	global_store_short v[34:35], v36, off
	v_cvt_f16_f32_e32 v36, v41
	v_add_u32_e32 v34, v57, v52
	v_ashrrev_i32_e32 v35, 31, v34
	v_lshl_add_u64 v[34:35], v[34:35], 1, s[34:35]
	global_store_short v[34:35], v36, off
	v_cvt_f16_f32_e32 v36, v42
	v_add_u32_e32 v34, v58, v52
	v_ashrrev_i32_e32 v35, 31, v34
	v_lshl_add_u64 v[34:35], v[34:35], 1, s[34:35]
	global_store_short v[34:35], v36, off
	v_cvt_f16_f32_e32 v36, v43
	v_add_u32_e32 v34, v59, v52
	v_ashrrev_i32_e32 v35, 31, v34
	v_lshl_add_u64 v[34:35], v[34:35], 1, s[34:35]
	global_store_short v[34:35], v36, off
	v_cvt_f16_f32_e32 v36, v44
	v_add_u32_e32 v34, v60, v52
	v_ashrrev_i32_e32 v35, 31, v34
	v_lshl_add_u64 v[34:35], v[34:35], 1, s[34:35]
	global_store_short v[34:35], v36, off
	v_cvt_f16_f32_e32 v36, v45
	v_add_u32_e32 v34, v61, v52
	v_ashrrev_i32_e32 v35, 31, v34
	v_lshl_add_u64 v[34:35], v[34:35], 1, s[34:35]
	global_store_short v[34:35], v36, off
	v_cvt_f16_f32_e32 v36, v46
	v_add_u32_e32 v34, v62, v52
	v_ashrrev_i32_e32 v35, 31, v34
	v_lshl_add_u64 v[34:35], v[34:35], 1, s[34:35]
	global_store_short v[34:35], v36, off
	v_cvt_f16_f32_e32 v36, v47
	v_add_u32_e32 v34, v63, v52
	v_ashrrev_i32_e32 v35, 31, v34
	v_lshl_add_u64 v[34:35], v[34:35], 1, s[34:35]
	global_store_short v[34:35], v36, off
	v_cvt_f16_f32_e32 v36, v48
	v_add_u32_e32 v34, v64, v52
	v_ashrrev_i32_e32 v35, 31, v34
	v_lshl_add_u64 v[34:35], v[34:35], 1, s[34:35]
	global_store_short v[34:35], v36, off
	v_cvt_f16_f32_e32 v36, v49
	v_add_u32_e32 v34, v65, v52
	v_ashrrev_i32_e32 v35, 31, v34
	v_lshl_add_u64 v[34:35], v[34:35], 1, s[34:35]
	global_store_short v[34:35], v36, off
	v_cvt_f16_f32_e32 v18, v18
	v_mad_u32_u24 v36, v70, s44, v205
	v_add_u32_e32 v34, v36, v71
	v_ashrrev_i32_e32 v35, 31, v34
	v_lshl_add_u64 v[34:35], v[34:35], 1, s[34:35]
	global_store_short v[34:35], v18, off
	v_cvt_f16_f32_e32 v34, v19
	v_mad_u32_u24 v35, v70, s44, v206
	v_add_u32_e32 v18, v35, v71
	v_ashrrev_i32_e32 v19, 31, v18
	v_lshl_add_u64 v[18:19], v[18:19], 1, s[34:35]
	global_store_short v[18:19], v34, off
	v_cvt_f16_f32_e32 v20, v20
	v_mad_u32_u24 v34, v70, s44, v207
	v_add_u32_e32 v18, v34, v71
	v_ashrrev_i32_e32 v19, 31, v18
	v_mul_u32_u24_e32 v73, 0x1600, v70
	v_lshl_add_u64 v[18:19], v[18:19], 1, s[34:35]
	global_store_short v[18:19], v20, off
	v_cvt_f16_f32_e32 v20, v21
	v_or_b32_e32 v21, 0x30200, v73
	v_add_u32_e32 v18, v21, v71
	v_ashrrev_i32_e32 v19, 31, v18
; DI int otid() { int t = threadIdx.x; asm volatile("" : "+v"(t)); return t; }
; DI bf16_t cv1(float x) { return (bf16_t)(pk2(x, 0.f) & 0xffffu); }
; DI int crow(int i, int h) { return (i & 3) + 8 * (i >> 2) + 4 * h; }
; template <int MT> DI void st_bf16(bf16_t* base, int ld, int d2, int col0, const f32x16 (&acc)[MT][NT]) {
;     const int lane = otid() & 63, r = lane & 31, h = lane >> 5;
; #pragma unroll
;     for (int mi = 0; mi < MT; ++mi)
; #pragma unroll
;         for (int nj = 0; nj < NT; ++nj)
; #pragma unroll
;             for (int i = 0; i < 16; ++i) base[(mi * 32 + crow(i, h) + (mi == 2 ? d2 : 0)) * ld + col0 + nj * 32 + r] = cv1(acc[mi][nj][i]);
; }
	v_lshl_add_u64 v[18:19], v[18:19], 1, s[34:35]
	global_store_short v[18:19], v20, off
	v_cvt_f16_f32_e32 v20, v22
	v_mad_u32_u24 v22, v70, s44, v208
	v_add_u32_e32 v18, v22, v71
	v_ashrrev_i32_e32 v19, 31, v18
	v_lshl_add_u64 v[18:19], v[18:19], 1, s[34:35]
	global_store_short v[18:19], v20, off
	v_cvt_f16_f32_e32 v20, v23
	v_or_b32_e32 v23, 0x38600, v73
	v_add_u32_e32 v18, v23, v71
	v_ashrrev_i32_e32 v19, 31, v18
	v_lshl_add_u64 v[18:19], v[18:19], 1, s[34:35]
	global_store_short v[18:19], v20, off
	v_cvt_f16_f32_e32 v20, v24
	v_mad_u32_u24 v24, v70, s44, v209
	v_add_u32_e32 v18, v24, v71
	v_ashrrev_i32_e32 v19, 31, v18
	v_lshl_add_u64 v[18:19], v[18:19], 1, s[34:35]
	global_store_short v[18:19], v20, off
	v_cvt_f16_f32_e32 v20, v25
	v_mad_u32_u24 v25, v70, s44, v210
	v_add_u32_e32 v18, v25, v71
	v_ashrrev_i32_e32 v19, 31, v18
	v_lshl_add_u64 v[18:19], v[18:19], 1, s[34:35]
	global_store_short v[18:19], v20, off
	v_cvt_f16_f32_e32 v20, v26
	v_mad_u32_u24 v26, v70, s44, v211
	v_add_u32_e32 v18, v26, v71
	v_ashrrev_i32_e32 v19, 31, v18
	v_lshl_add_u64 v[18:19], v[18:19], 1, s[34:35]
	global_store_short v[18:19], v20, off
	v_cvt_f16_f32_e32 v20, v27
	v_mad_u32_u24 v27, v70, s44, v212
	v_add_u32_e32 v18, v27, v71
	v_ashrrev_i32_e32 v19, 31, v18
	v_lshl_add_u64 v[18:19], v[18:19], 1, s[34:35]
	global_store_short v[18:19], v20, off
	v_cvt_f16_f32_e32 v20, v28
	v_mad_u32_u24 v28, v70, s44, v213
	v_add_u32_e32 v18, v28, v71
	v_ashrrev_i32_e32 v19, 31, v18
	v_lshl_add_u64 v[18:19], v[18:19], 1, s[34:35]
	global_store_short v[18:19], v20, off
	v_cvt_f16_f32_e32 v20, v29
	v_mad_u32_u24 v29, v70, s44, v214
	v_add_u32_e32 v18, v29, v71
	v_ashrrev_i32_e32 v19, 31, v18
	v_lshl_add_u64 v[18:19], v[18:19], 1, s[34:35]
	global_store_short v[18:19], v20, off
	v_cvt_f16_f32_e32 v20, v30
	v_mad_u32_u24 v30, v70, s44, v215
	v_add_u32_e32 v18, v30, v71
	v_ashrrev_i32_e32 v19, 31, v18
	v_lshl_add_u64 v[18:19], v[18:19], 1, s[34:35]
	global_store_short v[18:19], v20, off
	v_cvt_f16_f32_e32 v20, v31
	v_mad_u32_u24 v31, v70, s44, v216
	v_add_u32_e32 v18, v31, v71
	v_ashrrev_i32_e32 v19, 31, v18
	v_lshl_add_u64 v[18:19], v[18:19], 1, s[34:35]
	global_store_short v[18:19], v20, off
	v_cvt_f16_f32_e32 v20, v32
	v_mad_u32_u24 v32, v70, s44, v217
	v_add_u32_e32 v18, v32, v71
	v_ashrrev_i32_e32 v19, 31, v18
	v_lshl_add_u64 v[18:19], v[18:19], 1, s[34:35]
	global_store_short v[18:19], v20, off
	v_cvt_f16_f32_e32 v20, v33
	v_mad_u32_u24 v33, v70, s44, v218
	v_add_u32_e32 v18, v33, v71
	v_ashrrev_i32_e32 v19, 31, v18
	v_lshl_add_u64 v[18:19], v[18:19], 1, s[34:35]
	v_cvt_f16_f32_e32 v2, v2
	global_store_short v[18:19], v20, off
	v_add_u32_e32 v18, v36, v52
	v_ashrrev_i32_e32 v19, 31, v18
	v_lshl_add_u64 v[18:19], v[18:19], 1, s[34:35]
	global_store_short v[18:19], v2, off
	v_cvt_f16_f32_e32 v18, v3
	v_add_u32_e32 v2, v35, v52
	v_ashrrev_i32_e32 v3, 31, v2
	v_lshl_add_u64 v[2:3], v[2:3], 1, s[34:35]
	v_cvt_f16_f32_e32 v4, v4
	global_store_short v[2:3], v18, off
	v_add_u32_e32 v2, v34, v52
	v_ashrrev_i32_e32 v3, 31, v2
	v_lshl_add_u64 v[2:3], v[2:3], 1, s[34:35]
	global_store_short v[2:3], v4, off
	v_cvt_f16_f32_e32 v4, v5
	v_add_u32_e32 v2, v21, v52
	v_ashrrev_i32_e32 v3, 31, v2
	v_lshl_add_u64 v[2:3], v[2:3], 1, s[34:35]
	global_store_short v[2:3], v4, off
	v_cvt_f16_f32_e32 v4, v6
	v_add_u32_e32 v2, v22, v52
	v_ashrrev_i32_e32 v3, 31, v2
	v_lshl_add_u64 v[2:3], v[2:3], 1, s[34:35]
	global_store_short v[2:3], v4, off
	v_cvt_f16_f32_e32 v4, v7
	v_add_u32_e32 v2, v23, v52
	v_ashrrev_i32_e32 v3, 31, v2
	v_lshl_add_u64 v[2:3], v[2:3], 1, s[34:35]
	global_store_short v[2:3], v4, off
	v_cvt_f16_f32_e32 v4, v8
	v_add_u32_e32 v2, v24, v52
	v_ashrrev_i32_e32 v3, 31, v2
	v_lshl_add_u64 v[2:3], v[2:3], 1, s[34:35]
	global_store_short v[2:3], v4, off
	v_cvt_f16_f32_e32 v4, v9
	v_add_u32_e32 v2, v25, v52
	v_ashrrev_i32_e32 v3, 31, v2
	v_lshl_add_u64 v[2:3], v[2:3], 1, s[34:35]
	global_store_short v[2:3], v4, off
	v_cvt_f16_f32_e32 v4, v10
	v_add_u32_e32 v2, v26, v52
	v_ashrrev_i32_e32 v3, 31, v2
	v_lshl_add_u64 v[2:3], v[2:3], 1, s[34:35]
	global_store_short v[2:3], v4, off
	v_cvt_f16_f32_e32 v4, v11
	v_add_u32_e32 v2, v27, v52
	v_ashrrev_i32_e32 v3, 31, v2
	v_lshl_add_u64 v[2:3], v[2:3], 1, s[34:35]
	global_store_short v[2:3], v4, off
	v_cvt_f16_f32_e32 v4, v12
	v_add_u32_e32 v2, v28, v52
	v_ashrrev_i32_e32 v3, 31, v2
	v_lshl_add_u64 v[2:3], v[2:3], 1, s[34:35]
	global_store_short v[2:3], v4, off
	v_cvt_f16_f32_e32 v4, v13
	v_add_u32_e32 v2, v29, v52
	v_ashrrev_i32_e32 v3, 31, v2
	v_lshl_add_u64 v[2:3], v[2:3], 1, s[34:35]
	global_store_short v[2:3], v4, off
	v_cvt_f16_f32_e32 v4, v14
	v_add_u32_e32 v2, v30, v52
	v_ashrrev_i32_e32 v3, 31, v2
	v_lshl_add_u64 v[2:3], v[2:3], 1, s[34:35]
	global_store_short v[2:3], v4, off
	v_cvt_f16_f32_e32 v4, v15
	v_add_u32_e32 v2, v31, v52
	v_ashrrev_i32_e32 v3, 31, v2
	v_lshl_add_u64 v[2:3], v[2:3], 1, s[34:35]
	global_store_short v[2:3], v4, off
	v_cvt_f16_f32_e32 v4, v16
	v_add_u32_e32 v2, v32, v52
	v_ashrrev_i32_e32 v3, 31, v2
	v_lshl_add_u64 v[2:3], v[2:3], 1, s[34:35]
	global_store_short v[2:3], v4, off
	v_cvt_f16_f32_e32 v4, v17
	v_add_u32_e32 v2, v33, v52
	v_ashrrev_i32_e32 v3, 31, v2
	s_add_i32 s2, s29, 8
	v_lshl_add_u64 v[2:3], v[2:3], 1, s[34:35]
	s_cmp_lt_i32 s29, 0
	s_mov_b32 s29, s2
	global_store_short v[2:3], v4, off
	s_cbranch_scc1 .LBB0_523
	s_movk_i32 s17, 0x810
	s_movk_i32 s64, 0x3fff

; #define MFMA32(a, b, c) __builtin_amdgcn_mfma_f32_32x32x16_f16((a), (b), (c), 0, 0, 0)
; template <int K, class Epi>
; DI void gemm64_res(const bf16_t* A, int lda, const bf16_t* Wp, int NU, unsigned char* lds, const Epi& epi) {
;     ...
;     for (int unit = wave; unit < NU; unit += NWAVE) {
;         const u32x4* bp = Bw + (size_t)(unit * NT) * 64 + lane;
;         f32x16 acc[2][NT];
; #pragma unroll
;         for (int mi = 0; mi < 2; ++mi)
; #pragma unroll
;             for (int nj = 0; nj < NT; ++nj)
; #pragma unroll
;                 for (int i = 0; i < 16; ++i) acc[mi][nj][i] = 0.f;
;         u32x4 bq[PD][NT];
; #pragma unroll
;         for (int s = 0; s < PD; ++s)
; #pragma unroll
;             for (int j = 0; j < NT; ++j) bq[s][j] = bp[(size_t)((s + rot) & (KS - 1)) * kstr + j * 64];
; #pragma unroll 1
;         for (int kk = 0; kk < KS; kk += PD) {
; #pragma unroll
;             for (int s = 0; s < PD; ++s) {
;                 const int ks = kk + s, ksr = (ks + rot) & (KS - 1);
;                 const bf16x8 a0 = *(const bf16x8*)(ab + ksr * 32), a1 = *(const bf16x8*)(ab + 32 * LD + ksr * 32);
; #pragma unroll
;                 for (int j = 0; j < NT; ++j) { acc[0][j] = MFMA32(a0, __builtin_bit_cast(bf16x8, bq[s][j]), acc[0][j]); acc[1][j] = MFMA32(a1, __builtin_bit_cast(bf16x8, bq[s][j]), acc[1][j]); }
;                 int nk = ks + PD; nk = nk < KS ? nk : KS - 1; nk = (nk + rot) & (KS - 1);
; #pragma unroll
;                 for (int j = 0; j < NT; ++j) bq[s][j] = bp[(size_t)nk * kstr + j * 64];
;             }
;         }
.LBB0_533:
	s_lshl_b32 s6, s2, 1
	s_ashr_i32 s7, s6, 31
	s_lshl_b64 s[6:7], s[6:7], 10
	v_mov_b32_e32 v2, 0
	v_lshl_add_u64 v[68:69], v[66:67], 0, s[6:7]
	s_mov_b32 s3, -4
	v_readlane_b32 s6, v254, 45
	s_mov_b32 s7, s85
	v_readlane_b32 s28, v253, 29
	v_readlane_b32 s9, v253, 28
	s_mov_b32 s8, s87
	v_mov_b32_e32 v3, v2
	v_mov_b32_e32 v4, v2
	v_mov_b32_e32 v5, v2
	v_mov_b32_e32 v6, v2
	v_mov_b32_e32 v7, v2
	v_mov_b32_e32 v8, v2
	v_mov_b32_e32 v9, v2
	v_mov_b32_e32 v10, v2
	v_mov_b32_e32 v11, v2
	v_mov_b32_e32 v12, v2
	v_mov_b32_e32 v13, v2
	v_mov_b32_e32 v14, v2
	v_mov_b32_e32 v15, v2
	v_mov_b32_e32 v16, v2
	v_mov_b32_e32 v17, v2
	v_mov_b32_e32 v18, v2
	v_mov_b32_e32 v19, v2
	v_mov_b32_e32 v20, v2
	v_mov_b32_e32 v21, v2
	v_mov_b32_e32 v22, v2
	v_mov_b32_e32 v23, v2
	v_mov_b32_e32 v24, v2
	v_mov_b32_e32 v25, v2
	v_mov_b32_e32 v26, v2
	v_mov_b32_e32 v27, v2
	v_mov_b32_e32 v28, v2
	v_mov_b32_e32 v29, v2
	v_mov_b32_e32 v30, v2
	v_mov_b32_e32 v31, v2
	v_mov_b32_e32 v32, v2
	v_mov_b32_e32 v33, v2
	v_mov_b32_e32 v34, v2
	v_mov_b32_e32 v35, v2
	v_mov_b32_e32 v36, v2
	v_mov_b32_e32 v37, v2
	v_mov_b32_e32 v38, v2
	v_mov_b32_e32 v39, v2
	v_mov_b32_e32 v40, v2
	v_mov_b32_e32 v41, v2
	v_mov_b32_e32 v42, v2
	v_mov_b32_e32 v43, v2
	v_mov_b32_e32 v44, v2
	v_mov_b32_e32 v45, v2
	v_mov_b32_e32 v46, v2
	v_mov_b32_e32 v47, v2
	v_mov_b32_e32 v48, v2
	v_mov_b32_e32 v49, v2
	v_mov_b32_e32 v50, v2
	v_mov_b32_e32 v51, v2
	v_mov_b32_e32 v52, v2
	v_mov_b32_e32 v53, v2
	v_mov_b32_e32 v54, v2
	v_mov_b32_e32 v55, v2
	v_mov_b32_e32 v56, v2
	v_mov_b32_e32 v57, v2
	v_mov_b32_e32 v58, v2
	v_mov_b32_e32 v59, v2
	v_mov_b32_e32 v60, v2
	v_mov_b32_e32 v61, v2
	v_mov_b32_e32 v62, v2
	v_mov_b32_e32 v63, v2
	v_mov_b32_e32 v64, v2
	v_mov_b32_e32 v65, v2
	v_readlane_b32 s3, v254, 45
	s_nop 3
	s_lshr_b32 s3, s3, 5
	s_mov_b32 s101, 0
	s_mov_b32 s7, s3
	s_and_b32 s8, s7, 31
	s_add_i32 s7, s7, 1
	s_mul_i32 s100, s8, 0x8000
	v_lshl_add_u64 v[70:71], v[68:69], 0, s[100:101]
	global_load_dwordx4 v[72:75], v[70:71], off
	global_load_dwordx4 v[76:79], v[70:71], off offset:1024
	s_and_b32 s8, s7, 31
	s_add_i32 s7, s7, 1
	s_mul_i32 s100, s8, 0x8000
	v_lshl_add_u64 v[70:71], v[68:69], 0, s[100:101]
	global_load_dwordx4 v[80:83], v[70:71], off
	global_load_dwordx4 v[84:87], v[70:71], off offset:1024
	s_and_b32 s8, s7, 31
	s_add_i32 s7, s7, 1
	s_mul_i32 s100, s8, 0x8000
	v_lshl_add_u64 v[70:71], v[68:69], 0, s[100:101]
	global_load_dwordx4 v[88:91], v[70:71], off
	global_load_dwordx4 v[92:95], v[70:71], off offset:1024
	s_and_b32 s8, s7, 31
	s_add_i32 s7, s7, 1
	s_mul_i32 s100, s8, 0x8000
	v_lshl_add_u64 v[70:71], v[68:69], 0, s[100:101]
	global_load_dwordx4 v[96:99], v[70:71], off
	global_load_dwordx4 v[100:103], v[70:71], off offset:1024
	s_and_b32 s8, s7, 31
	s_add_i32 s7, s7, 1
	s_mul_i32 s100, s8, 0x8000
	v_lshl_add_u64 v[70:71], v[68:69], 0, s[100:101]
	global_load_dwordx4 v[104:107], v[70:71], off
	global_load_dwordx4 v[108:111], v[70:71], off offset:1024
	s_and_b32 s8, s7, 31
	s_add_i32 s7, s7, 1
	s_mul_i32 s100, s8, 0x8000
	v_lshl_add_u64 v[70:71], v[68:69], 0, s[100:101]
	global_load_dwordx4 v[116:119], v[70:71], off
	global_load_dwordx4 v[120:123], v[70:71], off offset:1024
	s_and_b32 s8, s7, 31
	s_add_i32 s7, s7, 1
	s_mul_i32 s100, s8, 0x8000
	v_lshl_add_u64 v[70:71], v[68:69], 0, s[100:101]
	global_load_dwordx4 v[124:127], v[70:71], off
	global_load_dwordx4 v[128:131], v[70:71], off offset:1024
	s_and_b32 s8, s7, 31
	s_add_i32 s7, s7, 1
	s_mul_i32 s100, s8, 0x8000
	v_lshl_add_u64 v[70:71], v[68:69], 0, s[100:101]
	global_load_dwordx4 v[132:135], v[70:71], off
	global_load_dwordx4 v[136:139], v[70:71], off offset:1024
	s_mov_b32 s6, s3
	s_and_b32 s8, s6, 31
	s_lshl_b32 s8, s8, 5
	s_add_i32 s6, s6, 1
	v_add_u32_e32 v112, s8, v0
	ds_read_b128 v[140:143], v112
	ds_read_b128 v[144:147], v112 offset:33280
	s_mov_b32 s9, 3
.Lkxo2_loop:
	s_and_b32 s8, s6, 31
	s_lshl_b32 s8, s8, 5
	s_add_i32 s6, s6, 1
	v_add_u32_e32 v112, s8, v0
	ds_read_b128 v[148:151], v112
	ds_read_b128 v[152:155], v112 offset:33280
	s_waitcnt vmcnt(15) lgkmcnt(2)
	v_mfma_f32_32x32x16_f16 v[50:65], v[140:143], v[72:75], v[50:65]
	v_mfma_f32_32x32x16_f16 v[18:33], v[144:147], v[72:75], v[18:33]
	s_waitcnt vmcnt(14)
	v_mfma_f32_32x32x16_f16 v[34:49], v[140:143], v[76:79], v[34:49]
	v_mfma_f32_32x32x16_f16 v[2:17], v[144:147], v[76:79], v[2:17]
	s_and_b32 s8, s7, 31
	s_add_i32 s7, s7, 1
	s_mul_i32 s100, s8, 0x8000
	v_lshl_add_u64 v[70:71], v[68:69], 0, s[100:101]
	global_load_dwordx4 v[72:75], v[70:71], off
	global_load_dwordx4 v[76:79], v[70:71], off offset:1024
	s_and_b32 s8, s6, 31
	s_lshl_b32 s8, s8, 5
	s_add_i32 s6, s6, 1
	v_add_u32_e32 v112, s8, v0
	ds_read_b128 v[140:143], v112
	ds_read_b128 v[144:147], v112 offset:33280
	s_waitcnt vmcnt(15) lgkmcnt(2)
	v_mfma_f32_32x32x16_f16 v[50:65], v[148:151], v[80:83], v[50:65]
	v_mfma_f32_32x32x16_f16 v[18:33], v[152:155], v[80:83], v[18:33]
	s_waitcnt vmcnt(14)
	v_mfma_f32_32x32x16_f16 v[34:49], v[148:151], v[84:87], v[34:49]
	v_mfma_f32_32x32x16_f16 v[2:17], v[152:155], v[84:87], v[2:17]
	s_and_b32 s8, s7, 31
	s_add_i32 s7, s7, 1
	s_mul_i32 s100, s8, 0x8000
	v_lshl_add_u64 v[70:71], v[68:69], 0, s[100:101]
	global_load_dwordx4 v[80:83], v[70:71], off
	global_load_dwordx4 v[84:87], v[70:71], off offset:1024
	s_and_b32 s8, s6, 31
	s_lshl_b32 s8, s8, 5
	s_add_i32 s6, s6, 1
	v_add_u32_e32 v112, s8, v0
	ds_read_b128 v[148:151], v112
	ds_read_b128 v[152:155], v112 offset:33280
	s_waitcnt vmcnt(15) lgkmcnt(2)
	v_mfma_f32_32x32x16_f16 v[50:65], v[140:143], v[88:91], v[50:65]
	v_mfma_f32_32x32x16_f16 v[18:33], v[144:147], v[88:91], v[18:33]
	s_waitcnt vmcnt(14)
; #define MFMA32(a, b, c) __builtin_amdgcn_mfma_f32_32x32x16_f16((a), (b), (c), 0, 0, 0)
; template <int K, class Epi>
; DI void gemm64_res(const bf16_t* A, int lda, const bf16_t* Wp, int NU, unsigned char* lds, const Epi& epi) {
;     ...
; #pragma unroll 1
;         for (int kk = 0; kk < KS; kk += PD) {
; #pragma unroll
;             for (int s = 0; s < PD; ++s) {
;                 const int ks = kk + s, ksr = (ks + rot) & (KS - 1);
;                 const bf16x8 a0 = *(const bf16x8*)(ab + ksr * 32), a1 = *(const bf16x8*)(ab + 32 * LD + ksr * 32);
; #pragma unroll
;                 for (int j = 0; j < NT; ++j) { acc[0][j] = MFMA32(a0, __builtin_bit_cast(bf16x8, bq[s][j]), acc[0][j]); acc[1][j] = MFMA32(a1, __builtin_bit_cast(bf16x8, bq[s][j]), acc[1][j]); }
;                 int nk = ks + PD; nk = nk < KS ? nk : KS - 1; nk = (nk + rot) & (KS - 1);
; #pragma unroll
;                 for (int j = 0; j < NT; ++j) bq[s][j] = bp[(size_t)nk * kstr + j * 64];
;             }
;         }
	v_mfma_f32_32x32x16_f16 v[34:49], v[140:143], v[92:95], v[34:49]
	v_mfma_f32_32x32x16_f16 v[2:17], v[144:147], v[92:95], v[2:17]
	s_and_b32 s8, s7, 31
	s_add_i32 s7, s7, 1
	s_mul_i32 s100, s8, 0x8000
	v_lshl_add_u64 v[70:71], v[68:69], 0, s[100:101]
	global_load_dwordx4 v[88:91], v[70:71], off
	global_load_dwordx4 v[92:95], v[70:71], off offset:1024
	s_and_b32 s8, s6, 31
	s_lshl_b32 s8, s8, 5
	s_add_i32 s6, s6, 1
	v_add_u32_e32 v112, s8, v0
	ds_read_b128 v[140:143], v112
	ds_read_b128 v[144:147], v112 offset:33280
	s_waitcnt vmcnt(15) lgkmcnt(2)
	v_mfma_f32_32x32x16_f16 v[50:65], v[148:151], v[96:99], v[50:65]
	v_mfma_f32_32x32x16_f16 v[18:33], v[152:155], v[96:99], v[18:33]
	s_waitcnt vmcnt(14)
	v_mfma_f32_32x32x16_f16 v[34:49], v[148:151], v[100:103], v[34:49]
	v_mfma_f32_32x32x16_f16 v[2:17], v[152:155], v[100:103], v[2:17]
	s_and_b32 s8, s7, 31
	s_add_i32 s7, s7, 1
	s_mul_i32 s100, s8, 0x8000
	v_lshl_add_u64 v[70:71], v[68:69], 0, s[100:101]
	global_load_dwordx4 v[96:99], v[70:71], off
	global_load_dwordx4 v[100:103], v[70:71], off offset:1024
	s_and_b32 s8, s6, 31
	s_lshl_b32 s8, s8, 5
	s_add_i32 s6, s6, 1
	v_add_u32_e32 v112, s8, v0
	ds_read_b128 v[148:151], v112
	ds_read_b128 v[152:155], v112 offset:33280
	s_waitcnt vmcnt(15) lgkmcnt(2)
	v_mfma_f32_32x32x16_f16 v[50:65], v[140:143], v[104:107], v[50:65]
	v_mfma_f32_32x32x16_f16 v[18:33], v[144:147], v[104:107], v[18:33]
	s_waitcnt vmcnt(14)
	v_mfma_f32_32x32x16_f16 v[34:49], v[140:143], v[108:111], v[34:49]
	v_mfma_f32_32x32x16_f16 v[2:17], v[144:147], v[108:111], v[2:17]
	s_and_b32 s8, s7, 31
	s_add_i32 s7, s7, 1
	s_mul_i32 s100, s8, 0x8000
	v_lshl_add_u64 v[70:71], v[68:69], 0, s[100:101]
	global_load_dwordx4 v[104:107], v[70:71], off
	global_load_dwordx4 v[108:111], v[70:71], off offset:1024
	s_and_b32 s8, s6, 31
	s_lshl_b32 s8, s8, 5
	s_add_i32 s6, s6, 1
	v_add_u32_e32 v112, s8, v0
	ds_read_b128 v[140:143], v112
	ds_read_b128 v[144:147], v112 offset:33280
	s_waitcnt vmcnt(15) lgkmcnt(2)
	v_mfma_f32_32x32x16_f16 v[50:65], v[148:151], v[116:119], v[50:65]
	v_mfma_f32_32x32x16_f16 v[18:33], v[152:155], v[116:119], v[18:33]
	s_waitcnt vmcnt(14)
	v_mfma_f32_32x32x16_f16 v[34:49], v[148:151], v[120:123], v[34:49]
	v_mfma_f32_32x32x16_f16 v[2:17], v[152:155], v[120:123], v[2:17]
	s_and_b32 s8, s7, 31
	s_add_i32 s7, s7, 1
	s_mul_i32 s100, s8, 0x8000
	v_lshl_add_u64 v[70:71], v[68:69], 0, s[100:101]
	global_load_dwordx4 v[116:119], v[70:71], off
	global_load_dwordx4 v[120:123], v[70:71], off offset:1024
	s_and_b32 s8, s6, 31
	s_lshl_b32 s8, s8, 5
	s_add_i32 s6, s6, 1
	v_add_u32_e32 v112, s8, v0
	ds_read_b128 v[148:151], v112
	ds_read_b128 v[152:155], v112 offset:33280
	s_waitcnt vmcnt(15) lgkmcnt(2)
	v_mfma_f32_32x32x16_f16 v[50:65], v[140:143], v[124:127], v[50:65]
	v_mfma_f32_32x32x16_f16 v[18:33], v[144:147], v[124:127], v[18:33]
	s_waitcnt vmcnt(14)
	v_mfma_f32_32x32x16_f16 v[34:49], v[140:143], v[128:131], v[34:49]
	v_mfma_f32_32x32x16_f16 v[2:17], v[144:147], v[128:131], v[2:17]
	s_and_b32 s8, s7, 31
	s_add_i32 s7, s7, 1
	s_mul_i32 s100, s8, 0x8000
	v_lshl_add_u64 v[70:71], v[68:69], 0, s[100:101]
	global_load_dwordx4 v[124:127], v[70:71], off
	global_load_dwordx4 v[128:131], v[70:71], off offset:1024
	s_and_b32 s8, s6, 31
	s_lshl_b32 s8, s8, 5
	s_add_i32 s6, s6, 1
	v_add_u32_e32 v112, s8, v0
	ds_read_b128 v[140:143], v112
	ds_read_b128 v[144:147], v112 offset:33280
	s_waitcnt vmcnt(15) lgkmcnt(2)
	v_mfma_f32_32x32x16_f16 v[50:65], v[148:151], v[132:135], v[50:65]
	v_mfma_f32_32x32x16_f16 v[18:33], v[152:155], v[132:135], v[18:33]
	s_waitcnt vmcnt(14)
	v_mfma_f32_32x32x16_f16 v[34:49], v[148:151], v[136:139], v[34:49]
	v_mfma_f32_32x32x16_f16 v[2:17], v[152:155], v[136:139], v[2:17]
	s_and_b32 s8, s7, 31
	s_add_i32 s7, s7, 1
	s_mul_i32 s100, s8, 0x8000
	v_lshl_add_u64 v[70:71], v[68:69], 0, s[100:101]
	global_load_dwordx4 v[132:135], v[70:71], off
	global_load_dwordx4 v[136:139], v[70:71], off offset:1024
	s_add_i32 s9, s9, -1
	s_cmp_lg_u32 s9, 0
	s_cbranch_scc1 .Lkxo2_loop
	s_and_b32 s8, s6, 31
	s_lshl_b32 s8, s8, 5
	s_add_i32 s6, s6, 1
	v_add_u32_e32 v112, s8, v0
	ds_read_b128 v[148:151], v112
	ds_read_b128 v[152:155], v112 offset:33280
	s_waitcnt vmcnt(15) lgkmcnt(2)
	v_mfma_f32_32x32x16_f16 v[50:65], v[140:143], v[72:75], v[50:65]
	v_mfma_f32_32x32x16_f16 v[18:33], v[144:147], v[72:75], v[18:33]
	s_waitcnt vmcnt(14)
	v_mfma_f32_32x32x16_f16 v[34:49], v[140:143], v[76:79], v[34:49]
	v_mfma_f32_32x32x16_f16 v[2:17], v[144:147], v[76:79], v[2:17]
	s_and_b32 s8, s6, 31
	s_lshl_b32 s8, s8, 5
	s_add_i32 s6, s6, 1
	v_add_u32_e32 v112, s8, v0
	ds_read_b128 v[140:143], v112
	ds_read_b128 v[144:147], v112 offset:33280
	s_waitcnt vmcnt(13) lgkmcnt(2)
	v_mfma_f32_32x32x16_f16 v[50:65], v[148:151], v[80:83], v[50:65]
	v_mfma_f32_32x32x16_f16 v[18:33], v[152:155], v[80:83], v[18:33]
	s_waitcnt vmcnt(12)
	v_mfma_f32_32x32x16_f16 v[34:49], v[148:151], v[84:87], v[34:49]
	v_mfma_f32_32x32x16_f16 v[2:17], v[152:155], v[84:87], v[2:17]
	s_and_b32 s8, s6, 31
	s_lshl_b32 s8, s8, 5
	s_add_i32 s6, s6, 1
	v_add_u32_e32 v112, s8, v0
	ds_read_b128 v[148:151], v112
	ds_read_b128 v[152:155], v112 offset:33280
	s_waitcnt vmcnt(11) lgkmcnt(2)
	v_mfma_f32_32x32x16_f16 v[50:65], v[140:143], v[88:91], v[50:65]
	v_mfma_f32_32x32x16_f16 v[18:33], v[144:147], v[88:91], v[18:33]
	s_waitcnt vmcnt(10)
	v_mfma_f32_32x32x16_f16 v[34:49], v[140:143], v[92:95], v[34:49]
	v_mfma_f32_32x32x16_f16 v[2:17], v[144:147], v[92:95], v[2:17]
	s_and_b32 s8, s6, 31
	s_lshl_b32 s8, s8, 5
	s_add_i32 s6, s6, 1
	v_add_u32_e32 v112, s8, v0
	ds_read_b128 v[140:143], v112
	ds_read_b128 v[144:147], v112 offset:33280
	s_waitcnt vmcnt(9) lgkmcnt(2)
; #define MFMA32(a, b, c) __builtin_amdgcn_mfma_f32_32x32x16_f16((a), (b), (c), 0, 0, 0)
; DI int otid() { int t = threadIdx.x; asm volatile("" : "+v"(t)); return t; }
; DI int crow(int i, int h) { return (i & 3) + 8 * (i >> 2) + 4 * h; }
; template <int K, class Epi>
; DI void gemm64_res(const bf16_t* A, int lda, const bf16_t* Wp, int NU, unsigned char* lds, const Epi& epi) {
;     ...
; #pragma unroll 1
;         for (int kk = 0; kk < KS; kk += PD) {
; #pragma unroll
;             for (int s = 0; s < PD; ++s) {
;                 const int ks = kk + s, ksr = (ks + rot) & (KS - 1);
;                 const bf16x8 a0 = *(const bf16x8*)(ab + ksr * 32), a1 = *(const bf16x8*)(ab + 32 * LD + ksr * 32);
; #pragma unroll
;                 for (int j = 0; j < NT; ++j) { acc[0][j] = MFMA32(a0, __builtin_bit_cast(bf16x8, bq[s][j]), acc[0][j]); acc[1][j] = MFMA32(a1, __builtin_bit_cast(bf16x8, bq[s][j]), acc[1][j]); }
;                 int nk = ks + PD; nk = nk < KS ? nk : KS - 1; nk = (nk + rot) & (KS - 1);
; #pragma unroll
;                 for (int j = 0; j < NT; ++j) bq[s][j] = bp[(size_t)nk * kstr + j * 64];
;             }
;         }
;     DI void operator()(int unit, const f32x16 (&acc)[MT][NT]) const {
;         const int lane = otid() & 63, r = lane & 31, h = lane >> 5;
; #pragma unroll
;         for (int mi = 0; mi < MT; ++mi)
; #pragma unroll
;             for (int nj = 0; nj < NT; ++nj)
; #pragma unroll
;                 for (int i = 0; i < 16; ++i) { float* q = x + ((mi * 32 + crow(i, h) + (mi == 2 ? d2 : 0)) * DM + unit * UW + nj * 32 + r); *q = *q + acc[mi][nj][i]; if (i == 15) __builtin_amdgcn_sched_barrier(0); }
	v_mfma_f32_32x32x16_f16 v[50:65], v[148:151], v[96:99], v[50:65]
	v_mfma_f32_32x32x16_f16 v[18:33], v[152:155], v[96:99], v[18:33]
	s_waitcnt vmcnt(8)
	v_mfma_f32_32x32x16_f16 v[34:49], v[148:151], v[100:103], v[34:49]
	v_mfma_f32_32x32x16_f16 v[2:17], v[152:155], v[100:103], v[2:17]
	s_and_b32 s8, s6, 31
	s_lshl_b32 s8, s8, 5
	s_add_i32 s6, s6, 1
	v_add_u32_e32 v112, s8, v0
	ds_read_b128 v[148:151], v112
	ds_read_b128 v[152:155], v112 offset:33280
	s_waitcnt vmcnt(7) lgkmcnt(2)
	v_mfma_f32_32x32x16_f16 v[50:65], v[140:143], v[104:107], v[50:65]
	v_mfma_f32_32x32x16_f16 v[18:33], v[144:147], v[104:107], v[18:33]
	s_waitcnt vmcnt(6)
	v_mfma_f32_32x32x16_f16 v[34:49], v[140:143], v[108:111], v[34:49]
	v_mfma_f32_32x32x16_f16 v[2:17], v[144:147], v[108:111], v[2:17]
	s_and_b32 s8, s6, 31
	s_lshl_b32 s8, s8, 5
	s_add_i32 s6, s6, 1
	v_add_u32_e32 v112, s8, v0
	ds_read_b128 v[140:143], v112
	ds_read_b128 v[144:147], v112 offset:33280
	s_waitcnt vmcnt(5) lgkmcnt(2)
	v_mfma_f32_32x32x16_f16 v[50:65], v[148:151], v[116:119], v[50:65]
	v_mfma_f32_32x32x16_f16 v[18:33], v[152:155], v[116:119], v[18:33]
	s_waitcnt vmcnt(4)
	v_mfma_f32_32x32x16_f16 v[34:49], v[148:151], v[120:123], v[34:49]
	v_mfma_f32_32x32x16_f16 v[2:17], v[152:155], v[120:123], v[2:17]
	s_and_b32 s8, s6, 31
	s_lshl_b32 s8, s8, 5
	s_add_i32 s6, s6, 1
	v_add_u32_e32 v112, s8, v0
	ds_read_b128 v[148:151], v112
	ds_read_b128 v[152:155], v112 offset:33280
	s_waitcnt vmcnt(3) lgkmcnt(2)
	v_mfma_f32_32x32x16_f16 v[50:65], v[140:143], v[124:127], v[50:65]
	v_mfma_f32_32x32x16_f16 v[18:33], v[144:147], v[124:127], v[18:33]
	s_waitcnt vmcnt(2)
	v_mfma_f32_32x32x16_f16 v[34:49], v[140:143], v[128:131], v[34:49]
	v_mfma_f32_32x32x16_f16 v[2:17], v[144:147], v[128:131], v[2:17]
	s_waitcnt vmcnt(1) lgkmcnt(0)
	v_mfma_f32_32x32x16_f16 v[50:65], v[148:151], v[132:135], v[50:65]
	v_mfma_f32_32x32x16_f16 v[18:33], v[152:155], v[132:135], v[18:33]
	s_waitcnt vmcnt(0)
	v_mfma_f32_32x32x16_f16 v[34:49], v[148:151], v[136:139], v[34:49]
	v_mfma_f32_32x32x16_f16 v[2:17], v[152:155], v[136:139], v[2:17]
	s_nop 7
	s_nop 3
	s_waitcnt vmcnt(0)
	v_and_b32_e32 v68, 31, v176
	v_lshlrev_b32_e32 v69, 9, v176
	v_and_b32_e32 v69, 0x4000, v69
	v_lshl_or_b32 v70, v68, 2, v69
	v_lshl_add_u32 v70, s2, 8, v70
	v_add_u32_e32 v71, 0x1000, v70
	global_load_dword v79, v71, s[0:1] offset:-4096
	global_load_dword v80, v71, s[0:1] offset:-3968
	global_load_dword v81, v71, s[0:1] offset:0
	global_load_dword v82, v71, s[0:1] offset:128
	v_add_u32_e32 v72, 0x3000, v70
	global_load_dword v83, v72, s[0:1] offset:-4096
	global_load_dword v84, v72, s[0:1] offset:-3968
	global_load_dword v85, v72, s[0:1] offset:0
	global_load_dword v86, v72, s[0:1] offset:128
	v_add_u32_e32 v73, 0x9000, v70
	global_load_dword v87, v73, s[0:1] offset:-4096
	global_load_dword v88, v73, s[0:1] offset:-3968
	global_load_dword v89, v73, s[0:1] offset:0
	global_load_dword v90, v73, s[0:1] offset:128
	v_add_u32_e32 v74, 0xb000, v70
	global_load_dword v91, v74, s[0:1] offset:-4096
	global_load_dword v92, v74, s[0:1] offset:-3968
	global_load_dword v93, v74, s[0:1] offset:0
	global_load_dword v94, v74, s[0:1] offset:128
	v_add_u32_e32 v75, 0x11000, v70
	global_load_dword v95, v75, s[0:1] offset:-4096
	global_load_dword v96, v75, s[0:1] offset:-3968
	global_load_dword v97, v75, s[0:1] offset:0
	global_load_dword v98, v75, s[0:1] offset:128
	v_add_u32_e32 v76, 0x13000, v70
	global_load_dword v99, v76, s[0:1] offset:-4096
	global_load_dword v100, v76, s[0:1] offset:-3968
	global_load_dword v101, v76, s[0:1] offset:0
	global_load_dword v102, v76, s[0:1] offset:128
	v_add_u32_e32 v77, 0x19000, v70
	global_load_dword v103, v77, s[0:1] offset:-4096
	global_load_dword v104, v77, s[0:1] offset:-3968
	global_load_dword v105, v77, s[0:1] offset:0
	global_load_dword v106, v77, s[0:1] offset:128
	v_add_u32_e32 v78, 0x1b000, v70
	global_load_dword v107, v78, s[0:1] offset:-4096
	global_load_dword v108, v78, s[0:1] offset:-3968
	global_load_dword v109, v78, s[0:1] offset:0
	global_load_dword v110, v78, s[0:1] offset:128
	s_waitcnt vmcnt(0)
; DI int otid() { int t = threadIdx.x; asm volatile("" : "+v"(t)); return t; }
; DI int crow(int i, int h) { return (i & 3) + 8 * (i >> 2) + 4 * h; }
;     DI void operator()(int unit, const f32x16 (&acc)[MT][NT]) const {
;         const int lane = otid() & 63, r = lane & 31, h = lane >> 5;
; #pragma unroll
;         for (int mi = 0; mi < MT; ++mi)
; #pragma unroll
;             for (int nj = 0; nj < NT; ++nj)
; #pragma unroll
;                 for (int i = 0; i < 16; ++i) { float* q = x + ((mi * 32 + crow(i, h) + (mi == 2 ? d2 : 0)) * DM + unit * UW + nj * 32 + r); *q = *q + acc[mi][nj][i]; if (i == 15) __builtin_amdgcn_sched_barrier(0); }
;     }
	v_add_f32_e32 v79, v50, v79
	global_store_dword v71, v79, s[0:1] offset:-4096
	v_add_f32_e32 v80, v34, v80
	global_store_dword v71, v80, s[0:1] offset:-3968
	v_add_f32_e32 v81, v51, v81
	global_store_dword v71, v81, s[0:1] offset:0
	v_add_f32_e32 v82, v35, v82
	global_store_dword v71, v82, s[0:1] offset:128
	v_add_f32_e32 v83, v52, v83
	global_store_dword v72, v83, s[0:1] offset:-4096
	v_add_f32_e32 v84, v36, v84
	global_store_dword v72, v84, s[0:1] offset:-3968
	v_add_f32_e32 v85, v53, v85
	global_store_dword v72, v85, s[0:1] offset:0
	v_add_f32_e32 v86, v37, v86
	global_store_dword v72, v86, s[0:1] offset:128
	v_add_f32_e32 v87, v54, v87
	global_store_dword v73, v87, s[0:1] offset:-4096
	v_add_f32_e32 v88, v38, v88
	global_store_dword v73, v88, s[0:1] offset:-3968
	v_add_f32_e32 v89, v55, v89
	global_store_dword v73, v89, s[0:1] offset:0
	v_add_f32_e32 v90, v39, v90
	global_store_dword v73, v90, s[0:1] offset:128
	v_add_f32_e32 v91, v56, v91
	global_store_dword v74, v91, s[0:1] offset:-4096
	v_add_f32_e32 v92, v40, v92
	global_store_dword v74, v92, s[0:1] offset:-3968
	v_add_f32_e32 v93, v57, v93
	global_store_dword v74, v93, s[0:1] offset:0
	v_add_f32_e32 v94, v41, v94
	global_store_dword v74, v94, s[0:1] offset:128
	v_add_f32_e32 v95, v58, v95
	global_store_dword v75, v95, s[0:1] offset:-4096
	v_add_f32_e32 v96, v42, v96
	global_store_dword v75, v96, s[0:1] offset:-3968
	v_add_f32_e32 v97, v59, v97
	global_store_dword v75, v97, s[0:1] offset:0
	v_add_f32_e32 v98, v43, v98
	global_store_dword v75, v98, s[0:1] offset:128
	v_add_f32_e32 v99, v60, v99
	global_store_dword v76, v99, s[0:1] offset:-4096
	v_add_f32_e32 v100, v44, v100
	global_store_dword v76, v100, s[0:1] offset:-3968
	v_add_f32_e32 v101, v61, v101
	global_store_dword v76, v101, s[0:1] offset:0
	v_add_f32_e32 v102, v45, v102
	global_store_dword v76, v102, s[0:1] offset:128
	v_add_f32_e32 v103, v62, v103
	global_store_dword v77, v103, s[0:1] offset:-4096
	v_add_f32_e32 v104, v46, v104
	global_store_dword v77, v104, s[0:1] offset:-3968
	v_add_f32_e32 v105, v63, v105
	global_store_dword v77, v105, s[0:1] offset:0
	v_add_f32_e32 v106, v47, v106
	global_store_dword v77, v106, s[0:1] offset:128
	v_add_f32_e32 v107, v64, v107
	global_store_dword v78, v107, s[0:1] offset:-4096
	v_add_f32_e32 v108, v48, v108
	global_store_dword v78, v108, s[0:1] offset:-3968
	v_add_f32_e32 v109, v65, v109
	global_store_dword v78, v109, s[0:1] offset:0
	v_add_f32_e32 v110, v49, v110
	global_store_dword v78, v110, s[0:1] offset:128
	v_add_u32_e32 v71, 0x21000, v70
	global_load_dword v79, v71, s[0:1] offset:-4096
	global_load_dword v80, v71, s[0:1] offset:-3968
	global_load_dword v81, v71, s[0:1] offset:0
	global_load_dword v82, v71, s[0:1] offset:128
	v_add_u32_e32 v72, 0x23000, v70
	global_load_dword v83, v72, s[0:1] offset:-4096
	global_load_dword v84, v72, s[0:1] offset:-3968
	global_load_dword v85, v72, s[0:1] offset:0
	global_load_dword v86, v72, s[0:1] offset:128
	v_add_u32_e32 v73, 0x29000, v70
	global_load_dword v87, v73, s[0:1] offset:-4096
	global_load_dword v88, v73, s[0:1] offset:-3968
	global_load_dword v89, v73, s[0:1] offset:0
	global_load_dword v90, v73, s[0:1] offset:128
	v_add_u32_e32 v74, 0x2b000, v70
	global_load_dword v91, v74, s[0:1] offset:-4096
	global_load_dword v92, v74, s[0:1] offset:-3968
	global_load_dword v93, v74, s[0:1] offset:0
	global_load_dword v94, v74, s[0:1] offset:128
	v_add_u32_e32 v75, 0x31000, v70
	global_load_dword v95, v75, s[0:1] offset:-4096
	global_load_dword v96, v75, s[0:1] offset:-3968
	global_load_dword v97, v75, s[0:1] offset:0
	global_load_dword v98, v75, s[0:1] offset:128
	v_add_u32_e32 v76, 0x33000, v70
	global_load_dword v99, v76, s[0:1] offset:-4096
	global_load_dword v100, v76, s[0:1] offset:-3968
	global_load_dword v101, v76, s[0:1] offset:0
	global_load_dword v102, v76, s[0:1] offset:128
	v_add_u32_e32 v77, 0x39000, v70
	global_load_dword v103, v77, s[0:1] offset:-4096
	global_load_dword v104, v77, s[0:1] offset:-3968
	global_load_dword v105, v77, s[0:1] offset:0
	global_load_dword v106, v77, s[0:1] offset:128
	v_add_u32_e32 v78, 0x3b000, v70
	global_load_dword v107, v78, s[0:1] offset:-4096
	global_load_dword v108, v78, s[0:1] offset:-3968
	global_load_dword v109, v78, s[0:1] offset:0
	global_load_dword v110, v78, s[0:1] offset:128
	s_waitcnt vmcnt(0)
	v_add_f32_e32 v79, v18, v79
	global_store_dword v71, v79, s[0:1] offset:-4096
	v_add_f32_e32 v80, v2, v80
	global_store_dword v71, v80, s[0:1] offset:-3968
	v_add_f32_e32 v81, v19, v81
	global_store_dword v71, v81, s[0:1] offset:0
	v_add_f32_e32 v82, v3, v82
	global_store_dword v71, v82, s[0:1] offset:128
	v_add_f32_e32 v83, v20, v83
	global_store_dword v72, v83, s[0:1] offset:-4096
	v_add_f32_e32 v84, v4, v84
	global_store_dword v72, v84, s[0:1] offset:-3968
	v_add_f32_e32 v85, v21, v85
	global_store_dword v72, v85, s[0:1] offset:0
	v_add_f32_e32 v86, v5, v86
	global_store_dword v72, v86, s[0:1] offset:128
	v_add_f32_e32 v87, v22, v87
	global_store_dword v73, v87, s[0:1] offset:-4096
	v_add_f32_e32 v88, v6, v88
	global_store_dword v73, v88, s[0:1] offset:-3968
	v_add_f32_e32 v89, v23, v89
	global_store_dword v73, v89, s[0:1] offset:0
	v_add_f32_e32 v90, v7, v90
	global_store_dword v73, v90, s[0:1] offset:128
	v_add_f32_e32 v91, v24, v91
	global_store_dword v74, v91, s[0:1] offset:-4096
	v_add_f32_e32 v92, v8, v92
	global_store_dword v74, v92, s[0:1] offset:-3968
	v_add_f32_e32 v93, v25, v93
	global_store_dword v74, v93, s[0:1] offset:0
	v_add_f32_e32 v94, v9, v94
	global_store_dword v74, v94, s[0:1] offset:128
	v_add_f32_e32 v95, v26, v95
	global_store_dword v75, v95, s[0:1] offset:-4096
	v_add_f32_e32 v96, v10, v96
	global_store_dword v75, v96, s[0:1] offset:-3968
	v_add_f32_e32 v97, v27, v97
	global_store_dword v75, v97, s[0:1] offset:0
	v_add_f32_e32 v98, v11, v98
	global_store_dword v75, v98, s[0:1] offset:128
	v_add_f32_e32 v99, v28, v99
	global_store_dword v76, v99, s[0:1] offset:-4096
	v_add_f32_e32 v100, v12, v100
	global_store_dword v76, v100, s[0:1] offset:-3968
	v_add_f32_e32 v101, v29, v101
	global_store_dword v76, v101, s[0:1] offset:0
	v_add_f32_e32 v102, v13, v102
	global_store_dword v76, v102, s[0:1] offset:128
	v_add_f32_e32 v103, v30, v103
	global_store_dword v77, v103, s[0:1] offset:-4096
	v_add_f32_e32 v104, v14, v104
	global_store_dword v77, v104, s[0:1] offset:-3968
	v_add_f32_e32 v105, v31, v105
	global_store_dword v77, v105, s[0:1] offset:0
	v_add_f32_e32 v106, v15, v106
	global_store_dword v77, v106, s[0:1] offset:128
	v_add_f32_e32 v107, v32, v107
	global_store_dword v78, v107, s[0:1] offset:-4096
	v_add_f32_e32 v108, v16, v108
	global_store_dword v78, v108, s[0:1] offset:-3968
	v_add_f32_e32 v109, v33, v109
	global_store_dword v78, v109, s[0:1] offset:0
	v_add_f32_e32 v110, v17, v110
	global_store_dword v78, v110, s[0:1] offset:128
	s_waitcnt vmcnt(0)
	s_add_i32 s3, s2, 8
	s_cmp_lt_i32 s2, 8
	s_mov_b32 s2, s3
	s_cbranch_scc1 .LBB0_533
	s_movk_i32 s17, 0x810
	s_movk_i32 s64, 0x3fff

; #define MFMA32(a, b, c) __builtin_amdgcn_mfma_f32_32x32x16_f16((a), (b), (c), 0, 0, 0)
; template <int K, class Epi>
; DI void gemm64_res(const bf16_t* A, int lda, const bf16_t* Wp, int NU, unsigned char* lds, const Epi& epi) {
;     ...
;     for (int unit = wave; unit < NU; unit += NWAVE) {
;         const u32x4* bp = Bw + (size_t)(unit * NT) * 64 + lane;
;         f32x16 acc[2][NT];
; #pragma unroll
;         for (int mi = 0; mi < 2; ++mi)
; #pragma unroll
;             for (int nj = 0; nj < NT; ++nj)
; #pragma unroll
;                 for (int i = 0; i < 16; ++i) acc[mi][nj][i] = 0.f;
;         u32x4 bq[PD][NT];
; #pragma unroll
;         for (int s = 0; s < PD; ++s)
; #pragma unroll
;             for (int j = 0; j < NT; ++j) bq[s][j] = bp[(size_t)((s + rot) & (KS - 1)) * kstr + j * 64];
; #pragma unroll 1
;         for (int kk = 0; kk < KS; kk += PD) {
; #pragma unroll
;             for (int s = 0; s < PD; ++s) {
;                 const int ks = kk + s, ksr = (ks + rot) & (KS - 1);
;                 const bf16x8 a0 = *(const bf16x8*)(ab + ksr * 32), a1 = *(const bf16x8*)(ab + 32 * LD + ksr * 32);
; #pragma unroll
;                 for (int j = 0; j < NT; ++j) { acc[0][j] = MFMA32(a0, __builtin_bit_cast(bf16x8, bq[s][j]), acc[0][j]); acc[1][j] = MFMA32(a1, __builtin_bit_cast(bf16x8, bq[s][j]), acc[1][j]); }
;                 int nk = ks + PD; nk = nk < KS ? nk : KS - 1; nk = (nk + rot) & (KS - 1);
; #pragma unroll
;                 for (int j = 0; j < NT; ++j) bq[s][j] = bp[(size_t)nk * kstr + j * 64];
;             }
.LBB0_540:
	s_lshl_b32 s0, s31, 1
	s_ashr_i32 s1, s0, 31
	s_lshl_b64 s[0:1], s[0:1], 10
	v_lshl_add_u64 v[68:69], v[66:67], 0, s[0:1]
	v_readlane_b32 s0, v255, 11
	v_readlane_b32 s1, v255, 12
	s_mov_b32 s1, s65
	s_mov_b32 s2, s0
	v_lshl_add_u64 v[2:3], v[68:69], 0, s[0:1]
	s_mov_b64 s[0:1], 0x2c400
	v_writelane_b32 v255, s2, 11
	v_lshl_add_u64 v[70:71], v[2:3], 0, s[0:1]
	v_mov_b32_e32 v2, 0
	v_writelane_b32 v255, s3, 12
	s_mov_b32 s3, -4
	v_readlane_b32 s2, v254, 46
	v_readlane_b32 s5, v253, 40
	v_readlane_b32 s4, v253, 39
	v_readlane_b32 s0, v253, 38
	v_readlane_b32 s1, v254, 48
	v_mov_b32_e32 v3, v2
	v_mov_b32_e32 v4, v2
	v_mov_b32_e32 v5, v2
	v_mov_b32_e32 v6, v2
	v_mov_b32_e32 v7, v2
	v_mov_b32_e32 v8, v2
	v_mov_b32_e32 v9, v2
	v_mov_b32_e32 v10, v2
	v_mov_b32_e32 v11, v2
	v_mov_b32_e32 v12, v2
	v_mov_b32_e32 v13, v2
	v_mov_b32_e32 v14, v2
	v_mov_b32_e32 v15, v2
	v_mov_b32_e32 v16, v2
	v_mov_b32_e32 v17, v2
	v_mov_b32_e32 v18, v2
	v_mov_b32_e32 v19, v2
	v_mov_b32_e32 v20, v2
	v_mov_b32_e32 v21, v2
	v_mov_b32_e32 v22, v2
	v_mov_b32_e32 v23, v2
	v_mov_b32_e32 v24, v2
	v_mov_b32_e32 v25, v2
	v_mov_b32_e32 v26, v2
	v_mov_b32_e32 v27, v2
	v_mov_b32_e32 v28, v2
	v_mov_b32_e32 v29, v2
	v_mov_b32_e32 v30, v2
	v_mov_b32_e32 v31, v2
	v_mov_b32_e32 v32, v2
	v_mov_b32_e32 v33, v2
	v_mov_b32_e32 v34, v2
	v_mov_b32_e32 v35, v2
	v_mov_b32_e32 v36, v2
	v_mov_b32_e32 v37, v2
	v_mov_b32_e32 v38, v2
	v_mov_b32_e32 v39, v2
	v_mov_b32_e32 v40, v2
	v_mov_b32_e32 v41, v2
	v_mov_b32_e32 v42, v2
	v_mov_b32_e32 v43, v2
	v_mov_b32_e32 v44, v2
	v_mov_b32_e32 v45, v2
	v_mov_b32_e32 v46, v2
	v_mov_b32_e32 v47, v2
	v_mov_b32_e32 v48, v2
	v_mov_b32_e32 v49, v2
	v_mov_b32_e32 v50, v2
	v_mov_b32_e32 v51, v2
	v_mov_b32_e32 v52, v2
	v_mov_b32_e32 v53, v2
	v_mov_b32_e32 v54, v2
	v_mov_b32_e32 v55, v2
	v_mov_b32_e32 v56, v2
	v_mov_b32_e32 v57, v2
	v_mov_b32_e32 v58, v2
	v_mov_b32_e32 v59, v2
	v_mov_b32_e32 v60, v2
	v_mov_b32_e32 v61, v2
	v_mov_b32_e32 v62, v2
	v_mov_b32_e32 v63, v2
	v_mov_b32_e32 v64, v2
	v_mov_b32_e32 v65, v2
	v_readlane_b32 s0, v254, 48
	s_nop 3
	s_mov_b32 s101, 0
	s_mov_b32 s2, s0
	s_and_b32 s3, s2, 63
	s_add_i32 s2, s2, 1
	s_mul_i32 s100, s3, 0x2c000
	v_lshl_add_u64 v[74:75], v[68:69], 0, s[100:101]
	global_load_dwordx4 v[76:79], v[74:75], off
	global_load_dwordx4 v[80:83], v[74:75], off offset:1024
	s_and_b32 s3, s2, 63
	s_add_i32 s2, s2, 1
	s_mul_i32 s100, s3, 0x2c000
	v_lshl_add_u64 v[74:75], v[68:69], 0, s[100:101]
	global_load_dwordx4 v[84:87], v[74:75], off
	global_load_dwordx4 v[88:91], v[74:75], off offset:1024
	s_and_b32 s3, s2, 63
	s_add_i32 s2, s2, 1
	s_mul_i32 s100, s3, 0x2c000
	v_lshl_add_u64 v[74:75], v[68:69], 0, s[100:101]
	global_load_dwordx4 v[92:95], v[74:75], off
	global_load_dwordx4 v[96:99], v[74:75], off offset:1024
	s_and_b32 s3, s2, 63
	s_add_i32 s2, s2, 1
	s_mul_i32 s100, s3, 0x2c000
	v_lshl_add_u64 v[74:75], v[68:69], 0, s[100:101]
	global_load_dwordx4 v[100:103], v[74:75], off
	global_load_dwordx4 v[104:107], v[74:75], off offset:1024
	s_and_b32 s3, s2, 63
	s_add_i32 s2, s2, 1
	s_mul_i32 s100, s3, 0x2c000
	v_lshl_add_u64 v[74:75], v[68:69], 0, s[100:101]
	global_load_dwordx4 v[108:111], v[74:75], off
	global_load_dwordx4 v[116:119], v[74:75], off offset:1024
	s_and_b32 s3, s2, 63
	s_add_i32 s2, s2, 1
	s_mul_i32 s100, s3, 0x2c000
	v_lshl_add_u64 v[74:75], v[68:69], 0, s[100:101]
	global_load_dwordx4 v[120:123], v[74:75], off
	global_load_dwordx4 v[124:127], v[74:75], off offset:1024
	s_and_b32 s3, s2, 63
	s_add_i32 s2, s2, 1
	s_mul_i32 s100, s3, 0x2c000
	v_lshl_add_u64 v[74:75], v[68:69], 0, s[100:101]
	global_load_dwordx4 v[128:131], v[74:75], off
	global_load_dwordx4 v[132:135], v[74:75], off offset:1024
	s_and_b32 s3, s2, 63
	s_add_i32 s2, s2, 1
	s_mul_i32 s100, s3, 0x2c000
	v_lshl_add_u64 v[74:75], v[68:69], 0, s[100:101]
	global_load_dwordx4 v[136:139], v[74:75], off
	global_load_dwordx4 v[140:143], v[74:75], off offset:1024
	s_mov_b32 s1, s0
	s_and_b32 s3, s1, 63
	s_lshl_b32 s3, s3, 5
	s_add_i32 s1, s1, 1
	v_add_u32_e32 v73, s3, v0
	v_add_u32_e32 v112, s3, v72
	ds_read_b128 v[144:147], v73
	ds_read_b128 v[148:151], v112
	s_mov_b32 s4, 7
.Lkup2_loop:
	s_and_b32 s3, s1, 63
	s_lshl_b32 s3, s3, 5
	s_add_i32 s1, s1, 1
	v_add_u32_e32 v73, s3, v0
	v_add_u32_e32 v112, s3, v72
	ds_read_b128 v[152:155], v73
	ds_read_b128 v[156:159], v112
	s_waitcnt vmcnt(15) lgkmcnt(2)
	v_mfma_f32_32x32x16_f16 v[50:65], v[144:147], v[76:79], v[50:65]
	v_mfma_f32_32x32x16_f16 v[18:33], v[148:151], v[76:79], v[18:33]
	s_waitcnt vmcnt(14)
	v_mfma_f32_32x32x16_f16 v[34:49], v[144:147], v[80:83], v[34:49]
	v_mfma_f32_32x32x16_f16 v[2:17], v[148:151], v[80:83], v[2:17]
	s_and_b32 s3, s2, 63
	s_add_i32 s2, s2, 1
	s_mul_i32 s100, s3, 0x2c000
	v_lshl_add_u64 v[74:75], v[68:69], 0, s[100:101]
	global_load_dwordx4 v[76:79], v[74:75], off
	global_load_dwordx4 v[80:83], v[74:75], off offset:1024
	s_and_b32 s3, s1, 63
	s_lshl_b32 s3, s3, 5
	s_add_i32 s1, s1, 1
	v_add_u32_e32 v73, s3, v0
	v_add_u32_e32 v112, s3, v72
	ds_read_b128 v[144:147], v73
	ds_read_b128 v[148:151], v112
	s_waitcnt vmcnt(15) lgkmcnt(2)
	v_mfma_f32_32x32x16_f16 v[50:65], v[152:155], v[84:87], v[50:65]
	v_mfma_f32_32x32x16_f16 v[18:33], v[156:159], v[84:87], v[18:33]
	s_waitcnt vmcnt(14)
	v_mfma_f32_32x32x16_f16 v[34:49], v[152:155], v[88:91], v[34:49]
	v_mfma_f32_32x32x16_f16 v[2:17], v[156:159], v[88:91], v[2:17]
	s_and_b32 s3, s2, 63
	s_add_i32 s2, s2, 1
	s_mul_i32 s100, s3, 0x2c000
	v_lshl_add_u64 v[74:75], v[68:69], 0, s[100:101]
	global_load_dwordx4 v[84:87], v[74:75], off
	global_load_dwordx4 v[88:91], v[74:75], off offset:1024
	s_and_b32 s3, s1, 63
	s_lshl_b32 s3, s3, 5
	s_add_i32 s1, s1, 1
	v_add_u32_e32 v73, s3, v0
	v_add_u32_e32 v112, s3, v72
	ds_read_b128 v[152:155], v73
	ds_read_b128 v[156:159], v112
	s_waitcnt vmcnt(15) lgkmcnt(2)
; #define MFMA32(a, b, c) __builtin_amdgcn_mfma_f32_32x32x16_f16((a), (b), (c), 0, 0, 0)
; template <int K, class Epi>
; DI void gemm64_res(const bf16_t* A, int lda, const bf16_t* Wp, int NU, unsigned char* lds, const Epi& epi) {
;     ...
; #pragma unroll 1
;         for (int kk = 0; kk < KS; kk += PD) {
; #pragma unroll
;             for (int s = 0; s < PD; ++s) {
;                 const int ks = kk + s, ksr = (ks + rot) & (KS - 1);
;                 const bf16x8 a0 = *(const bf16x8*)(ab + ksr * 32), a1 = *(const bf16x8*)(ab + 32 * LD + ksr * 32);
; #pragma unroll
;                 for (int j = 0; j < NT; ++j) { acc[0][j] = MFMA32(a0, __builtin_bit_cast(bf16x8, bq[s][j]), acc[0][j]); acc[1][j] = MFMA32(a1, __builtin_bit_cast(bf16x8, bq[s][j]), acc[1][j]); }
;                 int nk = ks + PD; nk = nk < KS ? nk : KS - 1; nk = (nk + rot) & (KS - 1);
; #pragma unroll
;                 for (int j = 0; j < NT; ++j) bq[s][j] = bp[(size_t)nk * kstr + j * 64];
;             }
	v_mfma_f32_32x32x16_f16 v[50:65], v[144:147], v[92:95], v[50:65]
	v_mfma_f32_32x32x16_f16 v[18:33], v[148:151], v[92:95], v[18:33]
	s_waitcnt vmcnt(14)
	v_mfma_f32_32x32x16_f16 v[34:49], v[144:147], v[96:99], v[34:49]
	v_mfma_f32_32x32x16_f16 v[2:17], v[148:151], v[96:99], v[2:17]
	s_and_b32 s3, s2, 63
	s_add_i32 s2, s2, 1
	s_mul_i32 s100, s3, 0x2c000
	v_lshl_add_u64 v[74:75], v[68:69], 0, s[100:101]
	global_load_dwordx4 v[92:95], v[74:75], off
	global_load_dwordx4 v[96:99], v[74:75], off offset:1024
	s_and_b32 s3, s1, 63
	s_lshl_b32 s3, s3, 5
	s_add_i32 s1, s1, 1
	v_add_u32_e32 v73, s3, v0
	v_add_u32_e32 v112, s3, v72
	ds_read_b128 v[144:147], v73
	ds_read_b128 v[148:151], v112
	s_waitcnt vmcnt(15) lgkmcnt(2)
	v_mfma_f32_32x32x16_f16 v[50:65], v[152:155], v[100:103], v[50:65]
	v_mfma_f32_32x32x16_f16 v[18:33], v[156:159], v[100:103], v[18:33]
	s_waitcnt vmcnt(14)
	v_mfma_f32_32x32x16_f16 v[34:49], v[152:155], v[104:107], v[34:49]
	v_mfma_f32_32x32x16_f16 v[2:17], v[156:159], v[104:107], v[2:17]
	s_and_b32 s3, s2, 63
	s_add_i32 s2, s2, 1
	s_mul_i32 s100, s3, 0x2c000
	v_lshl_add_u64 v[74:75], v[68:69], 0, s[100:101]
	global_load_dwordx4 v[100:103], v[74:75], off
	global_load_dwordx4 v[104:107], v[74:75], off offset:1024
	s_and_b32 s3, s1, 63
	s_lshl_b32 s3, s3, 5
	s_add_i32 s1, s1, 1
	v_add_u32_e32 v73, s3, v0
	v_add_u32_e32 v112, s3, v72
	ds_read_b128 v[152:155], v73
	ds_read_b128 v[156:159], v112
	s_waitcnt vmcnt(15) lgkmcnt(2)
	v_mfma_f32_32x32x16_f16 v[50:65], v[144:147], v[108:111], v[50:65]
	v_mfma_f32_32x32x16_f16 v[18:33], v[148:151], v[108:111], v[18:33]
	s_waitcnt vmcnt(14)
	v_mfma_f32_32x32x16_f16 v[34:49], v[144:147], v[116:119], v[34:49]
	v_mfma_f32_32x32x16_f16 v[2:17], v[148:151], v[116:119], v[2:17]
	s_and_b32 s3, s2, 63
	s_add_i32 s2, s2, 1
	s_mul_i32 s100, s3, 0x2c000
	v_lshl_add_u64 v[74:75], v[68:69], 0, s[100:101]
	global_load_dwordx4 v[108:111], v[74:75], off
	global_load_dwordx4 v[116:119], v[74:75], off offset:1024
	s_and_b32 s3, s1, 63
	s_lshl_b32 s3, s3, 5
	s_add_i32 s1, s1, 1
	v_add_u32_e32 v73, s3, v0
	v_add_u32_e32 v112, s3, v72
	ds_read_b128 v[144:147], v73
	ds_read_b128 v[148:151], v112
	s_waitcnt vmcnt(15) lgkmcnt(2)
	v_mfma_f32_32x32x16_f16 v[50:65], v[152:155], v[120:123], v[50:65]
	v_mfma_f32_32x32x16_f16 v[18:33], v[156:159], v[120:123], v[18:33]
	s_waitcnt vmcnt(14)
	v_mfma_f32_32x32x16_f16 v[34:49], v[152:155], v[124:127], v[34:49]
	v_mfma_f32_32x32x16_f16 v[2:17], v[156:159], v[124:127], v[2:17]
	s_and_b32 s3, s2, 63
	s_add_i32 s2, s2, 1
	s_mul_i32 s100, s3, 0x2c000
	v_lshl_add_u64 v[74:75], v[68:69], 0, s[100:101]
	global_load_dwordx4 v[120:123], v[74:75], off
	global_load_dwordx4 v[124:127], v[74:75], off offset:1024
	s_and_b32 s3, s1, 63
	s_lshl_b32 s3, s3, 5
	s_add_i32 s1, s1, 1
	v_add_u32_e32 v73, s3, v0
	v_add_u32_e32 v112, s3, v72
	ds_read_b128 v[152:155], v73
	ds_read_b128 v[156:159], v112
	s_waitcnt vmcnt(15) lgkmcnt(2)
	v_mfma_f32_32x32x16_f16 v[50:65], v[144:147], v[128:131], v[50:65]
	v_mfma_f32_32x32x16_f16 v[18:33], v[148:151], v[128:131], v[18:33]
	s_waitcnt vmcnt(14)
	v_mfma_f32_32x32x16_f16 v[34:49], v[144:147], v[132:135], v[34:49]
	v_mfma_f32_32x32x16_f16 v[2:17], v[148:151], v[132:135], v[2:17]
	s_and_b32 s3, s2, 63
	s_add_i32 s2, s2, 1
	s_mul_i32 s100, s3, 0x2c000
	v_lshl_add_u64 v[74:75], v[68:69], 0, s[100:101]
	global_load_dwordx4 v[128:131], v[74:75], off
	global_load_dwordx4 v[132:135], v[74:75], off offset:1024
	s_and_b32 s3, s1, 63
	s_lshl_b32 s3, s3, 5
	s_add_i32 s1, s1, 1
	v_add_u32_e32 v73, s3, v0
	v_add_u32_e32 v112, s3, v72
	ds_read_b128 v[144:147], v73
	ds_read_b128 v[148:151], v112
	s_waitcnt vmcnt(15) lgkmcnt(2)
	v_mfma_f32_32x32x16_f16 v[50:65], v[152:155], v[136:139], v[50:65]
	v_mfma_f32_32x32x16_f16 v[18:33], v[156:159], v[136:139], v[18:33]
	s_waitcnt vmcnt(14)
	v_mfma_f32_32x32x16_f16 v[34:49], v[152:155], v[140:143], v[34:49]
	v_mfma_f32_32x32x16_f16 v[2:17], v[156:159], v[140:143], v[2:17]
	s_and_b32 s3, s2, 63
	s_add_i32 s2, s2, 1
	s_mul_i32 s100, s3, 0x2c000
	v_lshl_add_u64 v[74:75], v[68:69], 0, s[100:101]
	global_load_dwordx4 v[136:139], v[74:75], off
	global_load_dwordx4 v[140:143], v[74:75], off offset:1024
	s_add_i32 s4, s4, -1
	s_cmp_lg_u32 s4, 0
	s_cbranch_scc1 .Lkup2_loop
; #define MFMA32(a, b, c) __builtin_amdgcn_mfma_f32_32x32x16_f16((a), (b), (c), 0, 0, 0)
; DI int otid() { int t = threadIdx.x; asm volatile("" : "+v"(t)); return t; }
; DI bf16_t cv1(float x) { return (bf16_t)(pk2(x, 0.f) & 0xffffu); }
; DI int crow(int i, int h) { return (i & 3) + 8 * (i >> 2) + 4 * h; }
; template <int K, class Epi>
; DI void gemm64_res(const bf16_t* A, int lda, const bf16_t* Wp, int NU, unsigned char* lds, const Epi& epi) {
;     ...
; #pragma unroll 1
;         for (int kk = 0; kk < KS; kk += PD) {
; #pragma unroll
;             for (int s = 0; s < PD; ++s) {
;                 const int ks = kk + s, ksr = (ks + rot) & (KS - 1);
;                 const bf16x8 a0 = *(const bf16x8*)(ab + ksr * 32), a1 = *(const bf16x8*)(ab + 32 * LD + ksr * 32);
; #pragma unroll
;                 for (int j = 0; j < NT; ++j) { acc[0][j] = MFMA32(a0, __builtin_bit_cast(bf16x8, bq[s][j]), acc[0][j]); acc[1][j] = MFMA32(a1, __builtin_bit_cast(bf16x8, bq[s][j]), acc[1][j]); }
;                 int nk = ks + PD; nk = nk < KS ? nk : KS - 1; nk = (nk + rot) & (KS - 1);
; #pragma unroll
;                 for (int j = 0; j < NT; ++j) bq[s][j] = bp[(size_t)nk * kstr + j * 64];
;             }
; template <int MT> DI void st_bf16(bf16_t* base, int ld, int d2, int col0, const f32x16 (&acc)[MT][NT]) {
;     const int lane = otid() & 63, r = lane & 31, h = lane >> 5;
; #pragma unroll
;     for (int mi = 0; mi < MT; ++mi)
; #pragma unroll
;         for (int nj = 0; nj < NT; ++nj)
; #pragma unroll
;             for (int i = 0; i < 16; ++i) base[(mi * 32 + crow(i, h) + (mi == 2 ? d2 : 0)) * ld + col0 + nj * 32 + r] = cv1(acc[mi][nj][i]);
	s_and_b32 s3, s1, 63
	s_lshl_b32 s3, s3, 5
	s_add_i32 s1, s1, 1
	v_add_u32_e32 v73, s3, v0
	v_add_u32_e32 v112, s3, v72
	ds_read_b128 v[152:155], v73
	ds_read_b128 v[156:159], v112
	s_waitcnt vmcnt(15) lgkmcnt(2)
	v_mfma_f32_32x32x16_f16 v[50:65], v[144:147], v[76:79], v[50:65]
	v_mfma_f32_32x32x16_f16 v[18:33], v[148:151], v[76:79], v[18:33]
	s_waitcnt vmcnt(14)
	v_mfma_f32_32x32x16_f16 v[34:49], v[144:147], v[80:83], v[34:49]
	v_mfma_f32_32x32x16_f16 v[2:17], v[148:151], v[80:83], v[2:17]
	s_and_b32 s3, s1, 63
	s_lshl_b32 s3, s3, 5
	s_add_i32 s1, s1, 1
	v_add_u32_e32 v73, s3, v0
	v_add_u32_e32 v112, s3, v72
	ds_read_b128 v[144:147], v73
	ds_read_b128 v[148:151], v112
	s_waitcnt vmcnt(13) lgkmcnt(2)
	v_mfma_f32_32x32x16_f16 v[50:65], v[152:155], v[84:87], v[50:65]
	v_mfma_f32_32x32x16_f16 v[18:33], v[156:159], v[84:87], v[18:33]
	s_waitcnt vmcnt(12)
	v_mfma_f32_32x32x16_f16 v[34:49], v[152:155], v[88:91], v[34:49]
	v_mfma_f32_32x32x16_f16 v[2:17], v[156:159], v[88:91], v[2:17]
	s_and_b32 s3, s1, 63
	s_lshl_b32 s3, s3, 5
	s_add_i32 s1, s1, 1
	v_add_u32_e32 v73, s3, v0
	v_add_u32_e32 v112, s3, v72
	ds_read_b128 v[152:155], v73
	ds_read_b128 v[156:159], v112
	s_waitcnt vmcnt(11) lgkmcnt(2)
	v_mfma_f32_32x32x16_f16 v[50:65], v[144:147], v[92:95], v[50:65]
	v_mfma_f32_32x32x16_f16 v[18:33], v[148:151], v[92:95], v[18:33]
	s_waitcnt vmcnt(10)
	v_mfma_f32_32x32x16_f16 v[34:49], v[144:147], v[96:99], v[34:49]
	v_mfma_f32_32x32x16_f16 v[2:17], v[148:151], v[96:99], v[2:17]
	s_and_b32 s3, s1, 63
	s_lshl_b32 s3, s3, 5
	s_add_i32 s1, s1, 1
	v_add_u32_e32 v73, s3, v0
	v_add_u32_e32 v112, s3, v72
	ds_read_b128 v[144:147], v73
	ds_read_b128 v[148:151], v112
	s_waitcnt vmcnt(9) lgkmcnt(2)
	v_mfma_f32_32x32x16_f16 v[50:65], v[152:155], v[100:103], v[50:65]
	v_mfma_f32_32x32x16_f16 v[18:33], v[156:159], v[100:103], v[18:33]
	s_waitcnt vmcnt(8)
	v_mfma_f32_32x32x16_f16 v[34:49], v[152:155], v[104:107], v[34:49]
	v_mfma_f32_32x32x16_f16 v[2:17], v[156:159], v[104:107], v[2:17]
	s_and_b32 s3, s1, 63
	s_lshl_b32 s3, s3, 5
	s_add_i32 s1, s1, 1
	v_add_u32_e32 v73, s3, v0
	v_add_u32_e32 v112, s3, v72
	ds_read_b128 v[152:155], v73
	ds_read_b128 v[156:159], v112
	s_waitcnt vmcnt(7) lgkmcnt(2)
	v_mfma_f32_32x32x16_f16 v[50:65], v[144:147], v[108:111], v[50:65]
	v_mfma_f32_32x32x16_f16 v[18:33], v[148:151], v[108:111], v[18:33]
	s_waitcnt vmcnt(6)
	v_mfma_f32_32x32x16_f16 v[34:49], v[144:147], v[116:119], v[34:49]
	v_mfma_f32_32x32x16_f16 v[2:17], v[148:151], v[116:119], v[2:17]
	s_and_b32 s3, s1, 63
	s_lshl_b32 s3, s3, 5
	s_add_i32 s1, s1, 1
	v_add_u32_e32 v73, s3, v0
	v_add_u32_e32 v112, s3, v72
	ds_read_b128 v[144:147], v73
	ds_read_b128 v[148:151], v112
	s_waitcnt vmcnt(5) lgkmcnt(2)
	v_mfma_f32_32x32x16_f16 v[50:65], v[152:155], v[120:123], v[50:65]
	v_mfma_f32_32x32x16_f16 v[18:33], v[156:159], v[120:123], v[18:33]
	s_waitcnt vmcnt(4)
	v_mfma_f32_32x32x16_f16 v[34:49], v[152:155], v[124:127], v[34:49]
	v_mfma_f32_32x32x16_f16 v[2:17], v[156:159], v[124:127], v[2:17]
	s_and_b32 s3, s1, 63
	s_lshl_b32 s3, s3, 5
	s_add_i32 s1, s1, 1
	v_add_u32_e32 v73, s3, v0
	v_add_u32_e32 v112, s3, v72
	ds_read_b128 v[152:155], v73
	ds_read_b128 v[156:159], v112
	s_waitcnt vmcnt(3) lgkmcnt(2)
	v_mfma_f32_32x32x16_f16 v[50:65], v[144:147], v[128:131], v[50:65]
	v_mfma_f32_32x32x16_f16 v[18:33], v[148:151], v[128:131], v[18:33]
	s_waitcnt vmcnt(2)
	v_mfma_f32_32x32x16_f16 v[34:49], v[144:147], v[132:135], v[34:49]
	v_mfma_f32_32x32x16_f16 v[2:17], v[148:151], v[132:135], v[2:17]
	s_waitcnt vmcnt(1) lgkmcnt(0)
	v_mfma_f32_32x32x16_f16 v[50:65], v[152:155], v[136:139], v[50:65]
	v_mfma_f32_32x32x16_f16 v[18:33], v[156:159], v[136:139], v[18:33]
	s_waitcnt vmcnt(0)
	v_mfma_f32_32x32x16_f16 v[34:49], v[152:155], v[140:143], v[34:49]
	v_mfma_f32_32x32x16_f16 v[2:17], v[156:159], v[140:143], v[2:17]
	s_nop 7
	s_nop 3
	v_mov_b32_e32 v68, v176
	s_lshl_b32 s0, s31, 6
	s_nop 4
	v_cvt_f16_f32_e32 v50, v50
	v_lshrrev_b32_e32 v69, 3, v68
	v_and_b32_e32 v70, 4, v69
	v_and_or_b32 v71, v68, 31, s0
	v_mad_u32_u24 v68, v70, s44, v71
	v_ashrrev_i32_e32 v69, 31, v68
	v_lshl_add_u64 v[68:69], v[68:69], 1, s[34:35]
	v_cvt_f16_f32_e32 v74, v51
	v_mad_u32_u24 v75, v70, s44, s44
	global_store_short v[68:69], v50, off
	v_add_u32_e32 v50, v75, v71
	v_ashrrev_i32_e32 v51, 31, v50
	v_lshl_add_u64 v[50:51], v[50:51], 1, s[34:35]
	global_store_short v[50:51], v74, off
	v_cvt_f16_f32_e32 v52, v52
	v_mad_u32_u24 v74, v70, s44, v191
	v_add_u32_e32 v50, v74, v71
	v_ashrrev_i32_e32 v51, 31, v50
	v_lshl_add_u64 v[50:51], v[50:51], 1, s[34:35]
	global_store_short v[50:51], v52, off
	v_cvt_f16_f32_e32 v52, v53
	v_mad_u32_u24 v53, v70, s44, v192
	v_add_u32_e32 v50, v53, v71
	v_ashrrev_i32_e32 v51, 31, v50
	v_lshl_add_u64 v[50:51], v[50:51], 1, s[34:35]
	global_store_short v[50:51], v52, off
	v_cvt_f16_f32_e32 v52, v54
	v_mad_u32_u24 v54, v70, s44, v193
	v_add_u32_e32 v50, v54, v71
	v_ashrrev_i32_e32 v51, 31, v50
	v_lshl_add_u64 v[50:51], v[50:51], 1, s[34:35]
	global_store_short v[50:51], v52, off
	v_cvt_f16_f32_e32 v52, v55
	v_mad_u32_u24 v55, v70, s44, v194
	v_add_u32_e32 v50, v55, v71
	v_ashrrev_i32_e32 v51, 31, v50
	v_lshl_add_u64 v[50:51], v[50:51], 1, s[34:35]
	global_store_short v[50:51], v52, off
	v_cvt_f16_f32_e32 v52, v56
	v_mad_u32_u24 v56, v70, s44, v195
	v_add_u32_e32 v50, v56, v71
	v_ashrrev_i32_e32 v51, 31, v50
	v_lshl_add_u64 v[50:51], v[50:51], 1, s[34:35]
	global_store_short v[50:51], v52, off
	v_cvt_f16_f32_e32 v52, v57
	v_mad_u32_u24 v57, v70, s44, v196
	v_add_u32_e32 v50, v57, v71
	v_ashrrev_i32_e32 v51, 31, v50
	v_lshl_add_u64 v[50:51], v[50:51], 1, s[34:35]
	global_store_short v[50:51], v52, off
; DI int otid() { int t = threadIdx.x; asm volatile("" : "+v"(t)); return t; }
; DI bf16_t cv1(float x) { return (bf16_t)(pk2(x, 0.f) & 0xffffu); }
; DI int crow(int i, int h) { return (i & 3) + 8 * (i >> 2) + 4 * h; }
; template <int MT> DI void st_bf16(bf16_t* base, int ld, int d2, int col0, const f32x16 (&acc)[MT][NT]) {
;     const int lane = otid() & 63, r = lane & 31, h = lane >> 5;
; #pragma unroll
;     for (int mi = 0; mi < MT; ++mi)
; #pragma unroll
;         for (int nj = 0; nj < NT; ++nj)
; #pragma unroll
;             for (int i = 0; i < 16; ++i) base[(mi * 32 + crow(i, h) + (mi == 2 ? d2 : 0)) * ld + col0 + nj * 32 + r] = cv1(acc[mi][nj][i]);
	v_cvt_f16_f32_e32 v52, v58
	v_mad_u32_u24 v58, v70, s44, v197
	v_add_u32_e32 v50, v58, v71
	v_ashrrev_i32_e32 v51, 31, v50
	v_lshl_add_u64 v[50:51], v[50:51], 1, s[34:35]
	global_store_short v[50:51], v52, off
	v_cvt_f16_f32_e32 v52, v59
	v_mad_u32_u24 v59, v70, s44, v198
	v_add_u32_e32 v50, v59, v71
	v_ashrrev_i32_e32 v51, 31, v50
	v_lshl_add_u64 v[50:51], v[50:51], 1, s[34:35]
	global_store_short v[50:51], v52, off
	v_cvt_f16_f32_e32 v52, v60
	v_mad_u32_u24 v60, v70, s44, v199
	v_add_u32_e32 v50, v60, v71
	v_ashrrev_i32_e32 v51, 31, v50
	v_lshl_add_u64 v[50:51], v[50:51], 1, s[34:35]
	global_store_short v[50:51], v52, off
	v_cvt_f16_f32_e32 v52, v61
	v_mad_u32_u24 v61, v70, s44, v200
	v_add_u32_e32 v50, v61, v71
	v_ashrrev_i32_e32 v51, 31, v50
	v_lshl_add_u64 v[50:51], v[50:51], 1, s[34:35]
	global_store_short v[50:51], v52, off
	v_cvt_f16_f32_e32 v52, v62
	v_mad_u32_u24 v62, v70, s44, v201
	v_add_u32_e32 v50, v62, v71
	v_ashrrev_i32_e32 v51, 31, v50
	v_lshl_add_u64 v[50:51], v[50:51], 1, s[34:35]
	global_store_short v[50:51], v52, off
	v_cvt_f16_f32_e32 v52, v63
	v_mad_u32_u24 v63, v70, s44, v202
	v_add_u32_e32 v50, v63, v71
	v_ashrrev_i32_e32 v51, 31, v50
	v_lshl_add_u64 v[50:51], v[50:51], 1, s[34:35]
	global_store_short v[50:51], v52, off
	v_cvt_f16_f32_e32 v52, v64
	v_mad_u32_u24 v64, v70, s44, v203
	v_add_u32_e32 v50, v64, v71
	v_ashrrev_i32_e32 v51, 31, v50
	v_lshl_add_u64 v[50:51], v[50:51], 1, s[34:35]
	global_store_short v[50:51], v52, off
	v_cvt_f16_f32_e32 v52, v65
	v_mad_u32_u24 v65, v70, s44, v204
	v_add_u32_e32 v50, v65, v71
	v_cvt_f16_f32_e32 v34, v34
	v_ashrrev_i32_e32 v51, 31, v50
	v_lshl_add_u64 v[50:51], v[50:51], 1, s[34:35]
	global_store_short v[50:51], v52, off
	v_or_b32_e32 v50, 32, v71
	v_cvt_f16_f32_e32 v51, v35
	global_store_short v[68:69], v34, off offset:64
	v_add_u32_e32 v34, v75, v50
	v_ashrrev_i32_e32 v35, 31, v34
	v_lshl_add_u64 v[34:35], v[34:35], 1, s[34:35]
	v_cvt_f16_f32_e32 v36, v36
	global_store_short v[34:35], v51, off
	v_add_u32_e32 v34, v74, v50
	v_ashrrev_i32_e32 v35, 31, v34
	v_lshl_add_u64 v[34:35], v[34:35], 1, s[34:35]
	global_store_short v[34:35], v36, off
	v_cvt_f16_f32_e32 v36, v37
	v_add_u32_e32 v34, v53, v50
	v_ashrrev_i32_e32 v35, 31, v34
	v_lshl_add_u64 v[34:35], v[34:35], 1, s[34:35]
	global_store_short v[34:35], v36, off
	v_cvt_f16_f32_e32 v36, v38
	v_add_u32_e32 v34, v54, v50
	v_ashrrev_i32_e32 v35, 31, v34
	v_lshl_add_u64 v[34:35], v[34:35], 1, s[34:35]
	global_store_short v[34:35], v36, off
	v_cvt_f16_f32_e32 v36, v39
	v_add_u32_e32 v34, v55, v50
	v_ashrrev_i32_e32 v35, 31, v34
	v_lshl_add_u64 v[34:35], v[34:35], 1, s[34:35]
	global_store_short v[34:35], v36, off
	v_cvt_f16_f32_e32 v36, v40
	v_add_u32_e32 v34, v56, v50
	v_ashrrev_i32_e32 v35, 31, v34
	v_lshl_add_u64 v[34:35], v[34:35], 1, s[34:35]
	global_store_short v[34:35], v36, off
	v_cvt_f16_f32_e32 v36, v41
	v_add_u32_e32 v34, v57, v50
	v_ashrrev_i32_e32 v35, 31, v34
	v_lshl_add_u64 v[34:35], v[34:35], 1, s[34:35]
	global_store_short v[34:35], v36, off
	v_cvt_f16_f32_e32 v36, v42
	v_add_u32_e32 v34, v58, v50
	v_ashrrev_i32_e32 v35, 31, v34
	v_lshl_add_u64 v[34:35], v[34:35], 1, s[34:35]
	global_store_short v[34:35], v36, off
	v_cvt_f16_f32_e32 v36, v43
	v_add_u32_e32 v34, v59, v50
	v_ashrrev_i32_e32 v35, 31, v34
	v_lshl_add_u64 v[34:35], v[34:35], 1, s[34:35]
	global_store_short v[34:35], v36, off
	v_cvt_f16_f32_e32 v36, v44
	v_add_u32_e32 v34, v60, v50
	v_ashrrev_i32_e32 v35, 31, v34
	v_lshl_add_u64 v[34:35], v[34:35], 1, s[34:35]
	global_store_short v[34:35], v36, off
	v_cvt_f16_f32_e32 v36, v45
	v_add_u32_e32 v34, v61, v50
	v_ashrrev_i32_e32 v35, 31, v34
	v_lshl_add_u64 v[34:35], v[34:35], 1, s[34:35]
	global_store_short v[34:35], v36, off
	v_cvt_f16_f32_e32 v36, v46
	v_add_u32_e32 v34, v62, v50
	v_ashrrev_i32_e32 v35, 31, v34
	v_lshl_add_u64 v[34:35], v[34:35], 1, s[34:35]
	global_store_short v[34:35], v36, off
	v_cvt_f16_f32_e32 v36, v47
	v_add_u32_e32 v34, v63, v50
	v_ashrrev_i32_e32 v35, 31, v34
	v_lshl_add_u64 v[34:35], v[34:35], 1, s[34:35]
	global_store_short v[34:35], v36, off
	v_cvt_f16_f32_e32 v36, v48
	v_add_u32_e32 v34, v64, v50
	v_ashrrev_i32_e32 v35, 31, v34
	v_lshl_add_u64 v[34:35], v[34:35], 1, s[34:35]
	global_store_short v[34:35], v36, off
	v_cvt_f16_f32_e32 v36, v49
	v_add_u32_e32 v34, v65, v50
	v_ashrrev_i32_e32 v35, 31, v34
	v_lshl_add_u64 v[34:35], v[34:35], 1, s[34:35]
	global_store_short v[34:35], v36, off
	v_cvt_f16_f32_e32 v18, v18
	v_mad_u32_u24 v36, v70, s44, v205
	v_add_u32_e32 v34, v36, v71
	v_ashrrev_i32_e32 v35, 31, v34
	v_lshl_add_u64 v[34:35], v[34:35], 1, s[34:35]
	global_store_short v[34:35], v18, off
	v_cvt_f16_f32_e32 v34, v19
	v_mad_u32_u24 v35, v70, s44, v206
	v_add_u32_e32 v18, v35, v71
	v_ashrrev_i32_e32 v19, 31, v18
	v_lshl_add_u64 v[18:19], v[18:19], 1, s[34:35]
	global_store_short v[18:19], v34, off
	v_cvt_f16_f32_e32 v20, v20
	v_mad_u32_u24 v34, v70, s44, v207
	v_add_u32_e32 v18, v34, v71
	v_ashrrev_i32_e32 v19, 31, v18
	v_mul_u32_u24_e32 v73, 0x1600, v70
	v_lshl_add_u64 v[18:19], v[18:19], 1, s[34:35]
	global_store_short v[18:19], v20, off
	v_cvt_f16_f32_e32 v20, v21
	v_or_b32_e32 v21, 0x30200, v73
	v_add_u32_e32 v18, v21, v71
	v_ashrrev_i32_e32 v19, 31, v18
	v_lshl_add_u64 v[18:19], v[18:19], 1, s[34:35]
	global_store_short v[18:19], v20, off
	v_cvt_f16_f32_e32 v20, v22
	v_mad_u32_u24 v22, v70, s44, v208
	v_add_u32_e32 v18, v22, v71
	v_ashrrev_i32_e32 v19, 31, v18
	v_lshl_add_u64 v[18:19], v[18:19], 1, s[34:35]
	global_store_short v[18:19], v20, off
	v_cvt_f16_f32_e32 v20, v23
; DI int otid() { int t = threadIdx.x; asm volatile("" : "+v"(t)); return t; }
; DI bf16_t cv1(float x) { return (bf16_t)(pk2(x, 0.f) & 0xffffu); }
; DI int crow(int i, int h) { return (i & 3) + 8 * (i >> 2) + 4 * h; }
; template <int MT> DI void st_bf16(bf16_t* base, int ld, int d2, int col0, const f32x16 (&acc)[MT][NT]) {
;     const int lane = otid() & 63, r = lane & 31, h = lane >> 5;
; #pragma unroll
;     for (int mi = 0; mi < MT; ++mi)
; #pragma unroll
;         for (int nj = 0; nj < NT; ++nj)
; #pragma unroll
;             for (int i = 0; i < 16; ++i) base[(mi * 32 + crow(i, h) + (mi == 2 ? d2 : 0)) * ld + col0 + nj * 32 + r] = cv1(acc[mi][nj][i]);
;     DI void operator()(int unit, const f32x16 (&acc)[MT][NT]) const {
;     ...
;         const int lane = otid() & 63, r = lane & 31, h = lane >> 5;
; #pragma unroll
;         for (int mi = 1; mi < MT; ++mi)
; #pragma unroll
;             for (int nj = 0; nj < NT; ++nj)
; #pragma unroll
;                 for (int i = 0; i < 16; ++i) {
;                     const int lr = mi * 32 + crow(i, h), c = unit * UW + nj * 32 + r;
;                     if (mi == 1) { if (lr >= 62) { halo[(lr - 62) * DFF2 + c] = acc[mi][nj][i]; if (pconv) pconv[(lr - 62) * DFF2 + c] = acc[mi][nj][i]; } }
;                     else if ((lr & 15) >= 14) sconv[(((lr - 64) >> 4) * 2 + ((lr & 15) - 14)) * DFF2 + c] = acc[mi][nj][i];
;                 }
	v_or_b32_e32 v23, 0x38600, v73
	v_add_u32_e32 v18, v23, v71
	v_ashrrev_i32_e32 v19, 31, v18
	v_lshl_add_u64 v[18:19], v[18:19], 1, s[34:35]
	global_store_short v[18:19], v20, off
	v_cvt_f16_f32_e32 v20, v24
	v_mad_u32_u24 v24, v70, s44, v209
	v_add_u32_e32 v18, v24, v71
	v_ashrrev_i32_e32 v19, 31, v18
	v_lshl_add_u64 v[18:19], v[18:19], 1, s[34:35]
	global_store_short v[18:19], v20, off
	v_cvt_f16_f32_e32 v20, v25
	v_mad_u32_u24 v25, v70, s44, v210
	v_add_u32_e32 v18, v25, v71
	v_ashrrev_i32_e32 v19, 31, v18
	v_lshl_add_u64 v[18:19], v[18:19], 1, s[34:35]
	global_store_short v[18:19], v20, off
	v_cvt_f16_f32_e32 v20, v26
	v_mad_u32_u24 v26, v70, s44, v211
	v_add_u32_e32 v18, v26, v71
	v_ashrrev_i32_e32 v19, 31, v18
	v_lshl_add_u64 v[18:19], v[18:19], 1, s[34:35]
	global_store_short v[18:19], v20, off
	v_cvt_f16_f32_e32 v20, v27
	v_mad_u32_u24 v27, v70, s44, v212
	v_add_u32_e32 v18, v27, v71
	v_ashrrev_i32_e32 v19, 31, v18
	v_lshl_add_u64 v[18:19], v[18:19], 1, s[34:35]
	global_store_short v[18:19], v20, off
	v_cvt_f16_f32_e32 v20, v28
	v_mad_u32_u24 v28, v70, s44, v213
	v_add_u32_e32 v18, v28, v71
	v_ashrrev_i32_e32 v19, 31, v18
	v_lshl_add_u64 v[18:19], v[18:19], 1, s[34:35]
	global_store_short v[18:19], v20, off
	v_cvt_f16_f32_e32 v20, v29
	v_mad_u32_u24 v29, v70, s44, v214
	v_add_u32_e32 v18, v29, v71
	v_ashrrev_i32_e32 v19, 31, v18
	v_lshl_add_u64 v[18:19], v[18:19], 1, s[34:35]
	global_store_short v[18:19], v20, off
	v_cvt_f16_f32_e32 v20, v30
	v_mad_u32_u24 v30, v70, s44, v215
	v_add_u32_e32 v18, v30, v71
	v_ashrrev_i32_e32 v19, 31, v18
	v_lshl_add_u64 v[18:19], v[18:19], 1, s[34:35]
	global_store_short v[18:19], v20, off
	v_cvt_f16_f32_e32 v20, v31
	v_mad_u32_u24 v31, v70, s44, v216
	v_add_u32_e32 v18, v31, v71
	v_ashrrev_i32_e32 v19, 31, v18
	v_lshl_add_u64 v[18:19], v[18:19], 1, s[34:35]
	global_store_short v[18:19], v20, off
	v_cvt_f16_f32_e32 v20, v32
	v_mad_u32_u24 v37, v70, s44, v217
	v_add_u32_e32 v18, v37, v71
	v_ashrrev_i32_e32 v19, 31, v18
	v_lshl_add_u64 v[18:19], v[18:19], 1, s[34:35]
	global_store_short v[18:19], v20, off
	v_cvt_f16_f32_e32 v20, v33
	v_mad_u32_u24 v38, v70, s44, v218
	v_add_u32_e32 v18, v38, v71
	v_ashrrev_i32_e32 v19, 31, v18
	v_lshl_add_u64 v[18:19], v[18:19], 1, s[34:35]
	v_cvt_f16_f32_e32 v2, v2
	global_store_short v[18:19], v20, off
	v_add_u32_e32 v18, v36, v50
	v_ashrrev_i32_e32 v19, 31, v18
	v_lshl_add_u64 v[18:19], v[18:19], 1, s[34:35]
	global_store_short v[18:19], v2, off
	v_cvt_f16_f32_e32 v18, v3
	v_add_u32_e32 v2, v35, v50
	v_ashrrev_i32_e32 v3, 31, v2
	v_lshl_add_u64 v[2:3], v[2:3], 1, s[34:35]
	v_cvt_f16_f32_e32 v4, v4
	global_store_short v[2:3], v18, off
	v_add_u32_e32 v2, v34, v50
	v_ashrrev_i32_e32 v3, 31, v2
	v_lshl_add_u64 v[2:3], v[2:3], 1, s[34:35]
	global_store_short v[2:3], v4, off
	v_cvt_f16_f32_e32 v4, v5
	v_add_u32_e32 v2, v21, v50
	v_ashrrev_i32_e32 v3, 31, v2
	v_lshl_add_u64 v[2:3], v[2:3], 1, s[34:35]
	global_store_short v[2:3], v4, off
	v_cvt_f16_f32_e32 v4, v6
	v_add_u32_e32 v2, v22, v50
	v_ashrrev_i32_e32 v3, 31, v2
	v_lshl_add_u64 v[2:3], v[2:3], 1, s[34:35]
	global_store_short v[2:3], v4, off
	v_cvt_f16_f32_e32 v4, v7
	v_add_u32_e32 v2, v23, v50
	v_ashrrev_i32_e32 v3, 31, v2
	v_lshl_add_u64 v[2:3], v[2:3], 1, s[34:35]
	global_store_short v[2:3], v4, off
	v_cvt_f16_f32_e32 v4, v8
	v_add_u32_e32 v2, v24, v50
	v_ashrrev_i32_e32 v3, 31, v2
	v_lshl_add_u64 v[2:3], v[2:3], 1, s[34:35]
	global_store_short v[2:3], v4, off
	v_cvt_f16_f32_e32 v4, v9
	v_add_u32_e32 v2, v25, v50
	v_ashrrev_i32_e32 v3, 31, v2
	v_lshl_add_u64 v[2:3], v[2:3], 1, s[34:35]
	global_store_short v[2:3], v4, off
	v_cvt_f16_f32_e32 v4, v10
	v_add_u32_e32 v2, v26, v50
	v_ashrrev_i32_e32 v3, 31, v2
	v_lshl_add_u64 v[2:3], v[2:3], 1, s[34:35]
	global_store_short v[2:3], v4, off
	v_cvt_f16_f32_e32 v4, v11
	v_add_u32_e32 v2, v27, v50
	v_ashrrev_i32_e32 v3, 31, v2
	v_lshl_add_u64 v[2:3], v[2:3], 1, s[34:35]
	global_store_short v[2:3], v4, off
	v_cvt_f16_f32_e32 v4, v12
	v_add_u32_e32 v2, v28, v50
	v_ashrrev_i32_e32 v3, 31, v2
	v_lshl_add_u64 v[2:3], v[2:3], 1, s[34:35]
	global_store_short v[2:3], v4, off
	v_cvt_f16_f32_e32 v4, v13
	v_add_u32_e32 v2, v29, v50
	v_ashrrev_i32_e32 v3, 31, v2
	v_lshl_add_u64 v[2:3], v[2:3], 1, s[34:35]
	global_store_short v[2:3], v4, off
	v_cvt_f16_f32_e32 v4, v14
	v_add_u32_e32 v2, v30, v50
	v_ashrrev_i32_e32 v3, 31, v2
	v_lshl_add_u64 v[2:3], v[2:3], 1, s[34:35]
	global_store_short v[2:3], v4, off
	v_cvt_f16_f32_e32 v4, v15
	v_add_u32_e32 v2, v31, v50
	v_ashrrev_i32_e32 v3, 31, v2
	v_lshl_add_u64 v[2:3], v[2:3], 1, s[34:35]
	global_store_short v[2:3], v4, off
	v_cvt_f16_f32_e32 v4, v16
	v_add_u32_e32 v2, v37, v50
	v_ashrrev_i32_e32 v3, 31, v2
	v_lshl_add_u64 v[2:3], v[2:3], 1, s[34:35]
	global_store_short v[2:3], v4, off
	v_cvt_f16_f32_e32 v4, v17
	v_add_u32_e32 v2, v38, v50
	v_ashrrev_i32_e32 v3, 31, v2
	v_lshl_add_u64 v[2:3], v[2:3], 1, s[34:35]
	global_store_short v[2:3], v4, off
	v_mov_b32_e32 v2, v176
	s_add_i32 s0, s0, 0xfffd6c00
	v_lshrrev_b32_e32 v3, 3, v2
	v_and_or_b32 v6, v2, 31, s0
	v_and_b32_e32 v2, 32, v2
	v_and_b32_e32 v5, 4, v3
	v_cmp_ne_u32_e64 s[4:5], 0, v2
	v_cndmask_b32_e64 v2, 0, 1, s[28:29]
	v_or_b32_e32 v4, 26, v5
	v_cmp_ne_u32_e64 s[0:1], 1, v2
	s_and_saveexec_b64 s[2:3], s[4:5]
	s_cbranch_execz .LBB0_545
	v_mad_u32_u24 v2, v4, s44, v6
	v_ashrrev_i32_e32 v3, 31, v2
	v_lshl_add_u64 v[8:9], v[2:3], 2, s[8:9]
	s_and_b64 vcc, exec, s[0:1]
	global_store_dword v[8:9], v32, off
	s_cbranch_vccnz .LBB0_545
	v_lshl_add_u64 v[2:3], v[2:3], 2, s[58:59]
	global_store_dword v[2:3], v32, off

; DI int otid() { int t = threadIdx.x; asm volatile("" : "+v"(t)); return t; }
; DI bf16_t cv1(float x) { return (bf16_t)(pk2(x, 0.f) & 0xffffu); }
; DI int crow(int i, int h) { return (i & 3) + 8 * (i >> 2) + 4 * h; }
; template <int MT> DI void st_bf16(bf16_t* base, int ld, int d2, int col0, const f32x16 (&acc)[MT][NT]) {
;     const int lane = otid() & 63, r = lane & 31, h = lane >> 5;
; #pragma unroll
;     for (int mi = 0; mi < MT; ++mi)
; #pragma unroll
;         for (int nj = 0; nj < NT; ++nj)
; #pragma unroll
;             for (int i = 0; i < 16; ++i) base[(mi * 32 + crow(i, h) + (mi == 2 ? d2 : 0)) * ld + col0 + nj * 32 + r] = cv1(acc[mi][nj][i]);
; }
;     DI void operator()(int unit, const f32x16 (&acc)[MT][NT]) const {
;     ...
;         else if (unit < 20) st_bf16<MT>(priv, PRIVW, d2, PC_QB + (unit - 12) * UW, acc);
.LBB0_847:
	s_andn2_saveexec_b64 s[10:11], s[74:75]
	s_cbranch_execz .LBB0_849
	s_waitcnt vmcnt(0)
	v_and_b32_e32 v2, 31, v176
	v_lshrrev_b32_e32 v112, 3, v176
	v_and_b32_e32 v112, 4, v112
	v_mul_u32_u24_e32 v112, 0x2c00, v112
	v_lshl_add_u32 v113, v2, 1, v112
	v_lshl_add_u32 v113, v233, 7, v113
	v_add_u32_e32 v114, -512, v113
	v_cvt_f16_f32_e32 v119, v96
	global_store_short v114, v119, s[58:59]
	v_cvt_f16_f32_e32 v120, v80
	global_store_short v114, v120, s[58:59] offset:64
	v_add_u32_e32 v116, 0x2a00, v113
	v_cvt_f16_f32_e32 v121, v97
	global_store_short v116, v121, s[58:59]
	v_cvt_f16_f32_e32 v122, v81
	global_store_short v116, v122, s[58:59] offset:64
	v_add_u32_e32 v117, 0x5600, v113
	v_cvt_f16_f32_e32 v123, v98
	global_store_short v117, v123, s[58:59]
	v_cvt_f16_f32_e32 v124, v82
	global_store_short v117, v124, s[58:59] offset:64
	v_add_u32_e32 v118, 0x8200, v113
	v_cvt_f16_f32_e32 v125, v99
	global_store_short v118, v125, s[58:59]
	v_cvt_f16_f32_e32 v126, v83
	global_store_short v118, v126, s[58:59] offset:64
	v_add_u32_e32 v114, 0x15e00, v113
	v_cvt_f16_f32_e32 v119, v100
	global_store_short v114, v119, s[58:59]
	v_cvt_f16_f32_e32 v120, v84
	global_store_short v114, v120, s[58:59] offset:64
	v_add_u32_e32 v116, 0x18a00, v113
	v_cvt_f16_f32_e32 v121, v101
	global_store_short v116, v121, s[58:59]
	v_cvt_f16_f32_e32 v122, v85
	global_store_short v116, v122, s[58:59] offset:64
	v_add_u32_e32 v117, 0x1b600, v113
	v_cvt_f16_f32_e32 v123, v102
	global_store_short v117, v123, s[58:59]
	v_cvt_f16_f32_e32 v124, v86
	global_store_short v117, v124, s[58:59] offset:64
	v_add_u32_e32 v118, 0x1e200, v113
	v_cvt_f16_f32_e32 v125, v103
	global_store_short v118, v125, s[58:59]
	v_cvt_f16_f32_e32 v126, v87
	global_store_short v118, v126, s[58:59] offset:64
	v_add_u32_e32 v114, 0x2be00, v113
	v_cvt_f16_f32_e32 v119, v104
	global_store_short v114, v119, s[58:59]
	v_cvt_f16_f32_e32 v120, v88
	global_store_short v114, v120, s[58:59] offset:64
	v_add_u32_e32 v116, 0x2ea00, v113
	v_cvt_f16_f32_e32 v121, v105
	global_store_short v116, v121, s[58:59]
	v_cvt_f16_f32_e32 v122, v89
	global_store_short v116, v122, s[58:59] offset:64
	v_add_u32_e32 v117, 0x31600, v113
	v_cvt_f16_f32_e32 v123, v106
	global_store_short v117, v123, s[58:59]
	v_cvt_f16_f32_e32 v124, v90
	global_store_short v117, v124, s[58:59] offset:64
	v_add_u32_e32 v118, 0x34200, v113
	v_cvt_f16_f32_e32 v125, v107
	global_store_short v118, v125, s[58:59]
	v_cvt_f16_f32_e32 v126, v91
	global_store_short v118, v126, s[58:59] offset:64
	v_add_u32_e32 v114, 0x41e00, v113
	v_cvt_f16_f32_e32 v119, v108
	global_store_short v114, v119, s[58:59]
	v_cvt_f16_f32_e32 v120, v92
	global_store_short v114, v120, s[58:59] offset:64
	v_add_u32_e32 v116, 0x44a00, v113
	v_cvt_f16_f32_e32 v121, v109
	global_store_short v116, v121, s[58:59]
	v_cvt_f16_f32_e32 v122, v93
	global_store_short v116, v122, s[58:59] offset:64
	v_add_u32_e32 v117, 0x47600, v113
	v_cvt_f16_f32_e32 v123, v110
	global_store_short v117, v123, s[58:59]
	v_cvt_f16_f32_e32 v124, v94
	global_store_short v117, v124, s[58:59] offset:64
	v_add_u32_e32 v118, 0x4a200, v113
	v_cvt_f16_f32_e32 v125, v111
	global_store_short v118, v125, s[58:59]
	v_cvt_f16_f32_e32 v126, v95
	global_store_short v118, v126, s[58:59] offset:64
	v_add_u32_e32 v114, 0x57e00, v113
	v_cvt_f16_f32_e32 v119, v64
	global_store_short v114, v119, s[58:59]
	v_cvt_f16_f32_e32 v120, v48
	global_store_short v114, v120, s[58:59] offset:64
	v_add_u32_e32 v116, 0x5aa00, v113
	v_cvt_f16_f32_e32 v121, v65
	global_store_short v116, v121, s[58:59]
	v_cvt_f16_f32_e32 v122, v49
	global_store_short v116, v122, s[58:59] offset:64
	v_add_u32_e32 v117, 0x5d600, v113
	v_cvt_f16_f32_e32 v123, v66
	global_store_short v117, v123, s[58:59]
	v_cvt_f16_f32_e32 v124, v50
	global_store_short v117, v124, s[58:59] offset:64
	v_add_u32_e32 v118, 0x60200, v113
	v_cvt_f16_f32_e32 v125, v67
	global_store_short v118, v125, s[58:59]
	v_cvt_f16_f32_e32 v126, v51
	global_store_short v118, v126, s[58:59] offset:64
	v_add_u32_e32 v114, 0x6de00, v113
	v_cvt_f16_f32_e32 v119, v68
	global_store_short v114, v119, s[58:59]
	v_cvt_f16_f32_e32 v120, v52
	global_store_short v114, v120, s[58:59] offset:64
	v_add_u32_e32 v116, 0x70a00, v113
	v_cvt_f16_f32_e32 v121, v69
	global_store_short v116, v121, s[58:59]
	v_cvt_f16_f32_e32 v122, v53
	global_store_short v116, v122, s[58:59] offset:64
	v_add_u32_e32 v117, 0x73600, v113
	v_cvt_f16_f32_e32 v123, v70
	global_store_short v117, v123, s[58:59]
	v_cvt_f16_f32_e32 v124, v54
	global_store_short v117, v124, s[58:59] offset:64
	v_add_u32_e32 v118, 0x76200, v113
	v_cvt_f16_f32_e32 v125, v71
; DI int otid() { int t = threadIdx.x; asm volatile("" : "+v"(t)); return t; }
; DI bf16_t cv1(float x) { return (bf16_t)(pk2(x, 0.f) & 0xffffu); }
; DI int crow(int i, int h) { return (i & 3) + 8 * (i >> 2) + 4 * h; }
; template <int MT> DI void st_bf16(bf16_t* base, int ld, int d2, int col0, const f32x16 (&acc)[MT][NT]) {
;     const int lane = otid() & 63, r = lane & 31, h = lane >> 5;
; #pragma unroll
;     for (int mi = 0; mi < MT; ++mi)
; #pragma unroll
;         for (int nj = 0; nj < NT; ++nj)
; #pragma unroll
;             for (int i = 0; i < 16; ++i) base[(mi * 32 + crow(i, h) + (mi == 2 ? d2 : 0)) * ld + col0 + nj * 32 + r] = cv1(acc[mi][nj][i]);
; }
;     DI void operator()(int unit, const f32x16 (&acc)[MT][NT]) const {
;     ...
;         else if (unit < 20) st_bf16<MT>(priv, PRIVW, d2, PC_QB + (unit - 12) * UW, acc);
	global_store_short v118, v125, s[58:59]
	v_cvt_f16_f32_e32 v126, v55
	global_store_short v118, v126, s[58:59] offset:64
	v_add_u32_e32 v114, 0x83e00, v113
	v_cvt_f16_f32_e32 v119, v72
	global_store_short v114, v119, s[58:59]
	v_cvt_f16_f32_e32 v120, v56
	global_store_short v114, v120, s[58:59] offset:64
	v_add_u32_e32 v116, 0x86a00, v113
	v_cvt_f16_f32_e32 v121, v73
	global_store_short v116, v121, s[58:59]
	v_cvt_f16_f32_e32 v122, v57
	global_store_short v116, v122, s[58:59] offset:64
	v_add_u32_e32 v117, 0x89600, v113
	v_cvt_f16_f32_e32 v123, v74
	global_store_short v117, v123, s[58:59]
	v_cvt_f16_f32_e32 v124, v58
	global_store_short v117, v124, s[58:59] offset:64
	v_add_u32_e32 v118, 0x8c200, v113
	v_cvt_f16_f32_e32 v125, v75
	global_store_short v118, v125, s[58:59]
	v_cvt_f16_f32_e32 v126, v59
	global_store_short v118, v126, s[58:59] offset:64
	v_add_u32_e32 v114, 0x99e00, v113
	v_cvt_f16_f32_e32 v119, v76
	global_store_short v114, v119, s[58:59]
	v_cvt_f16_f32_e32 v120, v60
	global_store_short v114, v120, s[58:59] offset:64
	v_add_u32_e32 v116, 0x9ca00, v113
	v_cvt_f16_f32_e32 v121, v77
	global_store_short v116, v121, s[58:59]
	v_cvt_f16_f32_e32 v122, v61
	global_store_short v116, v122, s[58:59] offset:64
	v_add_u32_e32 v117, 0x9f600, v113
	v_cvt_f16_f32_e32 v123, v78
	global_store_short v117, v123, s[58:59]
	v_cvt_f16_f32_e32 v124, v62
	global_store_short v117, v124, s[58:59] offset:64
	v_add_u32_e32 v118, 0xa2200, v113
	v_cvt_f16_f32_e32 v125, v79
	global_store_short v118, v125, s[58:59]
	v_cvt_f16_f32_e32 v126, v63
	global_store_short v118, v126, s[58:59] offset:64
	s_sub_i32 s100, 0x4000, s94
	s_mul_i32 s101, s100, 0x2c00
	v_add_u32_e32 v112, s101, v113
	v_add_u32_e32 v114, -512, v112
	v_cvt_f16_f32_e32 v119, v32
	global_store_short v114, v119, s[58:59]
	v_cvt_f16_f32_e32 v120, v16
	global_store_short v114, v120, s[58:59] offset:64
	v_add_u32_e32 v116, 0x2a00, v112
	v_cvt_f16_f32_e32 v121, v33
	global_store_short v116, v121, s[58:59]
	v_cvt_f16_f32_e32 v122, v17
	global_store_short v116, v122, s[58:59] offset:64
	v_add_u32_e32 v117, 0x5600, v112
	v_cvt_f16_f32_e32 v123, v34
	global_store_short v117, v123, s[58:59]
	v_cvt_f16_f32_e32 v124, v18
	global_store_short v117, v124, s[58:59] offset:64
	v_add_u32_e32 v118, 0x8200, v112
	v_cvt_f16_f32_e32 v125, v35
	global_store_short v118, v125, s[58:59]
	v_cvt_f16_f32_e32 v126, v19
	global_store_short v118, v126, s[58:59] offset:64
	v_add_u32_e32 v114, 0x15e00, v112
	v_cvt_f16_f32_e32 v119, v36
	global_store_short v114, v119, s[58:59]
	v_cvt_f16_f32_e32 v120, v20
	global_store_short v114, v120, s[58:59] offset:64
	v_add_u32_e32 v116, 0x18a00, v112
	v_cvt_f16_f32_e32 v121, v37
	global_store_short v116, v121, s[58:59]
	v_cvt_f16_f32_e32 v122, v21
	global_store_short v116, v122, s[58:59] offset:64
	v_add_u32_e32 v117, 0x1b600, v112
	v_cvt_f16_f32_e32 v123, v38
	global_store_short v117, v123, s[58:59]
	v_cvt_f16_f32_e32 v124, v22
	global_store_short v117, v124, s[58:59] offset:64
	v_add_u32_e32 v118, 0x1e200, v112
	v_cvt_f16_f32_e32 v125, v39
	global_store_short v118, v125, s[58:59]
	v_cvt_f16_f32_e32 v126, v23
	global_store_short v118, v126, s[58:59] offset:64
	v_add_u32_e32 v114, 0x2be00, v112
	v_cvt_f16_f32_e32 v119, v40
	global_store_short v114, v119, s[58:59]
	v_cvt_f16_f32_e32 v120, v24
	global_store_short v114, v120, s[58:59] offset:64
	v_add_u32_e32 v116, 0x2ea00, v112
	v_cvt_f16_f32_e32 v121, v41
	global_store_short v116, v121, s[58:59]
	v_cvt_f16_f32_e32 v122, v25
	global_store_short v116, v122, s[58:59] offset:64
	v_add_u32_e32 v117, 0x31600, v112
	v_cvt_f16_f32_e32 v123, v42
	global_store_short v117, v123, s[58:59]
	v_cvt_f16_f32_e32 v124, v26
	global_store_short v117, v124, s[58:59] offset:64
	v_add_u32_e32 v118, 0x34200, v112
	v_cvt_f16_f32_e32 v125, v43
	global_store_short v118, v125, s[58:59]
	v_cvt_f16_f32_e32 v126, v27
	global_store_short v118, v126, s[58:59] offset:64
	v_add_u32_e32 v114, 0x41e00, v112
	v_cvt_f16_f32_e32 v119, v44
	global_store_short v114, v119, s[58:59]
	v_cvt_f16_f32_e32 v120, v28
	global_store_short v114, v120, s[58:59] offset:64
	v_add_u32_e32 v116, 0x44a00, v112
	v_cvt_f16_f32_e32 v121, v45
	global_store_short v116, v121, s[58:59]
	v_cvt_f16_f32_e32 v122, v29
	global_store_short v116, v122, s[58:59] offset:64
	v_add_u32_e32 v117, 0x47600, v112
	v_cvt_f16_f32_e32 v123, v46
	global_store_short v117, v123, s[58:59]
	v_cvt_f16_f32_e32 v124, v30
	global_store_short v117, v124, s[58:59] offset:64
	v_add_u32_e32 v118, 0x4a200, v112
	v_cvt_f16_f32_e32 v125, v47
	global_store_short v118, v125, s[58:59]
	v_cvt_f16_f32_e32 v126, v31
	global_store_short v118, v126, s[58:59] offset:64

; DI int otid() { int t = threadIdx.x; asm volatile("" : "+v"(t)); return t; }
; DI bf16_t cv1(float x) { return (bf16_t)(pk2(x, 0.f) & 0xffffu); }
; DI int crow(int i, int h) { return (i & 3) + 8 * (i >> 2) + 4 * h; }
; template <int MT> DI void st_bf16(bf16_t* base, int ld, int d2, int col0, const f32x16 (&acc)[MT][NT]) {
;     const int lane = otid() & 63, r = lane & 31, h = lane >> 5;
; #pragma unroll
;     for (int mi = 0; mi < MT; ++mi)
; #pragma unroll
;         for (int nj = 0; nj < NT; ++nj)
; #pragma unroll
;             for (int i = 0; i < 16; ++i) base[(mi * 32 + crow(i, h) + (mi == 2 ? d2 : 0)) * ld + col0 + nj * 32 + r] = cv1(acc[mi][nj][i]);
; }
;     DI void operator()(int unit, const f32x16 (&acc)[MT][NT]) const {
;         if (unit < 8) st_bf16<MT>(priv, PRIVW, d2, PC_QA + unit * UW, acc);
.LBB0_856:
	s_andn2_saveexec_b64 s[2:3], s[6:7]
	s_cbranch_execz .LBB0_822
	s_waitcnt vmcnt(0)
	v_and_b32_e32 v2, 31, v176
	v_lshrrev_b32_e32 v112, 3, v176
	v_and_b32_e32 v112, 4, v112
	v_mul_u32_u24_e32 v112, 0x2c00, v112
	v_lshl_add_u32 v113, v2, 1, v112
	v_lshl_add_u32 v113, v233, 7, v113
	v_add_u32_e32 v114, 0, v113
	v_cvt_f16_f32_e32 v119, v96
	global_store_short v114, v119, s[58:59]
	v_cvt_f16_f32_e32 v120, v80
	global_store_short v114, v120, s[58:59] offset:64
	v_add_u32_e32 v116, 0x2c00, v113
	v_cvt_f16_f32_e32 v121, v97
	global_store_short v116, v121, s[58:59]
	v_cvt_f16_f32_e32 v122, v81
	global_store_short v116, v122, s[58:59] offset:64
	v_add_u32_e32 v117, 0x5800, v113
	v_cvt_f16_f32_e32 v123, v98
	global_store_short v117, v123, s[58:59]
	v_cvt_f16_f32_e32 v124, v82
	global_store_short v117, v124, s[58:59] offset:64
	v_add_u32_e32 v118, 0x8400, v113
	v_cvt_f16_f32_e32 v125, v99
	global_store_short v118, v125, s[58:59]
	v_cvt_f16_f32_e32 v126, v83
	global_store_short v118, v126, s[58:59] offset:64
	v_add_u32_e32 v114, 0x16000, v113
	v_cvt_f16_f32_e32 v119, v100
	global_store_short v114, v119, s[58:59]
	v_cvt_f16_f32_e32 v120, v84
	global_store_short v114, v120, s[58:59] offset:64
	v_add_u32_e32 v116, 0x18c00, v113
	v_cvt_f16_f32_e32 v121, v101
	global_store_short v116, v121, s[58:59]
	v_cvt_f16_f32_e32 v122, v85
	global_store_short v116, v122, s[58:59] offset:64
	v_add_u32_e32 v117, 0x1b800, v113
	v_cvt_f16_f32_e32 v123, v102
	global_store_short v117, v123, s[58:59]
	v_cvt_f16_f32_e32 v124, v86
	global_store_short v117, v124, s[58:59] offset:64
	v_add_u32_e32 v118, 0x1e400, v113
	v_cvt_f16_f32_e32 v125, v103
	global_store_short v118, v125, s[58:59]
	v_cvt_f16_f32_e32 v126, v87
	global_store_short v118, v126, s[58:59] offset:64
	v_add_u32_e32 v114, 0x2c000, v113
	v_cvt_f16_f32_e32 v119, v104
	global_store_short v114, v119, s[58:59]
	v_cvt_f16_f32_e32 v120, v88
	global_store_short v114, v120, s[58:59] offset:64
	v_add_u32_e32 v116, 0x2ec00, v113
	v_cvt_f16_f32_e32 v121, v105
	global_store_short v116, v121, s[58:59]
	v_cvt_f16_f32_e32 v122, v89
	global_store_short v116, v122, s[58:59] offset:64
	v_add_u32_e32 v117, 0x31800, v113
	v_cvt_f16_f32_e32 v123, v106
	global_store_short v117, v123, s[58:59]
	v_cvt_f16_f32_e32 v124, v90
	global_store_short v117, v124, s[58:59] offset:64
	v_add_u32_e32 v118, 0x34400, v113
	v_cvt_f16_f32_e32 v125, v107
	global_store_short v118, v125, s[58:59]
	v_cvt_f16_f32_e32 v126, v91
	global_store_short v118, v126, s[58:59] offset:64
	v_add_u32_e32 v114, 0x42000, v113
	v_cvt_f16_f32_e32 v119, v108
	global_store_short v114, v119, s[58:59]
	v_cvt_f16_f32_e32 v120, v92
	global_store_short v114, v120, s[58:59] offset:64
	v_add_u32_e32 v116, 0x44c00, v113
	v_cvt_f16_f32_e32 v121, v109
	global_store_short v116, v121, s[58:59]
	v_cvt_f16_f32_e32 v122, v93
	global_store_short v116, v122, s[58:59] offset:64
	v_add_u32_e32 v117, 0x47800, v113
	v_cvt_f16_f32_e32 v123, v110
	global_store_short v117, v123, s[58:59]
	v_cvt_f16_f32_e32 v124, v94
	global_store_short v117, v124, s[58:59] offset:64
	v_add_u32_e32 v118, 0x4a400, v113
	v_cvt_f16_f32_e32 v125, v111
	global_store_short v118, v125, s[58:59]
	v_cvt_f16_f32_e32 v126, v95
	global_store_short v118, v126, s[58:59] offset:64
	v_add_u32_e32 v114, 0x58000, v113
	v_cvt_f16_f32_e32 v119, v64
	global_store_short v114, v119, s[58:59]
	v_cvt_f16_f32_e32 v120, v48
	global_store_short v114, v120, s[58:59] offset:64
	v_add_u32_e32 v116, 0x5ac00, v113
	v_cvt_f16_f32_e32 v121, v65
	global_store_short v116, v121, s[58:59]
	v_cvt_f16_f32_e32 v122, v49
	global_store_short v116, v122, s[58:59] offset:64
	v_add_u32_e32 v117, 0x5d800, v113
	v_cvt_f16_f32_e32 v123, v66
	global_store_short v117, v123, s[58:59]
	v_cvt_f16_f32_e32 v124, v50
	global_store_short v117, v124, s[58:59] offset:64
	v_add_u32_e32 v118, 0x60400, v113
	v_cvt_f16_f32_e32 v125, v67
	global_store_short v118, v125, s[58:59]
	v_cvt_f16_f32_e32 v126, v51
	global_store_short v118, v126, s[58:59] offset:64
	v_add_u32_e32 v114, 0x6e000, v113
	v_cvt_f16_f32_e32 v119, v68
	global_store_short v114, v119, s[58:59]
	v_cvt_f16_f32_e32 v120, v52
	global_store_short v114, v120, s[58:59] offset:64
	v_add_u32_e32 v116, 0x70c00, v113
	v_cvt_f16_f32_e32 v121, v69
	global_store_short v116, v121, s[58:59]
	v_cvt_f16_f32_e32 v122, v53
	global_store_short v116, v122, s[58:59] offset:64
	v_add_u32_e32 v117, 0x73800, v113
	v_cvt_f16_f32_e32 v123, v70
	global_store_short v117, v123, s[58:59]
	v_cvt_f16_f32_e32 v124, v54
	global_store_short v117, v124, s[58:59] offset:64
	v_add_u32_e32 v118, 0x76400, v113
	v_cvt_f16_f32_e32 v125, v71
	global_store_short v118, v125, s[58:59]
; DI int otid() { int t = threadIdx.x; asm volatile("" : "+v"(t)); return t; }
; DI bf16_t cv1(float x) { return (bf16_t)(pk2(x, 0.f) & 0xffffu); }
; DI int crow(int i, int h) { return (i & 3) + 8 * (i >> 2) + 4 * h; }
; template <int MT> DI void st_bf16(bf16_t* base, int ld, int d2, int col0, const f32x16 (&acc)[MT][NT]) {
;     const int lane = otid() & 63, r = lane & 31, h = lane >> 5;
; #pragma unroll
;     for (int mi = 0; mi < MT; ++mi)
; #pragma unroll
;         for (int nj = 0; nj < NT; ++nj)
; #pragma unroll
;             for (int i = 0; i < 16; ++i) base[(mi * 32 + crow(i, h) + (mi == 2 ? d2 : 0)) * ld + col0 + nj * 32 + r] = cv1(acc[mi][nj][i]);
; }
;     DI void operator()(int unit, const f32x16 (&acc)[MT][NT]) const {
;         if (unit < 8) st_bf16<MT>(priv, PRIVW, d2, PC_QA + unit * UW, acc);
	v_cvt_f16_f32_e32 v126, v55
	global_store_short v118, v126, s[58:59] offset:64
	v_add_u32_e32 v114, 0x84000, v113
	v_cvt_f16_f32_e32 v119, v72
	global_store_short v114, v119, s[58:59]
	v_cvt_f16_f32_e32 v120, v56
	global_store_short v114, v120, s[58:59] offset:64
	v_add_u32_e32 v116, 0x86c00, v113
	v_cvt_f16_f32_e32 v121, v73
	global_store_short v116, v121, s[58:59]
	v_cvt_f16_f32_e32 v122, v57
	global_store_short v116, v122, s[58:59] offset:64
	v_add_u32_e32 v117, 0x89800, v113
	v_cvt_f16_f32_e32 v123, v74
	global_store_short v117, v123, s[58:59]
	v_cvt_f16_f32_e32 v124, v58
	global_store_short v117, v124, s[58:59] offset:64
	v_add_u32_e32 v118, 0x8c400, v113
	v_cvt_f16_f32_e32 v125, v75
	global_store_short v118, v125, s[58:59]
	v_cvt_f16_f32_e32 v126, v59
	global_store_short v118, v126, s[58:59] offset:64
	v_add_u32_e32 v114, 0x9a000, v113
	v_cvt_f16_f32_e32 v119, v76
	global_store_short v114, v119, s[58:59]
	v_cvt_f16_f32_e32 v120, v60
	global_store_short v114, v120, s[58:59] offset:64
	v_add_u32_e32 v116, 0x9cc00, v113
	v_cvt_f16_f32_e32 v121, v77
	global_store_short v116, v121, s[58:59]
	v_cvt_f16_f32_e32 v122, v61
	global_store_short v116, v122, s[58:59] offset:64
	v_add_u32_e32 v117, 0x9f800, v113
	v_cvt_f16_f32_e32 v123, v78
	global_store_short v117, v123, s[58:59]
	v_cvt_f16_f32_e32 v124, v62
	global_store_short v117, v124, s[58:59] offset:64
	v_add_u32_e32 v118, 0xa2400, v113
	v_cvt_f16_f32_e32 v125, v79
	global_store_short v118, v125, s[58:59]
	v_cvt_f16_f32_e32 v126, v63
	global_store_short v118, v126, s[58:59] offset:64
	s_sub_i32 s100, 0x4000, s94
	s_mul_i32 s101, s100, 0x2c00
	v_add_u32_e32 v112, s101, v113
	v_add_u32_e32 v114, 0, v112
	v_cvt_f16_f32_e32 v119, v32
	global_store_short v114, v119, s[58:59]
	v_cvt_f16_f32_e32 v120, v16
	global_store_short v114, v120, s[58:59] offset:64
	v_add_u32_e32 v116, 0x2c00, v112
	v_cvt_f16_f32_e32 v121, v33
	global_store_short v116, v121, s[58:59]
	v_cvt_f16_f32_e32 v122, v17
	global_store_short v116, v122, s[58:59] offset:64
	v_add_u32_e32 v117, 0x5800, v112
	v_cvt_f16_f32_e32 v123, v34
	global_store_short v117, v123, s[58:59]
	v_cvt_f16_f32_e32 v124, v18
	global_store_short v117, v124, s[58:59] offset:64
	v_add_u32_e32 v118, 0x8400, v112
	v_cvt_f16_f32_e32 v125, v35
	global_store_short v118, v125, s[58:59]
	v_cvt_f16_f32_e32 v126, v19
	global_store_short v118, v126, s[58:59] offset:64
	v_add_u32_e32 v114, 0x16000, v112
	v_cvt_f16_f32_e32 v119, v36
	global_store_short v114, v119, s[58:59]
	v_cvt_f16_f32_e32 v120, v20
	global_store_short v114, v120, s[58:59] offset:64
	v_add_u32_e32 v116, 0x18c00, v112
	v_cvt_f16_f32_e32 v121, v37
	global_store_short v116, v121, s[58:59]
	v_cvt_f16_f32_e32 v122, v21
	global_store_short v116, v122, s[58:59] offset:64
	v_add_u32_e32 v117, 0x1b800, v112
	v_cvt_f16_f32_e32 v123, v38
	global_store_short v117, v123, s[58:59]
	v_cvt_f16_f32_e32 v124, v22
	global_store_short v117, v124, s[58:59] offset:64
	v_add_u32_e32 v118, 0x1e400, v112
	v_cvt_f16_f32_e32 v125, v39
	global_store_short v118, v125, s[58:59]
	v_cvt_f16_f32_e32 v126, v23
	global_store_short v118, v126, s[58:59] offset:64
	v_add_u32_e32 v114, 0x2c000, v112
	v_cvt_f16_f32_e32 v119, v40
	global_store_short v114, v119, s[58:59]
	v_cvt_f16_f32_e32 v120, v24
	global_store_short v114, v120, s[58:59] offset:64
	v_add_u32_e32 v116, 0x2ec00, v112
	v_cvt_f16_f32_e32 v121, v41
	global_store_short v116, v121, s[58:59]
	v_cvt_f16_f32_e32 v122, v25
	global_store_short v116, v122, s[58:59] offset:64
	v_add_u32_e32 v117, 0x31800, v112
	v_cvt_f16_f32_e32 v123, v42
	global_store_short v117, v123, s[58:59]
	v_cvt_f16_f32_e32 v124, v26
	global_store_short v117, v124, s[58:59] offset:64
	v_add_u32_e32 v118, 0x34400, v112
	v_cvt_f16_f32_e32 v125, v43
	global_store_short v118, v125, s[58:59]
	v_cvt_f16_f32_e32 v126, v27
	global_store_short v118, v126, s[58:59] offset:64
	v_add_u32_e32 v114, 0x42000, v112
	v_cvt_f16_f32_e32 v119, v44
	global_store_short v114, v119, s[58:59]
	v_cvt_f16_f32_e32 v120, v28
	global_store_short v114, v120, s[58:59] offset:64
	v_add_u32_e32 v116, 0x44c00, v112
	v_cvt_f16_f32_e32 v121, v45
	global_store_short v116, v121, s[58:59]
	v_cvt_f16_f32_e32 v122, v29
	global_store_short v116, v122, s[58:59] offset:64
	v_add_u32_e32 v117, 0x47800, v112
	v_cvt_f16_f32_e32 v123, v46
	global_store_short v117, v123, s[58:59]
	v_cvt_f16_f32_e32 v124, v30
	global_store_short v117, v124, s[58:59] offset:64
	v_add_u32_e32 v118, 0x4a400, v112
	v_cvt_f16_f32_e32 v125, v47
	global_store_short v118, v125, s[58:59]
	v_cvt_f16_f32_e32 v126, v31
	global_store_short v118, v126, s[58:59] offset:64
	s_branch .LBB0_822

; #define MFMA32(a, b, c) __builtin_amdgcn_mfma_f32_32x32x16_f16((a), (b), (c), 0, 0, 0)
; template <int K, class Epi>
; DI void gemm64_res(const bf16_t* A, int lda, const bf16_t* Wp, int NU, unsigned char* lds, const Epi& epi) {
;     ...
;     for (int unit = wave; unit < NU; unit += NWAVE) {
;         const u32x4* bp = Bw + (size_t)(unit * NT) * 64 + lane;
;         f32x16 acc[2][NT];
; #pragma unroll
;         for (int mi = 0; mi < 2; ++mi)
; #pragma unroll
;             for (int nj = 0; nj < NT; ++nj)
; #pragma unroll
;                 for (int i = 0; i < 16; ++i) acc[mi][nj][i] = 0.f;
;         u32x4 bq[PD][NT];
; #pragma unroll
;         for (int s = 0; s < PD; ++s)
; #pragma unroll
;             for (int j = 0; j < NT; ++j) bq[s][j] = bp[(size_t)((s + rot) & (KS - 1)) * kstr + j * 64];
; #pragma unroll 1
;         for (int kk = 0; kk < KS; kk += PD) {
; #pragma unroll
;             for (int s = 0; s < PD; ++s) {
;                 const int ks = kk + s, ksr = (ks + rot) & (KS - 1);
;                 const bf16x8 a0 = *(const bf16x8*)(ab + ksr * 32), a1 = *(const bf16x8*)(ab + 32 * LD + ksr * 32);
; #pragma unroll
;                 for (int j = 0; j < NT; ++j) { acc[0][j] = MFMA32(a0, __builtin_bit_cast(bf16x8, bq[s][j]), acc[0][j]); acc[1][j] = MFMA32(a1, __builtin_bit_cast(bf16x8, bq[s][j]), acc[1][j]); }
;                 int nk = ks + PD; nk = nk < KS ? nk : KS - 1; nk = (nk + rot) & (KS - 1);
; #pragma unroll
;                 for (int j = 0; j < NT; ++j) bq[s][j] = bp[(size_t)nk * kstr + j * 64];
;             }
.LBB0_889:
	s_lshl_b32 s2, s28, 1
	s_ashr_i32 s3, s2, 31
	s_lshl_b64 s[2:3], s[2:3], 10
	v_lshl_add_u64 v[68:69], v[66:67], 0, s[2:3]
	v_readlane_b32 s2, v255, 13
	v_readlane_b32 s3, v255, 14
	s_mov_b32 s3, s65
	s_mov_b32 s10, s2
	v_lshl_add_u64 v[2:3], v[68:69], 0, s[2:3]
	s_mov_b64 s[2:3], 0x22400
	v_writelane_b32 v255, s10, 13
	v_lshl_add_u64 v[70:71], v[2:3], 0, s[2:3]
	v_mov_b32_e32 v2, 0
	v_writelane_b32 v255, s11, 14
	s_mov_b32 s3, -4
	v_readlane_b32 s2, v254, 46
	v_readlane_b32 s85, v253, 40
	v_readlane_b32 s67, v253, 39
	v_readlane_b32 s10, v254, 49
	v_readlane_b32 s11, v254, 48
	v_mov_b32_e32 v3, v2
	v_mov_b32_e32 v4, v2
	v_mov_b32_e32 v5, v2
	v_mov_b32_e32 v6, v2
	v_mov_b32_e32 v7, v2
	v_mov_b32_e32 v8, v2
	v_mov_b32_e32 v9, v2
	v_mov_b32_e32 v10, v2
	v_mov_b32_e32 v11, v2
	v_mov_b32_e32 v12, v2
	v_mov_b32_e32 v13, v2
	v_mov_b32_e32 v14, v2
	v_mov_b32_e32 v15, v2
	v_mov_b32_e32 v16, v2
	v_mov_b32_e32 v17, v2
	v_mov_b32_e32 v18, v2
	v_mov_b32_e32 v19, v2
	v_mov_b32_e32 v20, v2
	v_mov_b32_e32 v21, v2
	v_mov_b32_e32 v22, v2
	v_mov_b32_e32 v23, v2
	v_mov_b32_e32 v24, v2
	v_mov_b32_e32 v25, v2
	v_mov_b32_e32 v26, v2
	v_mov_b32_e32 v27, v2
	v_mov_b32_e32 v28, v2
	v_mov_b32_e32 v29, v2
	v_mov_b32_e32 v30, v2
	v_mov_b32_e32 v31, v2
	v_mov_b32_e32 v32, v2
	v_mov_b32_e32 v33, v2
	v_mov_b32_e32 v34, v2
	v_mov_b32_e32 v35, v2
	v_mov_b32_e32 v36, v2
	v_mov_b32_e32 v37, v2
	v_mov_b32_e32 v38, v2
	v_mov_b32_e32 v39, v2
	v_mov_b32_e32 v40, v2
	v_mov_b32_e32 v41, v2
	v_mov_b32_e32 v42, v2
	v_mov_b32_e32 v43, v2
	v_mov_b32_e32 v44, v2
	v_mov_b32_e32 v45, v2
	v_mov_b32_e32 v46, v2
	v_mov_b32_e32 v47, v2
	v_mov_b32_e32 v48, v2
	v_mov_b32_e32 v49, v2
	v_mov_b32_e32 v50, v2
	v_mov_b32_e32 v51, v2
	v_mov_b32_e32 v52, v2
	v_mov_b32_e32 v53, v2
	v_mov_b32_e32 v54, v2
	v_mov_b32_e32 v55, v2
	v_mov_b32_e32 v56, v2
	v_mov_b32_e32 v57, v2
	v_mov_b32_e32 v58, v2
	v_mov_b32_e32 v59, v2
	v_mov_b32_e32 v60, v2
	v_mov_b32_e32 v61, v2
	v_mov_b32_e32 v62, v2
	v_mov_b32_e32 v63, v2
	v_mov_b32_e32 v64, v2
	v_mov_b32_e32 v65, v2
	v_readlane_b32 s2, v254, 48
	s_nop 3
	s_mov_b32 s101, 0
	s_mov_b32 s64, s2
	s_and_b32 s67, s64, 63
	s_add_i32 s64, s64, 1
	s_mul_i32 s100, s67, 0x22000
	v_lshl_add_u64 v[74:75], v[68:69], 0, s[100:101]
	global_load_dwordx4 v[76:79], v[74:75], off
	global_load_dwordx4 v[80:83], v[74:75], off offset:1024
	s_and_b32 s67, s64, 63
	s_add_i32 s64, s64, 1
	s_mul_i32 s100, s67, 0x22000
	v_lshl_add_u64 v[74:75], v[68:69], 0, s[100:101]
	global_load_dwordx4 v[84:87], v[74:75], off
	global_load_dwordx4 v[88:91], v[74:75], off offset:1024
	s_and_b32 s67, s64, 63
	s_add_i32 s64, s64, 1
	s_mul_i32 s100, s67, 0x22000
	v_lshl_add_u64 v[74:75], v[68:69], 0, s[100:101]
	global_load_dwordx4 v[92:95], v[74:75], off
	global_load_dwordx4 v[96:99], v[74:75], off offset:1024
	s_and_b32 s67, s64, 63
	s_add_i32 s64, s64, 1
	s_mul_i32 s100, s67, 0x22000
	v_lshl_add_u64 v[74:75], v[68:69], 0, s[100:101]
	global_load_dwordx4 v[100:103], v[74:75], off
	global_load_dwordx4 v[104:107], v[74:75], off offset:1024
	s_and_b32 s67, s64, 63
	s_add_i32 s64, s64, 1
	s_mul_i32 s100, s67, 0x22000
	v_lshl_add_u64 v[74:75], v[68:69], 0, s[100:101]
	global_load_dwordx4 v[108:111], v[74:75], off
	global_load_dwordx4 v[116:119], v[74:75], off offset:1024
	s_and_b32 s67, s64, 63
	s_add_i32 s64, s64, 1
	s_mul_i32 s100, s67, 0x22000
	v_lshl_add_u64 v[74:75], v[68:69], 0, s[100:101]
	global_load_dwordx4 v[120:123], v[74:75], off
	global_load_dwordx4 v[124:127], v[74:75], off offset:1024
	s_and_b32 s67, s64, 63
	s_add_i32 s64, s64, 1
	s_mul_i32 s100, s67, 0x22000
	v_lshl_add_u64 v[74:75], v[68:69], 0, s[100:101]
	global_load_dwordx4 v[128:131], v[74:75], off
	global_load_dwordx4 v[132:135], v[74:75], off offset:1024
	s_and_b32 s67, s64, 63
	s_add_i32 s64, s64, 1
	s_mul_i32 s100, s67, 0x22000
	v_lshl_add_u64 v[74:75], v[68:69], 0, s[100:101]
	global_load_dwordx4 v[136:139], v[74:75], off
	global_load_dwordx4 v[140:143], v[74:75], off offset:1024
	s_mov_b32 s3, s2
	s_and_b32 s67, s3, 63
	s_lshl_b32 s67, s67, 5
	s_add_i32 s3, s3, 1
	v_add_u32_e32 v112, s67, v72
	v_add_u32_e32 v113, s67, v73
	ds_read_b128 v[144:147], v112
	ds_read_b128 v[148:151], v113
	s_mov_b32 s85, 7
.Lka2_loop:
	s_and_b32 s67, s3, 63
	s_lshl_b32 s67, s67, 5
	s_add_i32 s3, s3, 1
	v_add_u32_e32 v112, s67, v72
	v_add_u32_e32 v113, s67, v73
	ds_read_b128 v[152:155], v112
	ds_read_b128 v[156:159], v113
	s_waitcnt vmcnt(15) lgkmcnt(2)
	v_mfma_f32_32x32x16_f16 v[50:65], v[144:147], v[76:79], v[50:65]
	v_mfma_f32_32x32x16_f16 v[18:33], v[148:151], v[76:79], v[18:33]
	s_waitcnt vmcnt(14)
	v_mfma_f32_32x32x16_f16 v[34:49], v[144:147], v[80:83], v[34:49]
	v_mfma_f32_32x32x16_f16 v[2:17], v[148:151], v[80:83], v[2:17]
	s_and_b32 s67, s64, 63
	s_add_i32 s64, s64, 1
	s_mul_i32 s100, s67, 0x22000
	v_lshl_add_u64 v[74:75], v[68:69], 0, s[100:101]
	global_load_dwordx4 v[76:79], v[74:75], off
	global_load_dwordx4 v[80:83], v[74:75], off offset:1024
	s_and_b32 s67, s3, 63
	s_lshl_b32 s67, s67, 5
	s_add_i32 s3, s3, 1
	v_add_u32_e32 v112, s67, v72
	v_add_u32_e32 v113, s67, v73
	ds_read_b128 v[144:147], v112
	ds_read_b128 v[148:151], v113
	s_waitcnt vmcnt(15) lgkmcnt(2)
	v_mfma_f32_32x32x16_f16 v[50:65], v[152:155], v[84:87], v[50:65]
	v_mfma_f32_32x32x16_f16 v[18:33], v[156:159], v[84:87], v[18:33]
	s_waitcnt vmcnt(14)
	v_mfma_f32_32x32x16_f16 v[34:49], v[152:155], v[88:91], v[34:49]
	v_mfma_f32_32x32x16_f16 v[2:17], v[156:159], v[88:91], v[2:17]
	s_and_b32 s67, s64, 63
	s_add_i32 s64, s64, 1
	s_mul_i32 s100, s67, 0x22000
	v_lshl_add_u64 v[74:75], v[68:69], 0, s[100:101]
	global_load_dwordx4 v[84:87], v[74:75], off
	global_load_dwordx4 v[88:91], v[74:75], off offset:1024
	s_and_b32 s67, s3, 63
	s_lshl_b32 s67, s67, 5
	s_add_i32 s3, s3, 1
	v_add_u32_e32 v112, s67, v72
	v_add_u32_e32 v113, s67, v73
	ds_read_b128 v[152:155], v112
	ds_read_b128 v[156:159], v113
	s_waitcnt vmcnt(15) lgkmcnt(2)
; #define MFMA32(a, b, c) __builtin_amdgcn_mfma_f32_32x32x16_f16((a), (b), (c), 0, 0, 0)
; template <int K, class Epi>
; DI void gemm64_res(const bf16_t* A, int lda, const bf16_t* Wp, int NU, unsigned char* lds, const Epi& epi) {
;     ...
; #pragma unroll 1
;         for (int kk = 0; kk < KS; kk += PD) {
; #pragma unroll
;             for (int s = 0; s < PD; ++s) {
;                 const int ks = kk + s, ksr = (ks + rot) & (KS - 1);
;                 const bf16x8 a0 = *(const bf16x8*)(ab + ksr * 32), a1 = *(const bf16x8*)(ab + 32 * LD + ksr * 32);
; #pragma unroll
;                 for (int j = 0; j < NT; ++j) { acc[0][j] = MFMA32(a0, __builtin_bit_cast(bf16x8, bq[s][j]), acc[0][j]); acc[1][j] = MFMA32(a1, __builtin_bit_cast(bf16x8, bq[s][j]), acc[1][j]); }
;                 int nk = ks + PD; nk = nk < KS ? nk : KS - 1; nk = (nk + rot) & (KS - 1);
; #pragma unroll
;                 for (int j = 0; j < NT; ++j) bq[s][j] = bp[(size_t)nk * kstr + j * 64];
;             }
	v_mfma_f32_32x32x16_f16 v[50:65], v[144:147], v[92:95], v[50:65]
	v_mfma_f32_32x32x16_f16 v[18:33], v[148:151], v[92:95], v[18:33]
	s_waitcnt vmcnt(14)
	v_mfma_f32_32x32x16_f16 v[34:49], v[144:147], v[96:99], v[34:49]
	v_mfma_f32_32x32x16_f16 v[2:17], v[148:151], v[96:99], v[2:17]
	s_and_b32 s67, s64, 63
	s_add_i32 s64, s64, 1
	s_mul_i32 s100, s67, 0x22000
	v_lshl_add_u64 v[74:75], v[68:69], 0, s[100:101]
	global_load_dwordx4 v[92:95], v[74:75], off
	global_load_dwordx4 v[96:99], v[74:75], off offset:1024
	s_and_b32 s67, s3, 63
	s_lshl_b32 s67, s67, 5
	s_add_i32 s3, s3, 1
	v_add_u32_e32 v112, s67, v72
	v_add_u32_e32 v113, s67, v73
	ds_read_b128 v[144:147], v112
	ds_read_b128 v[148:151], v113
	s_waitcnt vmcnt(15) lgkmcnt(2)
	v_mfma_f32_32x32x16_f16 v[50:65], v[152:155], v[100:103], v[50:65]
	v_mfma_f32_32x32x16_f16 v[18:33], v[156:159], v[100:103], v[18:33]
	s_waitcnt vmcnt(14)
	v_mfma_f32_32x32x16_f16 v[34:49], v[152:155], v[104:107], v[34:49]
	v_mfma_f32_32x32x16_f16 v[2:17], v[156:159], v[104:107], v[2:17]
	s_and_b32 s67, s64, 63
	s_add_i32 s64, s64, 1
	s_mul_i32 s100, s67, 0x22000
	v_lshl_add_u64 v[74:75], v[68:69], 0, s[100:101]
	global_load_dwordx4 v[100:103], v[74:75], off
	global_load_dwordx4 v[104:107], v[74:75], off offset:1024
	s_and_b32 s67, s3, 63
	s_lshl_b32 s67, s67, 5
	s_add_i32 s3, s3, 1
	v_add_u32_e32 v112, s67, v72
	v_add_u32_e32 v113, s67, v73
	ds_read_b128 v[152:155], v112
	ds_read_b128 v[156:159], v113
	s_waitcnt vmcnt(15) lgkmcnt(2)
	v_mfma_f32_32x32x16_f16 v[50:65], v[144:147], v[108:111], v[50:65]
	v_mfma_f32_32x32x16_f16 v[18:33], v[148:151], v[108:111], v[18:33]
	s_waitcnt vmcnt(14)
	v_mfma_f32_32x32x16_f16 v[34:49], v[144:147], v[116:119], v[34:49]
	v_mfma_f32_32x32x16_f16 v[2:17], v[148:151], v[116:119], v[2:17]
	s_and_b32 s67, s64, 63
	s_add_i32 s64, s64, 1
	s_mul_i32 s100, s67, 0x22000
	v_lshl_add_u64 v[74:75], v[68:69], 0, s[100:101]
	global_load_dwordx4 v[108:111], v[74:75], off
	global_load_dwordx4 v[116:119], v[74:75], off offset:1024
	s_and_b32 s67, s3, 63
	s_lshl_b32 s67, s67, 5
	s_add_i32 s3, s3, 1
	v_add_u32_e32 v112, s67, v72
	v_add_u32_e32 v113, s67, v73
	ds_read_b128 v[144:147], v112
	ds_read_b128 v[148:151], v113
	s_waitcnt vmcnt(15) lgkmcnt(2)
	v_mfma_f32_32x32x16_f16 v[50:65], v[152:155], v[120:123], v[50:65]
	v_mfma_f32_32x32x16_f16 v[18:33], v[156:159], v[120:123], v[18:33]
	s_waitcnt vmcnt(14)
	v_mfma_f32_32x32x16_f16 v[34:49], v[152:155], v[124:127], v[34:49]
	v_mfma_f32_32x32x16_f16 v[2:17], v[156:159], v[124:127], v[2:17]
	s_and_b32 s67, s64, 63
	s_add_i32 s64, s64, 1
	s_mul_i32 s100, s67, 0x22000
	v_lshl_add_u64 v[74:75], v[68:69], 0, s[100:101]
	global_load_dwordx4 v[120:123], v[74:75], off
	global_load_dwordx4 v[124:127], v[74:75], off offset:1024
	s_and_b32 s67, s3, 63
	s_lshl_b32 s67, s67, 5
	s_add_i32 s3, s3, 1
	v_add_u32_e32 v112, s67, v72
	v_add_u32_e32 v113, s67, v73
	ds_read_b128 v[152:155], v112
	ds_read_b128 v[156:159], v113
	s_waitcnt vmcnt(15) lgkmcnt(2)
	v_mfma_f32_32x32x16_f16 v[50:65], v[144:147], v[128:131], v[50:65]
	v_mfma_f32_32x32x16_f16 v[18:33], v[148:151], v[128:131], v[18:33]
	s_waitcnt vmcnt(14)
	v_mfma_f32_32x32x16_f16 v[34:49], v[144:147], v[132:135], v[34:49]
	v_mfma_f32_32x32x16_f16 v[2:17], v[148:151], v[132:135], v[2:17]
	s_and_b32 s67, s64, 63
	s_add_i32 s64, s64, 1
	s_mul_i32 s100, s67, 0x22000
	v_lshl_add_u64 v[74:75], v[68:69], 0, s[100:101]
	global_load_dwordx4 v[128:131], v[74:75], off
	global_load_dwordx4 v[132:135], v[74:75], off offset:1024
	s_and_b32 s67, s3, 63
	s_lshl_b32 s67, s67, 5
	s_add_i32 s3, s3, 1
	v_add_u32_e32 v112, s67, v72
	v_add_u32_e32 v113, s67, v73
	ds_read_b128 v[144:147], v112
	ds_read_b128 v[148:151], v113
	s_waitcnt vmcnt(15) lgkmcnt(2)
	v_mfma_f32_32x32x16_f16 v[50:65], v[152:155], v[136:139], v[50:65]
	v_mfma_f32_32x32x16_f16 v[18:33], v[156:159], v[136:139], v[18:33]
	s_waitcnt vmcnt(14)
	v_mfma_f32_32x32x16_f16 v[34:49], v[152:155], v[140:143], v[34:49]
	v_mfma_f32_32x32x16_f16 v[2:17], v[156:159], v[140:143], v[2:17]
	s_and_b32 s67, s64, 63
	s_add_i32 s64, s64, 1
	s_mul_i32 s100, s67, 0x22000
	v_lshl_add_u64 v[74:75], v[68:69], 0, s[100:101]
	global_load_dwordx4 v[136:139], v[74:75], off
	global_load_dwordx4 v[140:143], v[74:75], off offset:1024
	s_add_i32 s85, s85, -1
	s_cmp_lg_u32 s85, 0
	s_cbranch_scc1 .Lka2_loop
; #define MFMA32(a, b, c) __builtin_amdgcn_mfma_f32_32x32x16_f16((a), (b), (c), 0, 0, 0)
; template <int K, class Epi>
; DI void gemm64_res(const bf16_t* A, int lda, const bf16_t* Wp, int NU, unsigned char* lds, const Epi& epi) {
;     ...
; #pragma unroll 1
;         for (int kk = 0; kk < KS; kk += PD) {
; #pragma unroll
;             for (int s = 0; s < PD; ++s) {
;                 const int ks = kk + s, ksr = (ks + rot) & (KS - 1);
;                 const bf16x8 a0 = *(const bf16x8*)(ab + ksr * 32), a1 = *(const bf16x8*)(ab + 32 * LD + ksr * 32);
; #pragma unroll
;                 for (int j = 0; j < NT; ++j) { acc[0][j] = MFMA32(a0, __builtin_bit_cast(bf16x8, bq[s][j]), acc[0][j]); acc[1][j] = MFMA32(a1, __builtin_bit_cast(bf16x8, bq[s][j]), acc[1][j]); }
;                 int nk = ks + PD; nk = nk < KS ? nk : KS - 1; nk = (nk + rot) & (KS - 1);
; #pragma unroll
;                 for (int j = 0; j < NT; ++j) bq[s][j] = bp[(size_t)nk * kstr + j * 64];
;             }
;     DI void operator()(int unit, const f32x16 (&acc)[MT][NT]) const {
;         if (unit < 8) st_bf16<MT>(priv, PRIVW, d2, PC_QA + unit * UW, acc);
;         else if (unit < 10) { st_kp<MT>(ka, 2, 4, unit - 8, 0, tb0, tb2, acc); if (oak) st_f32<0, 2, MT>(oak, 128, (unit - 8) * UW, acc); if (MT == 3) st_f32<2, MT, MT>(sak, 128, (unit - 8) * UW, acc); }
;         else if (unit < 12) { st_vp<MT>(vta, 4, (unit - 10) * 2, tb0, tb2, acc); if (oav) st_f32<0, 2, MT>(oav, 128, (unit - 10) * UW, acc); if (MT == 3) st_f32<2, MT, MT>(sav, 128, (unit - 10) * UW, acc); }
;         else if (unit < 20) st_bf16<MT>(priv, PRIVW, d2, PC_QB + (unit - 12) * UW, acc);
;         else if (unit < 28) { st_kp<MT>(kb, 8, 4, unit - 20, 0, tb0, tb2, acc); if (obk) st_f32<0, 2, MT>(obk, 512, (unit - 20) * UW, acc); if (MT == 3) st_f32<2, MT, MT>(sbk, 512, (unit - 20) * UW, acc); }
;         else if (unit < 36) { st_vp<MT>(vtb, 16, (unit - 28) * 2, tb0, tb2, acc); if (obv) st_f32<0, 2, MT>(obv, 512, (unit - 28) * UW, acc); if (MT == 3) st_f32<2, MT, MT>(sbv, 512, (unit - 28) * UW, acc); }
;         else {
;             const int lane = otid() & 63, r = lane & 31, h = lane >> 5;
;             const int col0 = PC_GA + (unit - 36) * UW;
; #pragma unroll
;             for (int mi = 0; mi < MT; ++mi)
; #pragma unroll
;                 for (int nj = 0; nj < NT; ++nj)
; #pragma unroll
	s_and_b32 s67, s3, 63
	s_lshl_b32 s67, s67, 5
	s_add_i32 s3, s3, 1
	v_add_u32_e32 v112, s67, v72
	v_add_u32_e32 v113, s67, v73
	ds_read_b128 v[152:155], v112
	ds_read_b128 v[156:159], v113
	s_waitcnt vmcnt(15) lgkmcnt(2)
	v_mfma_f32_32x32x16_f16 v[50:65], v[144:147], v[76:79], v[50:65]
	v_mfma_f32_32x32x16_f16 v[18:33], v[148:151], v[76:79], v[18:33]
	s_waitcnt vmcnt(14)
	v_mfma_f32_32x32x16_f16 v[34:49], v[144:147], v[80:83], v[34:49]
	v_mfma_f32_32x32x16_f16 v[2:17], v[148:151], v[80:83], v[2:17]
	s_and_b32 s67, s3, 63
	s_lshl_b32 s67, s67, 5
	s_add_i32 s3, s3, 1
	v_add_u32_e32 v112, s67, v72
	v_add_u32_e32 v113, s67, v73
	ds_read_b128 v[144:147], v112
	ds_read_b128 v[148:151], v113
	s_waitcnt vmcnt(13) lgkmcnt(2)
	v_mfma_f32_32x32x16_f16 v[50:65], v[152:155], v[84:87], v[50:65]
	v_mfma_f32_32x32x16_f16 v[18:33], v[156:159], v[84:87], v[18:33]
	s_waitcnt vmcnt(12)
	v_mfma_f32_32x32x16_f16 v[34:49], v[152:155], v[88:91], v[34:49]
	v_mfma_f32_32x32x16_f16 v[2:17], v[156:159], v[88:91], v[2:17]
	s_and_b32 s67, s3, 63
	s_lshl_b32 s67, s67, 5
	s_add_i32 s3, s3, 1
	v_add_u32_e32 v112, s67, v72
	v_add_u32_e32 v113, s67, v73
	ds_read_b128 v[152:155], v112
	ds_read_b128 v[156:159], v113
	s_waitcnt vmcnt(11) lgkmcnt(2)
	v_mfma_f32_32x32x16_f16 v[50:65], v[144:147], v[92:95], v[50:65]
	v_mfma_f32_32x32x16_f16 v[18:33], v[148:151], v[92:95], v[18:33]
	s_waitcnt vmcnt(10)
	v_mfma_f32_32x32x16_f16 v[34:49], v[144:147], v[96:99], v[34:49]
	v_mfma_f32_32x32x16_f16 v[2:17], v[148:151], v[96:99], v[2:17]
	s_and_b32 s67, s3, 63
	s_lshl_b32 s67, s67, 5
	s_add_i32 s3, s3, 1
	v_add_u32_e32 v112, s67, v72
	v_add_u32_e32 v113, s67, v73
	ds_read_b128 v[144:147], v112
	ds_read_b128 v[148:151], v113
	s_waitcnt vmcnt(9) lgkmcnt(2)
	v_mfma_f32_32x32x16_f16 v[50:65], v[152:155], v[100:103], v[50:65]
	v_mfma_f32_32x32x16_f16 v[18:33], v[156:159], v[100:103], v[18:33]
	s_waitcnt vmcnt(8)
	v_mfma_f32_32x32x16_f16 v[34:49], v[152:155], v[104:107], v[34:49]
	v_mfma_f32_32x32x16_f16 v[2:17], v[156:159], v[104:107], v[2:17]
	s_and_b32 s67, s3, 63
	s_lshl_b32 s67, s67, 5
	s_add_i32 s3, s3, 1
	v_add_u32_e32 v112, s67, v72
	v_add_u32_e32 v113, s67, v73
	ds_read_b128 v[152:155], v112
	ds_read_b128 v[156:159], v113
	s_waitcnt vmcnt(7) lgkmcnt(2)
	v_mfma_f32_32x32x16_f16 v[50:65], v[144:147], v[108:111], v[50:65]
	v_mfma_f32_32x32x16_f16 v[18:33], v[148:151], v[108:111], v[18:33]
	s_waitcnt vmcnt(6)
	v_mfma_f32_32x32x16_f16 v[34:49], v[144:147], v[116:119], v[34:49]
	v_mfma_f32_32x32x16_f16 v[2:17], v[148:151], v[116:119], v[2:17]
	s_and_b32 s67, s3, 63
	s_lshl_b32 s67, s67, 5
	s_add_i32 s3, s3, 1
	v_add_u32_e32 v112, s67, v72
	v_add_u32_e32 v113, s67, v73
	ds_read_b128 v[144:147], v112
	ds_read_b128 v[148:151], v113
	s_waitcnt vmcnt(5) lgkmcnt(2)
	v_mfma_f32_32x32x16_f16 v[50:65], v[152:155], v[120:123], v[50:65]
	v_mfma_f32_32x32x16_f16 v[18:33], v[156:159], v[120:123], v[18:33]
	s_waitcnt vmcnt(4)
	v_mfma_f32_32x32x16_f16 v[34:49], v[152:155], v[124:127], v[34:49]
	v_mfma_f32_32x32x16_f16 v[2:17], v[156:159], v[124:127], v[2:17]
	s_and_b32 s67, s3, 63
	s_lshl_b32 s67, s67, 5
	s_add_i32 s3, s3, 1
	v_add_u32_e32 v112, s67, v72
	v_add_u32_e32 v113, s67, v73
	ds_read_b128 v[152:155], v112
	ds_read_b128 v[156:159], v113
	s_waitcnt vmcnt(3) lgkmcnt(2)
	v_mfma_f32_32x32x16_f16 v[50:65], v[144:147], v[128:131], v[50:65]
	v_mfma_f32_32x32x16_f16 v[18:33], v[148:151], v[128:131], v[18:33]
	s_waitcnt vmcnt(2)
	v_mfma_f32_32x32x16_f16 v[34:49], v[144:147], v[132:135], v[34:49]
	v_mfma_f32_32x32x16_f16 v[2:17], v[148:151], v[132:135], v[2:17]
	s_waitcnt vmcnt(1) lgkmcnt(0)
	v_mfma_f32_32x32x16_f16 v[50:65], v[152:155], v[136:139], v[50:65]
	v_mfma_f32_32x32x16_f16 v[18:33], v[156:159], v[136:139], v[18:33]
	s_waitcnt vmcnt(0)
	v_mfma_f32_32x32x16_f16 v[34:49], v[152:155], v[140:143], v[34:49]
	v_mfma_f32_32x32x16_f16 v[2:17], v[156:159], v[140:143], v[2:17]
	s_nop 7
	s_nop 3
	s_cmp_gt_i32 s28, 7
	s_mov_b64 s[2:3], -1
	s_cbranch_scc0 .LBB0_917
	s_cmp_gt_u32 s28, 9
	s_cbranch_scc0 .LBB0_913
	s_cmp_gt_u32 s28, 11
	s_cbranch_scc0 .LBB0_909
	s_cmp_gt_u32 s28, 19
	s_cbranch_scc0 .LBB0_906
	s_cmp_gt_u32 s28, 27
	s_cbranch_scc0 .LBB0_902
	s_cmp_gt_u32 s28, 35
	s_cbranch_scc0 .LBB0_898
	v_mov_b32_e32 v68, v176
	s_lshl_b32 s2, s28, 6
	s_addk_i32 s2, 0xfb00
	v_lshrrev_b32_e32 v0, 3, v68
	v_and_or_b32 v70, v68, 31, s2
	v_mul_f32_e32 v68, 0xbfb8aa3b, v50
	v_exp_f32_e32 v68, v68
	v_and_b32_e32 v0, 4, v0
	v_add_f32_e32 v68, 1.0, v68
	v_div_scale_f32 v69, s[2:3], v68, v68, 1.0
	v_rcp_f32_e32 v71, v69
	s_nop 0
	v_fma_f32 v74, -v69, v71, 1.0
	v_fmac_f32_e32 v71, v74, v71
	v_div_scale_f32 v74, vcc, 1.0, v68, 1.0
	v_mul_f32_e32 v75, v74, v71
	v_fma_f32 v76, -v69, v75, v74
	v_fmac_f32_e32 v75, v76, v71
	v_fma_f32 v69, -v69, v75, v74
	v_div_fmas_f32 v69, v69, v71, v75
	v_div_fixup_f32 v68, v69, v68, 1.0
	v_cvt_f16_f32_e32 v71, v68
	v_mad_u32_u24 v68, v0, s44, v70
	v_mov_b32_e32 v69, v1
	v_lshl_add_u64 v[68:69], v[68:69], 1, s[94:95]
	global_store_short v[68:69], v71, off
	v_mul_f32_e32 v71, 0xbfb8aa3b, v51
	v_exp_f32_e32 v71, v71
	v_mul_u32_u24_e32 v74, 0x1600, v0
	v_add_f32_e32 v71, 1.0, v71
	v_div_scale_f32 v75, s[2:3], v71, v71, 1.0
	v_rcp_f32_e32 v76, v75
	s_nop 0
	v_fma_f32 v77, -v75, v76, 1.0
	v_fmac_f32_e32 v76, v77, v76
	v_div_scale_f32 v77, vcc, 1.0, v71, 1.0
	v_mul_f32_e32 v78, v77, v76
	v_fma_f32 v79, -v75, v78, v77
	v_fmac_f32_e32 v78, v79, v76
	v_fma_f32 v75, -v75, v78, v77
	v_div_fmas_f32 v75, v75, v76, v78
	v_div_fixup_f32 v71, v75, v71, 1.0
	v_cvt_f16_f32_e32 v71, v71
	v_mad_u32_u24 v75, v0, s44, s44
	v_add_u32_e32 v76, v75, v70
	v_mov_b32_e32 v77, v1
	v_lshl_add_u64 v[76:77], v[76:77], 1, s[94:95]
; DI int otid() { int t = threadIdx.x; asm volatile("" : "+v"(t)); return t; }
; DI bf16_t cv1(float x) { return (bf16_t)(pk2(x, 0.f) & 0xffffu); }
; DI int crow(int i, int h) { return (i & 3) + 8 * (i >> 2) + 4 * h; }
; DI float sigm(float x) { return 1.f / (1.f + __expf(-x)); }
;     DI void operator()(int unit, const f32x16 (&acc)[MT][NT]) const {
;     ...
;         else {
;             const int lane = otid() & 63, r = lane & 31, h = lane >> 5;
;             const int col0 = PC_GA + (unit - 36) * UW;
; #pragma unroll
;             for (int mi = 0; mi < MT; ++mi)
; #pragma unroll
;                 for (int nj = 0; nj < NT; ++nj)
; #pragma unroll
;                     for (int i = 0; i < 16; ++i) priv[(mi * 32 + crow(i, h) + (mi == 2 ? d2 : 0)) * PRIVW + col0 + nj * 32 + r] = cv1(sigm(acc[mi][nj][i]));
;         }
	global_store_short v[76:77], v71, off
	v_mul_f32_e32 v71, 0xbfb8aa3b, v52
	v_exp_f32_e32 v71, v71
	s_nop 0
	v_add_f32_e32 v71, 1.0, v71
	v_div_scale_f32 v76, s[2:3], v71, v71, 1.0
	v_rcp_f32_e32 v77, v76
	s_nop 0
	v_fma_f32 v78, -v76, v77, 1.0
	v_fmac_f32_e32 v77, v78, v77
	v_div_scale_f32 v78, vcc, 1.0, v71, 1.0
	v_mul_f32_e32 v79, v78, v77
	v_fma_f32 v80, -v76, v79, v78
	v_fmac_f32_e32 v79, v80, v77
	v_fma_f32 v76, -v76, v79, v78
	v_div_fmas_f32 v76, v76, v77, v79
	v_div_fixup_f32 v71, v76, v71, 1.0
	v_cvt_f16_f32_e32 v71, v71
	v_mad_u32_u24 v76, v0, s44, v191
	v_add_u32_e32 v78, v76, v70
	v_mov_b32_e32 v79, v1
	v_lshl_add_u64 v[78:79], v[78:79], 1, s[94:95]
	global_store_short v[78:79], v71, off
	v_mul_f32_e32 v71, 0xbfb8aa3b, v53
	v_exp_f32_e32 v71, v71
	s_nop 0
	v_add_f32_e32 v71, 1.0, v71
	v_div_scale_f32 v77, s[2:3], v71, v71, 1.0
	v_rcp_f32_e32 v78, v77
	s_nop 0
	v_fma_f32 v79, -v77, v78, 1.0
	v_fmac_f32_e32 v78, v79, v78
	v_div_scale_f32 v79, vcc, 1.0, v71, 1.0
	v_mul_f32_e32 v80, v79, v78
	v_fma_f32 v81, -v77, v80, v79
	v_fmac_f32_e32 v80, v81, v78
	v_fma_f32 v77, -v77, v80, v79
	v_div_fmas_f32 v77, v77, v78, v80
	v_div_fixup_f32 v71, v77, v71, 1.0
	v_cvt_f16_f32_e32 v71, v71
	v_mad_u32_u24 v77, v0, s44, v192
	v_add_u32_e32 v78, v77, v70
	v_mov_b32_e32 v79, v1
	v_lshl_add_u64 v[78:79], v[78:79], 1, s[94:95]
	global_store_short v[78:79], v71, off
	v_mul_f32_e32 v71, 0xbfb8aa3b, v54
	v_exp_f32_e32 v71, v71
	s_nop 0
	v_add_f32_e32 v71, 1.0, v71
	v_div_scale_f32 v78, s[2:3], v71, v71, 1.0
	v_rcp_f32_e32 v79, v78
	s_nop 0
	v_fma_f32 v80, -v78, v79, 1.0
	v_fmac_f32_e32 v79, v80, v79
	v_div_scale_f32 v80, vcc, 1.0, v71, 1.0
	v_mul_f32_e32 v81, v80, v79
	v_fma_f32 v82, -v78, v81, v80
	v_fmac_f32_e32 v81, v82, v79
	v_fma_f32 v78, -v78, v81, v80
	v_div_fmas_f32 v78, v78, v79, v81
	v_div_fixup_f32 v71, v78, v71, 1.0
	v_cvt_f16_f32_e32 v71, v71
	v_mad_u32_u24 v78, v0, s44, v193
	v_add_u32_e32 v80, v78, v70
	v_mov_b32_e32 v81, v1
	v_lshl_add_u64 v[80:81], v[80:81], 1, s[94:95]
	global_store_short v[80:81], v71, off
	v_mul_f32_e32 v71, 0xbfb8aa3b, v55
	v_exp_f32_e32 v71, v71
	s_nop 0
	v_add_f32_e32 v71, 1.0, v71
	v_div_scale_f32 v79, s[2:3], v71, v71, 1.0
	v_rcp_f32_e32 v80, v79
	s_nop 0
	v_fma_f32 v81, -v79, v80, 1.0
	v_fmac_f32_e32 v80, v81, v80
	v_div_scale_f32 v81, vcc, 1.0, v71, 1.0
	v_mul_f32_e32 v82, v81, v80
	v_fma_f32 v83, -v79, v82, v81
	v_fmac_f32_e32 v82, v83, v80
	v_fma_f32 v79, -v79, v82, v81
	v_div_fmas_f32 v79, v79, v80, v82
	v_div_fixup_f32 v71, v79, v71, 1.0
	v_cvt_f16_f32_e32 v71, v71
	v_mad_u32_u24 v79, v0, s44, v194
	v_add_u32_e32 v80, v79, v70
	v_mov_b32_e32 v81, v1
	v_lshl_add_u64 v[80:81], v[80:81], 1, s[94:95]
	global_store_short v[80:81], v71, off
	v_mul_f32_e32 v71, 0xbfb8aa3b, v56
	v_exp_f32_e32 v71, v71
	s_nop 0
	v_add_f32_e32 v71, 1.0, v71
	v_div_scale_f32 v80, s[2:3], v71, v71, 1.0
	v_rcp_f32_e32 v81, v80
	s_nop 0
	v_fma_f32 v82, -v80, v81, 1.0
	v_fmac_f32_e32 v81, v82, v81
	v_div_scale_f32 v82, vcc, 1.0, v71, 1.0
	v_mul_f32_e32 v83, v82, v81
	v_fma_f32 v84, -v80, v83, v82
	v_fmac_f32_e32 v83, v84, v81
	v_fma_f32 v80, -v80, v83, v82
	v_div_fmas_f32 v80, v80, v81, v83
	v_div_fixup_f32 v71, v80, v71, 1.0
	v_cvt_f16_f32_e32 v71, v71
	v_mad_u32_u24 v80, v0, s44, v195
	v_add_u32_e32 v82, v80, v70
	v_mov_b32_e32 v83, v1
	v_lshl_add_u64 v[82:83], v[82:83], 1, s[94:95]
	global_store_short v[82:83], v71, off
	v_mul_f32_e32 v71, 0xbfb8aa3b, v57
	v_exp_f32_e32 v71, v71
	s_nop 0
	v_add_f32_e32 v71, 1.0, v71
	v_div_scale_f32 v81, s[2:3], v71, v71, 1.0
	v_rcp_f32_e32 v82, v81
	s_nop 0
	v_fma_f32 v83, -v81, v82, 1.0
	v_fmac_f32_e32 v82, v83, v82
	v_div_scale_f32 v83, vcc, 1.0, v71, 1.0
	v_mul_f32_e32 v84, v83, v82
	v_fma_f32 v85, -v81, v84, v83
	v_fmac_f32_e32 v84, v85, v82
	v_fma_f32 v81, -v81, v84, v83
	v_div_fmas_f32 v81, v81, v82, v84
	v_div_fixup_f32 v71, v81, v71, 1.0
	v_cvt_f16_f32_e32 v71, v71
	v_mad_u32_u24 v81, v0, s44, v196
	v_add_u32_e32 v82, v81, v70
	v_mov_b32_e32 v83, v1
	v_lshl_add_u64 v[82:83], v[82:83], 1, s[94:95]
	global_store_short v[82:83], v71, off
	v_mul_f32_e32 v71, 0xbfb8aa3b, v58
	v_exp_f32_e32 v71, v71
	s_nop 0
	v_add_f32_e32 v71, 1.0, v71
	v_div_scale_f32 v82, s[2:3], v71, v71, 1.0
	v_rcp_f32_e32 v83, v82
	s_nop 0
	v_fma_f32 v84, -v82, v83, 1.0
	v_fmac_f32_e32 v83, v84, v83
	v_div_scale_f32 v84, vcc, 1.0, v71, 1.0
	v_mul_f32_e32 v85, v84, v83
	v_fma_f32 v86, -v82, v85, v84
	v_fmac_f32_e32 v85, v86, v83
	v_fma_f32 v82, -v82, v85, v84
	v_div_fmas_f32 v82, v82, v83, v85
	v_div_fixup_f32 v71, v82, v71, 1.0
	v_cvt_f16_f32_e32 v71, v71
	v_mad_u32_u24 v82, v0, s44, v197
	v_add_u32_e32 v84, v82, v70
	v_mov_b32_e32 v85, v1
	v_lshl_add_u64 v[84:85], v[84:85], 1, s[94:95]
	global_store_short v[84:85], v71, off
	v_mul_f32_e32 v71, 0xbfb8aa3b, v59
	v_exp_f32_e32 v71, v71
	s_nop 0
	v_add_f32_e32 v71, 1.0, v71
	v_div_scale_f32 v83, s[2:3], v71, v71, 1.0
	v_rcp_f32_e32 v84, v83
	s_nop 0
	v_fma_f32 v85, -v83, v84, 1.0
	v_fmac_f32_e32 v84, v85, v84
	v_div_scale_f32 v85, vcc, 1.0, v71, 1.0
	v_mul_f32_e32 v86, v85, v84
	v_fma_f32 v87, -v83, v86, v85
	v_fmac_f32_e32 v86, v87, v84
	v_fma_f32 v83, -v83, v86, v85
	v_div_fmas_f32 v83, v83, v84, v86
	v_div_fixup_f32 v71, v83, v71, 1.0
	v_cvt_f16_f32_e32 v71, v71
	v_mad_u32_u24 v83, v0, s44, v198
	v_add_u32_e32 v84, v83, v70
	v_mov_b32_e32 v85, v1
	v_lshl_add_u64 v[84:85], v[84:85], 1, s[94:95]
	global_store_short v[84:85], v71, off
	v_mul_f32_e32 v71, 0xbfb8aa3b, v60
	v_exp_f32_e32 v71, v71
	s_nop 0
	v_add_f32_e32 v71, 1.0, v71
	v_div_scale_f32 v84, s[2:3], v71, v71, 1.0
	v_rcp_f32_e32 v85, v84
	s_nop 0
	v_fma_f32 v86, -v84, v85, 1.0
	v_fmac_f32_e32 v85, v86, v85
; DI int otid() { int t = threadIdx.x; asm volatile("" : "+v"(t)); return t; }
; DI bf16_t cv1(float x) { return (bf16_t)(pk2(x, 0.f) & 0xffffu); }
; DI int crow(int i, int h) { return (i & 3) + 8 * (i >> 2) + 4 * h; }
; DI float sigm(float x) { return 1.f / (1.f + __expf(-x)); }
;     DI void operator()(int unit, const f32x16 (&acc)[MT][NT]) const {
;     ...
;         else {
;             const int lane = otid() & 63, r = lane & 31, h = lane >> 5;
;             const int col0 = PC_GA + (unit - 36) * UW;
; #pragma unroll
;             for (int mi = 0; mi < MT; ++mi)
; #pragma unroll
;                 for (int nj = 0; nj < NT; ++nj)
; #pragma unroll
;                     for (int i = 0; i < 16; ++i) priv[(mi * 32 + crow(i, h) + (mi == 2 ? d2 : 0)) * PRIVW + col0 + nj * 32 + r] = cv1(sigm(acc[mi][nj][i]));
;         }
	v_div_scale_f32 v86, vcc, 1.0, v71, 1.0
	v_mul_f32_e32 v87, v86, v85
	v_fma_f32 v88, -v84, v87, v86
	v_fmac_f32_e32 v87, v88, v85
	v_fma_f32 v84, -v84, v87, v86
	v_div_fmas_f32 v84, v84, v85, v87
	v_div_fixup_f32 v71, v84, v71, 1.0
	v_cvt_f16_f32_e32 v71, v71
	v_mad_u32_u24 v84, v0, s44, v199
	v_add_u32_e32 v86, v84, v70
	v_mov_b32_e32 v87, v1
	v_lshl_add_u64 v[86:87], v[86:87], 1, s[94:95]
	global_store_short v[86:87], v71, off
	v_mul_f32_e32 v71, 0xbfb8aa3b, v61
	v_exp_f32_e32 v71, v71
	s_nop 0
	v_add_f32_e32 v71, 1.0, v71
	v_div_scale_f32 v85, s[2:3], v71, v71, 1.0
	v_rcp_f32_e32 v86, v85
	s_nop 0
	v_fma_f32 v87, -v85, v86, 1.0
	v_fmac_f32_e32 v86, v87, v86
	v_div_scale_f32 v87, vcc, 1.0, v71, 1.0
	v_mul_f32_e32 v88, v87, v86
	v_fma_f32 v89, -v85, v88, v87
	v_fmac_f32_e32 v88, v89, v86
	v_fma_f32 v85, -v85, v88, v87
	v_div_fmas_f32 v85, v85, v86, v88
	v_div_fixup_f32 v71, v85, v71, 1.0
	v_cvt_f16_f32_e32 v71, v71
	v_mad_u32_u24 v85, v0, s44, v200
	v_add_u32_e32 v86, v85, v70
	v_mov_b32_e32 v87, v1
	v_lshl_add_u64 v[86:87], v[86:87], 1, s[94:95]
	global_store_short v[86:87], v71, off
	v_mul_f32_e32 v71, 0xbfb8aa3b, v62
	v_exp_f32_e32 v71, v71
	s_nop 0
	v_add_f32_e32 v71, 1.0, v71
	v_div_scale_f32 v86, s[2:3], v71, v71, 1.0
	v_rcp_f32_e32 v87, v86
	s_nop 0
	v_fma_f32 v88, -v86, v87, 1.0
	v_fmac_f32_e32 v87, v88, v87
	v_div_scale_f32 v88, vcc, 1.0, v71, 1.0
	v_mul_f32_e32 v89, v88, v87
	v_fma_f32 v90, -v86, v89, v88
	v_fmac_f32_e32 v89, v90, v87
	v_fma_f32 v86, -v86, v89, v88
	v_div_fmas_f32 v86, v86, v87, v89
	v_div_fixup_f32 v71, v86, v71, 1.0
	v_cvt_f16_f32_e32 v71, v71
	v_mad_u32_u24 v86, v0, s44, v201
	v_add_u32_e32 v88, v86, v70
	v_mov_b32_e32 v89, v1
	v_lshl_add_u64 v[88:89], v[88:89], 1, s[94:95]
	global_store_short v[88:89], v71, off
	v_mul_f32_e32 v71, 0xbfb8aa3b, v63
	v_exp_f32_e32 v71, v71
	s_nop 0
	v_add_f32_e32 v71, 1.0, v71
	v_div_scale_f32 v87, s[2:3], v71, v71, 1.0
	v_rcp_f32_e32 v88, v87
	s_nop 0
	v_fma_f32 v89, -v87, v88, 1.0
	v_fmac_f32_e32 v88, v89, v88
	v_div_scale_f32 v89, vcc, 1.0, v71, 1.0
	v_mul_f32_e32 v90, v89, v88
	v_fma_f32 v91, -v87, v90, v89
	v_fmac_f32_e32 v90, v91, v88
	v_fma_f32 v87, -v87, v90, v89
	v_div_fmas_f32 v87, v87, v88, v90
	v_div_fixup_f32 v71, v87, v71, 1.0
	v_cvt_f16_f32_e32 v71, v71
	v_mad_u32_u24 v87, v0, s44, v202
	v_add_u32_e32 v88, v87, v70
	v_mov_b32_e32 v89, v1
	v_lshl_add_u64 v[88:89], v[88:89], 1, s[94:95]
	global_store_short v[88:89], v71, off
	v_mul_f32_e32 v71, 0xbfb8aa3b, v64
	v_exp_f32_e32 v71, v71
	s_nop 0
	v_add_f32_e32 v71, 1.0, v71
	v_div_scale_f32 v88, s[2:3], v71, v71, 1.0
	v_rcp_f32_e32 v89, v88
	s_nop 0
	v_fma_f32 v90, -v88, v89, 1.0
	v_fmac_f32_e32 v89, v90, v89
	v_div_scale_f32 v90, vcc, 1.0, v71, 1.0
	v_mul_f32_e32 v91, v90, v89
	v_fma_f32 v92, -v88, v91, v90
	v_fmac_f32_e32 v91, v92, v89
	v_fma_f32 v88, -v88, v91, v90
	v_div_fmas_f32 v88, v88, v89, v91
	v_div_fixup_f32 v71, v88, v71, 1.0
	v_cvt_f16_f32_e32 v71, v71
	v_mad_u32_u24 v88, v0, s44, v203
	v_add_u32_e32 v90, v88, v70
	v_mov_b32_e32 v91, v1
	v_lshl_add_u64 v[90:91], v[90:91], 1, s[94:95]
	global_store_short v[90:91], v71, off
	v_mul_f32_e32 v71, 0xbfb8aa3b, v65
	v_exp_f32_e32 v71, v71
	s_nop 0
	v_add_f32_e32 v71, 1.0, v71
	v_div_scale_f32 v89, s[2:3], v71, v71, 1.0
	v_rcp_f32_e32 v90, v89
	s_nop 0
	v_fma_f32 v91, -v89, v90, 1.0
	v_fmac_f32_e32 v90, v91, v90
	v_div_scale_f32 v91, vcc, 1.0, v71, 1.0
	v_mul_f32_e32 v92, v91, v90
	v_fma_f32 v93, -v89, v92, v91
	v_fmac_f32_e32 v92, v93, v90
	v_fma_f32 v89, -v89, v92, v91
	v_div_fmas_f32 v89, v89, v90, v92
	v_div_fixup_f32 v71, v89, v71, 1.0
	v_cvt_f16_f32_e32 v71, v71
	v_mad_u32_u24 v89, v0, s44, v204
	v_add_u32_e32 v90, v89, v70
	v_mov_b32_e32 v91, v1
	v_lshl_add_u64 v[90:91], v[90:91], 1, s[94:95]
	global_store_short v[90:91], v71, off
	v_mul_f32_e32 v90, 0xbfb8aa3b, v34
	v_exp_f32_e32 v90, v90
	v_or_b32_e32 v71, 32, v70
	v_add_f32_e32 v90, 1.0, v90
	v_div_scale_f32 v91, s[2:3], v90, v90, 1.0
	v_rcp_f32_e32 v92, v91
	s_nop 0
	v_fma_f32 v93, -v91, v92, 1.0
	v_fmac_f32_e32 v92, v93, v92
	v_div_scale_f32 v93, vcc, 1.0, v90, 1.0
	v_mul_f32_e32 v94, v93, v92
	v_fma_f32 v95, -v91, v94, v93
	v_fmac_f32_e32 v94, v95, v92
	v_fma_f32 v91, -v91, v94, v93
	v_div_fmas_f32 v91, v91, v92, v94
	v_div_fixup_f32 v90, v91, v90, 1.0
	v_cvt_f16_f32_e32 v90, v90
	global_store_short v[68:69], v90, off offset:64
	v_mul_f32_e32 v68, 0xbfb8aa3b, v35
	v_exp_f32_e32 v68, v68
	s_nop 0
	v_add_f32_e32 v68, 1.0, v68
	v_div_scale_f32 v69, s[2:3], v68, v68, 1.0
	v_rcp_f32_e32 v90, v69
	s_nop 0
	v_fma_f32 v91, -v69, v90, 1.0
	v_fmac_f32_e32 v90, v91, v90
	v_div_scale_f32 v91, vcc, 1.0, v68, 1.0
	v_mul_f32_e32 v92, v91, v90
	v_fma_f32 v93, -v69, v92, v91
	v_fmac_f32_e32 v92, v93, v90
	v_fma_f32 v69, -v69, v92, v91
	v_div_fmas_f32 v69, v69, v90, v92
	v_div_fixup_f32 v68, v69, v68, 1.0
	v_cvt_f16_f32_e32 v90, v68
	v_add_u32_e32 v68, v75, v71
	v_mov_b32_e32 v69, v1
	v_lshl_add_u64 v[68:69], v[68:69], 1, s[94:95]
	global_store_short v[68:69], v90, off
	v_mul_f32_e32 v68, 0xbfb8aa3b, v36
	v_exp_f32_e32 v68, v68
	s_nop 0
	v_add_f32_e32 v68, 1.0, v68
	v_div_scale_f32 v69, s[2:3], v68, v68, 1.0
	v_rcp_f32_e32 v75, v69
	s_nop 0
	v_fma_f32 v90, -v69, v75, 1.0
	v_fmac_f32_e32 v75, v90, v75
	v_div_scale_f32 v90, vcc, 1.0, v68, 1.0
	v_mul_f32_e32 v91, v90, v75
	v_fma_f32 v92, -v69, v91, v90
	v_fmac_f32_e32 v91, v92, v75
	v_fma_f32 v69, -v69, v91, v90
	v_div_fmas_f32 v69, v69, v75, v91
	v_div_fixup_f32 v68, v69, v68, 1.0
	v_cvt_f16_f32_e32 v75, v68
	v_add_u32_e32 v68, v76, v71
	v_mov_b32_e32 v69, v1
	v_lshl_add_u64 v[68:69], v[68:69], 1, s[94:95]
	global_store_short v[68:69], v75, off
	v_mul_f32_e32 v68, 0xbfb8aa3b, v37
; DI int otid() { int t = threadIdx.x; asm volatile("" : "+v"(t)); return t; }
; DI bf16_t cv1(float x) { return (bf16_t)(pk2(x, 0.f) & 0xffffu); }
; DI int crow(int i, int h) { return (i & 3) + 8 * (i >> 2) + 4 * h; }
; DI float sigm(float x) { return 1.f / (1.f + __expf(-x)); }
;     DI void operator()(int unit, const f32x16 (&acc)[MT][NT]) const {
;     ...
;         else {
;             const int lane = otid() & 63, r = lane & 31, h = lane >> 5;
;             const int col0 = PC_GA + (unit - 36) * UW;
; #pragma unroll
;             for (int mi = 0; mi < MT; ++mi)
; #pragma unroll
;                 for (int nj = 0; nj < NT; ++nj)
; #pragma unroll
;                     for (int i = 0; i < 16; ++i) priv[(mi * 32 + crow(i, h) + (mi == 2 ? d2 : 0)) * PRIVW + col0 + nj * 32 + r] = cv1(sigm(acc[mi][nj][i]));
;         }
	v_exp_f32_e32 v68, v68
	s_nop 0
	v_add_f32_e32 v68, 1.0, v68
	v_div_scale_f32 v69, s[2:3], v68, v68, 1.0
	v_rcp_f32_e32 v75, v69
	s_nop 0
	v_fma_f32 v76, -v69, v75, 1.0
	v_fmac_f32_e32 v75, v76, v75
	v_div_scale_f32 v76, vcc, 1.0, v68, 1.0
	v_mul_f32_e32 v90, v76, v75
	v_fma_f32 v91, -v69, v90, v76
	v_fmac_f32_e32 v90, v91, v75
	v_fma_f32 v69, -v69, v90, v76
	v_div_fmas_f32 v69, v69, v75, v90
	v_div_fixup_f32 v68, v69, v68, 1.0
	v_cvt_f16_f32_e32 v75, v68
	v_add_u32_e32 v68, v77, v71
	v_mov_b32_e32 v69, v1
	v_lshl_add_u64 v[68:69], v[68:69], 1, s[94:95]
	global_store_short v[68:69], v75, off
	v_mul_f32_e32 v68, 0xbfb8aa3b, v38
	v_exp_f32_e32 v68, v68
	s_nop 0
	v_add_f32_e32 v68, 1.0, v68
	v_div_scale_f32 v69, s[2:3], v68, v68, 1.0
	v_rcp_f32_e32 v75, v69
	s_nop 0
	v_fma_f32 v76, -v69, v75, 1.0
	v_fmac_f32_e32 v75, v76, v75
	v_div_scale_f32 v76, vcc, 1.0, v68, 1.0
	v_mul_f32_e32 v77, v76, v75
	v_fma_f32 v90, -v69, v77, v76
	v_fmac_f32_e32 v77, v90, v75
	v_fma_f32 v69, -v69, v77, v76
	v_div_fmas_f32 v69, v69, v75, v77
	v_div_fixup_f32 v68, v69, v68, 1.0
	v_cvt_f16_f32_e32 v75, v68
	v_add_u32_e32 v68, v78, v71
	v_mov_b32_e32 v69, v1
	v_lshl_add_u64 v[68:69], v[68:69], 1, s[94:95]
	global_store_short v[68:69], v75, off
	v_mul_f32_e32 v68, 0xbfb8aa3b, v39
	v_exp_f32_e32 v68, v68
	s_nop 0
	v_add_f32_e32 v68, 1.0, v68
	v_div_scale_f32 v69, s[2:3], v68, v68, 1.0
	v_rcp_f32_e32 v75, v69
	s_nop 0
	v_fma_f32 v76, -v69, v75, 1.0
	v_fmac_f32_e32 v75, v76, v75
	v_div_scale_f32 v76, vcc, 1.0, v68, 1.0
	v_mul_f32_e32 v77, v76, v75
	v_fma_f32 v78, -v69, v77, v76
	v_fmac_f32_e32 v77, v78, v75
	v_fma_f32 v69, -v69, v77, v76
	v_div_fmas_f32 v69, v69, v75, v77
	v_div_fixup_f32 v68, v69, v68, 1.0
	v_cvt_f16_f32_e32 v75, v68
	v_add_u32_e32 v68, v79, v71
	v_mov_b32_e32 v69, v1
	v_lshl_add_u64 v[68:69], v[68:69], 1, s[94:95]
	global_store_short v[68:69], v75, off
	v_mul_f32_e32 v68, 0xbfb8aa3b, v40
	v_exp_f32_e32 v68, v68
	s_nop 0
	v_add_f32_e32 v68, 1.0, v68
	v_div_scale_f32 v69, s[2:3], v68, v68, 1.0
	v_rcp_f32_e32 v75, v69
	s_nop 0
	v_fma_f32 v76, -v69, v75, 1.0
	v_fmac_f32_e32 v75, v76, v75
	v_div_scale_f32 v76, vcc, 1.0, v68, 1.0
	v_mul_f32_e32 v77, v76, v75
	v_fma_f32 v78, -v69, v77, v76
	v_fmac_f32_e32 v77, v78, v75
	v_fma_f32 v69, -v69, v77, v76
	v_div_fmas_f32 v69, v69, v75, v77
	v_div_fixup_f32 v68, v69, v68, 1.0
	v_cvt_f16_f32_e32 v75, v68
	v_add_u32_e32 v68, v80, v71
	v_mov_b32_e32 v69, v1
	v_lshl_add_u64 v[68:69], v[68:69], 1, s[94:95]
	global_store_short v[68:69], v75, off
	v_mul_f32_e32 v68, 0xbfb8aa3b, v41
	v_exp_f32_e32 v68, v68
	s_nop 0
	v_add_f32_e32 v68, 1.0, v68
	v_div_scale_f32 v69, s[2:3], v68, v68, 1.0
	v_rcp_f32_e32 v75, v69
	s_nop 0
	v_fma_f32 v76, -v69, v75, 1.0
	v_fmac_f32_e32 v75, v76, v75
	v_div_scale_f32 v76, vcc, 1.0, v68, 1.0
	v_mul_f32_e32 v77, v76, v75
	v_fma_f32 v78, -v69, v77, v76
	v_fmac_f32_e32 v77, v78, v75
	v_fma_f32 v69, -v69, v77, v76
	v_div_fmas_f32 v69, v69, v75, v77
	v_div_fixup_f32 v68, v69, v68, 1.0
	v_cvt_f16_f32_e32 v75, v68
	v_add_u32_e32 v68, v81, v71
	v_mov_b32_e32 v69, v1
	v_lshl_add_u64 v[68:69], v[68:69], 1, s[94:95]
	global_store_short v[68:69], v75, off
	v_mul_f32_e32 v68, 0xbfb8aa3b, v42
	v_exp_f32_e32 v68, v68
	s_nop 0
	v_add_f32_e32 v68, 1.0, v68
	v_div_scale_f32 v69, s[2:3], v68, v68, 1.0
	v_rcp_f32_e32 v75, v69
	s_nop 0
	v_fma_f32 v76, -v69, v75, 1.0
	v_fmac_f32_e32 v75, v76, v75
	v_div_scale_f32 v76, vcc, 1.0, v68, 1.0
	v_mul_f32_e32 v77, v76, v75
	v_fma_f32 v78, -v69, v77, v76
	v_fmac_f32_e32 v77, v78, v75
	v_fma_f32 v69, -v69, v77, v76
	v_div_fmas_f32 v69, v69, v75, v77
	v_div_fixup_f32 v68, v69, v68, 1.0
	v_cvt_f16_f32_e32 v75, v68
	v_add_u32_e32 v68, v82, v71
	v_mov_b32_e32 v69, v1
	v_lshl_add_u64 v[68:69], v[68:69], 1, s[94:95]
	global_store_short v[68:69], v75, off
	v_mul_f32_e32 v68, 0xbfb8aa3b, v43
	v_exp_f32_e32 v68, v68
	s_nop 0
	v_add_f32_e32 v68, 1.0, v68
	v_div_scale_f32 v69, s[2:3], v68, v68, 1.0
	v_rcp_f32_e32 v75, v69
	s_nop 0
	v_fma_f32 v76, -v69, v75, 1.0
	v_fmac_f32_e32 v75, v76, v75
	v_div_scale_f32 v76, vcc, 1.0, v68, 1.0
	v_mul_f32_e32 v77, v76, v75
	v_fma_f32 v78, -v69, v77, v76
	v_fmac_f32_e32 v77, v78, v75
	v_fma_f32 v69, -v69, v77, v76
	v_div_fmas_f32 v69, v69, v75, v77
	v_div_fixup_f32 v68, v69, v68, 1.0
	v_cvt_f16_f32_e32 v75, v68
	v_add_u32_e32 v68, v83, v71
	v_mov_b32_e32 v69, v1
	v_lshl_add_u64 v[68:69], v[68:69], 1, s[94:95]
	global_store_short v[68:69], v75, off
	v_mul_f32_e32 v68, 0xbfb8aa3b, v44
	v_exp_f32_e32 v68, v68
	s_nop 0
	v_add_f32_e32 v68, 1.0, v68
	v_div_scale_f32 v69, s[2:3], v68, v68, 1.0
	v_rcp_f32_e32 v75, v69
	s_nop 0
	v_fma_f32 v76, -v69, v75, 1.0
	v_fmac_f32_e32 v75, v76, v75
	v_div_scale_f32 v76, vcc, 1.0, v68, 1.0
	v_mul_f32_e32 v77, v76, v75
	v_fma_f32 v78, -v69, v77, v76
	v_fmac_f32_e32 v77, v78, v75
	v_fma_f32 v69, -v69, v77, v76
	v_div_fmas_f32 v69, v69, v75, v77
	v_div_fixup_f32 v68, v69, v68, 1.0
	v_cvt_f16_f32_e32 v75, v68
	v_add_u32_e32 v68, v84, v71
	v_mov_b32_e32 v69, v1
	v_lshl_add_u64 v[68:69], v[68:69], 1, s[94:95]
	global_store_short v[68:69], v75, off
	v_mul_f32_e32 v68, 0xbfb8aa3b, v45
	v_exp_f32_e32 v68, v68
	s_nop 0
	v_add_f32_e32 v68, 1.0, v68
	v_div_scale_f32 v69, s[2:3], v68, v68, 1.0
	v_rcp_f32_e32 v75, v69
	s_nop 0
	v_fma_f32 v76, -v69, v75, 1.0
	v_fmac_f32_e32 v75, v76, v75
	v_div_scale_f32 v76, vcc, 1.0, v68, 1.0
	v_mul_f32_e32 v77, v76, v75
	v_fma_f32 v78, -v69, v77, v76
	v_fmac_f32_e32 v77, v78, v75
	v_fma_f32 v69, -v69, v77, v76
	v_div_fmas_f32 v69, v69, v75, v77
	v_div_fixup_f32 v68, v69, v68, 1.0
	v_cvt_f16_f32_e32 v75, v68
	v_add_u32_e32 v68, v85, v71
	v_mov_b32_e32 v69, v1
	v_lshl_add_u64 v[68:69], v[68:69], 1, s[94:95]
; DI int otid() { int t = threadIdx.x; asm volatile("" : "+v"(t)); return t; }
; DI bf16_t cv1(float x) { return (bf16_t)(pk2(x, 0.f) & 0xffffu); }
; DI int crow(int i, int h) { return (i & 3) + 8 * (i >> 2) + 4 * h; }
; DI float sigm(float x) { return 1.f / (1.f + __expf(-x)); }
;     DI void operator()(int unit, const f32x16 (&acc)[MT][NT]) const {
;     ...
;         else {
;             const int lane = otid() & 63, r = lane & 31, h = lane >> 5;
;             const int col0 = PC_GA + (unit - 36) * UW;
; #pragma unroll
;             for (int mi = 0; mi < MT; ++mi)
; #pragma unroll
;                 for (int nj = 0; nj < NT; ++nj)
; #pragma unroll
;                     for (int i = 0; i < 16; ++i) priv[(mi * 32 + crow(i, h) + (mi == 2 ? d2 : 0)) * PRIVW + col0 + nj * 32 + r] = cv1(sigm(acc[mi][nj][i]));
;         }
	global_store_short v[68:69], v75, off
	v_mul_f32_e32 v68, 0xbfb8aa3b, v46
	v_exp_f32_e32 v68, v68
	s_nop 0
	v_add_f32_e32 v68, 1.0, v68
	v_div_scale_f32 v69, s[2:3], v68, v68, 1.0
	v_rcp_f32_e32 v75, v69
	s_nop 0
	v_fma_f32 v76, -v69, v75, 1.0
	v_fmac_f32_e32 v75, v76, v75
	v_div_scale_f32 v76, vcc, 1.0, v68, 1.0
	v_mul_f32_e32 v77, v76, v75
	v_fma_f32 v78, -v69, v77, v76
	v_fmac_f32_e32 v77, v78, v75
	v_fma_f32 v69, -v69, v77, v76
	v_div_fmas_f32 v69, v69, v75, v77
	v_div_fixup_f32 v68, v69, v68, 1.0
	v_cvt_f16_f32_e32 v75, v68
	v_add_u32_e32 v68, v86, v71
	v_mov_b32_e32 v69, v1
	v_lshl_add_u64 v[68:69], v[68:69], 1, s[94:95]
	global_store_short v[68:69], v75, off
	v_mul_f32_e32 v68, 0xbfb8aa3b, v47
	v_exp_f32_e32 v68, v68
	s_nop 0
	v_add_f32_e32 v68, 1.0, v68
	v_div_scale_f32 v69, s[2:3], v68, v68, 1.0
	v_rcp_f32_e32 v75, v69
	s_nop 0
	v_fma_f32 v76, -v69, v75, 1.0
	v_fmac_f32_e32 v75, v76, v75
	v_div_scale_f32 v76, vcc, 1.0, v68, 1.0
	v_mul_f32_e32 v77, v76, v75
	v_fma_f32 v78, -v69, v77, v76
	v_fmac_f32_e32 v77, v78, v75
	v_fma_f32 v69, -v69, v77, v76
	v_div_fmas_f32 v69, v69, v75, v77
	v_div_fixup_f32 v68, v69, v68, 1.0
	v_cvt_f16_f32_e32 v75, v68
	v_add_u32_e32 v68, v87, v71
	v_mov_b32_e32 v69, v1
	v_lshl_add_u64 v[68:69], v[68:69], 1, s[94:95]
	global_store_short v[68:69], v75, off
	v_mul_f32_e32 v68, 0xbfb8aa3b, v48
	v_exp_f32_e32 v68, v68
	s_nop 0
	v_add_f32_e32 v68, 1.0, v68
	v_div_scale_f32 v69, s[2:3], v68, v68, 1.0
	v_rcp_f32_e32 v75, v69
	s_nop 0
	v_fma_f32 v76, -v69, v75, 1.0
	v_fmac_f32_e32 v75, v76, v75
	v_div_scale_f32 v76, vcc, 1.0, v68, 1.0
	v_mul_f32_e32 v77, v76, v75
	v_fma_f32 v78, -v69, v77, v76
	v_fmac_f32_e32 v77, v78, v75
	v_fma_f32 v69, -v69, v77, v76
	v_div_fmas_f32 v69, v69, v75, v77
	v_div_fixup_f32 v68, v69, v68, 1.0
	v_cvt_f16_f32_e32 v75, v68
	v_add_u32_e32 v68, v88, v71
	v_mov_b32_e32 v69, v1
	v_lshl_add_u64 v[68:69], v[68:69], 1, s[94:95]
	global_store_short v[68:69], v75, off
	v_mul_f32_e32 v68, 0xbfb8aa3b, v49
	v_exp_f32_e32 v68, v68
	s_nop 0
	v_add_f32_e32 v68, 1.0, v68
	v_div_scale_f32 v69, s[2:3], v68, v68, 1.0
	v_rcp_f32_e32 v75, v69
	s_nop 0
	v_fma_f32 v76, -v69, v75, 1.0
	v_fmac_f32_e32 v75, v76, v75
	v_div_scale_f32 v76, vcc, 1.0, v68, 1.0
	v_mul_f32_e32 v77, v76, v75
	v_fma_f32 v78, -v69, v77, v76
	v_fmac_f32_e32 v77, v78, v75
	v_fma_f32 v69, -v69, v77, v76
	v_div_fmas_f32 v69, v69, v75, v77
	v_div_fixup_f32 v68, v69, v68, 1.0
	v_cvt_f16_f32_e32 v75, v68
	v_add_u32_e32 v68, v89, v71
	v_mov_b32_e32 v69, v1
	v_lshl_add_u64 v[68:69], v[68:69], 1, s[94:95]
	global_store_short v[68:69], v75, off
	v_mul_f32_e32 v68, 0xbfb8aa3b, v18
	v_exp_f32_e32 v68, v68
	s_nop 0
	v_add_f32_e32 v68, 1.0, v68
	v_div_scale_f32 v69, s[2:3], v68, v68, 1.0
	v_rcp_f32_e32 v75, v69
	s_nop 0
	v_fma_f32 v76, -v69, v75, 1.0
	v_fmac_f32_e32 v75, v76, v75
	v_div_scale_f32 v76, vcc, 1.0, v68, 1.0
	v_mul_f32_e32 v77, v76, v75
	v_fma_f32 v78, -v69, v77, v76
	v_fmac_f32_e32 v77, v78, v75
	v_fma_f32 v69, -v69, v77, v76
	v_div_fmas_f32 v69, v69, v75, v77
	v_div_fixup_f32 v68, v69, v68, 1.0
	v_cvt_f16_f32_e32 v69, v68
	v_mad_u32_u24 v68, v0, s44, v205
	v_add_u32_e32 v76, v68, v70
	v_mov_b32_e32 v77, v1
	v_lshl_add_u64 v[76:77], v[76:77], 1, s[94:95]
	global_store_short v[76:77], v69, off
	v_mul_f32_e32 v69, 0xbfb8aa3b, v19
	v_exp_f32_e32 v69, v69
	s_nop 0
	v_add_f32_e32 v69, 1.0, v69
	v_div_scale_f32 v75, s[2:3], v69, v69, 1.0
	v_rcp_f32_e32 v76, v75
	s_nop 0
	v_fma_f32 v77, -v75, v76, 1.0
	v_fmac_f32_e32 v76, v77, v76
	v_div_scale_f32 v77, vcc, 1.0, v69, 1.0
	v_mul_f32_e32 v78, v77, v76
	v_fma_f32 v79, -v75, v78, v77
	v_fmac_f32_e32 v78, v79, v76
	v_fma_f32 v75, -v75, v78, v77
	v_div_fmas_f32 v75, v75, v76, v78
	v_div_fixup_f32 v69, v75, v69, 1.0
	v_cvt_f16_f32_e32 v75, v69
	v_mad_u32_u24 v69, v0, s44, v206
	v_add_u32_e32 v76, v69, v70
	v_mov_b32_e32 v77, v1
	v_lshl_add_u64 v[76:77], v[76:77], 1, s[94:95]
	global_store_short v[76:77], v75, off
	v_mul_f32_e32 v75, 0xbfb8aa3b, v20
	v_exp_f32_e32 v75, v75
	s_nop 0
	v_add_f32_e32 v75, 1.0, v75
	v_div_scale_f32 v76, s[2:3], v75, v75, 1.0
	v_rcp_f32_e32 v77, v76
	s_nop 0
	v_fma_f32 v78, -v76, v77, 1.0
	v_fmac_f32_e32 v77, v78, v77
	v_div_scale_f32 v78, vcc, 1.0, v75, 1.0
	v_mul_f32_e32 v79, v78, v77
	v_fma_f32 v80, -v76, v79, v78
	v_fmac_f32_e32 v79, v80, v77
	v_fma_f32 v76, -v76, v79, v78
	v_div_fmas_f32 v76, v76, v77, v79
	v_div_fixup_f32 v75, v76, v75, 1.0
	v_cvt_f16_f32_e32 v78, v75
	v_mad_u32_u24 v75, v0, s44, v207
	v_add_u32_e32 v76, v75, v70
	v_mov_b32_e32 v77, v1
	v_lshl_add_u64 v[76:77], v[76:77], 1, s[94:95]
	global_store_short v[76:77], v78, off
	v_mul_f32_e32 v76, 0xbfb8aa3b, v21
	v_exp_f32_e32 v76, v76
	s_nop 0
	v_add_f32_e32 v76, 1.0, v76
	v_div_scale_f32 v77, s[2:3], v76, v76, 1.0
	v_rcp_f32_e32 v78, v77
	s_nop 0
	v_fma_f32 v79, -v77, v78, 1.0
	v_fmac_f32_e32 v78, v79, v78
	v_div_scale_f32 v79, vcc, 1.0, v76, 1.0
	v_mul_f32_e32 v80, v79, v78
	v_fma_f32 v81, -v77, v80, v79
	v_fmac_f32_e32 v80, v81, v78
	v_fma_f32 v77, -v77, v80, v79
	v_div_fmas_f32 v77, v77, v78, v80
	v_div_fixup_f32 v76, v77, v76, 1.0
	v_cvt_f16_f32_e32 v77, v76
	v_or_b32_e32 v76, 0x30200, v74
	v_add_u32_e32 v78, v76, v70
	v_mov_b32_e32 v79, v1
	v_lshl_add_u64 v[78:79], v[78:79], 1, s[94:95]
	global_store_short v[78:79], v77, off
	v_mul_f32_e32 v77, 0xbfb8aa3b, v22
	v_exp_f32_e32 v77, v77
	v_or_b32_e32 v74, 0x38600, v74
	v_add_f32_e32 v77, 1.0, v77
	v_div_scale_f32 v78, s[2:3], v77, v77, 1.0
	v_rcp_f32_e32 v79, v78
	s_nop 0
	v_fma_f32 v80, -v78, v79, 1.0
	v_fmac_f32_e32 v79, v80, v79
	v_div_scale_f32 v80, vcc, 1.0, v77, 1.0
	v_mul_f32_e32 v81, v80, v79
	v_fma_f32 v82, -v78, v81, v80
	v_fmac_f32_e32 v81, v82, v79
; DI int otid() { int t = threadIdx.x; asm volatile("" : "+v"(t)); return t; }
; DI bf16_t cv1(float x) { return (bf16_t)(pk2(x, 0.f) & 0xffffu); }
; DI int crow(int i, int h) { return (i & 3) + 8 * (i >> 2) + 4 * h; }
; DI float sigm(float x) { return 1.f / (1.f + __expf(-x)); }
;     DI void operator()(int unit, const f32x16 (&acc)[MT][NT]) const {
;     ...
;         else {
;             const int lane = otid() & 63, r = lane & 31, h = lane >> 5;
;             const int col0 = PC_GA + (unit - 36) * UW;
; #pragma unroll
;             for (int mi = 0; mi < MT; ++mi)
; #pragma unroll
;                 for (int nj = 0; nj < NT; ++nj)
; #pragma unroll
;                     for (int i = 0; i < 16; ++i) priv[(mi * 32 + crow(i, h) + (mi == 2 ? d2 : 0)) * PRIVW + col0 + nj * 32 + r] = cv1(sigm(acc[mi][nj][i]));
;         }
	v_fma_f32 v78, -v78, v81, v80
	v_div_fmas_f32 v78, v78, v79, v81
	v_div_fixup_f32 v77, v78, v77, 1.0
	v_cvt_f16_f32_e32 v80, v77
	v_mad_u32_u24 v77, v0, s44, v208
	v_add_u32_e32 v78, v77, v70
	v_mov_b32_e32 v79, v1
	v_lshl_add_u64 v[78:79], v[78:79], 1, s[94:95]
	global_store_short v[78:79], v80, off
	v_mul_f32_e32 v78, 0xbfb8aa3b, v23
	v_exp_f32_e32 v78, v78
	s_nop 0
	v_add_f32_e32 v78, 1.0, v78
	v_div_scale_f32 v79, s[2:3], v78, v78, 1.0
	v_rcp_f32_e32 v80, v79
	s_nop 0
	v_fma_f32 v81, -v79, v80, 1.0
	v_fmac_f32_e32 v80, v81, v80
	v_div_scale_f32 v81, vcc, 1.0, v78, 1.0
	v_mul_f32_e32 v82, v81, v80
	v_fma_f32 v83, -v79, v82, v81
	v_fmac_f32_e32 v82, v83, v80
	v_fma_f32 v79, -v79, v82, v81
	v_div_fmas_f32 v79, v79, v80, v82
	v_div_fixup_f32 v78, v79, v78, 1.0
	v_cvt_f16_f32_e32 v80, v78
	v_add_u32_e32 v78, v74, v70
	v_mov_b32_e32 v79, v1
	v_lshl_add_u64 v[78:79], v[78:79], 1, s[94:95]
	global_store_short v[78:79], v80, off
	v_mul_f32_e32 v78, 0xbfb8aa3b, v24
	v_exp_f32_e32 v78, v78
	s_nop 0
	v_add_f32_e32 v78, 1.0, v78
	v_div_scale_f32 v79, s[2:3], v78, v78, 1.0
	v_rcp_f32_e32 v80, v79
	s_nop 0
	v_fma_f32 v81, -v79, v80, 1.0
	v_fmac_f32_e32 v80, v81, v80
	v_div_scale_f32 v81, vcc, 1.0, v78, 1.0
	v_mul_f32_e32 v82, v81, v80
	v_fma_f32 v83, -v79, v82, v81
	v_fmac_f32_e32 v82, v83, v80
	v_fma_f32 v79, -v79, v82, v81
	v_div_fmas_f32 v79, v79, v80, v82
	v_div_fixup_f32 v78, v79, v78, 1.0
	v_cvt_f16_f32_e32 v79, v78
	v_mad_u32_u24 v78, v0, s44, v209
	v_add_u32_e32 v80, v78, v70
	v_mov_b32_e32 v81, v1
	v_lshl_add_u64 v[80:81], v[80:81], 1, s[94:95]
	global_store_short v[80:81], v79, off
	v_mul_f32_e32 v79, 0xbfb8aa3b, v25
	v_exp_f32_e32 v79, v79
	s_nop 0
	v_add_f32_e32 v79, 1.0, v79
	v_div_scale_f32 v80, s[2:3], v79, v79, 1.0
	v_rcp_f32_e32 v81, v80
	s_nop 0
	v_fma_f32 v82, -v80, v81, 1.0
	v_fmac_f32_e32 v81, v82, v81
	v_div_scale_f32 v82, vcc, 1.0, v79, 1.0
	v_mul_f32_e32 v83, v82, v81
	v_fma_f32 v84, -v80, v83, v82
	v_fmac_f32_e32 v83, v84, v81
	v_fma_f32 v80, -v80, v83, v82
	v_div_fmas_f32 v80, v80, v81, v83
	v_div_fixup_f32 v79, v80, v79, 1.0
	v_cvt_f16_f32_e32 v82, v79
	v_mad_u32_u24 v79, v0, s44, v210
	v_add_u32_e32 v80, v79, v70
	v_mov_b32_e32 v81, v1
	v_lshl_add_u64 v[80:81], v[80:81], 1, s[94:95]
	global_store_short v[80:81], v82, off
	v_mul_f32_e32 v80, 0xbfb8aa3b, v26
	v_exp_f32_e32 v80, v80
	s_nop 0
	v_add_f32_e32 v80, 1.0, v80
	v_div_scale_f32 v81, s[2:3], v80, v80, 1.0
	v_rcp_f32_e32 v82, v81
	s_nop 0
	v_fma_f32 v83, -v81, v82, 1.0
	v_fmac_f32_e32 v82, v83, v82
	v_div_scale_f32 v83, vcc, 1.0, v80, 1.0
	v_mul_f32_e32 v84, v83, v82
	v_fma_f32 v85, -v81, v84, v83
	v_fmac_f32_e32 v84, v85, v82
	v_fma_f32 v81, -v81, v84, v83
	v_div_fmas_f32 v81, v81, v82, v84
	v_div_fixup_f32 v80, v81, v80, 1.0
	v_cvt_f16_f32_e32 v81, v80
	v_mad_u32_u24 v80, v0, s44, v211
	v_add_u32_e32 v82, v80, v70
	v_mov_b32_e32 v83, v1
	v_lshl_add_u64 v[82:83], v[82:83], 1, s[94:95]
	global_store_short v[82:83], v81, off
	v_mul_f32_e32 v81, 0xbfb8aa3b, v27
	v_exp_f32_e32 v81, v81
	s_nop 0
	v_add_f32_e32 v81, 1.0, v81
	v_div_scale_f32 v82, s[2:3], v81, v81, 1.0
	v_rcp_f32_e32 v83, v82
	s_nop 0
	v_fma_f32 v84, -v82, v83, 1.0
	v_fmac_f32_e32 v83, v84, v83
	v_div_scale_f32 v84, vcc, 1.0, v81, 1.0
	v_mul_f32_e32 v85, v84, v83
	v_fma_f32 v86, -v82, v85, v84
	v_fmac_f32_e32 v85, v86, v83
	v_fma_f32 v82, -v82, v85, v84
	v_div_fmas_f32 v82, v82, v83, v85
	v_div_fixup_f32 v81, v82, v81, 1.0
	v_cvt_f16_f32_e32 v84, v81
	v_mad_u32_u24 v81, v0, s44, v212
	v_add_u32_e32 v82, v81, v70
	v_mov_b32_e32 v83, v1
	v_lshl_add_u64 v[82:83], v[82:83], 1, s[94:95]
	global_store_short v[82:83], v84, off
	v_mul_f32_e32 v82, 0xbfb8aa3b, v28
	v_exp_f32_e32 v82, v82
	s_nop 0
	v_add_f32_e32 v82, 1.0, v82
	v_div_scale_f32 v83, s[2:3], v82, v82, 1.0
	v_rcp_f32_e32 v84, v83
	s_nop 0
	v_fma_f32 v85, -v83, v84, 1.0
	v_fmac_f32_e32 v84, v85, v84
	v_div_scale_f32 v85, vcc, 1.0, v82, 1.0
	v_mul_f32_e32 v86, v85, v84
	v_fma_f32 v87, -v83, v86, v85
	v_fmac_f32_e32 v86, v87, v84
	v_fma_f32 v83, -v83, v86, v85
	v_div_fmas_f32 v83, v83, v84, v86
	v_div_fixup_f32 v82, v83, v82, 1.0
	v_cvt_f16_f32_e32 v83, v82
	v_mad_u32_u24 v82, v0, s44, v213
	v_add_u32_e32 v84, v82, v70
	v_mov_b32_e32 v85, v1
	v_lshl_add_u64 v[84:85], v[84:85], 1, s[94:95]
	global_store_short v[84:85], v83, off
	v_mul_f32_e32 v83, 0xbfb8aa3b, v29
	v_exp_f32_e32 v83, v83
	s_nop 0
	v_add_f32_e32 v83, 1.0, v83
	v_div_scale_f32 v84, s[2:3], v83, v83, 1.0
	v_rcp_f32_e32 v85, v84
	s_nop 0
	v_fma_f32 v86, -v84, v85, 1.0
	v_fmac_f32_e32 v85, v86, v85
	v_div_scale_f32 v86, vcc, 1.0, v83, 1.0
	v_mul_f32_e32 v87, v86, v85
	v_fma_f32 v88, -v84, v87, v86
	v_fmac_f32_e32 v87, v88, v85
	v_fma_f32 v84, -v84, v87, v86
	v_div_fmas_f32 v84, v84, v85, v87
	v_div_fixup_f32 v83, v84, v83, 1.0
	v_cvt_f16_f32_e32 v86, v83
	v_mad_u32_u24 v83, v0, s44, v214
	v_add_u32_e32 v84, v83, v70
	v_mov_b32_e32 v85, v1
	v_lshl_add_u64 v[84:85], v[84:85], 1, s[94:95]
	global_store_short v[84:85], v86, off
	v_mul_f32_e32 v84, 0xbfb8aa3b, v30
	v_exp_f32_e32 v84, v84
	s_nop 0
	v_add_f32_e32 v84, 1.0, v84
	v_div_scale_f32 v85, s[2:3], v84, v84, 1.0
	v_rcp_f32_e32 v86, v85
	s_nop 0
	v_fma_f32 v87, -v85, v86, 1.0
	v_fmac_f32_e32 v86, v87, v86
	v_div_scale_f32 v87, vcc, 1.0, v84, 1.0
	v_mul_f32_e32 v88, v87, v86
	v_fma_f32 v89, -v85, v88, v87
	v_fmac_f32_e32 v88, v89, v86
	v_fma_f32 v85, -v85, v88, v87
	v_div_fmas_f32 v85, v85, v86, v88
	v_div_fixup_f32 v84, v85, v84, 1.0
	v_cvt_f16_f32_e32 v85, v84
	v_mad_u32_u24 v84, v0, s44, v215
	v_add_u32_e32 v86, v84, v70
	v_mov_b32_e32 v87, v1
	v_lshl_add_u64 v[86:87], v[86:87], 1, s[94:95]
	global_store_short v[86:87], v85, off
; DI int otid() { int t = threadIdx.x; asm volatile("" : "+v"(t)); return t; }
; DI bf16_t cv1(float x) { return (bf16_t)(pk2(x, 0.f) & 0xffffu); }
; DI int crow(int i, int h) { return (i & 3) + 8 * (i >> 2) + 4 * h; }
; DI float sigm(float x) { return 1.f / (1.f + __expf(-x)); }
;     DI void operator()(int unit, const f32x16 (&acc)[MT][NT]) const {
;     ...
;         else {
;             const int lane = otid() & 63, r = lane & 31, h = lane >> 5;
;             const int col0 = PC_GA + (unit - 36) * UW;
; #pragma unroll
;             for (int mi = 0; mi < MT; ++mi)
; #pragma unroll
;                 for (int nj = 0; nj < NT; ++nj)
; #pragma unroll
;                     for (int i = 0; i < 16; ++i) priv[(mi * 32 + crow(i, h) + (mi == 2 ? d2 : 0)) * PRIVW + col0 + nj * 32 + r] = cv1(sigm(acc[mi][nj][i]));
;         }
	v_mul_f32_e32 v85, 0xbfb8aa3b, v31
	v_exp_f32_e32 v85, v85
	s_nop 0
	v_add_f32_e32 v85, 1.0, v85
	v_div_scale_f32 v86, s[2:3], v85, v85, 1.0
	v_rcp_f32_e32 v87, v86
	s_nop 0
	v_fma_f32 v88, -v86, v87, 1.0
	v_fmac_f32_e32 v87, v88, v87
	v_div_scale_f32 v88, vcc, 1.0, v85, 1.0
	v_mul_f32_e32 v89, v88, v87
	v_fma_f32 v90, -v86, v89, v88
	v_fmac_f32_e32 v89, v90, v87
	v_fma_f32 v86, -v86, v89, v88
	v_div_fmas_f32 v86, v86, v87, v89
	v_div_fixup_f32 v85, v86, v85, 1.0
	v_cvt_f16_f32_e32 v88, v85
	v_mad_u32_u24 v85, v0, s44, v216
	v_add_u32_e32 v86, v85, v70
	v_mov_b32_e32 v87, v1
	v_lshl_add_u64 v[86:87], v[86:87], 1, s[94:95]
	global_store_short v[86:87], v88, off
	v_mul_f32_e32 v86, 0xbfb8aa3b, v32
	v_exp_f32_e32 v86, v86
	s_nop 0
	v_add_f32_e32 v86, 1.0, v86
	v_div_scale_f32 v87, s[2:3], v86, v86, 1.0
	v_rcp_f32_e32 v88, v87
	s_nop 0
	v_fma_f32 v89, -v87, v88, 1.0
	v_fmac_f32_e32 v88, v89, v88
	v_div_scale_f32 v89, vcc, 1.0, v86, 1.0
	v_mul_f32_e32 v90, v89, v88
	v_fma_f32 v91, -v87, v90, v89
	v_fmac_f32_e32 v90, v91, v88
	v_fma_f32 v87, -v87, v90, v89
	v_div_fmas_f32 v87, v87, v88, v90
	v_div_fixup_f32 v86, v87, v86, 1.0
	v_cvt_f16_f32_e32 v87, v86
	v_mad_u32_u24 v86, v0, s44, v217
	v_add_u32_e32 v88, v86, v70
	v_mov_b32_e32 v89, v1
	v_lshl_add_u64 v[88:89], v[88:89], 1, s[94:95]
	global_store_short v[88:89], v87, off
	v_mul_f32_e32 v87, 0xbfb8aa3b, v33
	v_exp_f32_e32 v87, v87
	v_mad_u32_u24 v0, v0, s44, v218
	v_add_f32_e32 v87, 1.0, v87
	v_div_scale_f32 v88, s[2:3], v87, v87, 1.0
	v_rcp_f32_e32 v89, v88
	s_nop 0
	v_fma_f32 v90, -v88, v89, 1.0
	v_fmac_f32_e32 v89, v90, v89
	v_div_scale_f32 v90, vcc, 1.0, v87, 1.0
	v_mul_f32_e32 v91, v90, v89
	v_fma_f32 v92, -v88, v91, v90
	v_fmac_f32_e32 v91, v92, v89
	v_fma_f32 v88, -v88, v91, v90
	v_div_fmas_f32 v88, v88, v89, v91
	v_div_fixup_f32 v87, v88, v87, 1.0
	v_add_u32_e32 v88, v0, v70
	v_mul_f32_e32 v70, 0xbfb8aa3b, v2
	v_exp_f32_e32 v70, v70
	v_cvt_f16_f32_e32 v87, v87
	v_mov_b32_e32 v89, v1
	v_lshl_add_u64 v[88:89], v[88:89], 1, s[94:95]
	v_add_f32_e32 v70, 1.0, v70
	global_store_short v[88:89], v87, off
	v_div_scale_f32 v87, s[2:3], v70, v70, 1.0
	v_rcp_f32_e32 v88, v87
	s_nop 0
	v_fma_f32 v89, -v87, v88, 1.0
	v_fmac_f32_e32 v88, v89, v88
	v_div_scale_f32 v89, vcc, 1.0, v70, 1.0
	v_mul_f32_e32 v90, v89, v88
	v_fma_f32 v91, -v87, v90, v89
	v_fmac_f32_e32 v90, v91, v88
	v_fma_f32 v87, -v87, v90, v89
	v_div_fmas_f32 v87, v87, v88, v90
	v_add_u32_e32 v88, v68, v71
	v_mul_f32_e32 v68, 0xbfb8aa3b, v3
	v_div_fixup_f32 v70, v87, v70, 1.0
	v_exp_f32_e32 v68, v68
	v_cvt_f16_f32_e32 v70, v70
	v_mov_b32_e32 v89, v1
	v_lshl_add_u64 v[88:89], v[88:89], 1, s[94:95]
	v_add_f32_e32 v68, 1.0, v68
	global_store_short v[88:89], v70, off
	v_div_scale_f32 v70, s[2:3], v68, v68, 1.0
	v_rcp_f32_e32 v87, v70
	s_nop 0
	v_fma_f32 v88, -v70, v87, 1.0
	v_fmac_f32_e32 v87, v88, v87
	v_div_scale_f32 v88, vcc, 1.0, v68, 1.0
	v_mul_f32_e32 v89, v88, v87
	v_fma_f32 v90, -v70, v89, v88
	v_fmac_f32_e32 v89, v90, v87
	v_fma_f32 v70, -v70, v89, v88
	v_div_fmas_f32 v70, v70, v87, v89
	v_div_fixup_f32 v68, v70, v68, 1.0
	v_cvt_f16_f32_e32 v70, v68
	v_add_u32_e32 v68, v69, v71
	v_mov_b32_e32 v69, v1
	v_lshl_add_u64 v[68:69], v[68:69], 1, s[94:95]
	global_store_short v[68:69], v70, off
	v_mul_f32_e32 v68, 0xbfb8aa3b, v4
	v_exp_f32_e32 v68, v68
	s_nop 0
	v_add_f32_e32 v68, 1.0, v68
	v_div_scale_f32 v69, s[2:3], v68, v68, 1.0
	v_rcp_f32_e32 v70, v69
	s_nop 0
	v_fma_f32 v87, -v69, v70, 1.0
	v_fmac_f32_e32 v70, v87, v70
	v_div_scale_f32 v87, vcc, 1.0, v68, 1.0
	v_mul_f32_e32 v88, v87, v70
	v_fma_f32 v89, -v69, v88, v87
	v_fmac_f32_e32 v88, v89, v70
	v_fma_f32 v69, -v69, v88, v87
	v_div_fmas_f32 v69, v69, v70, v88
	v_div_fixup_f32 v68, v69, v68, 1.0
	v_cvt_f16_f32_e32 v70, v68
	v_add_u32_e32 v68, v75, v71
	v_mov_b32_e32 v69, v1
	v_lshl_add_u64 v[68:69], v[68:69], 1, s[94:95]
	global_store_short v[68:69], v70, off
	v_mul_f32_e32 v68, 0xbfb8aa3b, v5
	v_exp_f32_e32 v68, v68
	s_nop 0
	v_add_f32_e32 v68, 1.0, v68
	v_div_scale_f32 v69, s[2:3], v68, v68, 1.0
	v_rcp_f32_e32 v70, v69
	s_nop 0
	v_fma_f32 v75, -v69, v70, 1.0
	v_fmac_f32_e32 v70, v75, v70
	v_div_scale_f32 v75, vcc, 1.0, v68, 1.0
	v_mul_f32_e32 v87, v75, v70
	v_fma_f32 v88, -v69, v87, v75
	v_fmac_f32_e32 v87, v88, v70
	v_fma_f32 v69, -v69, v87, v75
	v_div_fmas_f32 v69, v69, v70, v87
	v_div_fixup_f32 v68, v69, v68, 1.0
	v_cvt_f16_f32_e32 v70, v68
	v_add_u32_e32 v68, v76, v71
	v_mov_b32_e32 v69, v1
	v_lshl_add_u64 v[68:69], v[68:69], 1, s[94:95]
	global_store_short v[68:69], v70, off
	v_mul_f32_e32 v68, 0xbfb8aa3b, v6
	v_exp_f32_e32 v68, v68
	s_nop 0
	v_add_f32_e32 v68, 1.0, v68
	v_div_scale_f32 v69, s[2:3], v68, v68, 1.0
	v_rcp_f32_e32 v70, v69
	s_nop 0
	v_fma_f32 v75, -v69, v70, 1.0
	v_fmac_f32_e32 v70, v75, v70
	v_div_scale_f32 v75, vcc, 1.0, v68, 1.0
	v_mul_f32_e32 v76, v75, v70
	v_fma_f32 v87, -v69, v76, v75
	v_fmac_f32_e32 v76, v87, v70
	v_fma_f32 v69, -v69, v76, v75
	v_div_fmas_f32 v69, v69, v70, v76
	v_div_fixup_f32 v68, v69, v68, 1.0
	v_cvt_f16_f32_e32 v70, v68
	v_add_u32_e32 v68, v77, v71
	v_mov_b32_e32 v69, v1
	v_lshl_add_u64 v[68:69], v[68:69], 1, s[94:95]
	global_store_short v[68:69], v70, off
	v_mul_f32_e32 v68, 0xbfb8aa3b, v7
	v_exp_f32_e32 v68, v68
	s_nop 0
	v_add_f32_e32 v68, 1.0, v68
	v_div_scale_f32 v69, s[2:3], v68, v68, 1.0
	v_rcp_f32_e32 v70, v69
	s_nop 0
	v_fma_f32 v75, -v69, v70, 1.0
	v_fmac_f32_e32 v70, v75, v70
	v_div_scale_f32 v75, vcc, 1.0, v68, 1.0
	v_mul_f32_e32 v76, v75, v70
	v_fma_f32 v77, -v69, v76, v75
	v_fmac_f32_e32 v76, v77, v70
	v_fma_f32 v69, -v69, v76, v75
	v_div_fmas_f32 v69, v69, v70, v76
	v_div_fixup_f32 v68, v69, v68, 1.0
	v_cvt_f16_f32_e32 v70, v68
; DI int otid() { int t = threadIdx.x; asm volatile("" : "+v"(t)); return t; }
; DI bf16_t cv1(float x) { return (bf16_t)(pk2(x, 0.f) & 0xffffu); }
; DI int crow(int i, int h) { return (i & 3) + 8 * (i >> 2) + 4 * h; }
; DI float sigm(float x) { return 1.f / (1.f + __expf(-x)); }
;     DI void operator()(int unit, const f32x16 (&acc)[MT][NT]) const {
;     ...
;         else {
;             const int lane = otid() & 63, r = lane & 31, h = lane >> 5;
;             const int col0 = PC_GA + (unit - 36) * UW;
; #pragma unroll
;             for (int mi = 0; mi < MT; ++mi)
; #pragma unroll
;                 for (int nj = 0; nj < NT; ++nj)
; #pragma unroll
;                     for (int i = 0; i < 16; ++i) priv[(mi * 32 + crow(i, h) + (mi == 2 ? d2 : 0)) * PRIVW + col0 + nj * 32 + r] = cv1(sigm(acc[mi][nj][i]));
;         }
	v_add_u32_e32 v68, v74, v71
	v_mov_b32_e32 v69, v1
	v_lshl_add_u64 v[68:69], v[68:69], 1, s[94:95]
	global_store_short v[68:69], v70, off
	v_mul_f32_e32 v68, 0xbfb8aa3b, v8
	v_exp_f32_e32 v68, v68
	s_nop 0
	v_add_f32_e32 v68, 1.0, v68
	v_div_scale_f32 v69, s[2:3], v68, v68, 1.0
	v_rcp_f32_e32 v70, v69
	s_nop 0
	v_fma_f32 v74, -v69, v70, 1.0
	v_fmac_f32_e32 v70, v74, v70
	v_div_scale_f32 v74, vcc, 1.0, v68, 1.0
	v_mul_f32_e32 v75, v74, v70
	v_fma_f32 v76, -v69, v75, v74
	v_fmac_f32_e32 v75, v76, v70
	v_fma_f32 v69, -v69, v75, v74
	v_div_fmas_f32 v69, v69, v70, v75
	v_div_fixup_f32 v68, v69, v68, 1.0
	v_cvt_f16_f32_e32 v70, v68
	v_add_u32_e32 v68, v78, v71
	v_mov_b32_e32 v69, v1
	v_lshl_add_u64 v[68:69], v[68:69], 1, s[94:95]
	global_store_short v[68:69], v70, off
	v_mul_f32_e32 v68, 0xbfb8aa3b, v9
	v_exp_f32_e32 v68, v68
	s_nop 0
	v_add_f32_e32 v68, 1.0, v68
	v_div_scale_f32 v69, s[2:3], v68, v68, 1.0
	v_rcp_f32_e32 v70, v69
	s_nop 0
	v_fma_f32 v74, -v69, v70, 1.0
	v_fmac_f32_e32 v70, v74, v70
	v_div_scale_f32 v74, vcc, 1.0, v68, 1.0
	v_mul_f32_e32 v75, v74, v70
	v_fma_f32 v76, -v69, v75, v74
	v_fmac_f32_e32 v75, v76, v70
	v_fma_f32 v69, -v69, v75, v74
	v_div_fmas_f32 v69, v69, v70, v75
	v_div_fixup_f32 v68, v69, v68, 1.0
	v_cvt_f16_f32_e32 v70, v68
	v_add_u32_e32 v68, v79, v71
	v_mov_b32_e32 v69, v1
	v_lshl_add_u64 v[68:69], v[68:69], 1, s[94:95]
	global_store_short v[68:69], v70, off
	v_mul_f32_e32 v68, 0xbfb8aa3b, v10
	v_exp_f32_e32 v68, v68
	s_nop 0
	v_add_f32_e32 v68, 1.0, v68
	v_div_scale_f32 v69, s[2:3], v68, v68, 1.0
	v_rcp_f32_e32 v70, v69
	s_nop 0
	v_fma_f32 v74, -v69, v70, 1.0
	v_fmac_f32_e32 v70, v74, v70
	v_div_scale_f32 v74, vcc, 1.0, v68, 1.0
	v_mul_f32_e32 v75, v74, v70
	v_fma_f32 v76, -v69, v75, v74
	v_fmac_f32_e32 v75, v76, v70
	v_fma_f32 v69, -v69, v75, v74
	v_div_fmas_f32 v69, v69, v70, v75
	v_div_fixup_f32 v68, v69, v68, 1.0
	v_cvt_f16_f32_e32 v70, v68
	v_add_u32_e32 v68, v80, v71
	v_mov_b32_e32 v69, v1
	v_lshl_add_u64 v[68:69], v[68:69], 1, s[94:95]
	global_store_short v[68:69], v70, off
	v_mul_f32_e32 v68, 0xbfb8aa3b, v11
	v_exp_f32_e32 v68, v68
	s_nop 0
	v_add_f32_e32 v68, 1.0, v68
	v_div_scale_f32 v69, s[2:3], v68, v68, 1.0
	v_rcp_f32_e32 v70, v69
	s_nop 0
	v_fma_f32 v74, -v69, v70, 1.0
	v_fmac_f32_e32 v70, v74, v70
	v_div_scale_f32 v74, vcc, 1.0, v68, 1.0
	v_mul_f32_e32 v75, v74, v70
	v_fma_f32 v76, -v69, v75, v74
	v_fmac_f32_e32 v75, v76, v70
	v_fma_f32 v69, -v69, v75, v74
	v_div_fmas_f32 v69, v69, v70, v75
	v_div_fixup_f32 v68, v69, v68, 1.0
	v_cvt_f16_f32_e32 v70, v68
	v_add_u32_e32 v68, v81, v71
	v_mov_b32_e32 v69, v1
	v_lshl_add_u64 v[68:69], v[68:69], 1, s[94:95]
	global_store_short v[68:69], v70, off
	v_mul_f32_e32 v68, 0xbfb8aa3b, v12
	v_exp_f32_e32 v68, v68
	s_nop 0
	v_add_f32_e32 v68, 1.0, v68
	v_div_scale_f32 v69, s[2:3], v68, v68, 1.0
	v_rcp_f32_e32 v70, v69
	s_nop 0
	v_fma_f32 v74, -v69, v70, 1.0
	v_fmac_f32_e32 v70, v74, v70
	v_div_scale_f32 v74, vcc, 1.0, v68, 1.0
	v_mul_f32_e32 v75, v74, v70
	v_fma_f32 v76, -v69, v75, v74
	v_fmac_f32_e32 v75, v76, v70
	v_fma_f32 v69, -v69, v75, v74
	v_div_fmas_f32 v69, v69, v70, v75
	v_div_fixup_f32 v68, v69, v68, 1.0
	v_cvt_f16_f32_e32 v70, v68
	v_add_u32_e32 v68, v82, v71
	v_mov_b32_e32 v69, v1
	v_lshl_add_u64 v[68:69], v[68:69], 1, s[94:95]
	global_store_short v[68:69], v70, off
	v_mul_f32_e32 v68, 0xbfb8aa3b, v13
	v_exp_f32_e32 v68, v68
	s_nop 0
	v_add_f32_e32 v68, 1.0, v68
	v_div_scale_f32 v69, s[2:3], v68, v68, 1.0
	v_rcp_f32_e32 v70, v69
	s_nop 0
	v_fma_f32 v74, -v69, v70, 1.0
	v_fmac_f32_e32 v70, v74, v70
	v_div_scale_f32 v74, vcc, 1.0, v68, 1.0
	v_mul_f32_e32 v75, v74, v70
	v_fma_f32 v76, -v69, v75, v74
	v_fmac_f32_e32 v75, v76, v70
	v_fma_f32 v69, -v69, v75, v74
	v_div_fmas_f32 v69, v69, v70, v75
	v_div_fixup_f32 v68, v69, v68, 1.0
	v_cvt_f16_f32_e32 v70, v68
	v_add_u32_e32 v68, v83, v71
	v_mov_b32_e32 v69, v1
	v_lshl_add_u64 v[68:69], v[68:69], 1, s[94:95]
	global_store_short v[68:69], v70, off
	v_mul_f32_e32 v68, 0xbfb8aa3b, v14
	v_exp_f32_e32 v68, v68
	s_nop 0
	v_add_f32_e32 v68, 1.0, v68
	v_div_scale_f32 v69, s[2:3], v68, v68, 1.0
	v_rcp_f32_e32 v70, v69
	s_nop 0
	v_fma_f32 v74, -v69, v70, 1.0
	v_fmac_f32_e32 v70, v74, v70
	v_div_scale_f32 v74, vcc, 1.0, v68, 1.0
	v_mul_f32_e32 v75, v74, v70
	v_fma_f32 v76, -v69, v75, v74
	v_fmac_f32_e32 v75, v76, v70
	v_fma_f32 v69, -v69, v75, v74
	v_div_fmas_f32 v69, v69, v70, v75
	v_div_fixup_f32 v68, v69, v68, 1.0
	v_cvt_f16_f32_e32 v70, v68
	v_add_u32_e32 v68, v84, v71
	v_mov_b32_e32 v69, v1
	v_lshl_add_u64 v[68:69], v[68:69], 1, s[94:95]
	global_store_short v[68:69], v70, off
	v_mul_f32_e32 v68, 0xbfb8aa3b, v15
	v_exp_f32_e32 v68, v68
	s_nop 0
	v_add_f32_e32 v68, 1.0, v68
	v_div_scale_f32 v69, s[2:3], v68, v68, 1.0
	v_rcp_f32_e32 v70, v69
	s_nop 0
	v_fma_f32 v74, -v69, v70, 1.0
	v_fmac_f32_e32 v70, v74, v70
	v_div_scale_f32 v74, vcc, 1.0, v68, 1.0
	v_mul_f32_e32 v75, v74, v70
	v_fma_f32 v76, -v69, v75, v74
	v_fmac_f32_e32 v75, v76, v70
	v_fma_f32 v69, -v69, v75, v74
	v_div_fmas_f32 v69, v69, v70, v75
	v_div_fixup_f32 v68, v69, v68, 1.0
	v_cvt_f16_f32_e32 v70, v68
	v_add_u32_e32 v68, v85, v71
	v_mov_b32_e32 v69, v1
	v_lshl_add_u64 v[68:69], v[68:69], 1, s[94:95]
	global_store_short v[68:69], v70, off
	v_mul_f32_e32 v68, 0xbfb8aa3b, v16
	v_exp_f32_e32 v68, v68
	s_nop 0
	v_add_f32_e32 v68, 1.0, v68
	v_div_scale_f32 v69, s[2:3], v68, v68, 1.0
	v_rcp_f32_e32 v70, v69
	s_nop 0
	v_fma_f32 v74, -v69, v70, 1.0
	v_fmac_f32_e32 v70, v74, v70
	v_div_scale_f32 v74, vcc, 1.0, v68, 1.0
	v_mul_f32_e32 v75, v74, v70
	v_fma_f32 v76, -v69, v75, v74
	v_fmac_f32_e32 v75, v76, v70
	v_fma_f32 v69, -v69, v75, v74
	v_div_fmas_f32 v69, v69, v70, v75
	v_div_fixup_f32 v68, v69, v68, 1.0
	v_cvt_f16_f32_e32 v70, v68
	v_add_u32_e32 v68, v86, v71
	v_mov_b32_e32 v69, v1
	v_lshl_add_u64 v[68:69], v[68:69], 1, s[94:95]
	global_store_short v[68:69], v70, off
	v_mul_f32_e32 v68, 0xbfb8aa3b, v17
	v_exp_f32_e32 v68, v68
	s_nop 0
	v_add_f32_e32 v68, 1.0, v68
	v_div_scale_f32 v69, s[2:3], v68, v68, 1.0
	v_rcp_f32_e32 v70, v69
	s_mov_b64 s[2:3], 0
	v_fma_f32 v74, -v69, v70, 1.0
	v_fmac_f32_e32 v70, v74, v70
	v_div_scale_f32 v74, vcc, 1.0, v68, 1.0
	v_mul_f32_e32 v75, v74, v70
	v_fma_f32 v76, -v69, v75, v74
	v_fmac_f32_e32 v75, v76, v70
	v_fma_f32 v69, -v69, v75, v74
	v_div_fmas_f32 v69, v69, v70, v75
	v_div_fixup_f32 v68, v69, v68, 1.0
	v_cvt_f16_f32_e32 v70, v68
	v_add_u32_e32 v68, v0, v71
	v_mov_b32_e32 v69, v1
	v_lshl_add_u64 v[68:69], v[68:69], 1, s[94:95]
	global_store_short v[68:69], v70, off
